# ret_m3 and hg_m3 gate-row loads: 8 dwordx4 + v_permlane16_swap instead of 16 dwordx2 per item
# baseline (speedup 1.0000x reference)
; #define LAS __attribute__((address_space(3)))
; __device__ __forceinline__ float ret_lg(int h) { return log1pf(-exp2f(-5.0f - (float)h)); }
; __device__ __forceinline__ void w_store_vT(LAS bf16_t* vN, const bf16_t* src, int lane) {
; #pragma unroll
;     for (int i = 0; i < 8; ++i) { const int m = (lane >> 3) + 8 * i, e0 = 8 * (lane & 7); *(LAS u32x4*)(vN + m * LD + e0) = *(const u32x4*)(src + (size_t)m * NIN + e0); }
; }
; __device__ __forceinline__ void w_ret_m3(const Args& a, int l, unsigned char* ws, const bf16_t* proj, bf16_t* y, LAS unsigned char* wl, int b, int ck_, int h, int lane) {
;     LAS bf16_t* vT = (LAS bf16_t*)wl;
;     const int row0 = b * SEQ + 64 * ck_, lo = lane & 15, fq = lane >> 4; const float lg = ret_lg(h);
;     const float* cosT = (const float*)(ws + WS_ROPE); const float* sinT = cosT + SEQ * 32;
;     w_store_vT(vT, proj + (size_t)row0 * NIN + C_RV + 64 * h, lane);
.LBB0_187:
	s_lshr_b32 s20, s46, 8
	s_lshr_b32 s21, s46, 9
	s_add_i32 s20, s20, s46
	s_and_b32 s21, s21, 12
	s_add_i32 s20, s20, s21
	s_and_b32 s21, s20, 12
	s_cmp_lg_u32 s21, 8
	s_cbranch_scc1 .LBB0_186
	s_and_b32 s27, s20, 11
	s_ashr_i32 s20, s46, 31
	s_ashr_i32 s21, s46, 4
	s_lshr_b32 s20, s20, 25
	s_add_i32 s27, s27, -8
	s_add_i32 s24, s21, s20
	v_cvt_f32_u32_e32 v0, s27
	s_ashr_i32 s20, s24, 7
	s_and_b32 s24, s24, 0xffffff80
	s_sub_i32 s21, s21, s24
	s_lshl_b32 s24, s20, 13
	s_lshl_b32 s38, s21, 6
	s_add_i32 s34, s38, s24
	v_sub_f32_e32 v0, 0xc0a00000, v0
	s_mov_b32 s24, 0xc2fc0000
	v_cmp_gt_f32_e32 vcc, s24, v0
	s_and_b64 s[40:41], vcc, exec
	s_cselect_b32 s24, 0xffffffc0, 0
	v_cndmask_b32_e32 v1, 0, v204, vcc
	v_add_f32_e32 v0, v0, v1
	v_exp_f32_e32 v0, v0
	s_ashr_i32 s35, s34, 31
	s_mul_i32 s39, s34, 0x1800
	s_add_u32 s39, s8, s39
	v_ldexp_f32 v102, v0, s24
	v_sub_f32_e32 v2, 1.0, v102
	v_add_f32_e32 v0, -1.0, v2
	v_sub_f32_e32 v1, v0, v2
	v_add_f32_e32 v1, 1.0, v1
	v_sub_f32_e64 v0, -v102, v0
	v_add_f32_e32 v4, v0, v1
	v_frexp_mant_f32_e32 v0, v2
	v_cmp_gt_f32_e32 vcc, s77, v0
	v_cvt_f64_f32_e32 v[0:1], v2
	v_frexp_exp_i32_f64_e32 v0, v[0:1]
	v_subbrev_co_u32_e32 v10, vcc, 0, v0, vcc
	v_sub_u32_e32 v0, 0, v10
	v_ldexp_f32 v1, v2, v0
	v_add_f32_e32 v2, -1.0, v1
	v_add_f32_e32 v5, 1.0, v1
	v_ldexp_f32 v0, v4, v0
	v_add_f32_e32 v4, 1.0, v2
	v_add_f32_e32 v6, -1.0, v5
	v_sub_f32_e32 v4, v1, v4
	v_sub_f32_e32 v1, v1, v6
	v_add_f32_e32 v4, v0, v4
	v_add_f32_e32 v0, v0, v1
	v_add_f32_e32 v11, v5, v0
	v_rcp_f32_e32 v13, v11
	v_sub_f32_e32 v1, v11, v5
	v_sub_f32_e32 v12, v0, v1
	v_add_f32_e32 v1, v2, v4
	v_sub_f32_e32 v0, v1, v2
	v_mul_f32_e32 v14, v1, v13
	v_sub_f32_e32 v2, v4, v0
	v_mul_f32_e32 v4, v11, v14
	v_fma_f32 v6, v14, v11, -v4
	v_fmac_f32_e32 v6, v14, v12
	v_add_f32_e32 v0, v4, v6
	v_sub_f32_e32 v5, v1, v0
	v_pk_add_f32 v[8:9], v[0:1], v[4:5] neg_lo:[0,1] neg_hi:[0,1]
	v_mov_b32_e32 v7, v0
	v_pk_add_f32 v[0:1], v[8:9], v[6:7] neg_lo:[0,1] neg_hi:[0,1]
	s_mul_hi_i32 s24, s34, 0x1800
	v_add_f32_e32 v1, v2, v1
	v_add_f32_e32 v0, v0, v1
	v_add_f32_e32 v1, v5, v0
	v_mul_f32_e32 v2, v13, v1
	v_mul_f32_e32 v4, v11, v2
	v_fma_f32 v6, v2, v11, -v4
	v_fmac_f32_e32 v6, v2, v12
	v_sub_f32_e32 v5, v5, v1
	v_add_f32_e32 v11, v0, v5
	v_add_f32_e32 v0, v4, v6
	v_sub_f32_e32 v5, v1, v0
	v_pk_add_f32 v[8:9], v[0:1], v[4:5] neg_lo:[0,1] neg_hi:[0,1]
	v_mov_b32_e32 v7, v0
	v_pk_add_f32 v[0:1], v[8:9], v[6:7] neg_lo:[0,1] neg_hi:[0,1]
	v_mov_b32_e32 v101, v132
	v_add_f32_e32 v1, v11, v1
	v_add_f32_e32 v0, v0, v1
	v_add_f32_e32 v1, v14, v2
	v_add_f32_e32 v0, v5, v0
	v_sub_f32_e32 v4, v1, v14
	v_mul_f32_e32 v0, v13, v0
	v_sub_f32_e32 v2, v2, v4
	v_add_f32_e32 v2, v2, v0
	v_add_f32_e32 v4, v1, v2
	v_mul_f32_e32 v6, v4, v4
	v_fmamk_f32 v0, v6, 0x3e9b6dac, v201
	v_fmaak_f32 v169, v6, v0, 0x3f2aaada
	v_cvt_f32_i32_e32 v0, v10
	v_sub_f32_e32 v1, v4, v1
	v_sub_f32_e32 v1, v2, v1
	v_ldexp_f32 v2, v1, 1
	v_mul_f32_e32 v1, v4, v6
	v_pk_mul_f32 v[6:7], v[0:1], v[168:169]
	v_ldexp_f32 v5, v4, 1
	v_fma_f32 v4, v0, s94, -v6
	v_fmac_f32_e32 v4, 0xb102e308, v0
	v_pk_add_f32 v[8:9], v[6:7], v[4:5]
	v_mov_b32_e32 v10, v6
	v_sub_f32_e32 v0, v9, v5
	v_sub_f32_e32 v0, v7, v0
	v_add_f32_e32 v11, v2, v0
	v_pk_add_f32 v[6:7], v[8:9], v[6:7] neg_lo:[0,1] neg_hi:[0,1]
	v_pk_add_f32 v[12:13], v[8:9], v[10:11]
	v_mov_b32_e32 v5, v8
	v_mov_b32_e32 v7, v13
	v_pk_add_f32 v[0:1], v[4:5], v[6:7] neg_lo:[0,1] neg_hi:[0,1]
	v_pk_add_f32 v[4:5], v[4:5], v[6:7]
	v_mov_b32_e32 v16, v9
	v_pk_add_f32 v[6:7], v[4:5], v[8:9] op_sel:[1,0] op_sel_hi:[0,1] neg_lo:[0,1] neg_hi:[0,1]
	v_pk_add_f32 v[14:15], v[12:13], v[6:7] op_sel_hi:[1,0] neg_lo:[0,1] neg_hi:[0,1]
	v_mov_b32_e32 v12, v13
	v_mov_b32_e32 v13, v5
	v_mov_b32_e32 v17, v6
	v_pk_add_f32 v[6:7], v[12:13], v[16:17] neg_lo:[0,1] neg_hi:[0,1]
	v_mov_b32_e32 v10, v11
	v_mov_b32_e32 v11, v8
	v_pk_add_f32 v[6:7], v[10:11], v[6:7] neg_lo:[0,1] neg_hi:[0,1]
	v_mov_b32_e32 v14, v0
	v_pk_add_f32 v[14:15], v[14:15], v[6:7]
	s_addc_u32 s43, s9, s24
	s_lshl_b32 s24, s27, 6
	s_lshl_b32 s40, s27, 7
	v_pk_add_f32 v[8:9], v[14:15], v[14:15] op_sel:[0,1] op_sel_hi:[1,0]
	s_add_u32 s42, s39, s40
	v_lshlrev_b32_e32 v2, 4, v101
	v_pk_add_f32 v[12:13], v[4:5], v[8:9] op_sel:[1,0] op_sel_hi:[0,1]
	s_addc_u32 s43, s43, 0
	v_and_b32_e32 v2, 0x70, v2
	v_mov_b32_e32 v1, v5
	v_mov_b32_e32 v15, v12
	v_mov_b32_e32 v7, v8
	v_ashrrev_i32_e32 v10, 3, v101
	v_lshl_add_u64 v[8:9], s[42:43], 0, v[2:3]
	v_pk_add_f32 v[18:19], v[14:15], v[0:1] neg_lo:[0,1] neg_hi:[0,1]
	v_mad_i64_i32 v[4:5], s[44:45], v10, s72, v[8:9]
	v_pk_add_f32 v[16:17], v[6:7], v[18:19] neg_lo:[0,1] neg_hi:[0,1]
	global_load_dwordx4 v[222:225], v[4:5], off offset:3072
	v_add_u32_e32 v4, 8, v10
	v_mad_i64_i32 v[4:5], s[44:45], v4, s72, v[8:9]
	global_load_dwordx4 v[226:229], v[4:5], off offset:3072
	v_add_u32_e32 v4, 16, v10
	v_mad_i64_i32 v[4:5], s[44:45], v4, s72, v[8:9]
	global_load_dwordx4 v[230:233], v[4:5], off offset:3072
	v_add_u32_e32 v4, 24, v10
	v_mad_i64_i32 v[4:5], s[44:45], v4, s72, v[8:9]
	global_load_dwordx4 v[234:237], v[4:5], off offset:3072
	v_add_u32_e32 v4, 32, v10
	v_mad_i64_i32 v[4:5], s[44:45], v4, s72, v[8:9]
	global_load_dwordx4 v[238:241], v[4:5], off offset:3072
	v_add_u32_e32 v4, 40, v10
	v_mad_i64_i32 v[4:5], s[44:45], v4, s72, v[8:9]
	global_load_dwordx4 v[242:245], v[4:5], off offset:3072
	v_add_u32_e32 v4, 48, v10
	v_mad_i64_i32 v[4:5], s[44:45], v4, s72, v[8:9]
	global_load_dwordx4 v[246:249], v[4:5], off offset:3072
	v_add_u32_e32 v4, 56, v10
	v_mad_i64_i32 v[4:5], s[44:45], v4, s72, v[8:9]
	global_load_dwordx4 v[250:253], v[4:5], off offset:3072
	v_mul_lo_u32 v11, v10, s23
	v_add3_u32 v2, s2, v2, v11
	v_and_b32_e32 v133, 15, v101
	v_ashrrev_i32_e32 v100, 4, v101
	s_mov_b32 s41, s25
	v_or_b32_e32 v144, 16, v133
	v_or_b32_e32 v136, 32, v133
	v_or_b32_e32 v134, 48, v133
	s_lshl_b32 s20, s20, 9
	s_lshl_b32 s21, s21, 2
	s_add_i32 s21, s21, s20
	s_or_b32 s20, s27, s21
	s_ashr_i32 s21, s20, 31
	s_lshl_b64 s[20:21], s[20:21], 13
	s_waitcnt lgkmcnt(0)
; __device__ __forceinline__ void ld8bf(const bf16_t* p, float (&o)[8]) { unpack8(*(const u32x4*)p, o); }
; __device__ __forceinline__ bf16x8 pack_frag(const float (&v)[8]) { return __builtin_bit_cast(bf16x8, pack8(v)); }
; template <int KIND>
; __device__ __forceinline__ void w_m3_core(const bf16x8 (&Qf)[4][2], const bf16x8 (&Kf)[4][2], const bf16x8 (&Sf)[4][2], const LAS bf16_t* vT, float lg,
;                                           const bf16_t* gsrc, const float* nw, bf16_t* ydst, int lo, int fq) {
;     ...
;             const unsigned long long gw_ = *(const unsigned long long*)(gsrc + n * NIN + e0); const f32x4 w4 = *(const f32x4*)(nw + e0);
; __device__ __forceinline__ void w_ret_m3(const Args& a, int l, unsigned char* ws, const bf16_t* proj, bf16_t* y, LAS unsigned char* wl, int b, int ck_, int h, int lane) {
;     ...
;     for (int tb = 0; tb < 4; ++tb) { const int n = 16 * tb + lo; float x1[8], x2[8], o1[8], o2[8], cs[8], sn[8];
;         const float* cp_ = cosT + (64 * ck_ + n) * 32 + 8 * fq; const float* sp_ = sinT + (64 * ck_ + n) * 32 + 8 * fq;
; #pragma unroll
;         for (int j = 0; j < 8; ++j) { cs[j] = cp_[j]; sn[j] = sp_[j]; }
;         const bf16_t* qs = proj + (size_t)(row0 + n) * NIN + C_RQ + 64 * h + 8 * fq;
;         ld8bf(qs, x1); ld8bf(qs + 32, x2);
; #pragma unroll
;         for (int j = 0; j < 8; ++j) { o1[j] = x1[j] * cs[j] - x2[j] * sn[j]; o2[j] = x2[j] * cs[j] + x1[j] * sn[j]; }
;         Qf[tb][0] = pack_frag(o1); Qf[tb][1] = pack_frag(o2);
;         const bf16_t* ks = proj + (size_t)(row0 + n) * NIN + C_RK + 64 * h + 8 * fq;
;         ld8bf(ks, x1); ld8bf(ks + 32, x2);
; #pragma unroll
;         for (int j = 0; j < 8; ++j) { o1[j] = (x1[j] * cs[j] - x2[j] * sn[j]) * 0.125f; o2[j] = (x2[j] * cs[j] + x1[j] * sn[j]) * 0.125f; }
;         Kf[tb][0] = pack_frag(o1); Kf[tb][1] = pack_frag(o2);
	s_add_u32 s20, s48, s20
	s_addc_u32 s21, s49, s21
	v_cmp_gt_f32_e32 vcc, s95, v102
	v_lshlrev_b32_e32 v124, 2, v100
	v_add_u32_e32 v140, 16, v124
	v_lshlrev_b32_e32 v1, 3, v101
	v_not_b32_e32 v143, v124
	v_and_b32_e32 v1, 24, v1
	v_or_b32_e32 v141, 3, v124
	v_or_b32_e32 v142, 2, v124
	v_add_u32_e32 v104, s2, v1
	v_sub_u32_e32 v1, v133, v141
	v_cvt_f32_i32_e32 v1, v1
	v_ashrrev_i32_e32 v125, 31, v124
	v_mov_b32_e32 v186, v2
	v_lshlrev_b32_e32 v10, 3, v100
	v_ashrrev_i32_e32 v11, 31, v10
	v_or_b32_e32 v2, s38, v133
	v_lshlrev_b32_e32 v8, 5, v2
	v_lshlrev_b64 v[6:7], 2, v[10:11]
	v_ashrrev_i32_e32 v9, 31, v8
	v_lshl_add_u64 v[4:5], s[60:61], 0, v[6:7]
	v_lshl_add_u64 v[6:7], s[62:63], 0, v[6:7]
	v_lshlrev_b64 v[8:9], 2, v[8:9]
	v_lshl_add_u64 v[46:47], v[4:5], 0, v[8:9]
	v_lshl_add_u64 v[48:49], v[6:7], 0, v[8:9]
	v_or_b32_e32 v2, s34, v133
	v_mov_b64_e32 v[8:9], s[8:9]
	v_mad_i64_i32 v[20:21], s[44:45], v2, s72, v[8:9]
	v_lshl_add_u64 v[22:23], v[20:21], 0, s[40:41]
	v_lshlrev_b64 v[20:21], 1, v[10:11]
	v_lshl_add_u64 v[10:11], v[22:23], 0, v[20:21]
	global_load_dwordx4 v[22:25], v[10:11], off offset:2048
	global_load_dwordx4 v[26:29], v[10:11], off offset:2112
	global_load_dwordx4 v[30:33], v[10:11], off offset:2560
	global_load_dwordx4 v[34:37], v[10:11], off offset:2624
	global_load_dwordx4 v[38:41], v[46:47], off
	global_load_dwordx4 v[42:45], v[48:49], off
	global_load_dwordx4 v[174:177], v[46:47], off offset:16
	global_load_dwordx4 v[178:181], v[48:49], off offset:16
	s_waitcnt vmcnt(8)
	ds_write_b128 v186, v[222:225]
	ds_write_b128 v186, v[226:229] offset:1152
	ds_write_b128 v186, v[230:233] offset:2304
	ds_write_b128 v186, v[234:237] offset:3456
	ds_write_b128 v186, v[238:241] offset:4608
	ds_write_b128 v186, v[242:245] offset:5760
	ds_write_b128 v186, v[246:249] offset:6912
	ds_write_b128 v186, v[250:253] offset:8064
	v_lshlrev_b64 v[182:183], 1, v[124:125]
	v_lshl_add_u64 v[182:183], s[42:43], 0, v[182:183]
	v_and_b32_e32 v184, 16, v132
	v_lshrrev_b32_e32 v185, 1, v184
	v_add_u32_e32 v184, v184, v185
	v_mov_b32_e32 v185, 0
	v_lshl_add_u64 v[182:183], v[182:183], 0, v[184:185]
	v_mad_u64_u32 v[184:185], s[44:45], v133, s72, v[182:183]
	global_load_dwordx4 v[222:225], v[184:185], off offset:3584
	global_load_dwordx4 v[226:229], v[184:185], off offset:3648
	v_mad_u64_u32 v[184:185], s[44:45], v144, s72, v[182:183]
	global_load_dwordx4 v[230:233], v[184:185], off offset:3584
	global_load_dwordx4 v[234:237], v[184:185], off offset:3648
	v_mad_u64_u32 v[184:185], s[44:45], v136, s72, v[182:183]
	global_load_dwordx4 v[238:241], v[184:185], off offset:3584
	global_load_dwordx4 v[242:245], v[184:185], off offset:3648
	v_mad_u64_u32 v[184:185], s[44:45], v134, s72, v[182:183]
	global_load_dwordx4 v[246:249], v[184:185], off offset:3584
	global_load_dwordx4 v[250:253], v[184:185], off offset:3648
	v_mov_b32_e32 v184, 0x18000
	v_mov_b32_e32 v185, 0
	v_lshl_add_u64 v[182:183], v[10:11], 0, v[184:185]
	global_load_dwordx4 v[108:111], v[182:183], off offset:2048
	global_load_dwordx4 v[112:115], v[182:183], off offset:2112
	global_load_dwordx4 v[116:119], v[182:183], off offset:2560
	global_load_dwordx4 v[120:123], v[182:183], off offset:2624
	v_lshl_add_u64 v[182:183], v[182:183], 0, v[184:185]
	global_load_dwordx4 v[126:129], v[182:183], off offset:2048
	global_load_dwordx4 v[146:149], v[182:183], off offset:2112
	global_load_dwordx4 v[150:153], v[182:183], off offset:2560
	global_load_dwordx4 v[154:157], v[182:183], off offset:2624
	v_lshl_add_u64 v[182:183], v[182:183], 0, v[184:185]
	global_load_dwordx4 v[158:161], v[182:183], off offset:2048
	global_load_dwordx4 v[188:191], v[182:183], off offset:2112
	global_load_dwordx4 v[192:195], v[182:183], off offset:2560
	global_load_dwordx4 v[196:199], v[182:183], off offset:2624
	v_or_b32_e32 v2, s38, v144
	s_waitcnt vmcnt(20) lgkmcnt(0)
	v_lshlrev_b32_e32 v10, 16, v22
	v_lshlrev_b32_e32 v50, 16, v26
	v_and_b32_e32 v51, 0xffff0000, v26
	v_and_b32_e32 v11, 0xffff0000, v22
	v_pk_mul_f32 v[52:53], v[38:39], v[50:51]
	v_pk_mul_f32 v[50:51], v[42:43], v[50:51]
	v_pk_fma_f32 v[52:53], v[42:43], v[10:11], v[52:53]
	v_pk_fma_f32 v[10:11], v[38:39], v[10:11], v[50:51] neg_lo:[0,0,1] neg_hi:[0,0,1]
	v_lshlrev_b32_e32 v50, 16, v34
	v_and_b32_e32 v51, 0xffff0000, v34
	v_cvt_pk_bf16_f32 v96, v10, v11
	v_cvt_pk_bf16_f32 v92, v52, v53
	v_lshlrev_b32_e32 v10, 16, v30
	v_and_b32_e32 v11, 0xffff0000, v30
	v_pk_mul_f32 v[52:53], v[38:39], v[50:51]
	v_lshlrev_b32_e32 v26, 16, v27
	v_pk_fma_f32 v[52:53], v[42:43], v[10:11], v[52:53]
	v_pk_mul_f32 v[42:43], v[42:43], v[50:51]
	v_and_b32_e32 v27, 0xffff0000, v27
	v_pk_fma_f32 v[10:11], v[38:39], v[10:11], v[42:43] neg_lo:[0,0,1] neg_hi:[0,0,1]
	v_lshlrev_b32_e32 v22, 16, v23
	v_and_b32_e32 v23, 0xffff0000, v23
	v_pk_mul_f32 v[38:39], v[40:41], v[26:27]
	v_pk_mul_f32 v[26:27], v[44:45], v[26:27]
	v_pk_fma_f32 v[38:39], v[44:45], v[22:23], v[38:39]
	v_pk_fma_f32 v[22:23], v[40:41], v[22:23], v[26:27] neg_lo:[0,0,1] neg_hi:[0,0,1]
	v_lshlrev_b32_e32 v26, 16, v35
	v_and_b32_e32 v27, 0xffff0000, v35
	v_cvt_pk_bf16_f32 v97, v22, v23
	v_lshlrev_b32_e32 v22, 16, v31
	v_and_b32_e32 v23, 0xffff0000, v31
	v_pk_mul_f32 v[30:31], v[40:41], v[26:27]
	v_pk_mul_f32 v[26:27], v[44:45], v[26:27]
	v_cvt_pk_bf16_f32 v93, v38, v39
	v_pk_fma_f32 v[30:31], v[44:45], v[22:23], v[30:31]
	v_pk_fma_f32 v[22:23], v[40:41], v[22:23], v[26:27] neg_lo:[0,0,1] neg_hi:[0,0,1]
	v_mov_b64_e32 v[38:39], v[174:175]
	v_mov_b64_e32 v[40:41], v[176:177]
	v_mov_b64_e32 v[42:43], v[178:179]
	v_mov_b64_e32 v[44:45], v[180:181]
	v_lshlrev_b32_e32 v34, 16, v28
	v_and_b32_e32 v35, 0xffff0000, v28
	v_lshlrev_b32_e32 v26, 16, v24
	v_and_b32_e32 v27, 0xffff0000, v24
	v_lshlrev_b32_e32 v28, 16, v29
	v_and_b32_e32 v29, 0xffff0000, v29
	v_pk_mul_f32 v[10:11], v[10:11], s[16:17] op_sel_hi:[1,0]
	v_lshlrev_b32_e32 v24, 16, v25
	v_and_b32_e32 v25, 0xffff0000, v25
	v_pk_mul_f32 v[22:23], v[22:23], s[16:17] op_sel_hi:[1,0]
	v_cvt_pk_bf16_f32 v64, v10, v11
	v_lshlrev_b32_e32 v10, 5, v2
	v_or_b32_e32 v2, s34, v144
	v_cvt_pk_bf16_f32 v65, v22, v23
	v_mad_i64_i32 v[22:23], s[44:45], v2, s72, v[8:9]
	v_ashrrev_i32_e32 v11, 31, v10
	v_lshl_add_u64 v[22:23], v[22:23], 0, s[40:41]
	v_pk_mul_f32 v[30:31], v[30:31], s[16:17] op_sel_hi:[1,0]
	v_lshlrev_b64 v[10:11], 2, v[10:11]
	v_cvt_pk_bf16_f32 v73, v30, v31
	v_or_b32_e32 v2, s38, v136
	v_pk_mul_f32 v[52:53], v[52:53], s[16:17] op_sel_hi:[1,0]
	s_waitcnt vmcnt(0) lgkmcnt(0)
; __device__ __forceinline__ void ld8bf(const bf16_t* p, float (&o)[8]) { unpack8(*(const u32x4*)p, o); }
; __device__ __forceinline__ bf16x8 pack_frag(const float (&v)[8]) { return __builtin_bit_cast(bf16x8, pack8(v)); }
; __device__ __forceinline__ void w_ret_m3(const Args& a, int l, unsigned char* ws, const bf16_t* proj, bf16_t* y, LAS unsigned char* wl, int b, int ck_, int h, int lane) {
;     ...
;     for (int tb = 0; tb < 4; ++tb) { const int n = 16 * tb + lo; float x1[8], x2[8], o1[8], o2[8], cs[8], sn[8];
;         const float* cp_ = cosT + (64 * ck_ + n) * 32 + 8 * fq; const float* sp_ = sinT + (64 * ck_ + n) * 32 + 8 * fq;
; #pragma unroll
;         for (int j = 0; j < 8; ++j) { cs[j] = cp_[j]; sn[j] = sp_[j]; }
;         const bf16_t* qs = proj + (size_t)(row0 + n) * NIN + C_RQ + 64 * h + 8 * fq;
;         ld8bf(qs, x1); ld8bf(qs + 32, x2);
; #pragma unroll
;         for (int j = 0; j < 8; ++j) { o1[j] = x1[j] * cs[j] - x2[j] * sn[j]; o2[j] = x2[j] * cs[j] + x1[j] * sn[j]; }
;         Qf[tb][0] = pack_frag(o1); Qf[tb][1] = pack_frag(o2);
;         const bf16_t* ks = proj + (size_t)(row0 + n) * NIN + C_RK + 64 * h + 8 * fq;
;         ld8bf(ks, x1); ld8bf(ks + 32, x2);
; #pragma unroll
;         for (int j = 0; j < 8; ++j) { o1[j] = (x1[j] * cs[j] - x2[j] * sn[j]) * 0.125f; o2[j] = (x2[j] * cs[j] + x1[j] * sn[j]) * 0.125f; }
;         Kf[tb][0] = pack_frag(o1); Kf[tb][1] = pack_frag(o2);
	v_pk_mul_f32 v[46:47], v[38:39], v[34:35]
	v_pk_mul_f32 v[34:35], v[42:43], v[34:35]
	v_pk_fma_f32 v[46:47], v[42:43], v[26:27], v[46:47]
	v_pk_fma_f32 v[26:27], v[38:39], v[26:27], v[34:35] neg_lo:[0,0,1] neg_hi:[0,0,1]
	v_lshlrev_b32_e32 v34, 16, v36
	v_and_b32_e32 v35, 0xffff0000, v36
	v_cvt_pk_bf16_f32 v98, v26, v27
	v_cvt_pk_bf16_f32 v94, v46, v47
	v_lshlrev_b32_e32 v26, 16, v32
	v_and_b32_e32 v27, 0xffff0000, v32
	v_pk_mul_f32 v[46:47], v[38:39], v[34:35]
	v_pk_mul_f32 v[34:35], v[42:43], v[34:35]
	v_pk_fma_f32 v[46:47], v[42:43], v[26:27], v[46:47]
	v_pk_fma_f32 v[26:27], v[38:39], v[26:27], v[34:35] neg_lo:[0,0,1] neg_hi:[0,0,1]
	v_pk_mul_f32 v[34:35], v[40:41], v[28:29]
	v_pk_mul_f32 v[28:29], v[44:45], v[28:29]
	v_pk_fma_f32 v[34:35], v[44:45], v[24:25], v[34:35]
	v_pk_fma_f32 v[24:25], v[40:41], v[24:25], v[28:29] neg_lo:[0,0,1] neg_hi:[0,0,1]
	v_lshlrev_b32_e32 v28, 16, v37
	v_and_b32_e32 v29, 0xffff0000, v37
	v_cvt_pk_bf16_f32 v99, v24, v25
	v_lshlrev_b32_e32 v24, 16, v33
	v_and_b32_e32 v25, 0xffff0000, v33
	v_pk_mul_f32 v[32:33], v[40:41], v[28:29]
	v_pk_mul_f32 v[28:29], v[44:45], v[28:29]
	v_pk_fma_f32 v[32:33], v[44:45], v[24:25], v[32:33]
	v_pk_fma_f32 v[24:25], v[40:41], v[24:25], v[28:29] neg_lo:[0,0,1] neg_hi:[0,0,1]
	v_pk_mul_f32 v[46:47], v[46:47], s[16:17] op_sel_hi:[1,0]
	v_pk_mul_f32 v[26:27], v[26:27], s[16:17] op_sel_hi:[1,0]
	v_cvt_pk_bf16_f32 v95, v34, v35
	v_pk_mul_f32 v[32:33], v[32:33], s[16:17] op_sel_hi:[1,0]
	v_pk_mul_f32 v[24:25], v[24:25], s[16:17] op_sel_hi:[1,0]
	v_lshl_add_u64 v[34:35], v[22:23], 0, v[20:21]
	v_cvt_pk_bf16_f32 v66, v26, v27
	v_cvt_pk_bf16_f32 v67, v24, v25
	v_cvt_pk_bf16_f32 v74, v46, v47
	v_cvt_pk_bf16_f32 v75, v32, v33
	v_lshl_add_u64 v[46:47], v[4:5], 0, v[10:11]
	v_lshl_add_u64 v[10:11], v[6:7], 0, v[10:11]
	v_mov_b64_e32 v[22:23], v[108:109]
	v_mov_b64_e32 v[24:25], v[110:111]
	v_mov_b64_e32 v[26:27], v[112:113]
	v_mov_b64_e32 v[28:29], v[114:115]
	v_mov_b64_e32 v[30:31], v[116:117]
	v_mov_b64_e32 v[32:33], v[118:119]
	s_nop 0
	v_mov_b64_e32 v[34:35], v[120:121]
	v_mov_b64_e32 v[36:37], v[122:123]
	s_nop 0
	global_load_dwordx2 v[42:43], v[46:47], off
	global_load_dwordx4 v[38:41], v[10:11], off
	global_load_dwordx4 v[174:177], v[46:47], off offset:8
	global_load_dwordx4 v[178:181], v[10:11], off offset:16
	global_load_dwordx2 v[182:183], v[46:47], off offset:24
	v_cvt_pk_bf16_f32 v72, v52, v53
	s_waitcnt vmcnt(0) lgkmcnt(0)
	v_lshlrev_b32_e32 v44, 16, v22
	v_lshlrev_b32_e32 v48, 16, v26
	v_and_b32_e32 v49, 0xffff0000, v26
	v_and_b32_e32 v45, 0xffff0000, v22
	v_pk_mul_f32 v[50:51], v[42:43], v[48:49]
	v_pk_mul_f32 v[48:49], v[38:39], v[48:49]
	v_pk_fma_f32 v[50:51], v[38:39], v[44:45], v[50:51]
	v_pk_fma_f32 v[44:45], v[42:43], v[44:45], v[48:49] neg_lo:[0,0,1] neg_hi:[0,0,1]
	v_lshlrev_b32_e32 v48, 16, v34
	v_and_b32_e32 v49, 0xffff0000, v34
	v_cvt_pk_bf16_f32 v88, v44, v45
	v_cvt_pk_bf16_f32 v84, v50, v51
	v_lshlrev_b32_e32 v44, 16, v30
	v_and_b32_e32 v45, 0xffff0000, v30
	v_pk_mul_f32 v[50:51], v[42:43], v[48:49]
	v_lshlrev_b32_e32 v26, 16, v27
	v_pk_fma_f32 v[50:51], v[38:39], v[44:45], v[50:51]
	v_pk_mul_f32 v[38:39], v[38:39], v[48:49]
	v_and_b32_e32 v27, 0xffff0000, v27
	v_pk_fma_f32 v[38:39], v[42:43], v[44:45], v[38:39] neg_lo:[0,0,1] neg_hi:[0,0,1]
	v_mov_b64_e32 v[42:43], v[174:175]
	v_mov_b64_e32 v[44:45], v[176:177]
	v_pk_mul_f32 v[48:49], v[38:39], s[16:17] op_sel_hi:[1,0]
	v_lshlrev_b32_e32 v22, 16, v23
	v_and_b32_e32 v23, 0xffff0000, v23
	v_pk_mul_f32 v[50:51], v[50:51], s[16:17] op_sel_hi:[1,0]
	v_cvt_pk_bf16_f32 v60, v48, v49
	v_cvt_pk_bf16_f32 v68, v50, v51
	s_waitcnt vmcnt(0) lgkmcnt(0)
	v_pk_mul_f32 v[38:39], v[42:43], v[26:27]
	v_pk_mul_f32 v[26:27], v[40:41], v[26:27]
	v_pk_fma_f32 v[38:39], v[40:41], v[22:23], v[38:39]
	v_pk_fma_f32 v[22:23], v[42:43], v[22:23], v[26:27] neg_lo:[0,0,1] neg_hi:[0,0,1]
	v_lshlrev_b32_e32 v26, 16, v35
	v_and_b32_e32 v27, 0xffff0000, v35
	v_cvt_pk_bf16_f32 v89, v22, v23
	v_lshlrev_b32_e32 v22, 16, v31
	v_and_b32_e32 v23, 0xffff0000, v31
	v_pk_mul_f32 v[30:31], v[42:43], v[26:27]
	v_cvt_pk_bf16_f32 v85, v38, v39
	v_pk_fma_f32 v[30:31], v[40:41], v[22:23], v[30:31]
	v_pk_mul_f32 v[26:27], v[40:41], v[26:27]
	v_mov_b64_e32 v[38:39], v[178:179]
	v_mov_b64_e32 v[40:41], v[180:181]
	v_pk_fma_f32 v[22:23], v[42:43], v[22:23], v[26:27] neg_lo:[0,0,1] neg_hi:[0,0,1]
	v_lshlrev_b32_e32 v26, 16, v28
	v_and_b32_e32 v27, 0xffff0000, v28
	v_lshlrev_b32_e32 v10, 16, v24
	v_and_b32_e32 v11, 0xffff0000, v24
	v_pk_mul_f32 v[34:35], v[44:45], v[26:27]
	v_lshlrev_b32_e32 v28, 16, v29
	v_and_b32_e32 v29, 0xffff0000, v29
	v_lshlrev_b32_e32 v24, 16, v25
	v_and_b32_e32 v25, 0xffff0000, v25
	v_pk_mul_f32 v[22:23], v[22:23], s[16:17] op_sel_hi:[1,0]
	v_pk_mul_f32 v[30:31], v[30:31], s[16:17] op_sel_hi:[1,0]
	v_cvt_pk_bf16_f32 v61, v22, v23
	v_cvt_pk_bf16_f32 v69, v30, v31
	s_waitcnt vmcnt(0) lgkmcnt(0)
	v_pk_mul_f32 v[26:27], v[38:39], v[26:27]
	v_pk_fma_f32 v[34:35], v[38:39], v[10:11], v[34:35]
	v_pk_fma_f32 v[10:11], v[44:45], v[10:11], v[26:27] neg_lo:[0,0,1] neg_hi:[0,0,1]
	v_lshlrev_b32_e32 v26, 16, v36
	v_and_b32_e32 v27, 0xffff0000, v36
	v_cvt_pk_bf16_f32 v90, v10, v11
	v_cvt_pk_bf16_f32 v86, v34, v35
	v_lshlrev_b32_e32 v10, 16, v32
	v_and_b32_e32 v11, 0xffff0000, v32
	v_pk_mul_f32 v[34:35], v[44:45], v[26:27]
	v_pk_mul_f32 v[26:27], v[38:39], v[26:27]
	v_pk_fma_f32 v[34:35], v[38:39], v[10:11], v[34:35]
	v_pk_fma_f32 v[10:11], v[44:45], v[10:11], v[26:27] neg_lo:[0,0,1] neg_hi:[0,0,1]
	v_mov_b64_e32 v[26:27], v[182:183]
	v_pk_mul_f32 v[10:11], v[10:11], s[16:17] op_sel_hi:[1,0]
	v_pk_mul_f32 v[34:35], v[34:35], s[16:17] op_sel_hi:[1,0]
	v_cvt_pk_bf16_f32 v62, v10, v11
	v_lshlrev_b32_e32 v10, 5, v2
	v_or_b32_e32 v2, s34, v136
	v_mad_i64_i32 v[22:23], s[44:45], v2, s72, v[8:9]
	v_ashrrev_i32_e32 v11, 31, v10
	v_lshl_add_u64 v[22:23], v[22:23], 0, s[40:41]
	v_cvt_pk_bf16_f32 v70, v34, v35
	v_lshlrev_b64 v[10:11], 2, v[10:11]
	v_lshl_add_u64 v[34:35], v[22:23], 0, v[20:21]
	v_lshl_add_u64 v[46:47], v[4:5], 0, v[10:11]
	v_lshl_add_u64 v[10:11], v[6:7], 0, v[10:11]
	v_or_b32_e32 v2, s38, v134
	s_waitcnt vmcnt(0) lgkmcnt(0)
; __device__ __forceinline__ void ld8bf(const bf16_t* p, float (&o)[8]) { unpack8(*(const u32x4*)p, o); }
; __device__ __forceinline__ bf16x8 pack_frag(const float (&v)[8]) { return __builtin_bit_cast(bf16x8, pack8(v)); }
; __device__ __forceinline__ void w_ret_m3(const Args& a, int l, unsigned char* ws, const bf16_t* proj, bf16_t* y, LAS unsigned char* wl, int b, int ck_, int h, int lane) {
;     ...
;     for (int tb = 0; tb < 4; ++tb) { const int n = 16 * tb + lo; float x1[8], x2[8], o1[8], o2[8], cs[8], sn[8];
;         const float* cp_ = cosT + (64 * ck_ + n) * 32 + 8 * fq; const float* sp_ = sinT + (64 * ck_ + n) * 32 + 8 * fq;
; #pragma unroll
;         for (int j = 0; j < 8; ++j) { cs[j] = cp_[j]; sn[j] = sp_[j]; }
;         const bf16_t* qs = proj + (size_t)(row0 + n) * NIN + C_RQ + 64 * h + 8 * fq;
;         ld8bf(qs, x1); ld8bf(qs + 32, x2);
; #pragma unroll
;         for (int j = 0; j < 8; ++j) { o1[j] = x1[j] * cs[j] - x2[j] * sn[j]; o2[j] = x2[j] * cs[j] + x1[j] * sn[j]; }
;         Qf[tb][0] = pack_frag(o1); Qf[tb][1] = pack_frag(o2);
;         const bf16_t* ks = proj + (size_t)(row0 + n) * NIN + C_RK + 64 * h + 8 * fq;
;         ld8bf(ks, x1); ld8bf(ks + 32, x2);
; #pragma unroll
;         for (int j = 0; j < 8; ++j) { o1[j] = (x1[j] * cs[j] - x2[j] * sn[j]) * 0.125f; o2[j] = (x2[j] * cs[j] + x1[j] * sn[j]) * 0.125f; }
;         Kf[tb][0] = pack_frag(o1); Kf[tb][1] = pack_frag(o2);
	v_pk_mul_f32 v[38:39], v[26:27], v[28:29]
	v_pk_mul_f32 v[28:29], v[40:41], v[28:29]
	v_pk_fma_f32 v[38:39], v[40:41], v[24:25], v[38:39]
	v_pk_fma_f32 v[24:25], v[26:27], v[24:25], v[28:29] neg_lo:[0,0,1] neg_hi:[0,0,1]
	v_lshlrev_b32_e32 v28, 16, v37
	v_and_b32_e32 v29, 0xffff0000, v37
	v_cvt_pk_bf16_f32 v91, v24, v25
	v_lshlrev_b32_e32 v24, 16, v33
	v_and_b32_e32 v25, 0xffff0000, v33
	v_pk_mul_f32 v[32:33], v[26:27], v[28:29]
	v_pk_mul_f32 v[28:29], v[40:41], v[28:29]
	v_pk_fma_f32 v[32:33], v[40:41], v[24:25], v[32:33]
	v_pk_fma_f32 v[24:25], v[26:27], v[24:25], v[28:29] neg_lo:[0,0,1] neg_hi:[0,0,1]
	v_pk_mul_f32 v[32:33], v[32:33], s[16:17] op_sel_hi:[1,0]
	v_pk_mul_f32 v[24:25], v[24:25], s[16:17] op_sel_hi:[1,0]
	v_cvt_pk_bf16_f32 v87, v38, v39
	v_cvt_pk_bf16_f32 v63, v24, v25
	v_cvt_pk_bf16_f32 v71, v32, v33
	v_mov_b64_e32 v[22:23], v[126:127]
	v_mov_b64_e32 v[24:25], v[128:129]
	v_mov_b64_e32 v[26:27], v[146:147]
	v_mov_b64_e32 v[28:29], v[148:149]
	v_mov_b64_e32 v[30:31], v[150:151]
	v_mov_b64_e32 v[32:33], v[152:153]
	s_nop 0
	v_mov_b64_e32 v[34:35], v[154:155]
	v_mov_b64_e32 v[36:37], v[156:157]
	s_nop 0
	global_load_dwordx4 v[38:41], v[46:47], off
	global_load_dwordx4 v[42:45], v[10:11], off
	global_load_dwordx4 v[174:177], v[46:47], off offset:16
	global_load_dwordx4 v[178:181], v[10:11], off offset:16
	s_waitcnt vmcnt(0) lgkmcnt(0)
	v_lshlrev_b32_e32 v48, 16, v22
	v_lshlrev_b32_e32 v50, 16, v26
	v_and_b32_e32 v51, 0xffff0000, v26
	v_and_b32_e32 v49, 0xffff0000, v22
	v_pk_mul_f32 v[52:53], v[38:39], v[50:51]
	v_pk_mul_f32 v[50:51], v[42:43], v[50:51]
	v_pk_fma_f32 v[52:53], v[42:43], v[48:49], v[52:53]
	v_pk_fma_f32 v[48:49], v[38:39], v[48:49], v[50:51] neg_lo:[0,0,1] neg_hi:[0,0,1]
	v_lshlrev_b32_e32 v50, 16, v34
	v_and_b32_e32 v51, 0xffff0000, v34
	v_cvt_pk_bf16_f32 v80, v48, v49
	v_cvt_pk_bf16_f32 v76, v52, v53
	v_lshlrev_b32_e32 v48, 16, v30
	v_and_b32_e32 v49, 0xffff0000, v30
	v_pk_mul_f32 v[52:53], v[38:39], v[50:51]
	v_lshlrev_b32_e32 v26, 16, v27
	v_pk_fma_f32 v[52:53], v[42:43], v[48:49], v[52:53]
	v_pk_mul_f32 v[42:43], v[42:43], v[50:51]
	v_and_b32_e32 v27, 0xffff0000, v27
	v_pk_fma_f32 v[38:39], v[38:39], v[48:49], v[42:43] neg_lo:[0,0,1] neg_hi:[0,0,1]
	v_lshlrev_b32_e32 v22, 16, v23
	v_pk_mul_f32 v[48:49], v[38:39], s[16:17] op_sel_hi:[1,0]
	v_and_b32_e32 v23, 0xffff0000, v23
	v_pk_mul_f32 v[38:39], v[40:41], v[26:27]
	v_pk_mul_f32 v[26:27], v[44:45], v[26:27]
	v_pk_fma_f32 v[38:39], v[44:45], v[22:23], v[38:39]
	v_pk_fma_f32 v[22:23], v[40:41], v[22:23], v[26:27] neg_lo:[0,0,1] neg_hi:[0,0,1]
	v_lshlrev_b32_e32 v26, 16, v35
	v_and_b32_e32 v27, 0xffff0000, v35
	v_cvt_pk_bf16_f32 v81, v22, v23
	v_lshlrev_b32_e32 v22, 16, v31
	v_and_b32_e32 v23, 0xffff0000, v31
	v_pk_mul_f32 v[30:31], v[40:41], v[26:27]
	v_pk_mul_f32 v[26:27], v[44:45], v[26:27]
	v_cvt_pk_bf16_f32 v77, v38, v39
	v_pk_fma_f32 v[30:31], v[44:45], v[22:23], v[30:31]
	v_pk_fma_f32 v[22:23], v[40:41], v[22:23], v[26:27] neg_lo:[0,0,1] neg_hi:[0,0,1]
	v_mov_b64_e32 v[38:39], v[174:175]
	v_mov_b64_e32 v[40:41], v[176:177]
	v_mov_b64_e32 v[42:43], v[178:179]
	v_mov_b64_e32 v[44:45], v[180:181]
	v_lshlrev_b32_e32 v26, 16, v28
	v_and_b32_e32 v27, 0xffff0000, v28
	v_lshlrev_b32_e32 v10, 16, v24
	v_and_b32_e32 v11, 0xffff0000, v24
	v_lshlrev_b32_e32 v24, 16, v25
	v_and_b32_e32 v25, 0xffff0000, v25
	v_pk_mul_f32 v[30:31], v[30:31], s[16:17] op_sel_hi:[1,0]
	v_pk_mul_f32 v[22:23], v[22:23], s[16:17] op_sel_hi:[1,0]
	v_pk_mul_f32 v[52:53], v[52:53], s[16:17] op_sel_hi:[1,0]
	s_waitcnt vmcnt(0) lgkmcnt(0)
	v_pk_mul_f32 v[34:35], v[38:39], v[26:27]
	v_pk_mul_f32 v[26:27], v[42:43], v[26:27]
	v_pk_fma_f32 v[34:35], v[42:43], v[10:11], v[34:35]
	v_pk_fma_f32 v[10:11], v[38:39], v[10:11], v[26:27] neg_lo:[0,0,1] neg_hi:[0,0,1]
	v_lshlrev_b32_e32 v26, 16, v36
	v_and_b32_e32 v27, 0xffff0000, v36
	v_cvt_pk_bf16_f32 v82, v10, v11
	v_cvt_pk_bf16_f32 v78, v34, v35
	v_lshlrev_b32_e32 v10, 16, v32
	v_and_b32_e32 v11, 0xffff0000, v32
	v_pk_mul_f32 v[34:35], v[38:39], v[26:27]
	v_pk_mul_f32 v[26:27], v[42:43], v[26:27]
	v_pk_fma_f32 v[34:35], v[42:43], v[10:11], v[34:35]
	v_pk_fma_f32 v[10:11], v[38:39], v[10:11], v[26:27] neg_lo:[0,0,1] neg_hi:[0,0,1]
	v_lshlrev_b32_e32 v26, 16, v29
	v_pk_mul_f32 v[10:11], v[10:11], s[16:17] op_sel_hi:[1,0]
	v_and_b32_e32 v27, 0xffff0000, v29
	v_cvt_pk_bf16_f32 v46, v10, v11
	v_lshlrev_b32_e32 v10, 5, v2
	v_pk_mul_f32 v[28:29], v[40:41], v[26:27]
	v_pk_mul_f32 v[26:27], v[44:45], v[26:27]
	v_ashrrev_i32_e32 v11, 31, v10
	v_pk_fma_f32 v[28:29], v[44:45], v[24:25], v[28:29]
	v_pk_fma_f32 v[24:25], v[40:41], v[24:25], v[26:27] neg_lo:[0,0,1] neg_hi:[0,0,1]
	v_lshlrev_b32_e32 v26, 16, v37
	v_and_b32_e32 v27, 0xffff0000, v37
	v_lshlrev_b64 v[10:11], 2, v[10:11]
	v_or_b32_e32 v2, s34, v134
	v_cvt_pk_bf16_f32 v83, v24, v25
	v_cvt_pk_bf16_f32 v79, v28, v29
	v_lshlrev_b32_e32 v24, 16, v33
	v_and_b32_e32 v25, 0xffff0000, v33
	v_pk_mul_f32 v[28:29], v[40:41], v[26:27]
	v_pk_mul_f32 v[26:27], v[44:45], v[26:27]
	v_lshl_add_u64 v[38:39], v[4:5], 0, v[10:11]
	v_mad_i64_i32 v[4:5], s[38:39], v2, s72, v[8:9]
	v_pk_fma_f32 v[28:29], v[44:45], v[24:25], v[28:29]
	v_pk_fma_f32 v[24:25], v[40:41], v[24:25], v[26:27] neg_lo:[0,0,1] neg_hi:[0,0,1]
	v_lshl_add_u64 v[4:5], v[4:5], 0, s[40:41]
	v_pk_mul_f32 v[34:35], v[34:35], s[16:17] op_sel_hi:[1,0]
	v_pk_mul_f32 v[28:29], v[28:29], s[16:17] op_sel_hi:[1,0]
	v_pk_mul_f32 v[24:25], v[24:25], s[16:17] op_sel_hi:[1,0]
	v_lshl_add_u64 v[26:27], v[4:5], 0, v[20:21]
	v_cvt_pk_bf16_f32 v44, v48, v49
	v_cvt_pk_bf16_f32 v45, v22, v23
	v_cvt_pk_bf16_f32 v47, v24, v25
	v_cvt_pk_bf16_f32 v49, v30, v31
	v_cvt_pk_bf16_f32 v50, v34, v35
	v_cvt_pk_bf16_f32 v51, v28, v29
	v_lshl_add_u64 v[40:41], v[6:7], 0, v[10:11]
	v_mov_b64_e32 v[4:5], v[158:159]
	v_mov_b64_e32 v[6:7], v[160:161]
	v_mov_b64_e32 v[8:9], v[188:189]
	v_mov_b64_e32 v[10:11], v[190:191]
	v_mov_b64_e32 v[22:23], v[192:193]
	v_mov_b64_e32 v[24:25], v[194:195]
	s_nop 0
	v_mov_b64_e32 v[26:27], v[196:197]
	v_mov_b64_e32 v[28:29], v[198:199]
	s_nop 0
	global_load_dwordx4 v[30:33], v[38:39], off
	global_load_dwordx4 v[34:37], v[40:41], off
	global_load_dwordx4 v[174:177], v[38:39], off offset:16
	global_load_dwordx4 v[178:181], v[40:41], off offset:16
	v_cvt_pk_bf16_f32 v48, v52, v53
	v_sub_f32_e32 v2, v14, v18
	v_sub_f32_e32 v0, v0, v2
	v_add_f32_e32 v0, v16, v0
	v_add_f32_e32 v0, v0, v17
	v_add_f32_e32 v0, v12, v0
	v_cmp_nlt_f32_e64 s[38:39], 1.0, v102
	v_lshl_add_u64 v[12:13], s[20:21], 0, v[20:21]
	v_lshlrev_b32_e32 v2, 7, v133
	v_cndmask_b32_e64 v0, v205, v0, s[38:39]
	v_cmp_neq_f32_e64 s[38:39], 1.0, v102
	s_mov_b32 s20, 10
	s_waitcnt vmcnt(0) lgkmcnt(0)
; template <int KIND>
; __device__ __forceinline__ void w_m3_core(const bf16x8 (&Qf)[4][2], const bf16x8 (&Kf)[4][2], const bf16x8 (&Sf)[4][2], const LAS bf16_t* vT, float lg,
;                                           const bf16_t* gsrc, const float* nw, bf16_t* ydst, int lo, int fq) {
;     ...
;                     s = __builtin_amdgcn_mfma_f32_16x16x32_bf16(Kf[mb][0], Qf[nb][0], s, 0, 0, 0); s = __builtin_amdgcn_mfma_f32_16x16x32_bf16(Kf[mb][1], Qf[nb][1], s, 0, 0, 0);
; #pragma unroll
;                     for (int r = 0; r < 4; ++r) { const int m = 16 * mb + 4 * fq + r, n = 16 * nb + lo; float v = s[r];
;                         if (KIND == 0) v *= __expf((float)(n - m) * lg);
;                         if (mb == nb) v = (m <= n) ? v : 0.f;
;                         pv[4 * hh + r] = v; }
; __device__ __forceinline__ void w_ret_m3(const Args& a, int l, unsigned char* ws, const bf16_t* proj, bf16_t* y, LAS unsigned char* wl, int b, int ck_, int h, int lane) {
;     ...
;     for (int tb = 0; tb < 4; ++tb) { const int n = 16 * tb + lo; float x1[8], x2[8], o1[8], o2[8], cs[8], sn[8];
;         const float* cp_ = cosT + (64 * ck_ + n) * 32 + 8 * fq; const float* sp_ = sinT + (64 * ck_ + n) * 32 + 8 * fq;
; #pragma unroll
;         for (int j = 0; j < 8; ++j) { cs[j] = cp_[j]; sn[j] = sp_[j]; }
;         const bf16_t* qs = proj + (size_t)(row0 + n) * NIN + C_RQ + 64 * h + 8 * fq;
;         ld8bf(qs, x1); ld8bf(qs + 32, x2);
; #pragma unroll
;         for (int j = 0; j < 8; ++j) { o1[j] = x1[j] * cs[j] - x2[j] * sn[j]; o2[j] = x2[j] * cs[j] + x1[j] * sn[j]; }
;         Qf[tb][0] = pack_frag(o1); Qf[tb][1] = pack_frag(o2);
;         const bf16_t* ks = proj + (size_t)(row0 + n) * NIN + C_RK + 64 * h + 8 * fq;
;         ld8bf(ks, x1); ld8bf(ks + 32, x2);
; #pragma unroll
;         for (int j = 0; j < 8; ++j) { o1[j] = (x1[j] * cs[j] - x2[j] * sn[j]) * 0.125f; o2[j] = (x2[j] * cs[j] + x1[j] * sn[j]) * 0.125f; }
;         Kf[tb][0] = pack_frag(o1); Kf[tb][1] = pack_frag(o2);
;     }
;     const bf16_t* Sb = (const bf16_t*)((const unsigned char*)a.out + OUT_SBR) + (size_t)((b * NCH + ck_) * 4 + h) * 4096;
; #pragma unroll
;     for (int eb = 0; eb < 4; ++eb)
; #pragma unroll
;         for (int kk = 0; kk < 2; ++kk) Sf[eb][kk] = *(const bf16x8*)(Sb + (16 * eb + lo) * 64 + 32 * kk + 8 * fq);
	v_lshlrev_b32_e32 v42, 16, v4
	v_lshlrev_b32_e32 v52, 16, v8
	v_and_b32_e32 v53, 0xffff0000, v8
	v_and_b32_e32 v43, 0xffff0000, v4
	v_pk_mul_f32 v[54:55], v[30:31], v[52:53]
	v_pk_mul_f32 v[52:53], v[34:35], v[52:53]
	v_pk_fma_f32 v[54:55], v[34:35], v[42:43], v[54:55]
	v_pk_fma_f32 v[42:43], v[30:31], v[42:43], v[52:53] neg_lo:[0,0,1] neg_hi:[0,0,1]
	v_lshlrev_b32_e32 v52, 16, v26
	v_and_b32_e32 v53, 0xffff0000, v26
	v_cvt_pk_bf16_f32 v8, v42, v43
	v_cvt_pk_bf16_f32 v4, v54, v55
	v_lshlrev_b32_e32 v42, 16, v22
	v_and_b32_e32 v43, 0xffff0000, v22
	v_pk_mul_f32 v[54:55], v[30:31], v[52:53]
	v_lshlrev_b32_e32 v26, 16, v27
	v_pk_fma_f32 v[54:55], v[34:35], v[42:43], v[54:55]
	v_pk_mul_f32 v[34:35], v[34:35], v[52:53]
	v_and_b32_e32 v27, 0xffff0000, v27
	v_pk_fma_f32 v[30:31], v[30:31], v[42:43], v[34:35] neg_lo:[0,0,1] neg_hi:[0,0,1]
	v_lshlrev_b32_e32 v34, 16, v9
	v_and_b32_e32 v35, 0xffff0000, v9
	v_pk_mul_f32 v[42:43], v[30:31], s[16:17] op_sel_hi:[1,0]
	v_lshlrev_b32_e32 v30, 16, v5
	v_and_b32_e32 v31, 0xffff0000, v5
	v_pk_mul_f32 v[52:53], v[32:33], v[34:35]
	v_pk_mul_f32 v[34:35], v[36:37], v[34:35]
	v_pk_fma_f32 v[52:53], v[36:37], v[30:31], v[52:53]
	v_pk_fma_f32 v[30:31], v[32:33], v[30:31], v[34:35] neg_lo:[0,0,1] neg_hi:[0,0,1]
	v_lshlrev_b32_e32 v22, 16, v23
	v_cvt_pk_bf16_f32 v9, v30, v31
	v_and_b32_e32 v23, 0xffff0000, v23
	v_pk_mul_f32 v[30:31], v[32:33], v[26:27]
	v_pk_mul_f32 v[26:27], v[36:37], v[26:27]
	v_pk_fma_f32 v[30:31], v[36:37], v[22:23], v[30:31]
	v_pk_fma_f32 v[22:23], v[32:33], v[22:23], v[26:27] neg_lo:[0,0,1] neg_hi:[0,0,1]
	v_pk_mul_f32 v[58:59], v[30:31], s[16:17] op_sel_hi:[1,0]
	v_mov_b64_e32 v[30:31], v[174:175]
	v_mov_b64_e32 v[32:33], v[176:177]
	v_mov_b64_e32 v[34:35], v[178:179]
	v_mov_b64_e32 v[36:37], v[180:181]
	v_lshlrev_b32_e32 v38, 16, v10
	v_and_b32_e32 v39, 0xffff0000, v10
	v_lshlrev_b32_e32 v26, 16, v6
	v_and_b32_e32 v27, 0xffff0000, v6
	v_cndmask_b32_e64 v0, v206, v0, s[38:39]
	v_pk_mul_f32 v[56:57], v[54:55], s[16:17] op_sel_hi:[1,0]
	v_pk_mul_f32 v[22:23], v[22:23], s[16:17] op_sel_hi:[1,0]
	v_cvt_pk_bf16_f32 v5, v52, v53
	v_cvt_pk_bf16_f32 v52, v42, v43
	v_cvt_pk_bf16_f32 v53, v22, v23
	v_cvt_pk_bf16_f32 v56, v56, v57
	v_cvt_pk_bf16_f32 v57, v58, v59
	v_cndmask_b32_e64 v135, v0, -v102, vcc
	v_bfe_u32 v0, v101, 2, 2
	v_or_b32_e32 v105, v124, v0
	v_or_b32_e32 v106, v140, v0
	v_lshlrev_b32_e32 v0, 6, v100
	v_mfma_f32_16x16x32_bf16 v[100:103], v[64:67], v[96:99], 0
	v_cmp_lt_i32_e32 vcc, v133, v124
	v_mul_f32_e32 v1, v135, v1
	v_mul_f32_e32 v1, 0x3fb8aa3b, v1
	v_mfma_f32_16x16x32_bf16 v[100:103], v[72:75], v[92:95], v[100:103]
	v_exp_f32_e32 v1, v1
	s_waitcnt vmcnt(0) lgkmcnt(0)
	v_pk_mul_f32 v[40:41], v[30:31], v[38:39]
	v_pk_mul_f32 v[38:39], v[34:35], v[38:39]
	v_pk_fma_f32 v[40:41], v[34:35], v[26:27], v[40:41]
	v_pk_fma_f32 v[26:27], v[30:31], v[26:27], v[38:39] neg_lo:[0,0,1] neg_hi:[0,0,1]
	v_lshlrev_b32_e32 v38, 16, v28
	v_and_b32_e32 v39, 0xffff0000, v28
	v_cvt_pk_bf16_f32 v10, v26, v27
	v_cvt_pk_bf16_f32 v6, v40, v41
	v_lshlrev_b32_e32 v26, 16, v24
	v_and_b32_e32 v27, 0xffff0000, v24
	v_pk_mul_f32 v[40:41], v[30:31], v[38:39]
	v_lshlrev_b32_e32 v28, 16, v29
	v_pk_fma_f32 v[40:41], v[34:35], v[26:27], v[40:41]
	v_pk_mul_f32 v[34:35], v[34:35], v[38:39]
	v_and_b32_e32 v29, 0xffff0000, v29
	v_pk_fma_f32 v[26:27], v[30:31], v[26:27], v[34:35] neg_lo:[0,0,1] neg_hi:[0,0,1]
	v_lshlrev_b32_e32 v34, 16, v11
	v_and_b32_e32 v35, 0xffff0000, v11
	v_lshlrev_b32_e32 v30, 16, v7
	v_and_b32_e32 v31, 0xffff0000, v7
	v_pk_mul_f32 v[38:39], v[32:33], v[34:35]
	v_pk_mul_f32 v[34:35], v[36:37], v[34:35]
	v_pk_fma_f32 v[38:39], v[36:37], v[30:31], v[38:39]
	v_pk_fma_f32 v[30:31], v[32:33], v[30:31], v[34:35] neg_lo:[0,0,1] neg_hi:[0,0,1]
	v_lshlrev_b32_e32 v24, 16, v25
	v_cvt_pk_bf16_f32 v11, v30, v31
	v_and_b32_e32 v25, 0xffff0000, v25
	v_pk_mul_f32 v[30:31], v[32:33], v[28:29]
	v_pk_mul_f32 v[28:29], v[36:37], v[28:29]
	v_pk_fma_f32 v[30:31], v[36:37], v[24:25], v[30:31]
	v_pk_fma_f32 v[24:25], v[32:33], v[24:25], v[28:29] neg_lo:[0,0,1] neg_hi:[0,0,1]
	v_lshl_add_u64 v[28:29], v[12:13], 0, v[2:3]
	v_add_co_u32_e64 v32, s[38:39], s73, v28
	v_pk_mul_f32 v[40:41], v[40:41], s[16:17] op_sel_hi:[1,0]
	v_pk_mul_f32 v[26:27], v[26:27], s[16:17] op_sel_hi:[1,0]
	v_pk_mul_f32 v[30:31], v[30:31], s[16:17] op_sel_hi:[1,0]
	v_pk_mul_f32 v[24:25], v[24:25], s[16:17] op_sel_hi:[1,0]
	v_addc_co_u32_e64 v33, s[38:39], 0, v29, s[38:39]
	v_cvt_pk_bf16_f32 v7, v38, v39
	v_cvt_pk_bf16_f32 v54, v26, v27
	v_cvt_pk_bf16_f32 v55, v24, v25
	v_cvt_pk_bf16_f32 v58, v40, v41
	v_cvt_pk_bf16_f32 v59, v30, v31
	global_load_dwordx4 v[20:23], v[28:29], off
	global_load_dwordx4 v[12:15], v[28:29], off offset:64
	global_load_dwordx4 v[24:27], v[28:29], off offset:2048
	global_load_dwordx4 v[16:19], v[28:29], off offset:2112
	global_load_dwordx4 v[36:39], v[32:33], off
	s_nop 0
	global_load_dwordx4 v[28:31], v[32:33], off offset:64
	global_load_dwordx4 v[40:43], v[32:33], off offset:2048
	s_nop 0
	global_load_dwordx4 v[32:35], v[32:33], off offset:2112
	v_lshlrev_b32_e32 v2, 2, v133
	v_bitop3_b32 v138, v0, 64, v2 bitop3:0x36
	v_bitop3_b32 v137, v0, s96, v2 bitop3:0x36
	v_sub_u32_e32 v0, v133, v124
	v_cvt_f32_i32_e32 v0, v0
	s_waitcnt lgkmcnt(0)
	s_ashr_i32 s21, s20, 31
	v_mul_f32_e32 v0, v135, v0
	v_mul_f32_e32 v0, 0x3fb8aa3b, v0
	v_exp_f32_e32 v139, v0
	s_lshl_b64 s[20:21], s[20:21], 3
	s_add_u32 s20, s0, s20
	s_addc_u32 s21, s1, s21
	v_mul_f32_e32 v0, v139, v100
	v_cndmask_b32_e64 v2, v0, 0, vcc
	v_add_u32_e32 v0, v133, v143
	v_cvt_f32_i32_e32 v0, v0
	s_load_dwordx2 s[20:21], s[20:21], 0x0
	s_lshl_b64 s[38:39], s[36:37], 2
	s_waitcnt vmcnt(7)
; template <int KIND>
; __device__ __forceinline__ void w_m3_core(const bf16x8 (&Qf)[4][2], const bf16x8 (&Kf)[4][2], const bf16x8 (&Sf)[4][2], const LAS bf16_t* vT, float lg,
;                                           const bf16_t* gsrc, const float* nw, bf16_t* ydst, int lo, int fq) {
;     ...
;     for (int nb = 0; nb < 4; ++nb) {
;         f32x4 O[4], O2[4];
; #pragma unroll
;         for (int eb = 0; eb < 4; ++eb) { O[eb] = (f32x4){0.f, 0.f, 0.f, 0.f}; O2[eb] = (f32x4){0.f, 0.f, 0.f, 0.f}; }
; #pragma unroll
;         for (int kk2 = 0; kk2 < 2; ++kk2) {
;             if (2 * kk2 > nb) continue;
;             float pv[8];
; #pragma unroll
;             for (int hh = 0; hh < 2; ++hh) { const int mb = 2 * kk2 + hh;
;                 if (mb <= nb) { f32x4 s = {0.f, 0.f, 0.f, 0.f};
;                     s = __builtin_amdgcn_mfma_f32_16x16x32_bf16(Kf[mb][0], Qf[nb][0], s, 0, 0, 0); s = __builtin_amdgcn_mfma_f32_16x16x32_bf16(Kf[mb][1], Qf[nb][1], s, 0, 0, 0);
; #pragma unroll
;                     for (int r = 0; r < 4; ++r) { const int m = 16 * mb + 4 * fq + r, n = 16 * nb + lo; float v = s[r];
;                         if (KIND == 0) v *= __expf((float)(n - m) * lg);
;                         if (mb == nb) v = (m <= n) ? v : 0.f;
;                         pv[4 * hh + r] = v; }
;                 } else {
; #pragma unroll
;                     for (int r = 0; r < 4; ++r) pv[4 * hh + r] = 0.f; }
;             }
;             const bf16x8 Pf = pack_frag(pv);
; #pragma unroll
;             for (int eb = 0; eb < 4; ++eb)
;                 O[eb] = __builtin_amdgcn_mfma_f32_16x16x32_bf16(tr_frag(vT, 32 * kk2 + 4 * fq, 32 * kk2 + 16 + 4 * fq, 16 * eb, lo), Pf, O[eb], 0, 0, 0);
;         }
; #pragma unroll
;         for (int kk = 0; kk < 2; ++kk)
; #pragma unroll
;             for (int eb = 0; eb < 4; ++eb) O2[eb] = __builtin_amdgcn_mfma_f32_16x16x32_bf16(Sf[eb][kk], Qf[nb][kk], O2[eb], 0, 0, 0);
;         const float osc = KIND == 0 ? __expf((float)(16 * nb + lo + 1) * lg) : 1.0f;
; #pragma unroll
;         for (int eb = 0; eb < 4; ++eb) O[eb] = O[eb] + O2[eb] * osc;
;         float ss = 0.f;
; #pragma unroll
;         for (int eb = 0; eb < 4; ++eb) ss += (O[eb][0] * O[eb][0] + O[eb][1] * O[eb][1]) + (O[eb][2] * O[eb][2] + O[eb][3] * O[eb][3]);
;         { const int ln = (fq << 4) | lo; ss += bperm_f(ln ^ 16, ss); ss += bperm_f(ln ^ 32, ss); }
	v_mfma_f32_16x16x32_bf16 v[116:119], v[20:23], v[96:99], 0
	v_mul_f32_e32 v0, v135, v0
	v_mul_f32_e32 v0, 0x3fb8aa3b, v0
	v_exp_f32_e32 v0, v0
	s_waitcnt lgkmcnt(0)
	s_add_u32 s27, s20, s38
	s_addc_u32 s38, s21, s39
	s_lshl_b64 s[20:21], s[24:25], 2
	s_add_u32 s44, s27, s20
	s_addc_u32 s45, s38, s21
	v_lshl_add_u64 v[182:183], v[124:125], 2, s[44:45]
	global_load_dwordx4 v[184:187], v[182:183], off
	global_load_dwordx4 v[188:191], v[182:183], off offset:64
	global_load_dwordx4 v[192:195], v[182:183], off offset:128
	global_load_dwordx4 v[196:199], v[182:183], off offset:192
	v_mul_f32_e32 v0, v0, v101
	v_cmp_gt_i32_e64 s[38:39], v133, v124
	s_lshl_b64 s[20:21], s[34:35], 11
	s_add_u32 s20, s10, s20
	v_cndmask_b32_e64 v107, 0, v0, s[38:39]
	v_sub_u32_e32 v0, v133, v142
	v_cvt_f32_i32_e32 v0, v0
	s_addc_u32 s21, s11, s21
	s_add_u32 s40, s20, s40
	s_addc_u32 s41, s21, 0
	v_mul_f32_e32 v0, v135, v0
	v_mul_f32_e32 v0, 0x3fb8aa3b, v0
	v_exp_f32_e32 v0, v0
	v_mad_u64_u32 v[126:127], s[20:21], v106, s23, v[104:105]
	v_mad_u64_u32 v[128:129], s[20:21], v105, s23, v[104:105]
	v_pk_mul_f32 v[100:101], v[0:1], v[102:103]
	v_cmp_ge_i32_e64 s[38:39], v133, v142
	v_cvt_pk_bf16_f32 v1, v100, v101
	ds_read_b64_tr_b16 v[102:103], v126
	ds_read_b64_tr_b16 v[110:111], v126 offset:32
	ds_read_b64_tr_b16 v[100:101], v128
	ds_read_b64_tr_b16 v[108:109], v128 offset:32
	v_cvt_pk_bf16_f32 v0, v2, v107
	v_cndmask_b32_e64 v2, 0, v1, s[38:39]
	v_lshrrev_b32_e32 v1, 16, v1
	v_cmp_ge_i32_e64 s[38:39], v133, v141
	s_waitcnt vmcnt(9)
	v_mfma_f32_16x16x32_bf16 v[146:149], v[24:27], v[96:99], 0
	v_cndmask_b32_e64 v1, 0, v1, s[38:39]
	v_perm_b32 v1, v1, v2, s53
	v_mov_b32_e32 v2, v3
	s_waitcnt vmcnt(7)
	v_mfma_f32_16x16x32_bf16 v[150:153], v[36:39], v[96:99], 0
	s_waitcnt lgkmcnt(1)
	v_mfma_f32_16x16x32_bf16 v[104:107], v[100:103], v[0:3], 0
	s_waitcnt lgkmcnt(0)
	v_mfma_f32_16x16x32_bf16 v[100:103], v[108:111], v[0:3], 0
	ds_read_b64_tr_b16 v[108:109], v128 offset:64
	ds_read_b64_tr_b16 v[110:111], v126 offset:64
	ds_read_b64_tr_b16 v[112:113], v128 offset:96
	ds_read_b64_tr_b16 v[114:115], v126 offset:96
	s_waitcnt lgkmcnt(2)
	v_mfma_f32_16x16x32_bf16 v[108:111], v[108:111], v[0:3], 0
	s_waitcnt lgkmcnt(0)
	v_mfma_f32_16x16x32_bf16 v[112:115], v[112:115], v[0:3], 0
	v_add_u32_e32 v0, 1, v133
	v_cvt_f32_ubyte0_e32 v0, v0
	v_mul_f32_e32 v0, v135, v0
	s_waitcnt vmcnt(5)
	v_mfma_f32_16x16x32_bf16 v[154:157], v[40:43], v[96:99], 0
	v_mul_f32_e32 v0, 0x3fb8aa3b, v0
	v_exp_f32_e32 v2, v0
	v_mfma_f32_16x16x32_bf16 v[120:123], v[12:15], v[92:95], v[116:119]
	v_mfma_f32_16x16x32_bf16 v[116:119], v[16:19], v[92:95], v[146:149]
	v_mfma_f32_16x16x32_bf16 v[96:99], v[28:31], v[92:95], v[150:153]
	s_nop 5
	v_fma_f32 v122, v2, v122, v106
	v_fma_f32 v123, v2, v123, v107
	v_pk_fma_f32 v[120:121], v[2:3], v[120:121], v[104:105] op_sel_hi:[0,1,1]
	v_pk_fma_f32 v[118:119], v[2:3], v[118:119], v[102:103] op_sel_hi:[0,1,1]
	s_waitcnt vmcnt(4)
	v_mfma_f32_16x16x32_bf16 v[92:95], v[32:35], v[92:95], v[154:157]
	v_fma_f32 v116, v2, v116, v100
	v_fma_f32 v117, v2, v117, v101
	v_pk_fma_f32 v[108:109], v[2:3], v[96:97], v[108:109] op_sel_hi:[0,1,1]
	v_pk_fma_f32 v[106:107], v[2:3], v[98:99], v[110:111] op_sel_hi:[0,1,1]
	v_lshl_add_u64 v[100:101], v[124:125], 2, s[44:45]
	s_nop 2
	v_pk_fma_f32 v[0:1], v[2:3], v[94:95], v[114:115] op_sel_hi:[0,1,1]
	v_pk_fma_f32 v[104:105], v[2:3], v[92:93], v[112:113] op_sel_hi:[0,1,1]
	v_pk_mul_f32 v[92:93], v[122:123], v[122:123]
	v_pk_mul_f32 v[94:95], v[120:121], v[120:121]
	v_mul_f32_e32 v2, v104, v104
	v_pk_mov_b32 v[96:97], v[94:95], v[92:93] op_sel:[1,0]
	v_mov_b32_e32 v95, v93
	v_pk_add_f32 v[92:93], v[96:97], v[94:95]
	v_pk_mul_f32 v[94:95], v[118:119], v[118:119]
	v_pk_mul_f32 v[96:97], v[116:117], v[116:117]
	v_pk_add_f32 v[92:93], v[92:93], v[92:93] op_sel:[0,1] op_sel_hi:[1,0]
	v_pk_mov_b32 v[98:99], v[96:97], v[94:95] op_sel:[1,0]
	v_mov_b32_e32 v97, v95
	v_pk_add_f32 v[94:95], v[98:99], v[96:97]
	v_mul_f32_e32 v96, v105, v105
	v_pk_add_f32 v[94:95], v[94:95], v[94:95] op_sel:[0,1] op_sel_hi:[1,0]
	v_mov_b32_e32 v93, v2
	v_mov_b32_e32 v95, v96
	v_mul_f32_e32 v2, v109, v109
	v_mul_f32_e32 v97, v0, v0
	v_pk_add_f32 v[92:93], v[92:93], v[94:95]
	v_pk_fma_f32 v[94:95], v[108:109], v[108:109], v[2:3] op_sel_hi:[1,1,0]
	v_mul_f32_e32 v2, v107, v107
	v_mul_f32_e32 v98, v1, v1
	v_mov_b32_e32 v95, v97
	v_pk_fma_f32 v[96:97], v[106:107], v[106:107], v[2:3] op_sel_hi:[1,1,0]
	s_nop 0
	v_mov_b32_e32 v97, v98
	v_pk_add_f32 v[94:95], v[94:95], v[96:97]
	v_mov_b64_e32 v[98:99], s[42:43]
	v_pk_add_f32 v[92:93], v[92:93], v[94:95]
	v_lshlrev_b64 v[96:97], 1, v[124:125]
	v_add_f32_e32 v2, v92, v93
	ds_bpermute_b32 v92, v138, v2
	s_waitcnt lgkmcnt(0)
	v_add_f32_e32 v2, v2, v92
	ds_bpermute_b32 v92, v137, v2
	s_waitcnt lgkmcnt(0)
	v_add_f32_e32 v2, v2, v92
	v_fmamk_f32 v2, v2, 0x3c800000, v200
	v_cmp_gt_f32_e64 s[38:39], s29, v2
	v_mul_f32_e32 v92, 0x4b800000, v2
	s_nop 0
	v_cndmask_b32_e64 v2, v2, v92, s[38:39]
	v_rsq_f32_e32 v2, v2
	s_nop 0
	v_mul_f32_e32 v92, 0x45800000, v2
	v_cndmask_b32_e64 v102, v2, v92, s[38:39]
	v_mad_u64_u32 v[92:93], s[20:21], v133, s72, v[98:99]
	v_lshl_add_u64 v[110:111], v[92:93], 0, v[96:97]
	s_waitcnt vmcnt(0)
; __device__ __forceinline__ unsigned pk2(float lo, float hi) { const f32x2_t v = {lo, hi}; const bf16x2_t b = __builtin_convertvector(v, bf16x2_t); return __builtin_bit_cast(unsigned, b); }
; __device__ __forceinline__ float sigmoidf_(float x) { return __builtin_amdgcn_rcpf(1.0f + __expf(-x)); }
; template <int KIND>
; __device__ __forceinline__ void w_m3_core(const bf16x8 (&Qf)[4][2], const bf16x8 (&Kf)[4][2], const bf16x8 (&Sf)[4][2], const LAS bf16_t* vT, float lg,
;                                           const bf16_t* gsrc, const float* nw, bf16_t* ydst, int lo, int fq) {
;     ...
;         const size_t n = 16 * nb + lo;
; #pragma unroll
;         for (int eb = 0; eb < 4; ++eb) { const int e0 = 16 * eb + 4 * fq;
;             const unsigned long long gw_ = *(const unsigned long long*)(gsrc + n * NIN + e0); const f32x4 w4 = *(const f32x4*)(nw + e0);
;             const float g0 = __uint_as_float((unsigned)gw_ << 16), g1 = __uint_as_float((unsigned)gw_ & 0xffff0000u), g2 = __uint_as_float((unsigned)(gw_ >> 32) << 16), g3 = __uint_as_float((unsigned)(gw_ >> 32) & 0xffff0000u);
;             const float o0 = O[eb][0] * rs * w4[0] * (g0 * sigmoidf_(g0)), o1 = O[eb][1] * rs * w4[1] * (g1 * sigmoidf_(g1));
;             const float o2 = O[eb][2] * rs * w4[2] * (g2 * sigmoidf_(g2)), o3 = O[eb][3] * rs * w4[3] * (g3 * sigmoidf_(g3));
;             *(unsigned long long*)(ydst + n * DM + e0) = (unsigned long long)pk2(o0, o1) | ((unsigned long long)pk2(o2, o3) << 32); }
	v_permlane16_swap_b32_e32 v222, v224
	v_permlane16_swap_b32_e32 v223, v225
	v_permlane16_swap_b32_e32 v226, v228
	v_permlane16_swap_b32_e32 v227, v229
	v_permlane16_swap_b32_e32 v230, v232
	v_permlane16_swap_b32_e32 v231, v233
	v_permlane16_swap_b32_e32 v234, v236
	v_permlane16_swap_b32_e32 v235, v237
	v_permlane16_swap_b32_e32 v238, v240
	v_permlane16_swap_b32_e32 v239, v241
	v_permlane16_swap_b32_e32 v242, v244
	v_permlane16_swap_b32_e32 v243, v245
	v_permlane16_swap_b32_e32 v246, v248
	v_permlane16_swap_b32_e32 v247, v249
	v_permlane16_swap_b32_e32 v250, v252
	v_permlane16_swap_b32_e32 v251, v253
	v_mov_b64_e32 v[114:115], v[222:223]
	v_mov_b64_e32 v[92:93], v[184:185]
	v_mov_b64_e32 v[94:95], v[186:187]
	v_lshlrev_b32_e32 v2, 11, v133
	v_lshl_add_u64 v[112:113], s[40:41], 0, v[2:3]
	v_pk_mul_f32 v[120:121], v[120:121], v[102:103] op_sel_hi:[1,0]
	v_pk_mul_f32 v[122:123], v[122:123], v[102:103] op_sel_hi:[1,0]
	v_lshl_add_u64 v[112:113], v[112:113], 0, v[96:97]
	v_pk_mul_f32 v[116:117], v[116:117], v[102:103] op_sel_hi:[1,0]
	v_pk_mul_f32 v[118:119], v[118:119], v[102:103] op_sel_hi:[1,0]
	v_pk_mul_f32 v[108:109], v[108:109], v[102:103] op_sel_hi:[1,0]
	s_waitcnt lgkmcnt(0)
	v_lshlrev_b32_e32 v130, 16, v114
	v_mul_f32_e32 v2, 0xbfb8aa3b, v130
	v_exp_f32_e32 v2, v2
	v_and_b32_e32 v131, 0xffff0000, v114
	v_lshlrev_b32_e32 v114, 16, v115
	v_and_b32_e32 v115, 0xffff0000, v115
	v_add_f32_e32 v2, 1.0, v2
	v_rcp_f32_e32 v146, v2
	v_mul_f32_e32 v2, 0xbfb8aa3b, v131
	v_exp_f32_e32 v2, v2
	v_pk_mul_f32 v[92:93], v[92:93], v[120:121]
	v_pk_mul_f32 v[94:95], v[94:95], v[122:123]
	v_add_f32_e32 v2, 1.0, v2
	v_rcp_f32_e32 v147, v2
	v_mul_f32_e32 v2, 0xbfb8aa3b, v114
	v_exp_f32_e32 v2, v2
	v_pk_mul_f32 v[120:121], v[146:147], v[130:131]
	s_nop 0
	v_pk_mul_f32 v[92:93], v[120:121], v[92:93]
	v_add_f32_e32 v2, 1.0, v2
	v_rcp_f32_e32 v120, v2
	v_mul_f32_e32 v2, 0xbfb8aa3b, v115
	v_exp_f32_e32 v2, v2
	v_cvt_pk_bf16_f32 v92, v92, v93
	v_add_f32_e32 v2, 1.0, v2
	v_rcp_f32_e32 v121, v2
	s_nop 0
	v_pk_mul_f32 v[114:115], v[120:121], v[114:115]
	s_nop 0
	v_pk_mul_f32 v[94:95], v[114:115], v[94:95]
	s_nop 0
	v_cvt_pk_bf16_f32 v93, v94, v95
	global_store_dwordx2 v[112:113], v[92:93], off offset:1024
	v_mov_b64_e32 v[114:115], v[224:225]
	s_nop 0
	v_mov_b64_e32 v[92:93], v[188:189]
	v_mov_b64_e32 v[94:95], v[190:191]
	s_waitcnt lgkmcnt(0)
	v_lshlrev_b32_e32 v120, 16, v114
	v_mul_f32_e32 v2, 0xbfb8aa3b, v120
	v_exp_f32_e32 v2, v2
	v_and_b32_e32 v121, 0xffff0000, v114
	v_lshlrev_b32_e32 v114, 16, v115
	v_and_b32_e32 v115, 0xffff0000, v115
	v_add_f32_e32 v2, 1.0, v2
	v_rcp_f32_e32 v122, v2
	v_mul_f32_e32 v2, 0xbfb8aa3b, v121
	v_exp_f32_e32 v2, v2
	v_pk_mul_f32 v[92:93], v[92:93], v[116:117]
	v_pk_mul_f32 v[94:95], v[94:95], v[118:119]
	v_add_f32_e32 v2, 1.0, v2
	v_rcp_f32_e32 v123, v2
	v_mul_f32_e32 v2, 0xbfb8aa3b, v114
	v_exp_f32_e32 v2, v2
	v_pk_mul_f32 v[116:117], v[122:123], v[120:121]
	s_nop 0
	v_pk_mul_f32 v[92:93], v[116:117], v[92:93]
	v_add_f32_e32 v2, 1.0, v2
	v_rcp_f32_e32 v116, v2
	v_mul_f32_e32 v2, 0xbfb8aa3b, v115
	v_exp_f32_e32 v2, v2
	v_cvt_pk_bf16_f32 v92, v92, v93
	v_add_f32_e32 v2, 1.0, v2
	v_rcp_f32_e32 v117, v2
	s_nop 0
	v_pk_mul_f32 v[114:115], v[116:117], v[114:115]
	s_nop 0
	v_pk_mul_f32 v[94:95], v[114:115], v[94:95]
	v_mul_f32_e32 v116, v106, v102
	v_cvt_pk_bf16_f32 v93, v94, v95
	global_store_dwordx2 v[112:113], v[92:93], off offset:1056
	v_mov_b64_e32 v[114:115], v[226:227]
	s_nop 0
	v_mov_b64_e32 v[92:93], v[192:193]
	v_mov_b64_e32 v[94:95], v[194:195]
	s_waitcnt lgkmcnt(0)
	v_lshlrev_b32_e32 v118, 16, v114
	v_mul_f32_e32 v2, 0xbfb8aa3b, v118
	v_exp_f32_e32 v2, v2
	v_and_b32_e32 v119, 0xffff0000, v114
	v_lshlrev_b32_e32 v117, 16, v115
	v_and_b32_e32 v115, 0xffff0000, v115
	v_add_f32_e32 v2, 1.0, v2
	v_rcp_f32_e32 v120, v2
	v_mul_f32_e32 v2, 0xbfb8aa3b, v119
	v_exp_f32_e32 v2, v2
	v_pk_mul_f32 v[92:93], v[92:93], v[108:109]
	v_mul_f32_e32 v114, v107, v102
	v_mov_b32_e32 v106, v95
	v_add_f32_e32 v2, 1.0, v2
	v_rcp_f32_e32 v121, v2
	v_mul_f32_e32 v2, 0xbfb8aa3b, v117
	v_exp_f32_e32 v2, v2
	v_pk_mul_f32 v[108:109], v[120:121], v[118:119]
	s_nop 0
	v_pk_mul_f32 v[92:93], v[108:109], v[92:93]
	v_add_f32_e32 v2, 1.0, v2
	v_rcp_f32_e32 v109, v2
	v_mul_f32_e32 v2, 0xbfb8aa3b, v115
	v_exp_f32_e32 v2, v2
	v_mov_b32_e32 v108, v94
	v_pk_mul_f32 v[108:109], v[108:109], v[116:117]
	v_cvt_pk_bf16_f32 v92, v92, v93
	v_add_f32_e32 v2, 1.0, v2
	v_rcp_f32_e32 v107, v2
	s_nop 0
	v_pk_mul_f32 v[94:95], v[106:107], v[114:115]
	v_mov_b32_e32 v106, v108
	v_mov_b32_e32 v107, v94
	v_mov_b32_e32 v94, v109
	v_pk_mul_f32 v[94:95], v[106:107], v[94:95]
	v_mul_f32_e32 v106, v0, v102
	v_cvt_pk_bf16_f32 v93, v94, v95
	global_store_dwordx2 v[112:113], v[92:93], off offset:1088
	v_mov_b64_e32 v[114:115], v[228:229]
	s_nop 0
	v_mov_b64_e32 v[92:93], v[196:197]
	v_mov_b64_e32 v[94:95], v[198:199]
	v_mul_f32_e32 v108, v105, v102
	v_mul_f32_e32 v110, v104, v102
	v_mul_f32_e32 v102, v1, v102
	s_waitcnt lgkmcnt(0)
; template <int KIND>
; __device__ __forceinline__ void w_m3_core(const bf16x8 (&Qf)[4][2], const bf16x8 (&Kf)[4][2], const bf16x8 (&Sf)[4][2], const LAS bf16_t* vT, float lg,
;                                           const bf16_t* gsrc, const float* nw, bf16_t* ydst, int lo, int fq) {
;     ...
;         for (int kk2 = 0; kk2 < 2; ++kk2) {
;             if (2 * kk2 > nb) continue;
;             float pv[8];
; #pragma unroll
;             for (int hh = 0; hh < 2; ++hh) { const int mb = 2 * kk2 + hh;
;                 if (mb <= nb) { f32x4 s = {0.f, 0.f, 0.f, 0.f};
;                     s = __builtin_amdgcn_mfma_f32_16x16x32_bf16(Kf[mb][0], Qf[nb][0], s, 0, 0, 0); s = __builtin_amdgcn_mfma_f32_16x16x32_bf16(Kf[mb][1], Qf[nb][1], s, 0, 0, 0);
; #pragma unroll
;                     for (int r = 0; r < 4; ++r) { const int m = 16 * mb + 4 * fq + r, n = 16 * nb + lo; float v = s[r];
;                         if (KIND == 0) v *= __expf((float)(n - m) * lg);
;                         if (mb == nb) v = (m <= n) ? v : 0.f;
;                         pv[4 * hh + r] = v; }
;                 } else {
; #pragma unroll
;                     for (int r = 0; r < 4; ++r) pv[4 * hh + r] = 0.f; }
;             }
;             const bf16x8 Pf = pack_frag(pv);
; #pragma unroll
;             for (int eb = 0; eb < 4; ++eb)
;                 O[eb] = __builtin_amdgcn_mfma_f32_16x16x32_bf16(tr_frag(vT, 32 * kk2 + 4 * fq, 32 * kk2 + 16 + 4 * fq, 16 * eb, lo), Pf, O[eb], 0, 0, 0);
;     ...
;         const size_t n = 16 * nb + lo;
; #pragma unroll
;         for (int eb = 0; eb < 4; ++eb) { const int e0 = 16 * eb + 4 * fq;
;             const unsigned long long gw_ = *(const unsigned long long*)(gsrc + n * NIN + e0); const f32x4 w4 = *(const f32x4*)(nw + e0);
;             const float g0 = __uint_as_float((unsigned)gw_ << 16), g1 = __uint_as_float((unsigned)gw_ & 0xffff0000u), g2 = __uint_as_float((unsigned)(gw_ >> 32) << 16), g3 = __uint_as_float((unsigned)(gw_ >> 32) & 0xffff0000u);
;             const float o0 = O[eb][0] * rs * w4[0] * (g0 * sigmoidf_(g0)), o1 = O[eb][1] * rs * w4[1] * (g1 * sigmoidf_(g1));
;             const float o2 = O[eb][2] * rs * w4[2] * (g2 * sigmoidf_(g2)), o3 = O[eb][3] * rs * w4[3] * (g3 * sigmoidf_(g3));
;             *(unsigned long long*)(ydst + n * DM + e0) = (unsigned long long)pk2(o0, o1) | ((unsigned long long)pk2(o2, o3) << 32); }
	v_lshlrev_b32_e32 v111, 16, v114
	v_mul_f32_e32 v2, 0xbfb8aa3b, v111
	v_exp_f32_e32 v2, v2
	v_and_b32_e32 v109, 0xffff0000, v114
	v_lshlrev_b32_e32 v107, 16, v115
	v_and_b32_e32 v103, 0xffff0000, v115
	v_add_f32_e32 v2, 1.0, v2
	v_rcp_f32_e32 v115, v2
	v_mul_f32_e32 v2, 0xbfb8aa3b, v109
	v_exp_f32_e32 v2, v2
	v_mul_f32_e32 v0, 0xbfb8aa3b, v107
	v_exp_f32_e32 v0, v0
	v_mov_b32_e32 v104, v93
	v_add_f32_e32 v2, 1.0, v2
	v_rcp_f32_e32 v105, v2
	v_add_f32_e32 v0, 1.0, v0
	v_mov_b32_e32 v114, v92
	v_pk_mul_f32 v[110:111], v[114:115], v[110:111]
	v_pk_mul_f32 v[92:93], v[104:105], v[108:109]
	v_rcp_f32_e32 v105, v0
	v_mul_f32_e32 v0, 0xbfb8aa3b, v103
	v_exp_f32_e32 v0, v0
	v_mov_b32_e32 v104, v94
	v_pk_mul_f32 v[104:105], v[104:105], v[106:107]
	v_mov_b32_e32 v94, v110
	v_add_f32_e32 v0, 1.0, v0
	v_rcp_f32_e32 v1, v0
	v_mov_b32_e32 v0, v95
	v_mov_b32_e32 v95, v92
	v_mov_b32_e32 v92, v111
	v_pk_mul_f32 v[0:1], v[0:1], v[102:103]
	v_pk_mul_f32 v[92:93], v[94:95], v[92:93]
	v_mov_b32_e32 v94, v104
	v_mov_b32_e32 v95, v0
	v_mov_b32_e32 v0, v105
	v_pk_mul_f32 v[0:1], v[94:95], v[0:1]
	v_cvt_pk_bf16_f32 v92, v92, v93
	v_cvt_pk_bf16_f32 v93, v0, v1
	global_store_dwordx2 v[112:113], v[92:93], off offset:1120
	v_sub_u32_e32 v0, v144, v124
	v_add_u32_e32 v1, v144, v143
	v_cvt_f32_i32_e32 v0, v0
	v_cvt_f32_i32_e32 v1, v1
	v_mfma_f32_16x16x32_bf16 v[92:95], v[64:67], v[88:91], 0
	v_sub_u32_e32 v2, v144, v142
	v_mul_f32_e32 v0, v135, v0
	v_mul_f32_e32 v1, v135, v1
	v_cvt_f32_i32_e32 v2, v2
	v_mul_f32_e32 v0, 0x3fb8aa3b, v0
	v_mul_f32_e32 v1, 0x3fb8aa3b, v1
	v_mfma_f32_16x16x32_bf16 v[92:95], v[72:75], v[84:87], v[92:95]
	v_exp_f32_e32 v0, v0
	v_exp_f32_e32 v1, v1
	v_mul_f32_e32 v2, v135, v2
	v_mul_f32_e32 v2, 0x3fb8aa3b, v2
	v_add_u32_e32 v115, 17, v124
	s_nop 2
	v_pk_mul_f32 v[0:1], v[0:1], v[92:93]
	v_exp_f32_e32 v92, v2
	v_sub_u32_e32 v2, v144, v141
	v_cvt_f32_i32_e32 v2, v2
	v_cmp_ge_i32_e64 s[38:39], v144, v115
	v_add_u32_e32 v114, 19, v124
	v_add_u32_e32 v116, 18, v124
	v_mul_f32_e32 v2, v135, v2
	v_mul_f32_e32 v2, 0x3fb8aa3b, v2
	v_exp_f32_e32 v93, v2
	v_mfma_f32_16x16x32_bf16 v[110:113], v[36:39], v[88:91], 0
	v_mul_f32_e64 v102, v92, v94
	v_mul_f32_e64 v103, v93, v95
	v_mfma_f32_16x16x32_bf16 v[92:95], v[60:63], v[88:91], 0
	v_mfma_f32_16x16x32_bf16 v[92:95], v[68:71], v[84:87], v[92:95]
	v_mfma_f32_16x16x32_bf16 v[158:161], v[28:31], v[84:87], v[110:113]
	s_nop 6
	v_mul_f32_e32 v2, v139, v92
	v_sub_u32_e32 v92, v144, v115
	v_cvt_f32_i32_e32 v92, v92
	v_cndmask_b32_e64 v2, v2, 0, vcc
	v_mul_f32_e32 v92, v135, v92
	v_mul_f32_e32 v92, 0x3fb8aa3b, v92
	v_exp_f32_e32 v92, v92
	s_nop 0
	v_mul_f32_e32 v92, v92, v93
	v_cndmask_b32_e64 v106, 0, v92, s[38:39]
	v_sub_u32_e32 v92, v144, v116
	v_sub_u32_e32 v93, v144, v114
	v_cvt_f32_i32_e32 v92, v92
	v_cvt_f32_i32_e32 v93, v93
	v_cmp_ge_i32_e64 s[38:39], v144, v116
	v_mul_f32_e32 v92, v135, v92
	v_mul_f32_e32 v93, v135, v93
	v_mul_f32_e32 v92, 0x3fb8aa3b, v92
	v_mul_f32_e32 v93, 0x3fb8aa3b, v93
	v_exp_f32_e32 v92, v92
	v_exp_f32_e32 v93, v93
	s_nop 0
	v_pk_mul_f32 v[104:105], v[92:93], v[94:95]
	v_cvt_pk_bf16_f32 v92, v0, v1
	v_cvt_pk_bf16_f32 v93, v102, v103
	v_cvt_pk_bf16_f32 v94, v2, v106
	v_cvt_pk_bf16_f32 v0, v104, v105
	ds_read_b64_tr_b16 v[104:105], v126
	ds_read_b64_tr_b16 v[108:109], v126 offset:32
	ds_read_b64_tr_b16 v[102:103], v128
	ds_read_b64_tr_b16 v[106:107], v128 offset:32
	v_cndmask_b32_e64 v1, 0, v0, s[38:39]
	v_lshrrev_b32_e32 v0, 16, v0
	v_cmp_ge_i32_e64 s[38:39], v144, v114
	s_nop 1
	v_cndmask_b32_e64 v0, 0, v0, s[38:39]
	v_perm_b32 v95, v0, v1, s53
	v_add_u32_e32 v0, 17, v133
	v_cvt_f32_ubyte0_e32 v0, v0
	s_waitcnt lgkmcnt(0)
	v_mfma_f32_16x16x32_bf16 v[118:121], v[106:109], v[92:95], 0
	ds_read_b64_tr_b16 v[106:107], v128 offset:64
	ds_read_b64_tr_b16 v[108:109], v126 offset:64
	v_mul_f32_e32 v0, v135, v0
	v_mul_f32_e32 v0, 0x3fb8aa3b, v0
	s_waitcnt lgkmcnt(0)
	v_mfma_f32_16x16x32_bf16 v[146:149], v[106:109], v[92:95], 0
	ds_read_b64_tr_b16 v[106:107], v128 offset:96
	ds_read_b64_tr_b16 v[108:109], v126 offset:96
	v_exp_f32_e32 v2, v0
	v_mfma_f32_16x16x32_bf16 v[102:105], v[102:105], v[92:95], 0
	s_waitcnt lgkmcnt(0)
	v_mfma_f32_16x16x32_bf16 v[150:153], v[106:109], v[92:95], 0
	v_mfma_f32_16x16x32_bf16 v[92:95], v[20:23], v[88:91], 0
	v_mfma_f32_16x16x32_bf16 v[106:109], v[24:27], v[88:91], 0
	v_mfma_f32_16x16x32_bf16 v[88:91], v[40:43], v[88:91], 0
	v_mfma_f32_16x16x32_bf16 v[92:95], v[12:15], v[84:87], v[92:95]
	v_mfma_f32_16x16x32_bf16 v[154:157], v[16:19], v[84:87], v[106:109]
	v_mfma_f32_16x16x32_bf16 v[84:87], v[32:35], v[84:87], v[88:91]
	s_nop 5
	v_fma_f32 v108, v2, v94, v104
	v_fma_f32 v109, v2, v95, v105
	v_pk_fma_f32 v[110:111], v[2:3], v[92:93], v[102:103] op_sel_hi:[0,1,1]
	v_pk_fma_f32 v[102:103], v[2:3], v[156:157], v[120:121] op_sel_hi:[0,1,1]
	v_pk_fma_f32 v[106:107], v[2:3], v[154:155], v[118:119] op_sel_hi:[0,1,1]
	v_pk_fma_f32 v[92:93], v[2:3], v[160:161], v[148:149] op_sel_hi:[0,1,1]
	v_pk_fma_f32 v[0:1], v[2:3], v[86:87], v[152:153] op_sel_hi:[0,1,1]
	v_pk_fma_f32 v[90:91], v[2:3], v[84:85], v[150:151] op_sel_hi:[0,1,1]
	v_pk_mul_f32 v[84:85], v[108:109], v[108:109]
	v_pk_mul_f32 v[86:87], v[110:111], v[110:111]
	v_pk_fma_f32 v[94:95], v[2:3], v[158:159], v[146:147] op_sel_hi:[0,1,1]
	v_pk_mov_b32 v[88:89], v[86:87], v[84:85] op_sel:[1,0]
	v_mov_b32_e32 v87, v85
	v_pk_add_f32 v[84:85], v[88:89], v[86:87]
	v_pk_mul_f32 v[86:87], v[102:103], v[102:103]
	v_pk_mul_f32 v[88:89], v[106:107], v[106:107]
	v_mul_f32_e32 v2, v90, v90
	v_pk_mov_b32 v[104:105], v[88:89], v[86:87] op_sel:[1,0]
	v_mov_b32_e32 v89, v87
	v_pk_add_f32 v[86:87], v[104:105], v[88:89]
	v_mul_f32_e32 v88, v91, v91
	v_pk_add_f32 v[84:85], v[84:85], v[84:85] op_sel:[0,1] op_sel_hi:[1,0]
	v_pk_add_f32 v[86:87], v[86:87], v[86:87] op_sel:[0,1] op_sel_hi:[1,0]
	v_mov_b32_e32 v85, v2
	v_mov_b32_e32 v87, v88
	v_mul_f32_e32 v2, v95, v95
	v_mul_f32_e32 v89, v0, v0
	v_pk_add_f32 v[84:85], v[84:85], v[86:87]
	v_pk_fma_f32 v[86:87], v[94:95], v[94:95], v[2:3] op_sel_hi:[1,1,0]
	v_mul_f32_e32 v2, v93, v93
	v_mul_f32_e32 v104, v1, v1
	v_mov_b32_e32 v87, v89
	v_pk_fma_f32 v[88:89], v[92:93], v[92:93], v[2:3] op_sel_hi:[1,1,0]
	s_nop 0
	v_mov_b32_e32 v89, v104
	v_pk_add_f32 v[86:87], v[86:87], v[88:89]
	s_nop 0
	v_pk_add_f32 v[84:85], v[84:85], v[86:87]
	s_nop 0
	v_add_f32_e32 v2, v84, v85
	ds_bpermute_b32 v84, v138, v2
	s_waitcnt lgkmcnt(0)
; __device__ __forceinline__ unsigned pk2(float lo, float hi) { const f32x2_t v = {lo, hi}; const bf16x2_t b = __builtin_convertvector(v, bf16x2_t); return __builtin_bit_cast(unsigned, b); }
; __device__ __forceinline__ float sigmoidf_(float x) { return __builtin_amdgcn_rcpf(1.0f + __expf(-x)); }
; __device__ __forceinline__ float bperm_f(int src_lane, float v) { return __builtin_bit_cast(float, __builtin_amdgcn_ds_bpermute(src_lane << 2, __builtin_bit_cast(int, v))); }
; template <int KIND>
; __device__ __forceinline__ void w_m3_core(const bf16x8 (&Qf)[4][2], const bf16x8 (&Kf)[4][2], const bf16x8 (&Sf)[4][2], const LAS bf16_t* vT, float lg,
;                                           const bf16_t* gsrc, const float* nw, bf16_t* ydst, int lo, int fq) {
;     ...
;         float ss = 0.f;
; #pragma unroll
;         for (int eb = 0; eb < 4; ++eb) ss += (O[eb][0] * O[eb][0] + O[eb][1] * O[eb][1]) + (O[eb][2] * O[eb][2] + O[eb][3] * O[eb][3]);
;         { const int ln = (fq << 4) | lo; ss += bperm_f(ln ^ 16, ss); ss += bperm_f(ln ^ 32, ss); }
;         const float rs = rsqrtf(ss * (1.0f / 64.0f) + EPS);
;         const size_t n = 16 * nb + lo;
; #pragma unroll
;         for (int eb = 0; eb < 4; ++eb) { const int e0 = 16 * eb + 4 * fq;
;             const unsigned long long gw_ = *(const unsigned long long*)(gsrc + n * NIN + e0); const f32x4 w4 = *(const f32x4*)(nw + e0);
;             const float g0 = __uint_as_float((unsigned)gw_ << 16), g1 = __uint_as_float((unsigned)gw_ & 0xffff0000u), g2 = __uint_as_float((unsigned)(gw_ >> 32) << 16), g3 = __uint_as_float((unsigned)(gw_ >> 32) & 0xffff0000u);
;             const float o0 = O[eb][0] * rs * w4[0] * (g0 * sigmoidf_(g0)), o1 = O[eb][1] * rs * w4[1] * (g1 * sigmoidf_(g1));
;             const float o2 = O[eb][2] * rs * w4[2] * (g2 * sigmoidf_(g2)), o3 = O[eb][3] * rs * w4[3] * (g3 * sigmoidf_(g3));
;             *(unsigned long long*)(ydst + n * DM + e0) = (unsigned long long)pk2(o0, o1) | ((unsigned long long)pk2(o2, o3) << 32); }
	v_add_f32_e32 v2, v2, v84
	ds_bpermute_b32 v84, v137, v2
	s_waitcnt lgkmcnt(0)
	v_add_f32_e32 v2, v2, v84
	v_fmamk_f32 v2, v2, 0x3c800000, v200
	v_cmp_gt_f32_e64 s[38:39], s29, v2
	v_mul_f32_e32 v84, 0x4b800000, v2
	s_nop 0
	v_cndmask_b32_e64 v2, v2, v84, s[38:39]
	v_rsq_f32_e32 v2, v2
	s_nop 0
	v_mul_f32_e32 v84, 0x45800000, v2
	v_cndmask_b32_e64 v88, v2, v84, s[38:39]
	v_mad_u64_u32 v[84:85], s[20:21], v144, s72, v[98:99]
	v_lshl_add_u64 v[104:105], v[84:85], 0, v[96:97]
	v_mov_b64_e32 v[118:119], v[230:231]
	v_mov_b64_e32 v[84:85], v[184:185]
	v_mov_b64_e32 v[86:87], v[186:187]
	v_lshlrev_b32_e32 v2, 11, v144
	v_lshl_add_u64 v[112:113], s[40:41], 0, v[2:3]
	v_pk_mul_f32 v[110:111], v[110:111], v[88:89] op_sel_hi:[1,0]
	v_pk_mul_f32 v[108:109], v[108:109], v[88:89] op_sel_hi:[1,0]
	v_pk_mul_f32 v[106:107], v[106:107], v[88:89] op_sel_hi:[1,0]
	v_pk_mul_f32 v[102:103], v[102:103], v[88:89] op_sel_hi:[1,0]
	v_pk_mul_f32 v[94:95], v[94:95], v[88:89] op_sel_hi:[1,0]
	s_waitcnt lgkmcnt(0)
	v_lshlrev_b32_e32 v120, 16, v118
	v_mul_f32_e32 v2, 0xbfb8aa3b, v120
	v_exp_f32_e32 v2, v2
	v_and_b32_e32 v121, 0xffff0000, v118
	v_lshlrev_b32_e32 v118, 16, v119
	v_and_b32_e32 v119, 0xffff0000, v119
	v_add_f32_e32 v2, 1.0, v2
	v_rcp_f32_e32 v122, v2
	v_mul_f32_e32 v2, 0xbfb8aa3b, v121
	v_exp_f32_e32 v2, v2
	v_pk_mul_f32 v[84:85], v[84:85], v[110:111]
	v_pk_mul_f32 v[86:87], v[86:87], v[108:109]
	v_add_f32_e32 v2, 1.0, v2
	v_rcp_f32_e32 v123, v2
	v_mul_f32_e32 v2, 0xbfb8aa3b, v118
	v_exp_f32_e32 v2, v2
	v_pk_mul_f32 v[110:111], v[122:123], v[120:121]
	s_nop 0
	v_pk_mul_f32 v[84:85], v[110:111], v[84:85]
	v_add_f32_e32 v2, 1.0, v2
	v_rcp_f32_e32 v110, v2
	v_mul_f32_e32 v2, 0xbfb8aa3b, v119
	v_exp_f32_e32 v2, v2
	s_nop 0
	v_add_f32_e32 v2, 1.0, v2
	v_rcp_f32_e32 v111, v2
	s_nop 0
	v_pk_mul_f32 v[108:109], v[110:111], v[118:119]
	s_nop 0
	v_pk_mul_f32 v[86:87], v[108:109], v[86:87]
	v_cvt_pk_bf16_f32 v108, v84, v85
	v_cvt_pk_bf16_f32 v109, v86, v87
	v_lshl_add_u64 v[84:85], v[112:113], 0, v[96:97]
	global_store_dwordx2 v[84:85], v[108:109], off offset:1024
	v_mov_b64_e32 v[86:87], v[232:233]
	s_nop 0
	v_mov_b64_e32 v[108:109], v[188:189]
	v_mov_b64_e32 v[110:111], v[190:191]
	s_waitcnt lgkmcnt(0)
	v_lshlrev_b32_e32 v112, 16, v86
	v_mul_f32_e32 v2, 0xbfb8aa3b, v112
	v_exp_f32_e32 v2, v2
	v_and_b32_e32 v113, 0xffff0000, v86
	v_lshlrev_b32_e32 v86, 16, v87
	v_and_b32_e32 v87, 0xffff0000, v87
	v_add_f32_e32 v2, 1.0, v2
	v_rcp_f32_e32 v118, v2
	v_mul_f32_e32 v2, 0xbfb8aa3b, v113
	v_exp_f32_e32 v2, v2
	v_pk_mul_f32 v[106:107], v[108:109], v[106:107]
	v_pk_mul_f32 v[102:103], v[110:111], v[102:103]
	v_mul_f32_e32 v110, v92, v88
	v_add_f32_e32 v2, 1.0, v2
	v_rcp_f32_e32 v119, v2
	v_mul_f32_e32 v2, 0xbfb8aa3b, v86
	v_exp_f32_e32 v2, v2
	v_pk_mul_f32 v[108:109], v[118:119], v[112:113]
	s_nop 0
	v_pk_mul_f32 v[106:107], v[108:109], v[106:107]
	v_add_f32_e32 v2, 1.0, v2
	v_rcp_f32_e32 v108, v2
	v_mul_f32_e32 v2, 0xbfb8aa3b, v87
	v_exp_f32_e32 v2, v2
	s_nop 0
	v_add_f32_e32 v2, 1.0, v2
	v_rcp_f32_e32 v109, v2
	s_nop 0
	v_pk_mul_f32 v[86:87], v[108:109], v[86:87]
	s_nop 0
	v_pk_mul_f32 v[86:87], v[86:87], v[102:103]
	v_cvt_pk_bf16_f32 v102, v106, v107
	v_cvt_pk_bf16_f32 v103, v86, v87
	global_store_dwordx2 v[84:85], v[102:103], off offset:1056
	v_mov_b64_e32 v[86:87], v[234:235]
	v_mov_b64_e32 v[106:107], v[192:193]
	v_mov_b64_e32 v[108:109], v[194:195]
	s_waitcnt lgkmcnt(0)
	v_lshlrev_b32_e32 v102, 16, v86
	v_mul_f32_e32 v2, 0xbfb8aa3b, v102
	v_exp_f32_e32 v2, v2
	v_and_b32_e32 v103, 0xffff0000, v86
	v_lshlrev_b32_e32 v111, 16, v87
	v_and_b32_e32 v87, 0xffff0000, v87
	v_add_f32_e32 v2, 1.0, v2
	v_rcp_f32_e32 v112, v2
	v_mul_f32_e32 v2, 0xbfb8aa3b, v103
	v_exp_f32_e32 v2, v2
	v_pk_mul_f32 v[94:95], v[106:107], v[94:95]
	v_mul_f32_e32 v86, v93, v88
	v_mov_b32_e32 v92, v109
	v_add_f32_e32 v2, 1.0, v2
	v_rcp_f32_e32 v113, v2
	v_mul_f32_e32 v2, 0xbfb8aa3b, v111
	v_exp_f32_e32 v2, v2
	v_mul_f32_e32 v106, v0, v88
	v_pk_mul_f32 v[102:103], v[112:113], v[102:103]
	v_add_f32_e32 v2, 1.0, v2
	v_pk_mul_f32 v[94:95], v[102:103], v[94:95]
	v_rcp_f32_e32 v103, v2
	v_mul_f32_e32 v2, 0xbfb8aa3b, v87
	v_exp_f32_e32 v2, v2
	v_mov_b32_e32 v102, v108
	v_pk_mul_f32 v[102:103], v[102:103], v[110:111]
	v_add_f32_e32 v2, 1.0, v2
	v_rcp_f32_e32 v93, v2
	s_nop 0
	v_pk_mul_f32 v[86:87], v[92:93], v[86:87]
	v_cvt_pk_bf16_f32 v92, v94, v95
	v_mov_b32_e32 v94, v102
	v_mov_b32_e32 v95, v86
	v_mov_b32_e32 v86, v103
	v_pk_mul_f32 v[86:87], v[94:95], v[86:87]
	v_mul_f32_e32 v102, v90, v88
	v_cvt_pk_bf16_f32 v93, v86, v87
	global_store_dwordx2 v[84:85], v[92:93], off offset:1088
	v_mov_b64_e32 v[86:87], v[236:237]
	s_nop 0
	v_mov_b64_e32 v[92:93], v[196:197]
	v_mov_b64_e32 v[94:95], v[198:199]
	v_mul_f32_e32 v104, v91, v88
	s_waitcnt lgkmcnt(0)
; template <int KIND>
; __device__ __forceinline__ void w_m3_core(const bf16x8 (&Qf)[4][2], const bf16x8 (&Kf)[4][2], const bf16x8 (&Sf)[4][2], const LAS bf16_t* vT, float lg,
;                                           const bf16_t* gsrc, const float* nw, bf16_t* ydst, int lo, int fq) {
;     ...
;         for (int kk2 = 0; kk2 < 2; ++kk2) {
;             if (2 * kk2 > nb) continue;
;             float pv[8];
; #pragma unroll
;             for (int hh = 0; hh < 2; ++hh) { const int mb = 2 * kk2 + hh;
;                 if (mb <= nb) { f32x4 s = {0.f, 0.f, 0.f, 0.f};
;                     s = __builtin_amdgcn_mfma_f32_16x16x32_bf16(Kf[mb][0], Qf[nb][0], s, 0, 0, 0); s = __builtin_amdgcn_mfma_f32_16x16x32_bf16(Kf[mb][1], Qf[nb][1], s, 0, 0, 0);
; #pragma unroll
;                     for (int r = 0; r < 4; ++r) { const int m = 16 * mb + 4 * fq + r, n = 16 * nb + lo; float v = s[r];
;                         if (KIND == 0) v *= __expf((float)(n - m) * lg);
;                         if (mb == nb) v = (m <= n) ? v : 0.f;
;                         pv[4 * hh + r] = v; }
;                 } else {
; #pragma unroll
;                     for (int r = 0; r < 4; ++r) pv[4 * hh + r] = 0.f; }
;             }
;             const bf16x8 Pf = pack_frag(pv);
; #pragma unroll
;             for (int eb = 0; eb < 4; ++eb)
;                 O[eb] = __builtin_amdgcn_mfma_f32_16x16x32_bf16(tr_frag(vT, 32 * kk2 + 4 * fq, 32 * kk2 + 16 + 4 * fq, 16 * eb, lo), Pf, O[eb], 0, 0, 0);
;     ...
;         const size_t n = 16 * nb + lo;
; #pragma unroll
;         for (int eb = 0; eb < 4; ++eb) { const int e0 = 16 * eb + 4 * fq;
;             const unsigned long long gw_ = *(const unsigned long long*)(gsrc + n * NIN + e0); const f32x4 w4 = *(const f32x4*)(nw + e0);
;             const float g0 = __uint_as_float((unsigned)gw_ << 16), g1 = __uint_as_float((unsigned)gw_ & 0xffff0000u), g2 = __uint_as_float((unsigned)(gw_ >> 32) << 16), g3 = __uint_as_float((unsigned)(gw_ >> 32) & 0xffff0000u);
;             const float o0 = O[eb][0] * rs * w4[0] * (g0 * sigmoidf_(g0)), o1 = O[eb][1] * rs * w4[1] * (g1 * sigmoidf_(g1));
;             const float o2 = O[eb][2] * rs * w4[2] * (g2 * sigmoidf_(g2)), o3 = O[eb][3] * rs * w4[3] * (g3 * sigmoidf_(g3));
;             *(unsigned long long*)(ydst + n * DM + e0) = (unsigned long long)pk2(o0, o1) | ((unsigned long long)pk2(o2, o3) << 32); }
	v_lshlrev_b32_e32 v103, 16, v86
	v_lshlrev_b32_e32 v107, 16, v87
	v_mul_f32_e32 v2, 0xbfb8aa3b, v103
	v_mul_f32_e32 v0, 0xbfb8aa3b, v107
	v_exp_f32_e32 v2, v2
	v_exp_f32_e32 v0, v0
	v_and_b32_e32 v105, 0xffff0000, v86
	v_and_b32_e32 v87, 0xffff0000, v87
	v_add_f32_e32 v2, 1.0, v2
	v_add_f32_e32 v0, 1.0, v0
	v_rcp_f32_e32 v109, v2
	v_mul_f32_e32 v2, 0xbfb8aa3b, v105
	v_mov_b32_e32 v90, v93
	v_rcp_f32_e32 v93, v0
	v_mul_f32_e32 v0, 0xbfb8aa3b, v87
	v_exp_f32_e32 v2, v2
	v_exp_f32_e32 v0, v0
	v_mul_f32_e32 v86, v1, v88
	v_mov_b32_e32 v108, v92
	v_add_f32_e32 v2, 1.0, v2
	v_add_f32_e32 v0, 1.0, v0
	v_rcp_f32_e32 v91, v2
	v_rcp_f32_e32 v1, v0
	v_mov_b32_e32 v92, v94
	v_mov_b32_e32 v0, v95
	v_pk_mul_f32 v[102:103], v[108:109], v[102:103]
	v_pk_mul_f32 v[90:91], v[90:91], v[104:105]
	v_pk_mul_f32 v[92:93], v[92:93], v[106:107]
	v_pk_mul_f32 v[0:1], v[0:1], v[86:87]
	v_mov_b32_e32 v86, v102
	v_mov_b32_e32 v87, v90
	v_mov_b32_e32 v90, v103
	v_mov_b32_e32 v88, v92
	v_mov_b32_e32 v89, v0
	v_mov_b32_e32 v0, v93
	v_pk_mul_f32 v[86:87], v[86:87], v[90:91]
	v_pk_mul_f32 v[0:1], v[88:89], v[0:1]
	v_cvt_pk_bf16_f32 v86, v86, v87
	v_cvt_pk_bf16_f32 v87, v0, v1
	global_store_dwordx2 v[84:85], v[86:87], off offset:1120
	v_sub_u32_e32 v0, v136, v124
	v_add_u32_e32 v1, v136, v143
	v_cvt_f32_i32_e32 v0, v0
	v_cvt_f32_i32_e32 v1, v1
	v_mfma_f32_16x16x32_bf16 v[84:87], v[64:67], v[80:83], 0
	v_sub_u32_e32 v2, v136, v142
	v_mul_f32_e32 v0, v135, v0
	v_mul_f32_e32 v1, v135, v1
	v_cvt_f32_i32_e32 v2, v2
	v_mul_f32_e32 v0, 0x3fb8aa3b, v0
	v_mul_f32_e32 v1, 0x3fb8aa3b, v1
	v_mfma_f32_16x16x32_bf16 v[84:87], v[72:75], v[76:79], v[84:87]
	v_exp_f32_e32 v0, v0
	v_exp_f32_e32 v1, v1
	v_mul_f32_e32 v2, v135, v2
	v_mul_f32_e32 v2, 0x3fb8aa3b, v2
	s_nop 3
	v_pk_mul_f32 v[0:1], v[0:1], v[84:85]
	v_exp_f32_e32 v84, v2
	v_sub_u32_e32 v2, v136, v141
	v_cvt_f32_i32_e32 v2, v2
	v_mul_f32_e32 v2, v135, v2
	v_mul_f32_e32 v2, 0x3fb8aa3b, v2
	v_exp_f32_e32 v85, v2
	v_sub_u32_e32 v2, v136, v114
	v_cvt_f32_i32_e32 v2, v2
	v_pk_mul_f32 v[88:89], v[84:85], v[86:87]
	v_mfma_f32_16x16x32_bf16 v[84:87], v[60:63], v[80:83], 0
	v_mul_f32_e32 v2, v135, v2
	v_mul_f32_e32 v2, 0x3fb8aa3b, v2
	v_exp_f32_e32 v91, v2
	v_sub_u32_e32 v2, v136, v140
	v_cvt_f32_i32_e32 v2, v2
	v_mfma_f32_16x16x32_bf16 v[84:87], v[68:71], v[76:79], v[84:87]
	v_mul_f32_e32 v2, v135, v2
	v_mul_f32_e32 v2, 0x3fb8aa3b, v2
	v_exp_f32_e32 v92, v2
	v_sub_u32_e32 v2, v136, v115
	v_cvt_f32_i32_e32 v2, v2
	v_mul_f32_e32 v2, v135, v2
	v_mul_f32_e32 v2, 0x3fb8aa3b, v2
	v_exp_f32_e32 v93, v2
	v_sub_u32_e32 v2, v136, v116
	v_cvt_f32_i32_e32 v2, v2
	v_pk_mul_f32 v[92:93], v[92:93], v[84:85]
	v_cvt_pk_bf16_f32 v85, v88, v89
	v_mul_f32_e32 v2, v135, v2
	v_mul_f32_e32 v2, 0x3fb8aa3b, v2
	v_exp_f32_e32 v90, v2
	v_cvt_pk_bf16_f32 v84, v0, v1
	v_pk_mul_f32 v[90:91], v[90:91], v[86:87]
	v_cvt_pk_bf16_f32 v86, v92, v93
	v_cvt_pk_bf16_f32 v87, v90, v91
	ds_read_b64_tr_b16 v[90:91], v126
	ds_read_b64_tr_b16 v[94:95], v126 offset:32
	ds_read_b64_tr_b16 v[88:89], v128
	ds_read_b64_tr_b16 v[92:93], v128 offset:32
	ds_read_b64_tr_b16 v[102:103], v128 offset:64
	ds_read_b64_tr_b16 v[104:105], v126 offset:64
	ds_read_b64_tr_b16 v[106:107], v128 offset:96
	ds_read_b64_tr_b16 v[108:109], v126 offset:96
	s_waitcnt lgkmcnt(0)
	v_mfma_f32_16x16x32_bf16 v[88:91], v[88:91], v[84:87], 0
	v_mfma_f32_16x16x32_bf16 v[92:95], v[92:95], v[84:87], 0
	v_mfma_f32_16x16x32_bf16 v[102:105], v[102:105], v[84:87], 0
	v_mfma_f32_16x16x32_bf16 v[84:87], v[106:109], v[84:87], 0
	v_mfma_f32_16x16x32_bf16 v[106:109], v[44:47], v[80:83], 0
	v_mfma_f32_16x16x32_bf16 v[108:111], v[48:51], v[76:79], v[106:109]
	s_nop 6
	v_add_u32_e32 v107, 33, v124
	v_mul_f32_e32 v0, v139, v108
	v_cndmask_b32_e64 v2, v0, 0, vcc
	v_sub_u32_e32 v0, v136, v107
	v_cvt_f32_i32_e32 v0, v0
	v_cmp_ge_i32_e64 s[38:39], v136, v107
	v_add_u32_e32 v106, 35, v124
	v_add_u32_e32 v108, 34, v124
	v_mul_f32_e32 v0, v135, v0
	v_mul_f32_e32 v0, 0x3fb8aa3b, v0
	v_exp_f32_e32 v0, v0
	v_sub_u32_e32 v1, v136, v106
	v_cvt_f32_i32_e32 v1, v1
	v_mul_f32_e32 v0, v0, v109
	v_cndmask_b32_e64 v109, 0, v0, s[38:39]
	v_sub_u32_e32 v0, v136, v108
	v_cvt_f32_i32_e32 v0, v0
	v_mul_f32_e32 v1, v135, v1
	v_mul_f32_e32 v1, 0x3fb8aa3b, v1
	v_exp_f32_e32 v1, v1
	v_mul_f32_e32 v0, v135, v0
	v_mul_f32_e32 v0, 0x3fb8aa3b, v0
	v_exp_f32_e32 v0, v0
	v_cmp_ge_i32_e64 s[38:39], v136, v108
	v_pk_mul_f32 v[110:111], v[0:1], v[110:111]
	s_nop 0
	v_cvt_pk_bf16_f32 v1, v110, v111
	ds_read_b64_tr_b16 v[110:111], v128 offset:4608
	ds_read_b64_tr_b16 v[112:113], v126 offset:4608
	v_cvt_pk_bf16_f32 v0, v2, v109
	v_cndmask_b32_e64 v2, 0, v1, s[38:39]
	v_lshrrev_b32_e32 v1, 16, v1
	v_cmp_ge_i32_e64 s[38:39], v136, v106
	s_nop 1
	v_cndmask_b32_e64 v1, 0, v1, s[38:39]
	v_perm_b32 v1, v1, v2, s53
	v_mov_b32_e32 v2, v3
	s_waitcnt lgkmcnt(0)
	s_nop 0
	v_mfma_f32_16x16x32_bf16 v[88:91], v[110:113], v[0:3], v[88:91]
	ds_read_b64_tr_b16 v[110:111], v128 offset:4640
	ds_read_b64_tr_b16 v[112:113], v126 offset:4640
	s_waitcnt lgkmcnt(0)
	v_mfma_f32_16x16x32_bf16 v[110:113], v[110:113], v[0:3], v[92:95]
	s_nop 2
	ds_read_b64_tr_b16 v[92:93], v128 offset:4672
	ds_read_b64_tr_b16 v[94:95], v126 offset:4672
	s_waitcnt lgkmcnt(0)
	v_mfma_f32_16x16x32_bf16 v[118:121], v[92:95], v[0:3], v[102:105]
	ds_read_b64_tr_b16 v[92:93], v128 offset:4704
	ds_read_b64_tr_b16 v[94:95], v126 offset:4704
	s_waitcnt lgkmcnt(0)
; __device__ __forceinline__ unsigned pk2(float lo, float hi) { const f32x2_t v = {lo, hi}; const bf16x2_t b = __builtin_convertvector(v, bf16x2_t); return __builtin_bit_cast(unsigned, b); }
; __device__ __forceinline__ float sigmoidf_(float x) { return __builtin_amdgcn_rcpf(1.0f + __expf(-x)); }
; __device__ __forceinline__ float bperm_f(int src_lane, float v) { return __builtin_bit_cast(float, __builtin_amdgcn_ds_bpermute(src_lane << 2, __builtin_bit_cast(int, v))); }
; template <int KIND>
; __device__ __forceinline__ void w_m3_core(const bf16x8 (&Qf)[4][2], const bf16x8 (&Kf)[4][2], const bf16x8 (&Sf)[4][2], const LAS bf16_t* vT, float lg,
;                                           const bf16_t* gsrc, const float* nw, bf16_t* ydst, int lo, int fq) {
;     ...
; #pragma unroll
;         for (int kk = 0; kk < 2; ++kk)
; #pragma unroll
;             for (int eb = 0; eb < 4; ++eb) O2[eb] = __builtin_amdgcn_mfma_f32_16x16x32_bf16(Sf[eb][kk], Qf[nb][kk], O2[eb], 0, 0, 0);
;         const float osc = KIND == 0 ? __expf((float)(16 * nb + lo + 1) * lg) : 1.0f;
; #pragma unroll
;         for (int eb = 0; eb < 4; ++eb) O[eb] = O[eb] + O2[eb] * osc;
;         float ss = 0.f;
; #pragma unroll
;         for (int eb = 0; eb < 4; ++eb) ss += (O[eb][0] * O[eb][0] + O[eb][1] * O[eb][1]) + (O[eb][2] * O[eb][2] + O[eb][3] * O[eb][3]);
;         { const int ln = (fq << 4) | lo; ss += bperm_f(ln ^ 16, ss); ss += bperm_f(ln ^ 32, ss); }
;         const float rs = rsqrtf(ss * (1.0f / 64.0f) + EPS);
;         const size_t n = 16 * nb + lo;
; #pragma unroll
;         for (int eb = 0; eb < 4; ++eb) { const int e0 = 16 * eb + 4 * fq;
;             const unsigned long long gw_ = *(const unsigned long long*)(gsrc + n * NIN + e0); const f32x4 w4 = *(const f32x4*)(nw + e0);
;             const float g0 = __uint_as_float((unsigned)gw_ << 16), g1 = __uint_as_float((unsigned)gw_ & 0xffff0000u), g2 = __uint_as_float((unsigned)(gw_ >> 32) << 16), g3 = __uint_as_float((unsigned)(gw_ >> 32) & 0xffff0000u);
;             const float o0 = O[eb][0] * rs * w4[0] * (g0 * sigmoidf_(g0)), o1 = O[eb][1] * rs * w4[1] * (g1 * sigmoidf_(g1));
;             const float o2 = O[eb][2] * rs * w4[2] * (g2 * sigmoidf_(g2)), o3 = O[eb][3] * rs * w4[3] * (g3 * sigmoidf_(g3));
;             *(unsigned long long*)(ydst + n * DM + e0) = (unsigned long long)pk2(o0, o1) | ((unsigned long long)pk2(o2, o3) << 32); }
	v_mfma_f32_16x16x32_bf16 v[144:147], v[92:95], v[0:3], v[84:87]
	v_add_u32_e32 v0, 33, v133
	v_cvt_f32_ubyte0_e32 v0, v0
	v_mul_f32_e32 v0, v135, v0
	v_mfma_f32_16x16x32_bf16 v[84:87], v[20:23], v[80:83], 0
	v_mul_f32_e32 v0, 0x3fb8aa3b, v0
	v_exp_f32_e32 v2, v0
	v_mfma_f32_16x16x32_bf16 v[92:95], v[24:27], v[80:83], 0
	v_mfma_f32_16x16x32_bf16 v[102:105], v[36:39], v[80:83], 0
	v_mfma_f32_16x16x32_bf16 v[80:83], v[40:43], v[80:83], 0
	v_mfma_f32_16x16x32_bf16 v[84:87], v[12:15], v[76:79], v[84:87]
	v_mfma_f32_16x16x32_bf16 v[148:151], v[16:19], v[76:79], v[92:95]
	v_mfma_f32_16x16x32_bf16 v[152:155], v[28:31], v[76:79], v[102:105]
	s_nop 5
	v_fma_f32 v94, v2, v86, v90
	v_fma_f32 v95, v2, v87, v91
	v_pk_fma_f32 v[92:93], v[2:3], v[148:149], v[110:111] op_sel_hi:[0,1,1]
	v_mfma_f32_16x16x32_bf16 v[76:79], v[32:35], v[76:79], v[80:83]
	v_fma_f32 v102, v2, v84, v88
	v_fma_f32 v103, v2, v85, v89
	v_pk_fma_f32 v[88:89], v[2:3], v[150:151], v[112:113] op_sel_hi:[0,1,1]
	v_pk_fma_f32 v[84:85], v[2:3], v[154:155], v[120:121] op_sel_hi:[0,1,1]
	v_pk_fma_f32 v[86:87], v[2:3], v[152:153], v[118:119] op_sel_hi:[0,1,1]
	s_nop 2
	v_pk_fma_f32 v[0:1], v[2:3], v[78:79], v[146:147] op_sel_hi:[0,1,1]
	v_pk_fma_f32 v[82:83], v[2:3], v[76:77], v[144:145] op_sel_hi:[0,1,1]
	v_pk_mul_f32 v[76:77], v[94:95], v[94:95]
	v_pk_mul_f32 v[78:79], v[102:103], v[102:103]
	v_mul_f32_e32 v2, v82, v82
	v_pk_mov_b32 v[80:81], v[78:79], v[76:77] op_sel:[1,0]
	v_mov_b32_e32 v79, v77
	v_pk_add_f32 v[76:77], v[80:81], v[78:79]
	v_pk_mul_f32 v[78:79], v[88:89], v[88:89]
	v_pk_mul_f32 v[80:81], v[92:93], v[92:93]
	v_pk_add_f32 v[76:77], v[76:77], v[76:77] op_sel:[0,1] op_sel_hi:[1,0]
	v_pk_mov_b32 v[90:91], v[80:81], v[78:79] op_sel:[1,0]
	v_mov_b32_e32 v81, v79
	v_pk_add_f32 v[78:79], v[90:91], v[80:81]
	v_mul_f32_e32 v80, v83, v83
	v_pk_add_f32 v[78:79], v[78:79], v[78:79] op_sel:[0,1] op_sel_hi:[1,0]
	v_mov_b32_e32 v77, v2
	v_mov_b32_e32 v79, v80
	v_mul_f32_e32 v2, v87, v87
	v_mul_f32_e32 v81, v0, v0
	v_pk_add_f32 v[76:77], v[76:77], v[78:79]
	v_pk_fma_f32 v[78:79], v[86:87], v[86:87], v[2:3] op_sel_hi:[1,1,0]
	v_mul_f32_e32 v2, v85, v85
	v_mul_f32_e32 v90, v1, v1
	v_mov_b32_e32 v79, v81
	v_pk_fma_f32 v[80:81], v[84:85], v[84:85], v[2:3] op_sel_hi:[1,1,0]
	s_nop 0
	v_mov_b32_e32 v81, v90
	v_pk_add_f32 v[78:79], v[78:79], v[80:81]
	s_nop 0
	v_pk_add_f32 v[76:77], v[76:77], v[78:79]
	s_nop 0
	v_add_f32_e32 v2, v76, v77
	ds_bpermute_b32 v76, v138, v2
	s_waitcnt lgkmcnt(0)
	v_add_f32_e32 v2, v2, v76
	ds_bpermute_b32 v76, v137, v2
	s_waitcnt lgkmcnt(0)
	v_add_f32_e32 v2, v2, v76
	v_fmamk_f32 v2, v2, 0x3c800000, v200
	v_cmp_gt_f32_e64 s[38:39], s29, v2
	v_mul_f32_e32 v76, 0x4b800000, v2
	s_nop 0
	v_cndmask_b32_e64 v2, v2, v76, s[38:39]
	v_rsq_f32_e32 v2, v2
	s_nop 0
	v_mul_f32_e32 v76, 0x45800000, v2
	v_cndmask_b32_e64 v80, v2, v76, s[38:39]
	v_mad_u64_u32 v[76:77], s[20:21], v136, s72, v[98:99]
	v_lshl_add_u64 v[90:91], v[76:77], 0, v[96:97]
	v_mov_b64_e32 v[110:111], v[238:239]
	v_mov_b64_e32 v[76:77], v[184:185]
	v_mov_b64_e32 v[78:79], v[186:187]
	v_lshlrev_b32_e32 v2, 11, v136
	v_lshl_add_u64 v[104:105], s[40:41], 0, v[2:3]
	v_pk_mul_f32 v[102:103], v[102:103], v[80:81] op_sel_hi:[1,0]
	v_pk_mul_f32 v[94:95], v[94:95], v[80:81] op_sel_hi:[1,0]
	v_pk_mul_f32 v[92:93], v[92:93], v[80:81] op_sel_hi:[1,0]
	v_pk_mul_f32 v[88:89], v[88:89], v[80:81] op_sel_hi:[1,0]
	v_pk_mul_f32 v[86:87], v[86:87], v[80:81] op_sel_hi:[1,0]
	s_waitcnt lgkmcnt(0)
	v_lshlrev_b32_e32 v112, 16, v110
	v_mul_f32_e32 v2, 0xbfb8aa3b, v112
	v_exp_f32_e32 v2, v2
	v_and_b32_e32 v113, 0xffff0000, v110
	v_lshlrev_b32_e32 v110, 16, v111
	v_and_b32_e32 v111, 0xffff0000, v111
	v_add_f32_e32 v2, 1.0, v2
	v_rcp_f32_e32 v118, v2
	v_mul_f32_e32 v2, 0xbfb8aa3b, v113
	v_exp_f32_e32 v2, v2
	v_pk_mul_f32 v[76:77], v[76:77], v[102:103]
	v_pk_mul_f32 v[78:79], v[78:79], v[94:95]
	v_add_f32_e32 v2, 1.0, v2
	v_rcp_f32_e32 v119, v2
	v_mul_f32_e32 v2, 0xbfb8aa3b, v110
	v_exp_f32_e32 v2, v2
	v_pk_mul_f32 v[102:103], v[118:119], v[112:113]
	s_nop 0
	v_pk_mul_f32 v[76:77], v[102:103], v[76:77]
	v_add_f32_e32 v2, 1.0, v2
	v_rcp_f32_e32 v102, v2
	v_mul_f32_e32 v2, 0xbfb8aa3b, v111
	v_exp_f32_e32 v2, v2
	s_nop 0
	v_add_f32_e32 v2, 1.0, v2
	v_rcp_f32_e32 v103, v2
	s_nop 0
	v_pk_mul_f32 v[94:95], v[102:103], v[110:111]
	s_nop 0
	v_pk_mul_f32 v[78:79], v[94:95], v[78:79]
	v_cvt_pk_bf16_f32 v94, v76, v77
	v_cvt_pk_bf16_f32 v95, v78, v79
	v_lshl_add_u64 v[76:77], v[104:105], 0, v[96:97]
	global_store_dwordx2 v[76:77], v[94:95], off offset:1024
	v_mov_b64_e32 v[78:79], v[240:241]
	v_mov_b64_e32 v[102:103], v[188:189]
	v_mov_b64_e32 v[104:105], v[190:191]
	s_waitcnt lgkmcnt(0)
	v_lshlrev_b32_e32 v94, 16, v78
	v_mul_f32_e32 v2, 0xbfb8aa3b, v94
	v_exp_f32_e32 v2, v2
	v_and_b32_e32 v95, 0xffff0000, v78
	v_lshlrev_b32_e32 v78, 16, v79
	v_and_b32_e32 v79, 0xffff0000, v79
	v_add_f32_e32 v2, 1.0, v2
	v_rcp_f32_e32 v110, v2
	v_mul_f32_e32 v2, 0xbfb8aa3b, v95
	v_exp_f32_e32 v2, v2
	v_pk_mul_f32 v[92:93], v[102:103], v[92:93]
	v_pk_mul_f32 v[88:89], v[104:105], v[88:89]
	v_mul_f32_e32 v102, v84, v80
	v_add_f32_e32 v2, 1.0, v2
	v_rcp_f32_e32 v111, v2
	v_mul_f32_e32 v2, 0xbfb8aa3b, v78
	v_exp_f32_e32 v2, v2
	v_pk_mul_f32 v[94:95], v[110:111], v[94:95]
	s_nop 0
	v_pk_mul_f32 v[92:93], v[94:95], v[92:93]
	v_add_f32_e32 v2, 1.0, v2
	v_rcp_f32_e32 v94, v2
	v_mul_f32_e32 v2, 0xbfb8aa3b, v79
	v_exp_f32_e32 v2, v2
	s_nop 0
	v_add_f32_e32 v2, 1.0, v2
	v_rcp_f32_e32 v95, v2
	s_nop 0
	v_pk_mul_f32 v[78:79], v[94:95], v[78:79]
	s_nop 0
	v_pk_mul_f32 v[78:79], v[78:79], v[88:89]
	v_cvt_pk_bf16_f32 v88, v92, v93
	v_cvt_pk_bf16_f32 v89, v78, v79
	global_store_dwordx2 v[76:77], v[88:89], off offset:1056
	v_mov_b64_e32 v[78:79], v[242:243]
	v_mov_b64_e32 v[92:93], v[192:193]
	v_mov_b64_e32 v[94:95], v[194:195]
	s_waitcnt lgkmcnt(0)
; __device__ __forceinline__ unsigned pk2(float lo, float hi) { const f32x2_t v = {lo, hi}; const bf16x2_t b = __builtin_convertvector(v, bf16x2_t); return __builtin_bit_cast(unsigned, b); }
; __device__ __forceinline__ float sigmoidf_(float x) { return __builtin_amdgcn_rcpf(1.0f + __expf(-x)); }
; template <int KIND>
; __device__ __forceinline__ void w_m3_core(const bf16x8 (&Qf)[4][2], const bf16x8 (&Kf)[4][2], const bf16x8 (&Sf)[4][2], const LAS bf16_t* vT, float lg,
;                                           const bf16_t* gsrc, const float* nw, bf16_t* ydst, int lo, int fq) {
;     ...
;         for (int kk2 = 0; kk2 < 2; ++kk2) {
;             if (2 * kk2 > nb) continue;
;             float pv[8];
; #pragma unroll
;             for (int hh = 0; hh < 2; ++hh) { const int mb = 2 * kk2 + hh;
;                 if (mb <= nb) { f32x4 s = {0.f, 0.f, 0.f, 0.f};
;                     s = __builtin_amdgcn_mfma_f32_16x16x32_bf16(Kf[mb][0], Qf[nb][0], s, 0, 0, 0); s = __builtin_amdgcn_mfma_f32_16x16x32_bf16(Kf[mb][1], Qf[nb][1], s, 0, 0, 0);
; #pragma unroll
;                     for (int r = 0; r < 4; ++r) { const int m = 16 * mb + 4 * fq + r, n = 16 * nb + lo; float v = s[r];
;                         if (KIND == 0) v *= __expf((float)(n - m) * lg);
;                         if (mb == nb) v = (m <= n) ? v : 0.f;
;                         pv[4 * hh + r] = v; }
;                 } else {
; #pragma unroll
;                     for (int r = 0; r < 4; ++r) pv[4 * hh + r] = 0.f; }
;             }
;     ...
;         const size_t n = 16 * nb + lo;
; #pragma unroll
;         for (int eb = 0; eb < 4; ++eb) { const int e0 = 16 * eb + 4 * fq;
;             const unsigned long long gw_ = *(const unsigned long long*)(gsrc + n * NIN + e0); const f32x4 w4 = *(const f32x4*)(nw + e0);
;             const float g0 = __uint_as_float((unsigned)gw_ << 16), g1 = __uint_as_float((unsigned)gw_ & 0xffff0000u), g2 = __uint_as_float((unsigned)(gw_ >> 32) << 16), g3 = __uint_as_float((unsigned)(gw_ >> 32) & 0xffff0000u);
;             const float o0 = O[eb][0] * rs * w4[0] * (g0 * sigmoidf_(g0)), o1 = O[eb][1] * rs * w4[1] * (g1 * sigmoidf_(g1));
;             const float o2 = O[eb][2] * rs * w4[2] * (g2 * sigmoidf_(g2)), o3 = O[eb][3] * rs * w4[3] * (g3 * sigmoidf_(g3));
;             *(unsigned long long*)(ydst + n * DM + e0) = (unsigned long long)pk2(o0, o1) | ((unsigned long long)pk2(o2, o3) << 32); }
	v_lshlrev_b32_e32 v88, 16, v78
	v_mul_f32_e32 v2, 0xbfb8aa3b, v88
	v_exp_f32_e32 v2, v2
	v_and_b32_e32 v89, 0xffff0000, v78
	v_lshlrev_b32_e32 v103, 16, v79
	v_and_b32_e32 v79, 0xffff0000, v79
	v_add_f32_e32 v2, 1.0, v2
	v_rcp_f32_e32 v104, v2
	v_mul_f32_e32 v2, 0xbfb8aa3b, v89
	v_exp_f32_e32 v2, v2
	v_pk_mul_f32 v[86:87], v[92:93], v[86:87]
	v_mul_f32_e32 v78, v85, v80
	v_mov_b32_e32 v84, v95
	v_add_f32_e32 v2, 1.0, v2
	v_rcp_f32_e32 v105, v2
	v_mul_f32_e32 v2, 0xbfb8aa3b, v103
	v_exp_f32_e32 v2, v2
	v_mul_f32_e32 v92, v0, v80
	v_pk_mul_f32 v[88:89], v[104:105], v[88:89]
	v_add_f32_e32 v2, 1.0, v2
	v_pk_mul_f32 v[86:87], v[88:89], v[86:87]
	v_rcp_f32_e32 v89, v2
	v_mul_f32_e32 v2, 0xbfb8aa3b, v79
	v_exp_f32_e32 v2, v2
	v_mov_b32_e32 v88, v94
	v_pk_mul_f32 v[88:89], v[88:89], v[102:103]
	v_add_f32_e32 v2, 1.0, v2
	v_rcp_f32_e32 v85, v2
	s_nop 0
	v_pk_mul_f32 v[78:79], v[84:85], v[78:79]
	v_cvt_pk_bf16_f32 v84, v86, v87
	v_mov_b32_e32 v86, v88
	v_mov_b32_e32 v87, v78
	v_mov_b32_e32 v78, v89
	v_pk_mul_f32 v[78:79], v[86:87], v[78:79]
	v_mul_f32_e32 v88, v82, v80
	v_cvt_pk_bf16_f32 v85, v78, v79
	global_store_dwordx2 v[76:77], v[84:85], off offset:1088
	v_mov_b64_e32 v[78:79], v[244:245]
	s_nop 0
	v_mov_b64_e32 v[84:85], v[196:197]
	v_mov_b64_e32 v[86:87], v[198:199]
	v_mul_f32_e32 v90, v83, v80
	s_waitcnt lgkmcnt(0)
	v_lshlrev_b32_e32 v89, 16, v78
	v_lshlrev_b32_e32 v93, 16, v79
	v_mul_f32_e32 v2, 0xbfb8aa3b, v89
	v_mul_f32_e32 v0, 0xbfb8aa3b, v93
	v_exp_f32_e32 v2, v2
	v_exp_f32_e32 v0, v0
	v_and_b32_e32 v91, 0xffff0000, v78
	v_and_b32_e32 v79, 0xffff0000, v79
	v_add_f32_e32 v2, 1.0, v2
	v_add_f32_e32 v0, 1.0, v0
	v_rcp_f32_e32 v95, v2
	v_mul_f32_e32 v2, 0xbfb8aa3b, v91
	v_mov_b32_e32 v82, v85
	v_rcp_f32_e32 v85, v0
	v_mul_f32_e32 v0, 0xbfb8aa3b, v79
	v_exp_f32_e32 v2, v2
	v_exp_f32_e32 v0, v0
	v_mul_f32_e32 v78, v1, v80
	v_mov_b32_e32 v94, v84
	v_add_f32_e32 v2, 1.0, v2
	v_add_f32_e32 v0, 1.0, v0
	v_rcp_f32_e32 v83, v2
	v_rcp_f32_e32 v1, v0
	v_mov_b32_e32 v84, v86
	v_mov_b32_e32 v0, v87
	v_pk_mul_f32 v[88:89], v[94:95], v[88:89]
	v_pk_mul_f32 v[82:83], v[82:83], v[90:91]
	v_pk_mul_f32 v[84:85], v[84:85], v[92:93]
	v_pk_mul_f32 v[0:1], v[0:1], v[78:79]
	v_mov_b32_e32 v78, v88
	v_mov_b32_e32 v79, v82
	v_mov_b32_e32 v82, v89
	v_mov_b32_e32 v80, v84
	v_mov_b32_e32 v81, v0
	v_mov_b32_e32 v0, v85
	v_pk_mul_f32 v[78:79], v[78:79], v[82:83]
	v_pk_mul_f32 v[0:1], v[80:81], v[0:1]
	v_cvt_pk_bf16_f32 v78, v78, v79
	v_cvt_pk_bf16_f32 v79, v0, v1
	global_store_dwordx2 v[76:77], v[78:79], off offset:1120
	v_sub_u32_e32 v2, v134, v124
	v_add_u32_e32 v1, v134, v143
	v_cvt_f32_i32_e32 v0, v2
	v_cvt_f32_i32_e32 v1, v1
	v_mfma_f32_16x16x32_bf16 v[64:67], v[64:67], v[8:11], 0
	v_mul_f32_e32 v0, v135, v0
	v_mul_f32_e32 v1, v135, v1
	v_mul_f32_e32 v0, 0x3fb8aa3b, v0
	v_mul_f32_e32 v1, 0x3fb8aa3b, v1
	v_mfma_f32_16x16x32_bf16 v[64:67], v[72:75], v[4:7], v[64:67]
	v_exp_f32_e32 v0, v0
	v_exp_f32_e32 v1, v1
	v_mfma_f32_16x16x32_bf16 v[60:63], v[60:63], v[8:11], 0
	v_mfma_f32_16x16x32_bf16 v[60:63], v[68:71], v[4:7], v[60:63]
	s_nop 3
	v_mul_f32_e64 v0, v0, v64
	v_mul_f32_e64 v1, v1, v65
	v_sub_u32_e32 v64, v134, v142
	v_cvt_pk_bf16_f32 v68, v0, v1
	v_subrev_u32_e32 v0, 32, v2
	v_sub_u32_e32 v1, v134, v107
	v_cvt_f32_i32_e32 v0, v0
	v_cvt_f32_i32_e32 v1, v1
	v_mfma_f32_16x16x32_bf16 v[44:47], v[44:47], v[8:11], 0
	v_sub_u32_e32 v2, v134, v108
	v_mul_f32_e32 v0, v135, v0
	v_mul_f32_e32 v1, v135, v1
	v_cvt_f32_i32_e32 v2, v2
	v_mul_f32_e32 v0, 0x3fb8aa3b, v0
	v_mul_f32_e32 v1, 0x3fb8aa3b, v1
	v_mfma_f32_16x16x32_bf16 v[44:47], v[48:51], v[4:7], v[44:47]
	v_exp_f32_e32 v0, v0
	v_exp_f32_e32 v1, v1
	v_mul_f32_e32 v2, v135, v2
	v_mul_f32_e32 v2, 0x3fb8aa3b, v2
	v_sub_u32_e32 v65, v134, v141
	s_nop 2
	v_pk_mul_f32 v[0:1], v[0:1], v[44:45]
	v_exp_f32_e32 v44, v2
	v_sub_u32_e32 v2, v134, v106
	v_cvt_f32_i32_e32 v2, v2
	v_cvt_f32_i32_e32 v64, v64
	v_cvt_f32_i32_e32 v65, v65
	v_mfma_f32_16x16x32_bf16 v[20:23], v[20:23], v[8:11], 0
	v_mul_f32_e32 v2, v135, v2
	v_mul_f32_e32 v2, 0x3fb8aa3b, v2
	v_exp_f32_e32 v45, v2
	v_mul_f32_e32 v64, v135, v64
	v_mul_f32_e32 v65, v135, v65
	v_mul_f32_e32 v64, 0x3fb8aa3b, v64
	v_pk_mul_f32 v[48:49], v[44:45], v[46:47]
	v_mfma_f32_16x16x32_bf16 v[44:47], v[52:55], v[8:11], 0
	v_mul_f32_e32 v65, 0x3fb8aa3b, v65
	v_exp_f32_e32 v64, v64
	v_exp_f32_e32 v65, v65
	v_mfma_f32_16x16x32_bf16 v[44:47], v[56:59], v[4:7], v[44:47]
	v_mul_f32_e64 v64, v64, v66
	v_mul_f32_e64 v65, v65, v67
	v_sub_u32_e32 v66, v134, v140
	v_sub_u32_e32 v67, v134, v115
	s_nop 3
	v_mul_f32_e32 v2, v139, v44
	v_add_u32_e32 v44, 49, v124
	v_sub_u32_e32 v50, v134, v44
	v_cvt_f32_i32_e32 v50, v50
	v_cvt_f32_i32_e32 v66, v66
	v_cvt_f32_i32_e32 v67, v67
	v_cndmask_b32_e64 v2, v2, 0, vcc
	v_mul_f32_e32 v50, v135, v50
	v_mul_f32_e32 v50, 0x3fb8aa3b, v50
	v_exp_f32_e32 v50, v50
	v_cmp_ge_i32_e32 vcc, v134, v44
	v_add_u32_e32 v44, 50, v124
	v_mul_f32_e32 v66, v135, v66
	v_mul_f32_e32 v45, v50, v45
	v_cndmask_b32_e32 v50, 0, v45, vcc
	v_sub_u32_e32 v45, v134, v44
	v_cvt_f32_i32_e32 v45, v45
	v_mul_f32_e32 v67, v135, v67
	v_mul_f32_e32 v66, 0x3fb8aa3b, v66
	v_mul_f32_e32 v67, 0x3fb8aa3b, v67
	v_exp_f32_e32 v66, v66
	v_exp_f32_e32 v67, v67
	v_mul_f32_e32 v45, v135, v45
	v_mul_f32_e32 v45, 0x3fb8aa3b, v45
	v_exp_f32_e32 v45, v45
	v_pk_mul_f32 v[60:61], v[66:67], v[60:61]
	v_sub_u32_e32 v66, v134, v116
	v_sub_u32_e32 v67, v134, v114
	v_cvt_f32_i32_e32 v66, v66
	v_cvt_f32_i32_e32 v67, v67
	v_mul_f32_e32 v45, v45, v46
	v_cmp_ge_i32_e32 vcc, v134, v44
	v_add_u32_e32 v44, 51, v124
	v_mul_f32_e32 v66, v135, v66
	v_cndmask_b32_e32 v51, 0, v45, vcc
	v_sub_u32_e32 v45, v134, v44
	v_mul_f32_e32 v67, v135, v67
	v_cvt_f32_i32_e32 v45, v45
	v_mul_f32_e32 v66, 0x3fb8aa3b, v66
	v_mul_f32_e32 v67, 0x3fb8aa3b, v67
	v_exp_f32_e32 v66, v66
	v_exp_f32_e32 v67, v67
	v_mul_f32_e32 v45, v135, v45
	v_mul_f32_e32 v45, 0x3fb8aa3b, v45
	v_exp_f32_e32 v45, v45
	v_pk_mul_f32 v[62:63], v[66:67], v[62:63]
	v_cvt_pk_bf16_f32 v69, v64, v65
	v_cvt_pk_bf16_f32 v70, v60, v61
	v_cvt_pk_bf16_f32 v71, v62, v63
	ds_read_b64_tr_b16 v[62:63], v126
	ds_read_b64_tr_b16 v[66:67], v126 offset:32
	ds_read_b64_tr_b16 v[60:61], v128
	ds_read_b64_tr_b16 v[64:65], v128 offset:32
	v_mul_f32_e32 v45, v45, v47
	v_cmp_ge_i32_e32 vcc, v134, v44
	s_waitcnt lgkmcnt(0)
; __device__ __forceinline__ unsigned pk2(float lo, float hi) { const f32x2_t v = {lo, hi}; const bf16x2_t b = __builtin_convertvector(v, bf16x2_t); return __builtin_bit_cast(unsigned, b); }
; template <int KIND>
; __device__ __forceinline__ void w_m3_core(const bf16x8 (&Qf)[4][2], const bf16x8 (&Kf)[4][2], const bf16x8 (&Sf)[4][2], const LAS bf16_t* vT, float lg,
;                                           const bf16_t* gsrc, const float* nw, bf16_t* ydst, int lo, int fq) {
;     ...
;             const bf16x8 Pf = pack_frag(pv);
; #pragma unroll
;             for (int eb = 0; eb < 4; ++eb)
;                 O[eb] = __builtin_amdgcn_mfma_f32_16x16x32_bf16(tr_frag(vT, 32 * kk2 + 4 * fq, 32 * kk2 + 16 + 4 * fq, 16 * eb, lo), Pf, O[eb], 0, 0, 0);
;         }
; #pragma unroll
;         for (int kk = 0; kk < 2; ++kk)
; #pragma unroll
;             for (int eb = 0; eb < 4; ++eb) O2[eb] = __builtin_amdgcn_mfma_f32_16x16x32_bf16(Sf[eb][kk], Qf[nb][kk], O2[eb], 0, 0, 0);
;         const float osc = KIND == 0 ? __expf((float)(16 * nb + lo + 1) * lg) : 1.0f;
; #pragma unroll
;         for (int eb = 0; eb < 4; ++eb) O[eb] = O[eb] + O2[eb] * osc;
;         float ss = 0.f;
; #pragma unroll
;         for (int eb = 0; eb < 4; ++eb) ss += (O[eb][0] * O[eb][0] + O[eb][1] * O[eb][1]) + (O[eb][2] * O[eb][2] + O[eb][3] * O[eb][3]);
;         { const int ln = (fq << 4) | lo; ss += bperm_f(ln ^ 16, ss); ss += bperm_f(ln ^ 32, ss); }
;         const float rs = rsqrtf(ss * (1.0f / 64.0f) + EPS);
;         const size_t n = 16 * nb + lo;
; #pragma unroll
;         for (int eb = 0; eb < 4; ++eb) { const int e0 = 16 * eb + 4 * fq;
;             const unsigned long long gw_ = *(const unsigned long long*)(gsrc + n * NIN + e0); const f32x4 w4 = *(const f32x4*)(nw + e0);
;             const float g0 = __uint_as_float((unsigned)gw_ << 16), g1 = __uint_as_float((unsigned)gw_ & 0xffff0000u), g2 = __uint_as_float((unsigned)(gw_ >> 32) << 16), g3 = __uint_as_float((unsigned)(gw_ >> 32) & 0xffff0000u);
;             const float o0 = O[eb][0] * rs * w4[0] * (g0 * sigmoidf_(g0)), o1 = O[eb][1] * rs * w4[1] * (g1 * sigmoidf_(g1));
;             const float o2 = O[eb][2] * rs * w4[2] * (g2 * sigmoidf_(g2)), o3 = O[eb][3] * rs * w4[3] * (g3 * sigmoidf_(g3));
;             *(unsigned long long*)(ydst + n * DM + e0) = (unsigned long long)pk2(o0, o1) | ((unsigned long long)pk2(o2, o3) << 32); }
	v_mfma_f32_16x16x32_bf16 v[72:75], v[60:63], v[68:71], 0
	v_cndmask_b32_e32 v47, 0, v45, vcc
	v_cvt_pk_bf16_f32 v45, v48, v49
	v_cvt_pk_bf16_f32 v46, v2, v50
	v_mfma_f32_16x16x32_bf16 v[60:63], v[64:67], v[68:71], 0
	ds_read_b64_tr_b16 v[64:65], v128 offset:64
	ds_read_b64_tr_b16 v[66:67], v126 offset:64
	ds_read_b64_tr_b16 v[76:77], v128 offset:96
	ds_read_b64_tr_b16 v[78:79], v126 offset:96
	v_cvt_pk_bf16_f32 v47, v51, v47
	ds_read_b64_tr_b16 v[48:49], v128 offset:4608
	ds_read_b64_tr_b16 v[50:51], v126 offset:4608
	ds_read_b64_tr_b16 v[52:53], v128 offset:4640
	ds_read_b64_tr_b16 v[54:55], v126 offset:4640
	v_cvt_pk_bf16_f32 v44, v0, v1
	ds_read_b64_tr_b16 v[56:57], v128 offset:4672
	ds_read_b64_tr_b16 v[58:59], v126 offset:4672
	s_waitcnt lgkmcnt(0)
	v_mfma_f32_16x16x32_bf16 v[52:55], v[52:55], v[44:47], v[60:63]
	s_nop 2
	ds_read_b64_tr_b16 v[60:61], v128 offset:4704
	ds_read_b64_tr_b16 v[62:63], v126 offset:4704
	v_add_u32_e32 v0, 49, v133
	v_cvt_f32_ubyte0_e32 v0, v0
	v_mfma_f32_16x16x32_bf16 v[64:67], v[64:67], v[68:71], 0
	v_mul_f32_e32 v0, v135, v0
	v_mul_f32_e32 v0, 0x3fb8aa3b, v0
	v_exp_f32_e32 v2, v0
	v_mfma_f32_16x16x32_bf16 v[68:71], v[76:79], v[68:71], 0
	v_mfma_f32_16x16x32_bf16 v[24:27], v[24:27], v[8:11], 0
	v_mfma_f32_16x16x32_bf16 v[36:39], v[36:39], v[8:11], 0
	v_mfma_f32_16x16x32_bf16 v[8:11], v[40:43], v[8:11], 0
	v_mfma_f32_16x16x32_bf16 v[48:51], v[48:51], v[44:47], v[72:75]
	v_mfma_f32_16x16x32_bf16 v[12:15], v[12:15], v[4:7], v[20:23]
	v_mfma_f32_16x16x32_bf16 v[56:59], v[56:59], v[44:47], v[64:67]
	s_waitcnt lgkmcnt(0)
	v_mfma_f32_16x16x32_bf16 v[44:47], v[60:63], v[44:47], v[68:71]
	s_nop 4
	v_fma_f32 v22, v2, v14, v50
	v_fma_f32 v23, v2, v15, v51
	v_mfma_f32_16x16x32_bf16 v[18:21], v[16:19], v[4:7], v[24:27]
	v_mfma_f32_16x16x32_bf16 v[26:29], v[28:31], v[4:7], v[36:39]
	s_nop 1
	v_fma_f32 v24, v2, v12, v48
	v_fma_f32 v25, v2, v13, v49
	s_nop 2
	v_pk_fma_f32 v[16:17], v[2:3], v[20:21], v[54:55] op_sel_hi:[0,1,1]
	v_pk_fma_f32 v[18:19], v[2:3], v[18:19], v[52:53] op_sel_hi:[0,1,1]
	v_mfma_f32_16x16x32_bf16 v[4:7], v[32:35], v[4:7], v[8:11]
	v_fma_f32 v12, v2, v28, v58
	v_fma_f32 v13, v2, v29, v59
	s_nop 5
	v_pk_fma_f32 v[0:1], v[2:3], v[6:7], v[46:47] op_sel_hi:[0,1,1]
	v_pk_fma_f32 v[10:11], v[2:3], v[4:5], v[44:45] op_sel_hi:[0,1,1]
	v_pk_mul_f32 v[4:5], v[22:23], v[22:23]
	v_pk_mul_f32 v[6:7], v[24:25], v[24:25]
	v_pk_fma_f32 v[14:15], v[2:3], v[26:27], v[56:57] op_sel_hi:[0,1,1]
	v_pk_mov_b32 v[8:9], v[6:7], v[4:5] op_sel:[1,0]
	v_mov_b32_e32 v7, v5
	v_pk_add_f32 v[4:5], v[8:9], v[6:7]
	v_pk_mul_f32 v[6:7], v[16:17], v[16:17]
	v_pk_mul_f32 v[8:9], v[18:19], v[18:19]
	v_mul_f32_e32 v2, v10, v10
	v_pk_mov_b32 v[20:21], v[8:9], v[6:7] op_sel:[1,0]
	v_mov_b32_e32 v9, v7
	v_pk_add_f32 v[6:7], v[20:21], v[8:9]
	v_mul_f32_e32 v8, v11, v11
	v_pk_add_f32 v[4:5], v[4:5], v[4:5] op_sel:[0,1] op_sel_hi:[1,0]
	v_pk_add_f32 v[6:7], v[6:7], v[6:7] op_sel:[0,1] op_sel_hi:[1,0]
	v_mov_b32_e32 v5, v2
	v_mov_b32_e32 v7, v8
	v_mul_f32_e32 v2, v15, v15
	v_mul_f32_e32 v9, v0, v0
	v_pk_add_f32 v[4:5], v[4:5], v[6:7]
	v_pk_fma_f32 v[6:7], v[14:15], v[14:15], v[2:3] op_sel_hi:[1,1,0]
	v_mul_f32_e32 v2, v13, v13
	v_mul_f32_e32 v20, v1, v1
	v_mov_b32_e32 v7, v9
	v_pk_fma_f32 v[8:9], v[12:13], v[12:13], v[2:3] op_sel_hi:[1,1,0]
	s_nop 0
	v_mov_b32_e32 v9, v20
	v_pk_add_f32 v[6:7], v[6:7], v[8:9]
	s_nop 0
	v_pk_add_f32 v[4:5], v[4:5], v[6:7]
	s_nop 0
	v_add_f32_e32 v2, v4, v5
	ds_bpermute_b32 v4, v138, v2
	s_waitcnt lgkmcnt(0)
	v_add_f32_e32 v2, v2, v4
	ds_bpermute_b32 v4, v137, v2
	s_waitcnt lgkmcnt(0)
	v_add_f32_e32 v2, v2, v4
	v_fmamk_f32 v2, v2, 0x3c800000, v200
	v_cmp_gt_f32_e32 vcc, s29, v2
	v_mul_f32_e32 v4, 0x4b800000, v2
	s_nop 0
	v_cndmask_b32_e32 v2, v2, v4, vcc
	v_rsq_f32_e32 v2, v2
	s_nop 0
	v_mul_f32_e32 v4, 0x45800000, v2
	v_cndmask_b32_e32 v8, v2, v4, vcc
	v_mad_u64_u32 v[4:5], s[20:21], v134, s72, v[98:99]
	v_lshl_add_u64 v[20:21], v[4:5], 0, v[96:97]
	v_mov_b64_e32 v[28:29], v[246:247]
	v_mov_b64_e32 v[4:5], v[184:185]
	v_mov_b64_e32 v[6:7], v[186:187]
	v_lshlrev_b32_e32 v2, 11, v134
	v_lshl_add_u64 v[26:27], s[40:41], 0, v[2:3]
	v_pk_mul_f32 v[24:25], v[24:25], v[8:9] op_sel_hi:[1,0]
	v_pk_mul_f32 v[22:23], v[22:23], v[8:9] op_sel_hi:[1,0]
	v_pk_mul_f32 v[18:19], v[18:19], v[8:9] op_sel_hi:[1,0]
	v_pk_mul_f32 v[16:17], v[16:17], v[8:9] op_sel_hi:[1,0]
	v_pk_mul_f32 v[14:15], v[14:15], v[8:9] op_sel_hi:[1,0]
	s_waitcnt lgkmcnt(0)
	v_lshlrev_b32_e32 v30, 16, v28
	v_mul_f32_e32 v2, 0xbfb8aa3b, v30
	v_exp_f32_e32 v2, v2
	v_and_b32_e32 v31, 0xffff0000, v28
	v_lshlrev_b32_e32 v28, 16, v29
	v_and_b32_e32 v29, 0xffff0000, v29
	v_add_f32_e32 v2, 1.0, v2
	v_rcp_f32_e32 v32, v2
	v_mul_f32_e32 v2, 0xbfb8aa3b, v31
	v_exp_f32_e32 v2, v2
	v_pk_mul_f32 v[4:5], v[4:5], v[24:25]
	v_pk_mul_f32 v[6:7], v[6:7], v[22:23]
	v_add_f32_e32 v2, 1.0, v2
	v_rcp_f32_e32 v33, v2
	v_mul_f32_e32 v2, 0xbfb8aa3b, v28
	v_exp_f32_e32 v2, v2
	v_pk_mul_f32 v[24:25], v[32:33], v[30:31]
	s_nop 0
	v_pk_mul_f32 v[4:5], v[24:25], v[4:5]
	v_add_f32_e32 v2, 1.0, v2
	v_rcp_f32_e32 v24, v2
	v_mul_f32_e32 v2, 0xbfb8aa3b, v29
	v_exp_f32_e32 v2, v2
	s_nop 0
	v_add_f32_e32 v2, 1.0, v2
	v_rcp_f32_e32 v25, v2
	s_nop 0
	v_pk_mul_f32 v[22:23], v[24:25], v[28:29]
	s_nop 0
	v_pk_mul_f32 v[6:7], v[22:23], v[6:7]
	v_cvt_pk_bf16_f32 v22, v4, v5
	v_cvt_pk_bf16_f32 v23, v6, v7
	v_lshl_add_u64 v[4:5], v[26:27], 0, v[96:97]
	global_store_dwordx2 v[4:5], v[22:23], off offset:1024
	v_mov_b64_e32 v[6:7], v[248:249]
	s_nop 0
	v_mov_b64_e32 v[22:23], v[188:189]
	v_mov_b64_e32 v[24:25], v[190:191]
	s_waitcnt lgkmcnt(0)
; #define LAS __attribute__((address_space(3)))
; template <int KIND>
; __device__ __forceinline__ void w_m3_core(const bf16x8 (&Qf)[4][2], const bf16x8 (&Kf)[4][2], const bf16x8 (&Sf)[4][2], const LAS bf16_t* vT, float lg,
;                                           const bf16_t* gsrc, const float* nw, bf16_t* ydst, int lo, int fq) {
;     ...
;         for (int eb = 0; eb < 4; ++eb) { const int e0 = 16 * eb + 4 * fq;
;             const unsigned long long gw_ = *(const unsigned long long*)(gsrc + n * NIN + e0); const f32x4 w4 = *(const f32x4*)(nw + e0);
;             const float g0 = __uint_as_float((unsigned)gw_ << 16), g1 = __uint_as_float((unsigned)gw_ & 0xffff0000u), g2 = __uint_as_float((unsigned)(gw_ >> 32) << 16), g3 = __uint_as_float((unsigned)(gw_ >> 32) & 0xffff0000u);
;             const float o0 = O[eb][0] * rs * w4[0] * (g0 * sigmoidf_(g0)), o1 = O[eb][1] * rs * w4[1] * (g1 * sigmoidf_(g1));
;             const float o2 = O[eb][2] * rs * w4[2] * (g2 * sigmoidf_(g2)), o3 = O[eb][3] * rs * w4[3] * (g3 * sigmoidf_(g3));
;             *(unsigned long long*)(ydst + n * DM + e0) = (unsigned long long)pk2(o0, o1) | ((unsigned long long)pk2(o2, o3) << 32); }
; __device__ __forceinline__ void w_hg_m3(const Args& a, int l, unsigned char* ws, const bf16_t* proj, bf16_t* y, LAS unsigned char* wl, int b, int ck_, int h, int lane) {
;     LAS bf16_t* vT = (LAS bf16_t*)wl;
;     const int row0 = b * SEQ + 64 * ck_, lo = lane & 15, fq = lane >> 4;
;     w_store_vT(vT, proj + (size_t)row0 * NIN + C_HI + 64 * h, lane);
;     bf16x8 Qf[4][2], Kf[4][2], Sf[4][2]; float er[2][8];
;     const bf16_t* Sb = (const bf16_t*)((const unsigned char*)a.out + OUT_SBH) + (size_t)((b * NCH + ck_) * 4 + h) * 4096;
; #pragma unroll
;     for (int kk = 0; kk < 2; ++kk) { float bb[4][8], r31[8], r63[8], lbv[8];
; #pragma unroll
;         for (int j = 0; j < 8; ++j) lbv[j] = hg_lb(a, l, 64 * h + 32 * kk + 8 * fq + j);
;         const bf16_t* fsrc = proj + (size_t)row0 * NIN + C_HF + 64 * h + 32 * kk + 8 * fq;
;         w_hg_scan(lbv, fsrc, lane, bb, r31, r63);
; #pragma unroll
;         for (int tb = 0; tb < 4; ++tb) { float fp[8], qv[8], a1[8], a2[8];
;             ld8bf(fsrc + (size_t)(16 * tb + lo) * NIN, fp); ld8bf(proj + (size_t)(row0 + 16 * tb + lo) * NIN + C_HQ + 64 * h + 32 * kk + 8 * fq, qv);
	v_lshlrev_b32_e32 v26, 16, v6
	v_mul_f32_e32 v2, 0xbfb8aa3b, v26
	v_exp_f32_e32 v2, v2
	v_and_b32_e32 v27, 0xffff0000, v6
	v_lshlrev_b32_e32 v6, 16, v7
	v_and_b32_e32 v7, 0xffff0000, v7
	v_add_f32_e32 v2, 1.0, v2
	v_rcp_f32_e32 v28, v2
	v_mul_f32_e32 v2, 0xbfb8aa3b, v27
	v_exp_f32_e32 v2, v2
	v_pk_mul_f32 v[18:19], v[22:23], v[18:19]
	v_pk_mul_f32 v[16:17], v[24:25], v[16:17]
	v_mul_f32_e32 v24, v12, v8
	v_add_f32_e32 v2, 1.0, v2
	v_rcp_f32_e32 v29, v2
	v_mul_f32_e32 v2, 0xbfb8aa3b, v6
	v_exp_f32_e32 v2, v2
	v_pk_mul_f32 v[22:23], v[28:29], v[26:27]
	s_nop 0
	v_pk_mul_f32 v[18:19], v[22:23], v[18:19]
	v_add_f32_e32 v2, 1.0, v2
	v_rcp_f32_e32 v22, v2
	v_mul_f32_e32 v2, 0xbfb8aa3b, v7
	v_exp_f32_e32 v2, v2
	s_nop 0
	v_add_f32_e32 v2, 1.0, v2
	v_rcp_f32_e32 v23, v2
	s_nop 0
	v_pk_mul_f32 v[6:7], v[22:23], v[6:7]
	s_nop 0
	v_pk_mul_f32 v[6:7], v[6:7], v[16:17]
	v_cvt_pk_bf16_f32 v16, v18, v19
	v_cvt_pk_bf16_f32 v17, v6, v7
	global_store_dwordx2 v[4:5], v[16:17], off offset:1056
	v_mov_b64_e32 v[6:7], v[250:251]
	s_nop 0
	v_mov_b64_e32 v[16:17], v[192:193]
	v_mov_b64_e32 v[18:19], v[194:195]
	s_waitcnt lgkmcnt(0)
	v_lshlrev_b32_e32 v22, 16, v6
	v_mul_f32_e32 v2, 0xbfb8aa3b, v22
	v_exp_f32_e32 v2, v2
	v_and_b32_e32 v23, 0xffff0000, v6
	v_lshlrev_b32_e32 v25, 16, v7
	v_and_b32_e32 v7, 0xffff0000, v7
	v_add_f32_e32 v2, 1.0, v2
	v_rcp_f32_e32 v26, v2
	v_mul_f32_e32 v2, 0xbfb8aa3b, v23
	v_exp_f32_e32 v2, v2
	v_pk_mul_f32 v[14:15], v[16:17], v[14:15]
	v_mul_f32_e32 v6, v13, v8
	v_mov_b32_e32 v12, v19
	v_add_f32_e32 v2, 1.0, v2
	v_rcp_f32_e32 v27, v2
	v_mul_f32_e32 v2, 0xbfb8aa3b, v25
	v_exp_f32_e32 v2, v2
	v_pk_mul_f32 v[16:17], v[26:27], v[22:23]
	s_nop 0
	v_pk_mul_f32 v[14:15], v[16:17], v[14:15]
	v_add_f32_e32 v2, 1.0, v2
	v_rcp_f32_e32 v17, v2
	v_mul_f32_e32 v2, 0xbfb8aa3b, v7
	v_exp_f32_e32 v2, v2
	v_mov_b32_e32 v16, v18
	v_pk_mul_f32 v[16:17], v[16:17], v[24:25]
	v_mul_f32_e32 v18, v11, v8
	v_add_f32_e32 v2, 1.0, v2
	v_rcp_f32_e32 v13, v2
	s_nop 0
	v_pk_mul_f32 v[6:7], v[12:13], v[6:7]
	v_cvt_pk_bf16_f32 v12, v14, v15
	v_mov_b32_e32 v14, v16
	v_mov_b32_e32 v15, v6
	v_mov_b32_e32 v6, v17
	v_pk_mul_f32 v[6:7], v[14:15], v[6:7]
	v_mul_f32_e32 v16, v10, v8
	v_cvt_pk_bf16_f32 v13, v6, v7
	global_store_dwordx2 v[4:5], v[12:13], off offset:1088
	v_mov_b64_e32 v[6:7], v[252:253]
	s_nop 0
	v_mov_b64_e32 v[12:13], v[196:197]
	v_mov_b64_e32 v[14:15], v[198:199]
	v_mul_f32_e32 v20, v0, v8
	s_waitcnt lgkmcnt(0)
	v_lshlrev_b32_e32 v17, 16, v6
	v_lshlrev_b32_e32 v21, 16, v7
	v_mul_f32_e32 v2, 0xbfb8aa3b, v17
	v_mul_f32_e32 v0, 0xbfb8aa3b, v21
	v_exp_f32_e32 v2, v2
	v_exp_f32_e32 v0, v0
	v_and_b32_e32 v19, 0xffff0000, v6
	v_and_b32_e32 v7, 0xffff0000, v7
	v_add_f32_e32 v2, 1.0, v2
	v_add_f32_e32 v0, 1.0, v0
	v_rcp_f32_e32 v23, v2
	v_mul_f32_e32 v2, 0xbfb8aa3b, v19
	v_mov_b32_e32 v10, v13
	v_rcp_f32_e32 v13, v0
	v_mul_f32_e32 v0, 0xbfb8aa3b, v7
	v_exp_f32_e32 v2, v2
	v_exp_f32_e32 v0, v0
	v_mul_f32_e32 v6, v1, v8
	v_mov_b32_e32 v22, v12
	v_add_f32_e32 v2, 1.0, v2
	v_add_f32_e32 v0, 1.0, v0
	v_rcp_f32_e32 v11, v2
	v_rcp_f32_e32 v1, v0
	v_mov_b32_e32 v12, v14
	v_mov_b32_e32 v0, v15
	v_pk_mul_f32 v[16:17], v[22:23], v[16:17]
	v_pk_mul_f32 v[10:11], v[10:11], v[18:19]
	v_pk_mul_f32 v[12:13], v[12:13], v[20:21]
	v_pk_mul_f32 v[0:1], v[0:1], v[6:7]
	v_mov_b32_e32 v6, v16
	v_mov_b32_e32 v7, v10
	v_mov_b32_e32 v10, v17
	v_mov_b32_e32 v8, v12
	v_mov_b32_e32 v9, v0
	v_mov_b32_e32 v0, v13
	v_pk_mul_f32 v[6:7], v[6:7], v[10:11]
	v_pk_mul_f32 v[0:1], v[8:9], v[0:1]
	v_cvt_pk_bf16_f32 v6, v6, v7
	v_cvt_pk_bf16_f32 v7, v0, v1
	global_store_dwordx2 v[4:5], v[6:7], off offset:1120
	s_waitcnt lgkmcnt(0)
	s_branch .LBB0_186
.LBB0_189:
	s_or_b64 exec, exec, s[34:35]
	v_and_b32_e32 v196, 15, v132
	v_lshrrev_b32_e32 v197, 4, v132
	v_mul_u32_u24_e32 v196, 0x1800, v196
	v_lshl_add_u32 v196, v197, 3, v196
	v_and_b32_e32 v197, 16, v132
	v_add_u32_e32 v196, v196, v197
	v_lshrrev_b32_e32 v197, 1, v197
	v_add_u32_e32 v196, v196, v197
	v_add_u32_e32 v196, s88, v196
	v_add_u32_e32 v196, 0x1600, v196
	v_mov_b32_e32 v197, 0
	v_mov_b32_e32 v198, s67
	v_mov_b32_e32 v199, s68
	v_lshl_add_u64 v[198:199], v[198:199], 0, v[196:197]
	global_load_dwordx4 v[222:225], v[198:199], off
	global_load_dwordx4 v[226:229], v[198:199], off offset:64
	v_add_u32_e32 v196, 0x18000, v196
	v_mov_b32_e32 v198, s67
	v_mov_b32_e32 v199, s68
	v_lshl_add_u64 v[198:199], v[198:199], 0, v[196:197]
	global_load_dwordx4 v[230:233], v[198:199], off
	global_load_dwordx4 v[234:237], v[198:199], off offset:64
	v_add_u32_e32 v196, 0x18000, v196
	v_mov_b32_e32 v198, s67
	v_mov_b32_e32 v199, s68
	v_lshl_add_u64 v[198:199], v[198:199], 0, v[196:197]
	global_load_dwordx4 v[238:241], v[198:199], off
	global_load_dwordx4 v[242:245], v[198:199], off offset:64
	v_add_u32_e32 v196, 0x18000, v196
	v_mov_b32_e32 v198, s67
	v_mov_b32_e32 v199, s68
	v_lshl_add_u64 v[198:199], v[198:199], 0, v[196:197]
	global_load_dwordx4 v[246:249], v[198:199], off
	global_load_dwordx4 v[250:253], v[198:199], off offset:64
	s_mov_b64 s[20:21], 0x1000
	v_lshl_add_u64 v[38:39], v[64:65], 0, s[20:21]
	v_lshl_add_u64 v[64:65], v[66:67], 0, s[20:21]
	v_mul_f32_e32 v52, 0x3fb8aa3b, v98
	v_lshlrev_b32_e32 v67, 16, v4
	v_or_b32_e32 v186, 60, v70
	v_lshl_add_u64 v[70:71], v[54:55], 0, s[20:21]
	v_exp_f32_e32 v81, v52
	v_mul_f32_e32 v52, 0x3fb8aa3b, v97
	v_and_b32_e32 v4, 0xffff0000, v4
	v_mul_f32_e64 v54, |v67|, s26
	v_exp_f32_e32 v80, v52
	v_mul_f32_e32 v52, 0x3fb8aa3b, v94
	v_exp_f32_e32 v54, v54
	v_mul_f32_e64 v55, |v4|, s26
	v_exp_f32_e32 v83, v52
	v_mul_f32_e32 v52, 0x3fb8aa3b, v93
	v_exp_f32_e32 v55, v55
	v_exp_f32_e32 v82, v52
	v_mul_f32_e32 v52, 0x3fb8aa3b, v90
; __device__ __forceinline__ void ld8bf(const bf16_t* p, float (&o)[8]) { unpack8(*(const u32x4*)p, o); }
; __device__ __forceinline__ float sigmoidf_(float x) { return __builtin_amdgcn_rcpf(1.0f + __expf(-x)); }
; __device__ __forceinline__ bf16x8 pack_frag(const float (&v)[8]) { return __builtin_bit_cast(bf16x8, pack8(v)); }
; __device__ __forceinline__ void hg_lf_key(float fp, float lb, float& lf, float& key) {
;     const float e = __expf(-fabsf(fp));
;     const float rc = __builtin_amdgcn_rcpf(1.0f + e);
;     const float sp = fp >= 0.f ? rc : e * rc;
;     const float sn = fp >= 0.f ? e * rc : rc;
;     const float lsig = (fp >= 0.f ? 0.f : fp) + __logf(rc);
;     lf = (lb == 0.f) ? lsig : __logf(lb + (1.0f - lb) * sp); key = (1.0f - lb) * sn;
; __device__ __forceinline__ void w_hg_m3(const Args& a, int l, unsigned char* ws, const bf16_t* proj, bf16_t* y, LAS unsigned char* wl, int b, int ck_, int h, int lane) {
;     ...
;         for (int tb = 0; tb < 4; ++tb) { float fp[8], qv[8], a1[8], a2[8];
;             ld8bf(fsrc + (size_t)(16 * tb + lo) * NIN, fp); ld8bf(proj + (size_t)(row0 + 16 * tb + lo) * NIN + C_HQ + 64 * h + 32 * kk + 8 * fq, qv);
; #pragma unroll
;             for (int j = 0; j < 8; ++j) { float lf, key; hg_lf_key(fp[j], lbv[j], lf, key);
;                 const float q = qv[j] * sigmoidf_(qv[j]); a1[j] = q * __expf(bb[tb][j] - r31[j]); a2[j] = key * __expf(r31[j] - bb[tb][j]); }
;             Qf[tb][kk] = pack_frag(a1); Kf[tb][kk] = pack_frag(a2); }
	v_exp_f32_e32 v85, v52
	v_mul_f32_e32 v52, 0x3fb8aa3b, v89
	v_add_f32_e32 v53, v151, v153
	v_exp_f32_e32 v84, v52
	v_mul_f32_e32 v52, 0x3fb8aa3b, v74
	v_add_f32_e32 v145, v53, v145
	v_add_f32_e32 v53, 1.0, v54
	v_lshl_add_u64 v[78:79], v[62:63], 0, s[20:21]
	v_exp_f32_e32 v87, v52
	v_mul_f32_e32 v52, 0x3fb8aa3b, v73
	v_rcp_f32_e32 v62, v53
	v_add_f32_e32 v53, 1.0, v55
	v_exp_f32_e32 v86, v52
	v_add_f32_e32 v52, v152, v154
	v_rcp_f32_e32 v63, v53
	v_add_f32_e32 v66, v52, v146
	v_sub_f32_e32 v52, v73, v66
	v_sub_f32_e32 v53, v74, v145
	v_mul_f32_e32 v52, 0x3fb8aa3b, v52
	v_mul_f32_e32 v53, 0x3fb8aa3b, v53
	v_exp_f32_e32 v52, v52
	v_exp_f32_e32 v53, v53
	v_pk_mul_f32 v[54:55], v[54:55], v[62:63]
	v_cmp_le_f32_e32 vcc, 0, v4
	v_pk_add_f32 v[42:43], v[42:43], 1.0 op_sel_hi:[1,0] neg_lo:[1,0] neg_hi:[1,0]
	s_lshl_b32 s20, s90, 2
	v_cndmask_b32_e32 v55, v63, v55, vcc
	v_cmp_le_f32_e32 vcc, 0, v67
	s_lshl_b32 s21, s71, 9
	s_add_i32 s20, s20, s21
	v_cndmask_b32_e32 v54, v62, v54, vcc
	v_pk_mul_f32 v[54:55], v[42:43], v[54:55]
	s_mov_b64 s[34:35], 0x18000
	v_pk_mul_f32 v[52:53], v[52:53], v[54:55]
	s_add_i32 s20, s20, s70
	v_cvt_pk_bf16_f32 v4, v52, v53
	v_pk_add_f32 v[52:53], v[44:45], 1.0 op_sel_hi:[1,0] neg_lo:[1,0] neg_hi:[1,0]
	v_add_f32_e32 v44, v148, v150
	v_add_f32_e32 v67, v44, v139
	v_lshlrev_b32_e32 v139, 16, v5
	v_and_b32_e32 v5, 0xffff0000, v5
	v_mul_f32_e64 v54, |v139|, s26
	v_exp_f32_e32 v54, v54
	v_mul_f32_e64 v55, |v5|, s26
	v_exp_f32_e32 v55, v55
	v_add_f32_e32 v45, v147, v149
	v_add_f32_e32 v138, v45, v138
	v_add_f32_e32 v45, 1.0, v54
	v_rcp_f32_e32 v62, v45
	v_add_f32_e32 v45, 1.0, v55
	v_rcp_f32_e32 v63, v45
	v_sub_f32_e32 v44, v89, v67
	v_sub_f32_e32 v45, v90, v138
	v_mul_f32_e32 v44, 0x3fb8aa3b, v44
	v_mul_f32_e32 v45, 0x3fb8aa3b, v45
	v_exp_f32_e32 v44, v44
	v_exp_f32_e32 v45, v45
	v_pk_mul_f32 v[54:55], v[54:55], v[62:63]
	v_cmp_le_f32_e32 vcc, 0, v5
	v_lshl_add_u64 v[36:37], v[48:49], 0, s[34:35]
	s_mov_b64 s[34:35], 0x30000
	v_cndmask_b32_e32 v55, v63, v55, vcc
	v_cmp_le_f32_e32 vcc, 0, v139
	v_lshlrev_b32_e32 v139, 16, v6
	v_and_b32_e32 v6, 0xffff0000, v6
	v_cndmask_b32_e32 v54, v62, v54, vcc
	v_pk_mul_f32 v[54:55], v[52:53], v[54:55]
	v_cmp_le_f32_e32 vcc, 0, v6
	v_pk_mul_f32 v[44:45], v[44:45], v[54:55]
	v_pk_add_f32 v[54:55], v[46:47], 1.0 op_sel_hi:[1,0] neg_lo:[1,0] neg_hi:[1,0]
	v_mul_f32_e64 v46, |v139|, s26
	v_exp_f32_e32 v46, v46
	v_mul_f32_e64 v47, |v6|, s26
	v_exp_f32_e32 v47, v47
	v_cvt_pk_bf16_f32 v5, v44, v45
	v_add_f32_e32 v45, v140, v142
	v_add_f32_e32 v131, v45, v131
	v_add_f32_e32 v45, 1.0, v46
	v_rcp_f32_e32 v62, v45
	v_add_f32_e32 v45, 1.0, v47
	v_add_f32_e32 v44, v141, v143
	v_rcp_f32_e32 v63, v45
	v_add_f32_e32 v133, v44, v133
	v_sub_f32_e32 v44, v93, v133
	v_sub_f32_e32 v45, v94, v131
	v_mul_f32_e32 v44, 0x3fb8aa3b, v44
	v_mul_f32_e32 v45, 0x3fb8aa3b, v45
	v_exp_f32_e32 v44, v44
	v_exp_f32_e32 v45, v45
	v_pk_mul_f32 v[46:47], v[46:47], v[62:63]
	s_ashr_i32 s21, s20, 31
	v_cndmask_b32_e32 v47, v63, v47, vcc
	v_cmp_le_f32_e32 vcc, 0, v139
	v_lshl_add_u64 v[76:77], v[48:49], 0, s[34:35]
	v_or_b32_e32 v128, 16, v114
	v_cndmask_b32_e32 v46, v62, v46, vcc
	v_pk_mul_f32 v[46:47], v[54:55], v[46:47]
	v_or_b32_e32 v127, 32, v114
	v_pk_mul_f32 v[44:45], v[44:45], v[46:47]
	v_or_b32_e32 v126, 48, v114
	v_cvt_pk_bf16_f32 v6, v44, v45
	v_add_f32_e32 v45, v134, v136
	v_lshlrev_b32_e32 v134, 16, v7
	v_and_b32_e32 v7, 0xffff0000, v7
	v_mul_f32_e64 v46, |v134|, s26
	v_exp_f32_e32 v46, v46
	v_mul_f32_e64 v47, |v7|, s26
	v_exp_f32_e32 v47, v47
	v_add_f32_e32 v125, v45, v125
	v_add_f32_e32 v45, 1.0, v46
	v_rcp_f32_e32 v62, v45
	v_add_f32_e32 v45, 1.0, v47
	v_add_f32_e32 v44, v135, v137
	v_rcp_f32_e32 v63, v45
	v_add_f32_e32 v129, v44, v129
	v_sub_f32_e32 v44, v97, v129
	v_sub_f32_e32 v45, v98, v125
	v_mul_f32_e32 v44, 0x3fb8aa3b, v44
	v_mul_f32_e32 v45, 0x3fb8aa3b, v45
	v_exp_f32_e32 v44, v44
	v_exp_f32_e32 v45, v45
	v_pk_mul_f32 v[46:47], v[46:47], v[62:63]
	v_cmp_le_f32_e32 vcc, 0, v7
	s_lshl_b64 s[40:41], s[20:21], 13
	s_nop 0
	v_cndmask_b32_e32 v47, v63, v47, vcc
	v_cmp_le_f32_e32 vcc, 0, v134
	s_nop 1
	v_cndmask_b32_e32 v46, v62, v46, vcc
	v_pk_mul_f32 v[46:47], v[40:41], v[46:47]
	s_nop 0
	v_pk_mul_f32 v[44:45], v[44:45], v[46:47]
	s_nop 0
	v_cvt_pk_bf16_f32 v7, v44, v45
	v_sub_f32_e32 v44, v66, v73
	v_mul_f32_e32 v46, 0x3fb8aa3b, v44
	v_lshlrev_b32_e32 v44, 16, v8
	v_and_b32_e32 v45, 0xffff0000, v8
	v_mul_f32_e32 v8, 0xbfb8aa3b, v44
	v_exp_f32_e32 v8, v8
	v_mul_f32_e32 v47, 0xbfb8aa3b, v45
	v_exp_f32_e32 v47, v47
	v_lshlrev_b32_e32 v66, 16, v9
	v_add_f32_e32 v8, 1.0, v8
	v_rcp_f32_e32 v62, v8
	v_add_f32_e32 v8, 1.0, v47
	v_rcp_f32_e32 v63, v8
	v_sub_f32_e32 v8, v145, v74
	v_mul_f32_e32 v8, 0x3fb8aa3b, v8
	v_exp_f32_e32 v47, v8
	v_sub_f32_e32 v8, v67, v89
	v_and_b32_e32 v67, 0xffff0000, v9
	v_mul_f32_e32 v9, 0xbfb8aa3b, v66
	v_pk_mul_f32 v[44:45], v[62:63], v[44:45]
	v_exp_f32_e32 v9, v9
	v_mul_f32_e32 v63, 0xbfb8aa3b, v67
	v_exp_f32_e32 v63, v63
	v_mul_f32_e32 v8, 0x3fb8aa3b, v8
	v_add_f32_e32 v9, 1.0, v9
	v_exp_f32_e32 v62, v8
	v_sub_f32_e32 v8, v138, v90
	v_rcp_f32_e32 v134, v9
	v_add_f32_e32 v9, 1.0, v63
	v_exp_f32_e32 v46, v46
	v_mul_f32_e32 v8, 0x3fb8aa3b, v8
	v_rcp_f32_e32 v135, v9
	v_exp_f32_e32 v63, v8
	v_pk_mul_f32 v[8:9], v[46:47], v[44:45]
	v_pk_mul_f32 v[44:45], v[134:135], v[66:67]
	s_nop 0
	v_pk_mul_f32 v[44:45], v[62:63], v[44:45]
	v_cvt_pk_bf16_f32 v8, v8, v9
	v_cvt_pk_bf16_f32 v9, v44, v45
	v_sub_f32_e32 v44, v133, v93
	v_mul_f32_e32 v46, 0x3fb8aa3b, v44
	v_lshlrev_b32_e32 v44, 16, v10
	v_and_b32_e32 v45, 0xffff0000, v10
	v_mul_f32_e32 v10, 0xbfb8aa3b, v44
	v_exp_f32_e32 v10, v10
; __device__ __forceinline__ void ld8bf(const bf16_t* p, float (&o)[8]) { unpack8(*(const u32x4*)p, o); }
; __device__ __forceinline__ float sigmoidf_(float x) { return __builtin_amdgcn_rcpf(1.0f + __expf(-x)); }
; __device__ __forceinline__ bf16x8 pack_frag(const float (&v)[8]) { return __builtin_bit_cast(bf16x8, pack8(v)); }
; __device__ __forceinline__ void hg_lf_key(float fp, float lb, float& lf, float& key) {
;     const float e = __expf(-fabsf(fp));
;     const float rc = __builtin_amdgcn_rcpf(1.0f + e);
;     const float sp = fp >= 0.f ? rc : e * rc;
;     const float sn = fp >= 0.f ? e * rc : rc;
;     const float lsig = (fp >= 0.f ? 0.f : fp) + __logf(rc);
;     lf = (lb == 0.f) ? lsig : __logf(lb + (1.0f - lb) * sp); key = (1.0f - lb) * sn;
; __device__ __forceinline__ void w_hg_m3(const Args& a, int l, unsigned char* ws, const bf16_t* proj, bf16_t* y, LAS unsigned char* wl, int b, int ck_, int h, int lane) {
;     ...
;         for (int tb = 0; tb < 4; ++tb) { float fp[8], qv[8], a1[8], a2[8];
;             ld8bf(fsrc + (size_t)(16 * tb + lo) * NIN, fp); ld8bf(proj + (size_t)(row0 + 16 * tb + lo) * NIN + C_HQ + 64 * h + 32 * kk + 8 * fq, qv);
; #pragma unroll
;             for (int j = 0; j < 8; ++j) { float lf, key; hg_lf_key(fp[j], lbv[j], lf, key);
;                 const float q = qv[j] * sigmoidf_(qv[j]); a1[j] = q * __expf(bb[tb][j] - r31[j]); a2[j] = key * __expf(r31[j] - bb[tb][j]); }
;             Qf[tb][kk] = pack_frag(a1); Kf[tb][kk] = pack_frag(a2); }
	v_mul_f32_e32 v47, 0xbfb8aa3b, v45
	v_exp_f32_e32 v47, v47
	v_lshlrev_b32_e32 v66, 16, v11
	v_add_f32_e32 v10, 1.0, v10
	v_rcp_f32_e32 v62, v10
	v_add_f32_e32 v10, 1.0, v47
	v_rcp_f32_e32 v63, v10
	v_and_b32_e32 v67, 0xffff0000, v11
	v_mul_f32_e32 v11, 0xbfb8aa3b, v66
	v_exp_f32_e32 v11, v11
	v_pk_mul_f32 v[44:45], v[62:63], v[44:45]
	v_mul_f32_e32 v63, 0xbfb8aa3b, v67
	v_sub_f32_e32 v10, v131, v94
	v_exp_f32_e32 v63, v63
	v_mul_f32_e32 v10, 0x3fb8aa3b, v10
	v_exp_f32_e32 v47, v10
	v_sub_f32_e32 v10, v129, v97
	v_mul_f32_e32 v10, 0x3fb8aa3b, v10
	v_add_f32_e32 v11, 1.0, v11
	v_exp_f32_e32 v62, v10
	v_sub_f32_e32 v10, v125, v98
	v_rcp_f32_e32 v134, v11
	v_add_f32_e32 v11, 1.0, v63
	v_exp_f32_e32 v46, v46
	v_mul_f32_e32 v10, 0x3fb8aa3b, v10
	v_rcp_f32_e32 v135, v11
	v_exp_f32_e32 v63, v10
	v_pk_mul_f32 v[10:11], v[46:47], v[44:45]
	v_pk_mul_f32 v[44:45], v[134:135], v[66:67]
	s_nop 0
	v_pk_mul_f32 v[44:45], v[62:63], v[44:45]
	v_cvt_pk_bf16_f32 v10, v10, v11
	v_cvt_pk_bf16_f32 v11, v44, v45
	v_sub_f32_e32 v44, v97, v121
	v_lshlrev_b32_e32 v66, 16, v31
	v_mul_f32_e32 v46, 0x3fb8aa3b, v44
	v_and_b32_e32 v31, 0xffff0000, v31
	v_mul_f32_e64 v44, |v66|, s26
	v_exp_f32_e32 v44, v44
	v_mul_f32_e64 v45, |v31|, s26
	v_exp_f32_e32 v45, v45
	v_cmp_le_f32_e32 vcc, 0, v31
	v_add_f32_e32 v47, 1.0, v44
	v_rcp_f32_e32 v62, v47
	v_add_f32_e32 v47, 1.0, v45
	v_rcp_f32_e32 v63, v47
	v_and_b32_e32 v67, 0xffff0000, v15
	v_sub_f32_e32 v31, v121, v97
	v_sub_f32_e32 v47, v98, v122
	v_pk_mul_f32 v[44:45], v[44:45], v[62:63]
	v_mul_f32_e32 v31, 0x3fb8aa3b, v31
	v_cndmask_b32_e32 v45, v63, v45, vcc
	v_cmp_le_f32_e32 vcc, 0, v66
	v_lshlrev_b32_e32 v66, 16, v15
	v_mul_f32_e32 v15, 0xbfb8aa3b, v66
	v_exp_f32_e32 v15, v15
	v_mul_f32_e32 v63, 0xbfb8aa3b, v67
	v_exp_f32_e32 v63, v63
	v_mul_f32_e32 v47, 0x3fb8aa3b, v47
	v_add_f32_e32 v15, 1.0, v15
	v_cndmask_b32_e32 v44, v62, v44, vcc
	v_exp_f32_e32 v62, v31
	v_sub_f32_e32 v31, v122, v98
	v_rcp_f32_e32 v134, v15
	v_add_f32_e32 v15, 1.0, v63
	v_lshlrev_b32_e32 v121, 16, v30
	v_exp_f32_e32 v46, v46
	v_exp_f32_e32 v47, v47
	v_mul_f32_e32 v31, 0x3fb8aa3b, v31
	v_rcp_f32_e32 v135, v15
	v_and_b32_e32 v122, 0xffff0000, v30
	v_mul_f32_e64 v30, |v121|, s26
	v_exp_f32_e32 v63, v31
	v_exp_f32_e32 v30, v30
	v_mul_f32_e64 v31, |v122|, s26
	v_exp_f32_e32 v31, v31
	v_pk_mul_f32 v[44:45], v[40:41], v[44:45]
	v_sub_f32_e32 v15, v93, v118
	v_pk_mul_f32 v[44:45], v[46:47], v[44:45]
	v_pk_mul_f32 v[46:47], v[134:135], v[66:67]
	v_mul_f32_e32 v15, 0x3fb8aa3b, v15
	v_pk_mul_f32 v[46:47], v[62:63], v[46:47]
	v_exp_f32_e32 v62, v15
	v_add_f32_e32 v15, 1.0, v30
	v_rcp_f32_e32 v66, v15
	v_add_f32_e32 v15, 1.0, v31
	v_rcp_f32_e32 v67, v15
	v_sub_f32_e32 v15, v94, v119
	v_mul_f32_e32 v15, 0x3fb8aa3b, v15
	v_exp_f32_e32 v63, v15
	v_pk_mul_f32 v[30:31], v[30:31], v[66:67]
	v_cmp_le_f32_e32 vcc, 0, v122
	v_sub_f32_e32 v15, v118, v93
	v_mul_f32_e32 v15, 0x3fb8aa3b, v15
	v_cndmask_b32_e32 v31, v67, v31, vcc
	v_cmp_le_f32_e32 vcc, 0, v121
	v_lshlrev_b32_e32 v118, 16, v14
	v_lshlrev_b32_e32 v134, 16, v13
	v_cndmask_b32_e32 v30, v66, v30, vcc
	v_exp_f32_e32 v66, v15
	v_sub_f32_e32 v15, v119, v94
	v_and_b32_e32 v119, 0xffff0000, v14
	v_mul_f32_e32 v14, 0xbfb8aa3b, v118
	v_mul_f32_e32 v67, 0xbfb8aa3b, v119
	v_exp_f32_e32 v14, v14
	v_exp_f32_e32 v67, v67
	v_mul_f32_e32 v121, 0x3fb8aa3b, v15
	v_pk_mul_f32 v[30:31], v[54:55], v[30:31]
	v_add_f32_e32 v14, 1.0, v14
	v_add_f32_e32 v15, 1.0, v67
	v_rcp_f32_e32 v14, v14
	v_rcp_f32_e32 v15, v15
	v_exp_f32_e32 v67, v121
	v_pk_mul_f32 v[30:31], v[62:63], v[30:31]
	v_lshlrev_b32_e32 v121, 16, v29
	v_pk_mul_f32 v[14:15], v[14:15], v[118:119]
	v_and_b32_e32 v29, 0xffff0000, v29
	v_pk_mul_f32 v[62:63], v[66:67], v[14:15]
	v_sub_f32_e32 v14, v89, v115
	v_mul_f32_e32 v66, 0x3fb8aa3b, v14
	v_mul_f32_e64 v14, |v121|, s26
	v_exp_f32_e32 v14, v14
	v_mul_f32_e64 v15, |v29|, s26
	v_exp_f32_e32 v15, v15
	v_and_b32_e32 v135, 0xffff0000, v13
	v_add_f32_e32 v67, 1.0, v14
	v_rcp_f32_e32 v118, v67
	v_add_f32_e32 v67, 1.0, v15
	v_rcp_f32_e32 v119, v67
	v_mul_f32_e32 v13, 0xbfb8aa3b, v134
	v_cmp_le_f32_e32 vcc, 0, v29
	v_sub_f32_e32 v29, v115, v89
	v_exp_f32_e32 v13, v13
	v_mul_f32_e32 v115, 0xbfb8aa3b, v135
	v_exp_f32_e32 v115, v115
	v_pk_mul_f32 v[14:15], v[14:15], v[118:119]
	v_sub_f32_e32 v67, v90, v116
	v_cndmask_b32_e32 v15, v119, v15, vcc
	v_cmp_le_f32_e32 vcc, 0, v121
	v_mul_f32_e32 v29, 0x3fb8aa3b, v29
	v_add_f32_e32 v13, 1.0, v13
	v_mul_f32_e32 v67, 0x3fb8aa3b, v67
	v_cndmask_b32_e32 v14, v118, v14, vcc
	v_exp_f32_e32 v118, v29
	v_sub_f32_e32 v29, v116, v90
	v_rcp_f32_e32 v136, v13
	v_add_f32_e32 v13, 1.0, v115
	v_lshlrev_b32_e32 v115, 16, v28
	v_exp_f32_e32 v66, v66
	v_exp_f32_e32 v67, v67
	v_mul_f32_e32 v29, 0x3fb8aa3b, v29
	v_rcp_f32_e32 v137, v13
	v_and_b32_e32 v116, 0xffff0000, v28
	v_mul_f32_e64 v28, |v115|, s26
	v_exp_f32_e32 v119, v29
	v_exp_f32_e32 v28, v28
	v_mul_f32_e64 v29, |v116|, s26
	v_exp_f32_e32 v29, v29
	v_pk_mul_f32 v[14:15], v[52:53], v[14:15]
	v_sub_f32_e32 v13, v73, v111
	v_pk_mul_f32 v[14:15], v[66:67], v[14:15]
	v_pk_mul_f32 v[66:67], v[136:137], v[134:135]
	v_mul_f32_e32 v13, 0x3fb8aa3b, v13
	v_pk_mul_f32 v[66:67], v[118:119], v[66:67]
	v_exp_f32_e32 v118, v13
	v_add_f32_e32 v13, 1.0, v28
	v_rcp_f32_e32 v134, v13
	v_add_f32_e32 v13, 1.0, v29
	v_rcp_f32_e32 v135, v13
	v_sub_f32_e32 v13, v74, v112
	v_mul_f32_e32 v13, 0x3fb8aa3b, v13
	v_lshlrev_b32_e32 v136, 16, v12
	v_and_b32_e32 v137, 0xffff0000, v12
	v_exp_f32_e32 v119, v13
	v_sub_f32_e32 v13, v111, v73
	v_mul_f32_e32 v12, 0xbfb8aa3b, v136
	v_mul_f32_e32 v111, 0xbfb8aa3b, v137
	v_exp_f32_e32 v12, v12
	v_exp_f32_e32 v111, v111
	v_pk_mul_f32 v[28:29], v[28:29], v[134:135]
; __device__ __forceinline__ void ld8bf(const bf16_t* p, float (&o)[8]) { unpack8(*(const u32x4*)p, o); }
; __device__ __forceinline__ float sigmoidf_(float x) { return __builtin_amdgcn_rcpf(1.0f + __expf(-x)); }
; __device__ __forceinline__ bf16x8 pack_frag(const float (&v)[8]) { return __builtin_bit_cast(bf16x8, pack8(v)); }
; __device__ __forceinline__ void hg_lf_key(float fp, float lb, float& lf, float& key) {
;     const float e = __expf(-fabsf(fp));
;     const float rc = __builtin_amdgcn_rcpf(1.0f + e);
;     const float sp = fp >= 0.f ? rc : e * rc;
;     const float sn = fp >= 0.f ? e * rc : rc;
;     const float lsig = (fp >= 0.f ? 0.f : fp) + __logf(rc);
;     lf = (lb == 0.f) ? lsig : __logf(lb + (1.0f - lb) * sp); key = (1.0f - lb) * sn;
; __device__ __forceinline__ void w_hg_m3(const Args& a, int l, unsigned char* ws, const bf16_t* proj, bf16_t* y, LAS unsigned char* wl, int b, int ck_, int h, int lane) {
;     ...
;         for (int tb = 0; tb < 4; ++tb) { float fp[8], qv[8], a1[8], a2[8];
;             ld8bf(fsrc + (size_t)(16 * tb + lo) * NIN, fp); ld8bf(proj + (size_t)(row0 + 16 * tb + lo) * NIN + C_HQ + 64 * h + 32 * kk + 8 * fq, qv);
; #pragma unroll
;             for (int j = 0; j < 8; ++j) { float lf, key; hg_lf_key(fp[j], lbv[j], lf, key);
;                 const float q = qv[j] * sigmoidf_(qv[j]); a1[j] = q * __expf(bb[tb][j] - r31[j]); a2[j] = key * __expf(r31[j] - bb[tb][j]); }
;             Qf[tb][kk] = pack_frag(a1); Kf[tb][kk] = pack_frag(a2); }
	v_cmp_le_f32_e32 vcc, 0, v116
	v_mul_f32_e32 v13, 0x3fb8aa3b, v13
	v_add_f32_e32 v12, 1.0, v12
	v_cndmask_b32_e32 v29, v135, v29, vcc
	v_cmp_le_f32_e32 vcc, 0, v115
	v_rcp_f32_e32 v12, v12
	s_nop 0
	v_cndmask_b32_e32 v28, v134, v28, vcc
	v_exp_f32_e32 v134, v13
	v_sub_f32_e32 v13, v112, v74
	v_mul_f32_e32 v112, 0x3fb8aa3b, v13
	v_add_f32_e32 v13, 1.0, v111
	v_rcp_f32_e32 v13, v13
	v_exp_f32_e32 v135, v112
	v_pk_mul_f32 v[28:29], v[42:43], v[28:29]
	v_pk_mul_f32 v[12:13], v[12:13], v[136:137]
	v_pk_mul_f32 v[28:29], v[118:119], v[28:29]
	v_pk_mul_f32 v[118:119], v[134:135], v[12:13]
	v_cvt_pk_bf16_f32 v12, v28, v29
	v_cvt_pk_bf16_f32 v13, v14, v15
	v_cvt_pk_bf16_f32 v15, v44, v45
	v_cvt_pk_bf16_f32 v29, v66, v67
	v_sub_f32_e32 v44, v97, v107
	v_lshlrev_b32_e32 v66, 16, v35
	v_cvt_pk_bf16_f32 v14, v30, v31
	v_cvt_pk_bf16_f32 v31, v46, v47
	v_mul_f32_e32 v46, 0x3fb8aa3b, v44
	v_and_b32_e32 v35, 0xffff0000, v35
	v_mul_f32_e64 v44, |v66|, s26
	v_exp_f32_e32 v44, v44
	v_mul_f32_e64 v45, |v35|, s26
	v_exp_f32_e32 v45, v45
	v_cvt_pk_bf16_f32 v30, v62, v63
	v_add_f32_e32 v47, 1.0, v44
	v_rcp_f32_e32 v62, v47
	v_add_f32_e32 v47, 1.0, v45
	v_rcp_f32_e32 v63, v47
	v_cmp_le_f32_e32 vcc, 0, v35
	v_and_b32_e32 v67, 0xffff0000, v19
	v_sub_f32_e32 v35, v107, v97
	v_pk_mul_f32 v[44:45], v[44:45], v[62:63]
	v_sub_f32_e32 v47, v98, v109
	v_cndmask_b32_e32 v45, v63, v45, vcc
	v_cmp_le_f32_e32 vcc, 0, v66
	v_lshlrev_b32_e32 v66, 16, v19
	v_mul_f32_e32 v19, 0xbfb8aa3b, v66
	v_exp_f32_e32 v19, v19
	v_mul_f32_e32 v63, 0xbfb8aa3b, v67
	v_exp_f32_e32 v63, v63
	v_mul_f32_e32 v35, 0x3fb8aa3b, v35
	v_add_f32_e32 v19, 1.0, v19
	v_cvt_pk_bf16_f32 v28, v118, v119
	v_mul_f32_e32 v47, 0x3fb8aa3b, v47
	v_cndmask_b32_e32 v44, v62, v44, vcc
	v_exp_f32_e32 v62, v35
	v_sub_f32_e32 v35, v109, v98
	v_rcp_f32_e32 v118, v19
	v_add_f32_e32 v19, 1.0, v63
	v_lshlrev_b32_e32 v107, 16, v34
	v_exp_f32_e32 v46, v46
	v_exp_f32_e32 v47, v47
	v_mul_f32_e32 v35, 0x3fb8aa3b, v35
	v_rcp_f32_e32 v119, v19
	v_and_b32_e32 v109, 0xffff0000, v34
	v_mul_f32_e64 v34, |v107|, s26
	v_exp_f32_e32 v63, v35
	v_exp_f32_e32 v34, v34
	v_mul_f32_e64 v35, |v109|, s26
	v_exp_f32_e32 v35, v35
	v_pk_mul_f32 v[44:45], v[40:41], v[44:45]
	v_sub_f32_e32 v19, v93, v104
	v_pk_mul_f32 v[44:45], v[46:47], v[44:45]
	v_pk_mul_f32 v[46:47], v[118:119], v[66:67]
	v_mul_f32_e32 v19, 0x3fb8aa3b, v19
	v_pk_mul_f32 v[62:63], v[62:63], v[46:47]
	v_exp_f32_e32 v46, v19
	v_add_f32_e32 v19, 1.0, v34
	v_rcp_f32_e32 v66, v19
	v_add_f32_e32 v19, 1.0, v35
	v_rcp_f32_e32 v67, v19
	v_sub_f32_e32 v19, v94, v105
	v_mul_f32_e32 v19, 0x3fb8aa3b, v19
	v_exp_f32_e32 v47, v19
	v_pk_mul_f32 v[34:35], v[34:35], v[66:67]
	v_cmp_le_f32_e32 vcc, 0, v109
	v_sub_f32_e32 v19, v104, v93
	v_mul_f32_e32 v19, 0x3fb8aa3b, v19
	v_cndmask_b32_e32 v35, v67, v35, vcc
	v_cmp_le_f32_e32 vcc, 0, v107
	v_lshlrev_b32_e32 v104, 16, v18
	v_lshlrev_b32_e32 v118, 16, v17
	v_cndmask_b32_e32 v34, v66, v34, vcc
	v_exp_f32_e32 v66, v19
	v_sub_f32_e32 v19, v105, v94
	v_and_b32_e32 v105, 0xffff0000, v18
	v_mul_f32_e32 v18, 0xbfb8aa3b, v104
	v_mul_f32_e32 v67, 0xbfb8aa3b, v105
	v_exp_f32_e32 v18, v18
	v_exp_f32_e32 v67, v67
	v_mul_f32_e32 v107, 0x3fb8aa3b, v19
	v_pk_mul_f32 v[34:35], v[54:55], v[34:35]
	v_add_f32_e32 v18, 1.0, v18
	v_add_f32_e32 v19, 1.0, v67
	v_rcp_f32_e32 v18, v18
	v_rcp_f32_e32 v19, v19
	v_exp_f32_e32 v67, v107
	v_pk_mul_f32 v[34:35], v[46:47], v[34:35]
	v_lshlrev_b32_e32 v107, 16, v33
	v_pk_mul_f32 v[18:19], v[18:19], v[104:105]
	v_and_b32_e32 v33, 0xffff0000, v33
	v_pk_mul_f32 v[46:47], v[66:67], v[18:19]
	v_sub_f32_e32 v18, v89, v101
	v_mul_f32_e32 v66, 0x3fb8aa3b, v18
	v_mul_f32_e64 v18, |v107|, s26
	v_exp_f32_e32 v18, v18
	v_mul_f32_e64 v19, |v33|, s26
	v_exp_f32_e32 v19, v19
	v_and_b32_e32 v119, 0xffff0000, v17
	v_add_f32_e32 v67, 1.0, v18
	v_rcp_f32_e32 v104, v67
	v_add_f32_e32 v67, 1.0, v19
	v_rcp_f32_e32 v105, v67
	v_mul_f32_e32 v17, 0xbfb8aa3b, v118
	v_cmp_le_f32_e32 vcc, 0, v33
	v_sub_f32_e32 v33, v101, v89
	v_exp_f32_e32 v17, v17
	v_mul_f32_e32 v101, 0xbfb8aa3b, v119
	v_exp_f32_e32 v101, v101
	v_pk_mul_f32 v[18:19], v[18:19], v[104:105]
	v_sub_f32_e32 v67, v90, v102
	v_cndmask_b32_e32 v19, v105, v19, vcc
	v_cmp_le_f32_e32 vcc, 0, v107
	v_mul_f32_e32 v33, 0x3fb8aa3b, v33
	v_add_f32_e32 v17, 1.0, v17
	v_mul_f32_e32 v67, 0x3fb8aa3b, v67
	v_cndmask_b32_e32 v18, v104, v18, vcc
	v_exp_f32_e32 v104, v33
	v_sub_f32_e32 v33, v102, v90
	v_rcp_f32_e32 v134, v17
	v_add_f32_e32 v17, 1.0, v101
	v_lshlrev_b32_e32 v101, 16, v32
	v_exp_f32_e32 v66, v66
	v_exp_f32_e32 v67, v67
	v_mul_f32_e32 v33, 0x3fb8aa3b, v33
	v_rcp_f32_e32 v135, v17
	v_and_b32_e32 v102, 0xffff0000, v32
	v_mul_f32_e64 v32, |v101|, s26
	v_exp_f32_e32 v105, v33
	v_exp_f32_e32 v32, v32
	v_mul_f32_e64 v33, |v102|, s26
	v_exp_f32_e32 v33, v33
	v_pk_mul_f32 v[18:19], v[52:53], v[18:19]
	v_sub_f32_e32 v17, v73, v99
	v_pk_mul_f32 v[18:19], v[66:67], v[18:19]
	v_pk_mul_f32 v[66:67], v[134:135], v[118:119]
	v_mul_f32_e32 v17, 0x3fb8aa3b, v17
	v_pk_mul_f32 v[66:67], v[104:105], v[66:67]
	v_exp_f32_e32 v104, v17
	v_add_f32_e32 v17, 1.0, v32
	v_rcp_f32_e32 v118, v17
	v_add_f32_e32 v17, 1.0, v33
	v_rcp_f32_e32 v119, v17
	v_sub_f32_e32 v17, v74, v100
	v_mul_f32_e32 v17, 0x3fb8aa3b, v17
	v_exp_f32_e32 v105, v17
	v_pk_mul_f32 v[32:33], v[32:33], v[118:119]
	v_cmp_le_f32_e32 vcc, 0, v102
	v_sub_f32_e32 v17, v99, v73
	v_mul_f32_e32 v17, 0x3fb8aa3b, v17
	v_cndmask_b32_e32 v33, v119, v33, vcc
	v_cmp_le_f32_e32 vcc, 0, v101
	v_and_b32_e32 v101, 0xffff0000, v16
	v_mul_f32_e32 v99, 0xbfb8aa3b, v101
	v_cndmask_b32_e32 v32, v118, v32, vcc
	v_exp_f32_e32 v118, v17
	v_sub_f32_e32 v17, v100, v74
	v_lshlrev_b32_e32 v100, 16, v16
; __device__ __forceinline__ void ld8bf(const bf16_t* p, float (&o)[8]) { unpack8(*(const u32x4*)p, o); }
; __device__ __forceinline__ float sigmoidf_(float x) { return __builtin_amdgcn_rcpf(1.0f + __expf(-x)); }
; __device__ __forceinline__ bf16x8 pack_frag(const float (&v)[8]) { return __builtin_bit_cast(bf16x8, pack8(v)); }
; __device__ __forceinline__ void hg_lf_key(float fp, float lb, float& lf, float& key) {
;     const float e = __expf(-fabsf(fp));
;     const float rc = __builtin_amdgcn_rcpf(1.0f + e);
;     const float sp = fp >= 0.f ? rc : e * rc;
;     const float sn = fp >= 0.f ? e * rc : rc;
;     const float lsig = (fp >= 0.f ? 0.f : fp) + __logf(rc);
;     lf = (lb == 0.f) ? lsig : __logf(lb + (1.0f - lb) * sp); key = (1.0f - lb) * sn;
; __device__ __forceinline__ void w_hg_m3(const Args& a, int l, unsigned char* ws, const bf16_t* proj, bf16_t* y, LAS unsigned char* wl, int b, int ck_, int h, int lane) {
;     ...
;         for (int tb = 0; tb < 4; ++tb) { float fp[8], qv[8], a1[8], a2[8];
;             ld8bf(fsrc + (size_t)(16 * tb + lo) * NIN, fp); ld8bf(proj + (size_t)(row0 + 16 * tb + lo) * NIN + C_HQ + 64 * h + 32 * kk + 8 * fq, qv);
; #pragma unroll
;             for (int j = 0; j < 8; ++j) { float lf, key; hg_lf_key(fp[j], lbv[j], lf, key);
;                 const float q = qv[j] * sigmoidf_(qv[j]); a1[j] = q * __expf(bb[tb][j] - r31[j]); a2[j] = key * __expf(r31[j] - bb[tb][j]); }
;             Qf[tb][kk] = pack_frag(a1); Kf[tb][kk] = pack_frag(a2); }
	v_mul_f32_e32 v16, 0xbfb8aa3b, v100
	v_exp_f32_e32 v16, v16
	v_exp_f32_e32 v99, v99
	v_mul_f32_e32 v102, 0x3fb8aa3b, v17
	v_exp_f32_e32 v119, v102
	v_add_f32_e32 v16, 1.0, v16
	v_add_f32_e32 v17, 1.0, v99
	v_rcp_f32_e32 v16, v16
	v_rcp_f32_e32 v17, v17
	v_pk_mul_f32 v[32:33], v[42:43], v[32:33]
	v_cvt_pk_bf16_f32 v46, v46, v47
	v_pk_mul_f32 v[32:33], v[104:105], v[32:33]
	v_pk_mul_f32 v[16:17], v[16:17], v[100:101]
	v_cvt_pk_bf16_f32 v47, v62, v63
	v_pk_mul_f32 v[100:101], v[118:119], v[16:17]
	v_cvt_pk_bf16_f32 v16, v32, v33
	v_cvt_pk_bf16_f32 v17, v18, v19
	v_cvt_pk_bf16_f32 v19, v44, v45
	v_cvt_pk_bf16_f32 v45, v66, v67
	v_sub_f32_e32 v32, v97, v95
	v_lshlrev_b32_e32 v66, 16, v27
	v_cvt_pk_bf16_f32 v18, v34, v35
	v_mul_f32_e32 v34, 0x3fb8aa3b, v32
	v_and_b32_e32 v27, 0xffff0000, v27
	v_mul_f32_e64 v32, |v66|, s26
	v_exp_f32_e32 v32, v32
	v_mul_f32_e64 v33, |v27|, s26
	v_exp_f32_e32 v33, v33
	v_cmp_le_f32_e32 vcc, 0, v27
	v_add_f32_e32 v35, 1.0, v32
	v_rcp_f32_e32 v62, v35
	v_add_f32_e32 v35, 1.0, v33
	v_rcp_f32_e32 v63, v35
	v_and_b32_e32 v67, 0xffff0000, v23
	v_sub_f32_e32 v27, v95, v97
	v_sub_f32_e32 v35, v98, v96
	v_pk_mul_f32 v[32:33], v[32:33], v[62:63]
	v_mul_f32_e32 v27, 0x3fb8aa3b, v27
	v_cndmask_b32_e32 v33, v63, v33, vcc
	v_cmp_le_f32_e32 vcc, 0, v66
	v_lshlrev_b32_e32 v66, 16, v23
	v_mul_f32_e32 v23, 0xbfb8aa3b, v66
	v_exp_f32_e32 v23, v23
	v_mul_f32_e32 v63, 0xbfb8aa3b, v67
	v_exp_f32_e32 v63, v63
	v_mul_f32_e32 v35, 0x3fb8aa3b, v35
	v_add_f32_e32 v23, 1.0, v23
	v_cndmask_b32_e32 v32, v62, v32, vcc
	v_exp_f32_e32 v62, v27
	v_sub_f32_e32 v27, v96, v98
	v_rcp_f32_e32 v96, v23
	v_add_f32_e32 v23, 1.0, v63
	v_exp_f32_e32 v34, v34
	v_exp_f32_e32 v35, v35
	v_rcp_f32_e32 v97, v23
	v_pk_mul_f32 v[32:33], v[40:41], v[32:33]
	v_mul_f32_e32 v27, 0x3fb8aa3b, v27
	v_pk_mul_f32 v[32:33], v[34:35], v[32:33]
	v_pk_mul_f32 v[34:35], v[96:97], v[66:67]
	v_lshlrev_b32_e32 v66, 16, v26
	v_and_b32_e32 v67, 0xffff0000, v26
	v_mul_f32_e64 v26, |v66|, s26
	v_exp_f32_e32 v63, v27
	v_exp_f32_e32 v26, v26
	v_mul_f32_e64 v27, |v67|, s26
	v_exp_f32_e32 v27, v27
	v_sub_f32_e32 v23, v93, v91
	v_mul_f32_e32 v23, 0x3fb8aa3b, v23
	v_exp_f32_e32 v40, v23
	v_add_f32_e32 v23, 1.0, v26
	v_pk_mul_f32 v[34:35], v[62:63], v[34:35]
	v_rcp_f32_e32 v62, v23
	v_add_f32_e32 v23, 1.0, v27
	v_rcp_f32_e32 v63, v23
	v_cmp_le_f32_e32 vcc, 0, v67
	v_and_b32_e32 v67, 0xffff0000, v22
	v_sub_f32_e32 v23, v94, v92
	v_pk_mul_f32 v[26:27], v[26:27], v[62:63]
	v_mul_f32_e32 v23, 0x3fb8aa3b, v23
	v_cndmask_b32_e32 v27, v63, v27, vcc
	v_cmp_le_f32_e32 vcc, 0, v66
	v_lshlrev_b32_e32 v66, 16, v22
	v_mul_f32_e32 v22, 0xbfb8aa3b, v66
	v_mul_f32_e32 v63, 0xbfb8aa3b, v67
	v_exp_f32_e32 v22, v22
	v_exp_f32_e32 v63, v63
	v_exp_f32_e32 v41, v23
	v_sub_f32_e32 v23, v91, v93
	v_mul_f32_e32 v23, 0x3fb8aa3b, v23
	v_cndmask_b32_e32 v26, v62, v26, vcc
	v_exp_f32_e32 v62, v23
	v_sub_f32_e32 v23, v92, v94
	v_mul_f32_e32 v91, 0x3fb8aa3b, v23
	v_add_f32_e32 v22, 1.0, v22
	v_add_f32_e32 v23, 1.0, v63
	v_rcp_f32_e32 v22, v22
	v_rcp_f32_e32 v23, v23
	v_exp_f32_e32 v63, v91
	v_pk_mul_f32 v[26:27], v[54:55], v[26:27]
	v_cvt_pk_bf16_f32 v44, v100, v101
	v_pk_mul_f32 v[22:23], v[22:23], v[66:67]
	v_pk_mul_f32 v[26:27], v[40:41], v[26:27]
	v_pk_mul_f32 v[40:41], v[62:63], v[22:23]
	v_sub_f32_e32 v22, v89, v75
	v_lshlrev_b32_e32 v66, 16, v25
	v_mul_f32_e32 v54, 0x3fb8aa3b, v22
	v_and_b32_e32 v25, 0xffff0000, v25
	v_mul_f32_e64 v22, |v66|, s26
	v_exp_f32_e32 v22, v22
	v_mul_f32_e64 v23, |v25|, s26
	v_exp_f32_e32 v23, v23
	v_cmp_le_f32_e32 vcc, 0, v25
	v_add_f32_e32 v55, 1.0, v22
	v_rcp_f32_e32 v62, v55
	v_add_f32_e32 v55, 1.0, v23
	v_rcp_f32_e32 v63, v55
	v_and_b32_e32 v67, 0xffff0000, v21
	v_sub_f32_e32 v25, v75, v89
	v_mul_f32_e32 v25, 0x3fb8aa3b, v25
	v_pk_mul_f32 v[22:23], v[22:23], v[62:63]
	v_sub_f32_e32 v55, v90, v88
	v_cndmask_b32_e32 v23, v63, v23, vcc
	v_cmp_le_f32_e32 vcc, 0, v66
	v_lshlrev_b32_e32 v66, 16, v21
	v_mul_f32_e32 v21, 0xbfb8aa3b, v66
	v_exp_f32_e32 v21, v21
	v_mul_f32_e32 v63, 0xbfb8aa3b, v67
	v_exp_f32_e32 v63, v63
	v_cndmask_b32_e32 v22, v62, v22, vcc
	v_add_f32_e32 v21, 1.0, v21
	v_exp_f32_e32 v62, v25
	v_sub_f32_e32 v25, v88, v90
	v_rcp_f32_e32 v88, v21
	v_add_f32_e32 v21, 1.0, v63
	v_rcp_f32_e32 v89, v21
	v_pk_mul_f32 v[22:23], v[52:53], v[22:23]
	v_mul_f32_e32 v55, 0x3fb8aa3b, v55
	v_mul_f32_e32 v25, 0x3fb8aa3b, v25
	v_pk_mul_f32 v[52:53], v[88:89], v[66:67]
	v_lshlrev_b32_e32 v66, 16, v24
	v_and_b32_e32 v67, 0xffff0000, v24
	v_mul_f32_e64 v24, |v66|, s26
	v_exp_f32_e32 v54, v54
	v_exp_f32_e32 v55, v55
	v_exp_f32_e32 v63, v25
	v_exp_f32_e32 v24, v24
	v_mul_f32_e64 v25, |v67|, s26
	v_exp_f32_e32 v25, v25
	v_sub_f32_e32 v21, v73, v2
	v_mul_f32_e32 v21, 0x3fb8aa3b, v21
	v_pk_mul_f32 v[22:23], v[54:55], v[22:23]
	v_pk_mul_f32 v[54:55], v[62:63], v[52:53]
	v_exp_f32_e32 v52, v21
	v_add_f32_e32 v21, 1.0, v24
	v_rcp_f32_e32 v62, v21
	v_add_f32_e32 v21, 1.0, v25
	v_rcp_f32_e32 v63, v21
	v_sub_f32_e32 v21, v74, v72
	v_cmp_le_f32_e32 vcc, 0, v67
	v_mul_f32_e32 v21, 0x3fb8aa3b, v21
	v_pk_mul_f32 v[24:25], v[24:25], v[62:63]
	v_and_b32_e32 v67, 0xffff0000, v20
	v_cndmask_b32_e32 v25, v63, v25, vcc
	v_cmp_le_f32_e32 vcc, 0, v66
	v_lshlrev_b32_e32 v66, 16, v20
	v_exp_f32_e32 v53, v21
	v_mul_f32_e32 v20, 0xbfb8aa3b, v66
	v_mul_f32_e32 v21, 0xbfb8aa3b, v67
	v_exp_f32_e32 v20, v20
	v_exp_f32_e32 v21, v21
	v_sub_f32_e32 v2, v2, v73
	v_mul_f32_e32 v2, 0x3fb8aa3b, v2
	v_cndmask_b32_e32 v24, v62, v24, vcc
	v_exp_f32_e32 v62, v2
	v_sub_f32_e32 v2, v72, v74
	v_add_f32_e32 v20, 1.0, v20
	v_add_f32_e32 v21, 1.0, v21
	v_mul_f32_e32 v2, 0x3fb8aa3b, v2
	v_rcp_f32_e32 v20, v20
	v_rcp_f32_e32 v21, v21
; __device__ __forceinline__ void ld8bf(const bf16_t* p, float (&o)[8]) { unpack8(*(const u32x4*)p, o); }
; __device__ __forceinline__ float bperm_f(int src_lane, float v) { return __builtin_bit_cast(float, __builtin_amdgcn_ds_bpermute(src_lane << 2, __builtin_bit_cast(int, v))); }
; __device__ __forceinline__ float row_sum_incl(float v) { v += dpp_shr0<1>(v); v += dpp_shr0<2>(v); v += dpp_shr0<4>(v); v += dpp_shr0<8>(v); return v; }
; __device__ __forceinline__ float bcast15(float v, int lane) { return bperm_f((lane & 48) | 15, v); }
; __device__ __forceinline__ void w_hg_scan(const float (&lbv)[8], const bf16_t* fsrc, int lane, float (&bb)[4][8], float (&r31)[8], float (&r63)[8]) {
;     const int lo = lane & 15;
; #pragma unroll
;     for (int tb = 0; tb < 4; ++tb) { float fp[8]; ld8bf(fsrc + (size_t)(16 * tb + lo) * NIN, fp);
; #pragma unroll
;         for (int j = 0; j < 8; ++j) { float key; hg_lf_key(fp[j], lbv[j], bb[tb][j], key); } }
;     float carry[8];
; #pragma unroll
;     for (int j = 0; j < 8; ++j) carry[j] = 0.f;
; #pragma unroll
;     for (int tb = 0; tb < 4; ++tb) {
; #pragma unroll
;         for (int j = 0; j < 8; ++j) { const float v = row_sum_incl(bb[tb][j]) + carry[j]; bb[tb][j] = v; carry[j] = bcast15(v, lane); if (tb == 1) r31[j] = carry[j]; if (tb == 3) r63[j] = carry[j]; }
;         __builtin_amdgcn_sched_barrier(0);
;     }
	v_exp_f32_e32 v63, v2
	v_pk_mul_f32 v[24:25], v[42:43], v[24:25]
	v_add_f32_dpp v2, v103, v103 row_shr:1 row_mask:0xf bank_mask:0xf bound_ctrl:1
	v_pk_mul_f32 v[24:25], v[52:53], v[24:25]
	v_pk_mul_f32 v[20:21], v[20:21], v[66:67]
	v_cvt_pk_bf16_f32 v53, v54, v55
	v_pk_mul_f32 v[42:43], v[62:63], v[20:21]
	v_cvt_pk_bf16_f32 v20, v24, v25
	v_cvt_pk_bf16_f32 v21, v22, v23
	v_cvt_pk_bf16_f32 v22, v26, v27
	v_cvt_pk_bf16_f32 v23, v32, v33
	v_cvt_pk_bf16_f32 v55, v34, v35
	v_add_f32_dpp v24, v106, v106 row_shr:1 row_mask:0xf bank_mask:0xf bound_ctrl:1
	v_add_f32_dpp v25, v110, v110 row_shr:1 row_mask:0xf bank_mask:0xf bound_ctrl:1
	v_add_f32_dpp v26, v113, v113 row_shr:1 row_mask:0xf bank_mask:0xf bound_ctrl:1
	v_add_f32_dpp v27, v117, v117 row_shr:1 row_mask:0xf bank_mask:0xf bound_ctrl:1
	v_add_f32_dpp v32, v120, v120 row_shr:1 row_mask:0xf bank_mask:0xf bound_ctrl:1
	v_add_f32_dpp v33, v123, v123 row_shr:1 row_mask:0xf bank_mask:0xf bound_ctrl:1
	v_add_f32_dpp v34, v124, v124 row_shr:1 row_mask:0xf bank_mask:0xf bound_ctrl:1
	v_add_f32_dpp v2, v2, v2 row_shr:2 row_mask:0xf bank_mask:0xf bound_ctrl:1
	v_add_f32_dpp v24, v24, v24 row_shr:2 row_mask:0xf bank_mask:0xf bound_ctrl:1
	v_add_f32_dpp v25, v25, v25 row_shr:2 row_mask:0xf bank_mask:0xf bound_ctrl:1
	v_add_f32_dpp v26, v26, v26 row_shr:2 row_mask:0xf bank_mask:0xf bound_ctrl:1
	v_add_f32_dpp v27, v27, v27 row_shr:2 row_mask:0xf bank_mask:0xf bound_ctrl:1
	v_add_f32_dpp v32, v32, v32 row_shr:2 row_mask:0xf bank_mask:0xf bound_ctrl:1
	v_add_f32_dpp v33, v33, v33 row_shr:2 row_mask:0xf bank_mask:0xf bound_ctrl:1
	v_add_f32_dpp v34, v34, v34 row_shr:2 row_mask:0xf bank_mask:0xf bound_ctrl:1
	v_add_f32_dpp v2, v2, v2 row_shr:4 row_mask:0xf bank_mask:0xf bound_ctrl:1
	v_add_f32_dpp v24, v24, v24 row_shr:4 row_mask:0xf bank_mask:0xf bound_ctrl:1
	v_add_f32_dpp v25, v25, v25 row_shr:4 row_mask:0xf bank_mask:0xf bound_ctrl:1
	v_add_f32_dpp v26, v26, v26 row_shr:4 row_mask:0xf bank_mask:0xf bound_ctrl:1
	v_add_f32_dpp v27, v27, v27 row_shr:4 row_mask:0xf bank_mask:0xf bound_ctrl:1
	v_add_f32_dpp v32, v32, v32 row_shr:4 row_mask:0xf bank_mask:0xf bound_ctrl:1
	v_add_f32_dpp v33, v33, v33 row_shr:4 row_mask:0xf bank_mask:0xf bound_ctrl:1
	v_add_f32_dpp v34, v34, v34 row_shr:4 row_mask:0xf bank_mask:0xf bound_ctrl:1
	v_add_f32_dpp v2, v2, v2 row_shr:8 row_mask:0xf bank_mask:0xf bound_ctrl:1
	v_add_f32_dpp v24, v24, v24 row_shr:8 row_mask:0xf bank_mask:0xf bound_ctrl:1
	v_add_f32_dpp v25, v25, v25 row_shr:8 row_mask:0xf bank_mask:0xf bound_ctrl:1
	v_add_f32_dpp v26, v26, v26 row_shr:8 row_mask:0xf bank_mask:0xf bound_ctrl:1
	v_add_f32_dpp v27, v27, v27 row_shr:8 row_mask:0xf bank_mask:0xf bound_ctrl:1
	v_add_f32_dpp v32, v32, v32 row_shr:8 row_mask:0xf bank_mask:0xf bound_ctrl:1
	v_add_f32_dpp v33, v33, v33 row_shr:8 row_mask:0xf bank_mask:0xf bound_ctrl:1
	v_add_f32_dpp v34, v34, v34 row_shr:8 row_mask:0xf bank_mask:0xf bound_ctrl:1
	v_cvt_pk_bf16_f32 v52, v42, v43
	v_cvt_pk_bf16_f32 v54, v40, v41
	v_add_f32_e32 v41, 0, v2
	v_add_f32_e32 v43, 0, v24
	v_add_f32_e32 v74, 0, v25
	v_add_f32_e32 v75, 0, v26
	v_add_f32_e32 v121, 0, v27
	v_add_f32_e32 v119, 0, v32
	v_add_f32_e32 v63, 0, v33
	v_add_f32_e32 v62, 0, v34
	ds_bpermute_b32 v2, v186, v41
	ds_bpermute_b32 v24, v186, v43
	ds_bpermute_b32 v25, v186, v74
	ds_bpermute_b32 v26, v186, v75
	ds_bpermute_b32 v27, v186, v121
	ds_bpermute_b32 v32, v186, v119
	ds_bpermute_b32 v33, v186, v63
	ds_bpermute_b32 v34, v186, v62
	v_add_f32_dpp v35, v130, v130 row_shr:1 row_mask:0xf bank_mask:0xf bound_ctrl:1
	s_nop 1
	v_add_f32_dpp v35, v35, v35 row_shr:2 row_mask:0xf bank_mask:0xf bound_ctrl:1
	s_nop 1
	v_add_f32_dpp v35, v35, v35 row_shr:4 row_mask:0xf bank_mask:0xf bound_ctrl:1
	s_nop 1
	v_add_f32_dpp v35, v35, v35 row_shr:8 row_mask:0xf bank_mask:0xf bound_ctrl:1
	s_waitcnt lgkmcnt(7)
	v_add_f32_e32 v118, v35, v2
	ds_bpermute_b32 v2, v186, v118
	v_add_f32_dpp v35, v144, v144 row_shr:1 row_mask:0xf bank_mask:0xf bound_ctrl:1
	s_nop 1
	v_add_f32_dpp v35, v35, v35 row_shr:2 row_mask:0xf bank_mask:0xf bound_ctrl:1
	s_nop 1
	v_add_f32_dpp v35, v35, v35 row_shr:4 row_mask:0xf bank_mask:0xf bound_ctrl:1
	s_nop 1
	v_add_f32_dpp v35, v35, v35 row_shr:8 row_mask:0xf bank_mask:0xf bound_ctrl:1
	s_waitcnt lgkmcnt(7)
	v_add_f32_e32 v117, v35, v24
	v_add_f32_dpp v24, v155, v155 row_shr:1 row_mask:0xf bank_mask:0xf bound_ctrl:1
	ds_bpermute_b32 v88, v186, v117
	s_nop 0
	v_add_f32_dpp v24, v24, v24 row_shr:2 row_mask:0xf bank_mask:0xf bound_ctrl:1
	s_nop 1
	v_add_f32_dpp v24, v24, v24 row_shr:4 row_mask:0xf bank_mask:0xf bound_ctrl:1
	s_nop 1
	v_add_f32_dpp v24, v24, v24 row_shr:8 row_mask:0xf bank_mask:0xf bound_ctrl:1
	s_waitcnt lgkmcnt(7)
	v_add_f32_e32 v116, v24, v25
	ds_bpermute_b32 v89, v186, v116
	v_add_f32_dpp v24, v156, v156 row_shr:1 row_mask:0xf bank_mask:0xf bound_ctrl:1
	s_nop 1
	v_add_f32_dpp v24, v24, v24 row_shr:2 row_mask:0xf bank_mask:0xf bound_ctrl:1
	s_nop 1
	v_add_f32_dpp v24, v24, v24 row_shr:4 row_mask:0xf bank_mask:0xf bound_ctrl:1
	s_nop 1
	v_add_f32_dpp v24, v24, v24 row_shr:8 row_mask:0xf bank_mask:0xf bound_ctrl:1
	s_waitcnt lgkmcnt(7)
	v_add_f32_e32 v115, v24, v26
	ds_bpermute_b32 v90, v186, v115
	v_add_f32_dpp v24, v157, v157 row_shr:1 row_mask:0xf bank_mask:0xf bound_ctrl:1
	s_nop 1
	v_add_f32_dpp v24, v24, v24 row_shr:2 row_mask:0xf bank_mask:0xf bound_ctrl:1
	s_nop 1
	v_add_f32_dpp v24, v24, v24 row_shr:4 row_mask:0xf bank_mask:0xf bound_ctrl:1
	s_nop 1
	v_add_f32_dpp v24, v24, v24 row_shr:8 row_mask:0xf bank_mask:0xf bound_ctrl:1
	s_waitcnt lgkmcnt(7)
; __device__ __forceinline__ void ld8bf(const bf16_t* p, float (&o)[8]) { unpack8(*(const u32x4*)p, o); }
; __device__ __forceinline__ float bperm_f(int src_lane, float v) { return __builtin_bit_cast(float, __builtin_amdgcn_ds_bpermute(src_lane << 2, __builtin_bit_cast(int, v))); }
; __device__ __forceinline__ float row_sum_incl(float v) { v += dpp_shr0<1>(v); v += dpp_shr0<2>(v); v += dpp_shr0<4>(v); v += dpp_shr0<8>(v); return v; }
; __device__ __forceinline__ float bcast15(float v, int lane) { return bperm_f((lane & 48) | 15, v); }
; __device__ __forceinline__ void w_hg_scan(const float (&lbv)[8], const bf16_t* fsrc, int lane, float (&bb)[4][8], float (&r31)[8], float (&r63)[8]) {
;     const int lo = lane & 15;
; #pragma unroll
;     for (int tb = 0; tb < 4; ++tb) { float fp[8]; ld8bf(fsrc + (size_t)(16 * tb + lo) * NIN, fp);
; #pragma unroll
;         for (int j = 0; j < 8; ++j) { float key; hg_lf_key(fp[j], lbv[j], bb[tb][j], key); } }
;     float carry[8];
; #pragma unroll
;     for (int j = 0; j < 8; ++j) carry[j] = 0.f;
; #pragma unroll
;     for (int tb = 0; tb < 4; ++tb) {
; #pragma unroll
;         for (int j = 0; j < 8; ++j) { const float v = row_sum_incl(bb[tb][j]) + carry[j]; bb[tb][j] = v; carry[j] = bcast15(v, lane); if (tb == 1) r31[j] = carry[j]; if (tb == 3) r63[j] = carry[j]; }
;         __builtin_amdgcn_sched_barrier(0);
;     }
	v_add_f32_e32 v113, v24, v27
	ds_bpermute_b32 v91, v186, v113
	v_add_f32_dpp v24, v158, v158 row_shr:1 row_mask:0xf bank_mask:0xf bound_ctrl:1
	s_nop 1
	v_add_f32_dpp v24, v24, v24 row_shr:2 row_mask:0xf bank_mask:0xf bound_ctrl:1
	s_nop 1
	v_add_f32_dpp v24, v24, v24 row_shr:4 row_mask:0xf bank_mask:0xf bound_ctrl:1
	s_nop 1
	v_add_f32_dpp v24, v24, v24 row_shr:8 row_mask:0xf bank_mask:0xf bound_ctrl:1
	s_waitcnt lgkmcnt(7)
	v_add_f32_e32 v112, v24, v32
	ds_bpermute_b32 v92, v186, v112
	v_add_f32_dpp v24, v159, v159 row_shr:1 row_mask:0xf bank_mask:0xf bound_ctrl:1
	s_nop 1
	v_add_f32_dpp v24, v24, v24 row_shr:2 row_mask:0xf bank_mask:0xf bound_ctrl:1
	s_nop 1
	v_add_f32_dpp v24, v24, v24 row_shr:4 row_mask:0xf bank_mask:0xf bound_ctrl:1
	s_nop 1
	v_add_f32_dpp v24, v24, v24 row_shr:8 row_mask:0xf bank_mask:0xf bound_ctrl:1
	s_waitcnt lgkmcnt(7)
	v_add_f32_e32 v111, v24, v33
	ds_bpermute_b32 v93, v186, v111
	v_add_f32_dpp v24, v160, v160 row_shr:1 row_mask:0xf bank_mask:0xf bound_ctrl:1
	s_nop 1
	v_add_f32_dpp v24, v24, v24 row_shr:2 row_mask:0xf bank_mask:0xf bound_ctrl:1
	s_nop 1
	v_add_f32_dpp v24, v24, v24 row_shr:4 row_mask:0xf bank_mask:0xf bound_ctrl:1
	s_nop 1
	v_add_f32_dpp v24, v24, v24 row_shr:8 row_mask:0xf bank_mask:0xf bound_ctrl:1
	s_waitcnt lgkmcnt(7)
	v_add_f32_e32 v110, v24, v34
	ds_bpermute_b32 v94, v186, v110
	v_add_f32_dpp v24, v161, v161 row_shr:1 row_mask:0xf bank_mask:0xf bound_ctrl:1
	v_add_f32_dpp v25, v162, v162 row_shr:1 row_mask:0xf bank_mask:0xf bound_ctrl:1
	v_add_f32_dpp v26, v163, v163 row_shr:1 row_mask:0xf bank_mask:0xf bound_ctrl:1
	v_add_f32_dpp v27, v169, v169 row_shr:1 row_mask:0xf bank_mask:0xf bound_ctrl:1
	v_add_f32_dpp v32, v174, v174 row_shr:1 row_mask:0xf bank_mask:0xf bound_ctrl:1
	v_add_f32_dpp v33, v175, v175 row_shr:1 row_mask:0xf bank_mask:0xf bound_ctrl:1
	v_add_f32_dpp v34, v176, v176 row_shr:1 row_mask:0xf bank_mask:0xf bound_ctrl:1
	v_add_f32_dpp v35, v177, v177 row_shr:1 row_mask:0xf bank_mask:0xf bound_ctrl:1
	v_add_f32_dpp v24, v24, v24 row_shr:2 row_mask:0xf bank_mask:0xf bound_ctrl:1
	v_add_f32_dpp v25, v25, v25 row_shr:2 row_mask:0xf bank_mask:0xf bound_ctrl:1
	v_add_f32_dpp v26, v26, v26 row_shr:2 row_mask:0xf bank_mask:0xf bound_ctrl:1
	v_add_f32_dpp v27, v27, v27 row_shr:2 row_mask:0xf bank_mask:0xf bound_ctrl:1
	v_add_f32_dpp v32, v32, v32 row_shr:2 row_mask:0xf bank_mask:0xf bound_ctrl:1
	v_add_f32_dpp v33, v33, v33 row_shr:2 row_mask:0xf bank_mask:0xf bound_ctrl:1
	v_add_f32_dpp v34, v34, v34 row_shr:2 row_mask:0xf bank_mask:0xf bound_ctrl:1
	v_add_f32_dpp v35, v35, v35 row_shr:2 row_mask:0xf bank_mask:0xf bound_ctrl:1
	v_add_f32_dpp v24, v24, v24 row_shr:4 row_mask:0xf bank_mask:0xf bound_ctrl:1
	v_add_f32_dpp v25, v25, v25 row_shr:4 row_mask:0xf bank_mask:0xf bound_ctrl:1
	v_add_f32_dpp v26, v26, v26 row_shr:4 row_mask:0xf bank_mask:0xf bound_ctrl:1
	v_add_f32_dpp v27, v27, v27 row_shr:4 row_mask:0xf bank_mask:0xf bound_ctrl:1
	v_add_f32_dpp v32, v32, v32 row_shr:4 row_mask:0xf bank_mask:0xf bound_ctrl:1
	v_add_f32_dpp v33, v33, v33 row_shr:4 row_mask:0xf bank_mask:0xf bound_ctrl:1
	v_add_f32_dpp v34, v34, v34 row_shr:4 row_mask:0xf bank_mask:0xf bound_ctrl:1
	v_add_f32_dpp v35, v35, v35 row_shr:4 row_mask:0xf bank_mask:0xf bound_ctrl:1
	v_add_f32_dpp v24, v24, v24 row_shr:8 row_mask:0xf bank_mask:0xf bound_ctrl:1
	v_add_f32_dpp v25, v25, v25 row_shr:8 row_mask:0xf bank_mask:0xf bound_ctrl:1
	v_add_f32_dpp v26, v26, v26 row_shr:8 row_mask:0xf bank_mask:0xf bound_ctrl:1
	v_add_f32_dpp v27, v27, v27 row_shr:8 row_mask:0xf bank_mask:0xf bound_ctrl:1
	v_add_f32_dpp v32, v32, v32 row_shr:8 row_mask:0xf bank_mask:0xf bound_ctrl:1
	v_add_f32_dpp v33, v33, v33 row_shr:8 row_mask:0xf bank_mask:0xf bound_ctrl:1
	v_add_f32_dpp v34, v34, v34 row_shr:8 row_mask:0xf bank_mask:0xf bound_ctrl:1
	v_add_f32_dpp v35, v35, v35 row_shr:8 row_mask:0xf bank_mask:0xf bound_ctrl:1
	s_waitcnt lgkmcnt(7)
	v_add_f32_e32 v109, v24, v2
	s_waitcnt lgkmcnt(6)
	v_add_f32_e32 v107, v25, v88
	s_waitcnt lgkmcnt(5)
	v_add_f32_e32 v106, v26, v89
	s_waitcnt lgkmcnt(4)
	v_add_f32_e32 v105, v27, v90
	s_waitcnt lgkmcnt(3)
	v_add_f32_e32 v104, v32, v91
	s_waitcnt lgkmcnt(2)
	v_add_f32_e32 v103, v33, v92
	s_waitcnt lgkmcnt(1)
	v_add_f32_e32 v67, v34, v93
	s_waitcnt lgkmcnt(0)
	v_add_f32_e32 v66, v35, v94
	ds_bpermute_b32 v24, v186, v109
	ds_bpermute_b32 v25, v186, v107
	ds_bpermute_b32 v26, v186, v106
	ds_bpermute_b32 v27, v186, v105
	ds_bpermute_b32 v32, v186, v104
	ds_bpermute_b32 v33, v186, v103
	ds_bpermute_b32 v34, v186, v67
	ds_bpermute_b32 v35, v186, v66
	v_add_f32_dpp v40, v178, v178 row_shr:1 row_mask:0xf bank_mask:0xf bound_ctrl:1
	s_nop 1
	v_add_f32_dpp v40, v40, v40 row_shr:2 row_mask:0xf bank_mask:0xf bound_ctrl:1
	s_nop 1
	v_add_f32_dpp v40, v40, v40 row_shr:4 row_mask:0xf bank_mask:0xf bound_ctrl:1
	s_nop 1
	v_add_f32_dpp v40, v40, v40 row_shr:8 row_mask:0xf bank_mask:0xf bound_ctrl:1
	s_waitcnt lgkmcnt(7)
	v_add_f32_e32 v102, v40, v24
	v_add_f32_dpp v24, v179, v179 row_shr:1 row_mask:0xf bank_mask:0xf bound_ctrl:1
	s_nop 1
	v_add_f32_dpp v24, v24, v24 row_shr:2 row_mask:0xf bank_mask:0xf bound_ctrl:1
	s_nop 1
	v_add_f32_dpp v24, v24, v24 row_shr:4 row_mask:0xf bank_mask:0xf bound_ctrl:1
	s_nop 1
	v_add_f32_dpp v24, v24, v24 row_shr:8 row_mask:0xf bank_mask:0xf bound_ctrl:1
	s_waitcnt lgkmcnt(6)
	v_add_f32_e32 v101, v24, v25
	v_add_f32_dpp v24, v180, v180 row_shr:1 row_mask:0xf bank_mask:0xf bound_ctrl:1
	s_nop 1
	v_add_f32_dpp v24, v24, v24 row_shr:2 row_mask:0xf bank_mask:0xf bound_ctrl:1
	s_nop 1
	v_add_f32_dpp v24, v24, v24 row_shr:4 row_mask:0xf bank_mask:0xf bound_ctrl:1
	s_nop 1
	v_add_f32_dpp v24, v24, v24 row_shr:8 row_mask:0xf bank_mask:0xf bound_ctrl:1
	s_waitcnt lgkmcnt(5)
; __device__ __forceinline__ void ld8bf(const bf16_t* p, float (&o)[8]) { unpack8(*(const u32x4*)p, o); }
; __device__ __forceinline__ float sigmoidf_(float x) { return __builtin_amdgcn_rcpf(1.0f + __expf(-x)); }
; __device__ __forceinline__ bf16x8 pack_frag(const float (&v)[8]) { return __builtin_bit_cast(bf16x8, pack8(v)); }
; __device__ __forceinline__ float row_sum_incl(float v) { v += dpp_shr0<1>(v); v += dpp_shr0<2>(v); v += dpp_shr0<4>(v); v += dpp_shr0<8>(v); return v; }
; __device__ __forceinline__ float bcast15(float v, int lane) { return bperm_f((lane & 48) | 15, v); }
; __device__ __forceinline__ void w_hg_scan(const float (&lbv)[8], const bf16_t* fsrc, int lane, float (&bb)[4][8], float (&r31)[8], float (&r63)[8]) {
;     ...
;     for (int tb = 0; tb < 4; ++tb) {
; #pragma unroll
;         for (int j = 0; j < 8; ++j) { const float v = row_sum_incl(bb[tb][j]) + carry[j]; bb[tb][j] = v; carry[j] = bcast15(v, lane); if (tb == 1) r31[j] = carry[j]; if (tb == 3) r63[j] = carry[j]; }
;         __builtin_amdgcn_sched_barrier(0);
;     }
; __device__ __forceinline__ void w_hg_m3(const Args& a, int l, unsigned char* ws, const bf16_t* proj, bf16_t* y, LAS unsigned char* wl, int b, int ck_, int h, int lane) {
;     ...
;         for (int tb = 0; tb < 4; ++tb) { float fp[8], qv[8], a1[8], a2[8];
;             ld8bf(fsrc + (size_t)(16 * tb + lo) * NIN, fp); ld8bf(proj + (size_t)(row0 + 16 * tb + lo) * NIN + C_HQ + 64 * h + 32 * kk + 8 * fq, qv);
; #pragma unroll
;             for (int j = 0; j < 8; ++j) { float lf, key; hg_lf_key(fp[j], lbv[j], lf, key);
;                 const float q = qv[j] * sigmoidf_(qv[j]); a1[j] = q * __expf(bb[tb][j] - r31[j]); a2[j] = key * __expf(r31[j] - bb[tb][j]); }
;             Qf[tb][kk] = pack_frag(a1); Kf[tb][kk] = pack_frag(a2); }
	v_add_f32_e32 v100, v24, v26
	v_add_f32_dpp v24, v181, v181 row_shr:1 row_mask:0xf bank_mask:0xf bound_ctrl:1
	s_nop 1
	v_add_f32_dpp v24, v24, v24 row_shr:2 row_mask:0xf bank_mask:0xf bound_ctrl:1
	s_nop 1
	v_add_f32_dpp v24, v24, v24 row_shr:4 row_mask:0xf bank_mask:0xf bound_ctrl:1
	s_nop 1
	v_add_f32_dpp v24, v24, v24 row_shr:8 row_mask:0xf bank_mask:0xf bound_ctrl:1
	s_waitcnt lgkmcnt(4)
	v_add_f32_e32 v99, v24, v27
	v_add_f32_dpp v24, v182, v182 row_shr:1 row_mask:0xf bank_mask:0xf bound_ctrl:1
	s_nop 1
	v_add_f32_dpp v24, v24, v24 row_shr:2 row_mask:0xf bank_mask:0xf bound_ctrl:1
	s_nop 1
	v_add_f32_dpp v24, v24, v24 row_shr:4 row_mask:0xf bank_mask:0xf bound_ctrl:1
	s_nop 1
	v_add_f32_dpp v24, v24, v24 row_shr:8 row_mask:0xf bank_mask:0xf bound_ctrl:1
	s_waitcnt lgkmcnt(3)
	v_add_f32_e32 v98, v24, v32
	v_add_f32_dpp v24, v183, v183 row_shr:1 row_mask:0xf bank_mask:0xf bound_ctrl:1
	s_nop 1
	v_add_f32_dpp v24, v24, v24 row_shr:2 row_mask:0xf bank_mask:0xf bound_ctrl:1
	s_nop 1
	v_add_f32_dpp v24, v24, v24 row_shr:4 row_mask:0xf bank_mask:0xf bound_ctrl:1
	s_nop 1
	v_add_f32_dpp v24, v24, v24 row_shr:8 row_mask:0xf bank_mask:0xf bound_ctrl:1
	s_waitcnt lgkmcnt(2)
	v_add_f32_e32 v97, v24, v33
	v_add_f32_dpp v24, v184, v184 row_shr:1 row_mask:0xf bank_mask:0xf bound_ctrl:1
	s_nop 1
	v_add_f32_dpp v24, v24, v24 row_shr:2 row_mask:0xf bank_mask:0xf bound_ctrl:1
	s_nop 1
	v_add_f32_dpp v24, v24, v24 row_shr:4 row_mask:0xf bank_mask:0xf bound_ctrl:1
	s_nop 1
	v_add_f32_dpp v24, v24, v24 row_shr:8 row_mask:0xf bank_mask:0xf bound_ctrl:1
	s_waitcnt lgkmcnt(1)
	v_add_f32_e32 v96, v24, v34
	v_add_f32_dpp v24, v185, v185 row_shr:1 row_mask:0xf bank_mask:0xf bound_ctrl:1
	s_nop 1
	v_add_f32_dpp v24, v24, v24 row_shr:2 row_mask:0xf bank_mask:0xf bound_ctrl:1
	s_nop 1
	v_add_f32_dpp v24, v24, v24 row_shr:4 row_mask:0xf bank_mask:0xf bound_ctrl:1
	s_nop 1
	v_add_f32_dpp v24, v24, v24 row_shr:8 row_mask:0xf bank_mask:0xf bound_ctrl:1
	s_waitcnt lgkmcnt(0)
	v_add_f32_e32 v95, v24, v35
	global_load_dwordx4 v[24:27], v[60:61], off
	global_load_dwordx4 v[32:35], v[70:71], off offset:64
	global_load_dwordx4 v[134:137], v[48:49], off offset:64
	global_load_dwordx4 v[138:141], v[78:79], off offset:64
	global_load_dwordx4 v[142:145], v[36:37], off offset:64
	global_load_dwordx4 v[146:149], v[38:39], off offset:64
	global_load_dwordx4 v[150:153], v[76:77], off offset:64
	global_load_dwordx4 v[122:125], v[64:65], off offset:64
	v_pk_add_f32 v[70:71], v[56:57], 1.0 op_sel_hi:[1,0] neg_lo:[1,0] neg_hi:[1,0]
	v_sub_f32_e32 v40, v41, v2
	v_sub_f32_e32 v41, v2, v41
	v_mul_f32_e32 v41, 0x3fb8aa3b, v41
	v_exp_f32_e32 v42, v41
	v_sub_f32_e32 v41, v43, v88
	v_mul_f32_e32 v40, 0x3fb8aa3b, v40
	v_mul_f32_e32 v41, 0x3fb8aa3b, v41
	v_exp_f32_e32 v40, v40
	v_exp_f32_e32 v41, v41
	v_pk_add_f32 v[72:73], v[58:59], 1.0 op_sel_hi:[1,0] neg_lo:[1,0] neg_hi:[1,0]
	s_waitcnt vmcnt(0) lgkmcnt(0)
	v_lshlrev_b32_e32 v56, 16, v32
	v_and_b32_e32 v57, 0xffff0000, v32
	v_mul_f32_e32 v32, 0xbfb8aa3b, v56
	v_exp_f32_e32 v32, v32
	s_nop 0
	v_add_f32_e32 v32, 1.0, v32
	v_rcp_f32_e32 v60, v32
	v_mul_f32_e32 v32, 0xbfb8aa3b, v57
	v_exp_f32_e32 v32, v32
	s_nop 0
	v_add_f32_e32 v32, 1.0, v32
	v_rcp_f32_e32 v61, v32
	v_sub_f32_e32 v32, v88, v43
	v_mul_f32_e32 v32, 0x3fb8aa3b, v32
	v_exp_f32_e32 v43, v32
	v_pk_mul_f32 v[56:57], v[60:61], v[56:57]
	v_lshlrev_b32_e32 v32, 16, v24
	v_pk_mul_f32 v[40:41], v[40:41], v[56:57]
	v_mul_f32_e64 v56, |v32|, s26
	v_exp_f32_e32 v56, v56
	v_and_b32_e32 v24, 0xffff0000, v24
	v_cmp_le_f32_e32 vcc, 0, v32
	v_cmp_le_f32_e64 s[38:39], 0, v24
	v_add_f32_e32 v57, 1.0, v56
	v_rcp_f32_e32 v60, v57
	v_mul_f32_e64 v57, |v24|, s26
	v_exp_f32_e32 v57, v57
	v_sub_f32_e32 v24, v74, v89
	v_mul_f32_e32 v24, 0x3fb8aa3b, v24
	v_lshlrev_b32_e32 v32, 16, v33
	v_add_f32_e32 v61, 1.0, v57
	v_rcp_f32_e32 v61, v61
	v_and_b32_e32 v33, 0xffff0000, v33
	v_pk_mul_f32 v[56:57], v[56:57], v[60:61]
	s_nop 0
	v_cndmask_b32_e64 v57, v61, v57, s[38:39]
	v_cndmask_b32_e32 v56, v60, v56, vcc
	v_pk_mul_f32 v[56:57], v[70:71], v[56:57]
	s_nop 0
	v_pk_mul_f32 v[42:43], v[42:43], v[56:57]
	v_exp_f32_e32 v56, v24
	v_sub_f32_e32 v24, v89, v74
	v_mul_f32_e32 v24, 0x3fb8aa3b, v24
	v_exp_f32_e32 v58, v24
	v_sub_f32_e32 v24, v75, v90
	v_mul_f32_e32 v24, 0x3fb8aa3b, v24
	v_exp_f32_e32 v57, v24
	v_mul_f32_e32 v24, 0xbfb8aa3b, v32
	v_exp_f32_e32 v24, v24
	s_nop 0
	v_add_f32_e32 v24, 1.0, v24
	v_rcp_f32_e32 v60, v24
	v_mul_f32_e32 v24, 0xbfb8aa3b, v33
	v_exp_f32_e32 v24, v24
	s_nop 0
	v_add_f32_e32 v24, 1.0, v24
	v_rcp_f32_e32 v61, v24
	v_sub_f32_e32 v24, v90, v75
	v_mul_f32_e32 v24, 0x3fb8aa3b, v24
	v_exp_f32_e32 v59, v24
	v_pk_mul_f32 v[32:33], v[60:61], v[32:33]
	v_lshlrev_b32_e32 v60, 16, v25
	v_mul_f32_e64 v24, |v60|, s26
	v_exp_f32_e32 v24, v24
	v_and_b32_e32 v61, 0xffff0000, v25
	v_pk_mul_f32 v[32:33], v[56:57], v[32:33]
	v_cmp_le_f32_e32 vcc, 0, v60
	v_add_f32_e32 v25, 1.0, v24
	v_rcp_f32_e32 v56, v25
	v_mul_f32_e64 v25, |v61|, s26
	v_exp_f32_e32 v25, v25
	v_cmp_le_f32_e64 s[38:39], 0, v61
	v_pk_add_f32 v[74:75], v[50:51], 1.0 op_sel_hi:[1,0] neg_lo:[1,0] neg_hi:[1,0]
	v_add_f32_e32 v57, 1.0, v25
	v_rcp_f32_e32 v57, v57
	s_nop 0
	v_pk_mul_f32 v[24:25], v[24:25], v[56:57]
	s_nop 0
	v_cndmask_b32_e64 v25, v57, v25, s[38:39]
	v_cndmask_b32_e32 v24, v56, v24, vcc
	v_pk_mul_f32 v[24:25], v[72:73], v[24:25]
	s_nop 0
	v_pk_mul_f32 v[56:57], v[58:59], v[24:25]
	v_lshlrev_b32_e32 v58, 16, v34
	v_and_b32_e32 v59, 0xffff0000, v34
	v_mul_f32_e32 v34, 0xbfb8aa3b, v58
	v_exp_f32_e32 v34, v34
	v_sub_f32_e32 v25, v91, v121
	v_mul_f32_e32 v25, 0x3fb8aa3b, v25
	v_sub_f32_e32 v24, v121, v91
	v_add_f32_e32 v34, 1.0, v34
; __device__ __forceinline__ void ld8bf(const bf16_t* p, float (&o)[8]) { unpack8(*(const u32x4*)p, o); }
; __device__ __forceinline__ float sigmoidf_(float x) { return __builtin_amdgcn_rcpf(1.0f + __expf(-x)); }
; __device__ __forceinline__ bf16x8 pack_frag(const float (&v)[8]) { return __builtin_bit_cast(bf16x8, pack8(v)); }
; __device__ __forceinline__ void hg_lf_key(float fp, float lb, float& lf, float& key) {
;     const float e = __expf(-fabsf(fp));
;     const float rc = __builtin_amdgcn_rcpf(1.0f + e);
;     const float sp = fp >= 0.f ? rc : e * rc;
;     const float sn = fp >= 0.f ? e * rc : rc;
;     const float lsig = (fp >= 0.f ? 0.f : fp) + __logf(rc);
;     lf = (lb == 0.f) ? lsig : __logf(lb + (1.0f - lb) * sp); key = (1.0f - lb) * sn;
; __device__ __forceinline__ void w_hg_m3(const Args& a, int l, unsigned char* ws, const bf16_t* proj, bf16_t* y, LAS unsigned char* wl, int b, int ck_, int h, int lane) {
;     ...
;         for (int tb = 0; tb < 4; ++tb) { float fp[8], qv[8], a1[8], a2[8];
;             ld8bf(fsrc + (size_t)(16 * tb + lo) * NIN, fp); ld8bf(proj + (size_t)(row0 + 16 * tb + lo) * NIN + C_HQ + 64 * h + 32 * kk + 8 * fq, qv);
; #pragma unroll
;             for (int j = 0; j < 8; ++j) { float lf, key; hg_lf_key(fp[j], lbv[j], lf, key);
;                 const float q = qv[j] * sigmoidf_(qv[j]); a1[j] = q * __expf(bb[tb][j] - r31[j]); a2[j] = key * __expf(r31[j] - bb[tb][j]); }
;             Qf[tb][kk] = pack_frag(a1); Kf[tb][kk] = pack_frag(a2); }
	v_rcp_f32_e32 v60, v34
	v_mul_f32_e32 v34, 0xbfb8aa3b, v59
	v_exp_f32_e32 v34, v34
	v_exp_f32_e32 v50, v25
	v_sub_f32_e32 v25, v119, v92
	v_mul_f32_e32 v24, 0x3fb8aa3b, v24
	v_add_f32_e32 v34, 1.0, v34
	v_mul_f32_e32 v25, 0x3fb8aa3b, v25
	v_rcp_f32_e32 v61, v34
	v_exp_f32_e32 v24, v24
	v_exp_f32_e32 v25, v25
	v_sub_f32_e32 v34, v92, v119
	v_mul_f32_e32 v34, 0x3fb8aa3b, v34
	v_pk_mul_f32 v[58:59], v[60:61], v[58:59]
	v_exp_f32_e32 v51, v34
	v_lshlrev_b32_e32 v34, 16, v26
	v_pk_mul_f32 v[24:25], v[24:25], v[58:59]
	v_mul_f32_e64 v58, |v34|, s26
	v_exp_f32_e32 v58, v58
	v_and_b32_e32 v26, 0xffff0000, v26
	v_cmp_le_f32_e32 vcc, 0, v34
	v_cmp_le_f32_e64 s[38:39], 0, v26
	v_add_f32_e32 v59, 1.0, v58
	v_rcp_f32_e32 v60, v59
	v_mul_f32_e64 v59, |v26|, s26
	v_exp_f32_e32 v59, v59
	v_sub_f32_e32 v26, v63, v93
	v_mul_f32_e32 v26, 0x3fb8aa3b, v26
	v_add_f32_e32 v61, 1.0, v59
	v_rcp_f32_e32 v61, v61
	s_nop 0
	v_pk_mul_f32 v[58:59], v[58:59], v[60:61]
	s_nop 0
	v_cndmask_b32_e64 v59, v61, v59, s[38:39]
	v_cndmask_b32_e32 v58, v60, v58, vcc
	v_pk_mul_f32 v[58:59], v[74:75], v[58:59]
	v_lshlrev_b32_e32 v60, 16, v35
	v_pk_mul_f32 v[50:51], v[50:51], v[58:59]
	v_exp_f32_e32 v58, v26
	v_sub_f32_e32 v26, v93, v63
	v_mul_f32_e32 v26, 0x3fb8aa3b, v26
	v_exp_f32_e32 v34, v26
	v_sub_f32_e32 v26, v62, v94
	v_mul_f32_e32 v26, 0x3fb8aa3b, v26
	v_exp_f32_e32 v59, v26
	v_mul_f32_e32 v26, 0xbfb8aa3b, v60
	v_exp_f32_e32 v26, v26
	v_and_b32_e32 v61, 0xffff0000, v35
	v_and_b32_e32 v63, 0xffff0000, v27
	v_cmp_le_f32_e64 s[38:39], 0, v63
	v_add_f32_e32 v26, 1.0, v26
	v_rcp_f32_e32 v120, v26
	v_mul_f32_e32 v26, 0xbfb8aa3b, v61
	v_exp_f32_e32 v26, v26
	s_nop 0
	v_add_f32_e32 v26, 1.0, v26
	v_rcp_f32_e32 v121, v26
	v_sub_f32_e32 v26, v94, v62
	v_mul_f32_e32 v26, 0x3fb8aa3b, v26
	v_lshlrev_b32_e32 v62, 16, v27
	v_exp_f32_e32 v35, v26
	v_mul_f32_e64 v26, |v62|, s26
	v_exp_f32_e32 v26, v26
	v_pk_mul_f32 v[60:61], v[120:121], v[60:61]
	v_cmp_le_f32_e32 vcc, 0, v62
	v_pk_mul_f32 v[58:59], v[58:59], v[60:61]
	v_add_f32_e32 v27, 1.0, v26
	v_rcp_f32_e32 v60, v27
	v_mul_f32_e64 v27, |v63|, s26
	v_exp_f32_e32 v27, v27
	v_cvt_pk_bf16_f32 v62, v24, v25
	v_cvt_pk_bf16_f32 v24, v42, v43
	v_cvt_pk_bf16_f32 v25, v56, v57
	v_add_f32_e32 v61, 1.0, v27
	v_rcp_f32_e32 v61, v61
	v_cvt_pk_bf16_f32 v63, v58, v59
	v_pk_mul_f32 v[26:27], v[26:27], v[60:61]
	s_nop 0
	v_cndmask_b32_e64 v27, v61, v27, s[38:39]
	v_cndmask_b32_e32 v26, v60, v26, vcc
	v_pk_mul_f32 v[26:27], v[68:69], v[26:27]
	v_cvt_pk_bf16_f32 v60, v40, v41
	v_pk_mul_f32 v[34:35], v[34:35], v[26:27]
	v_cvt_pk_bf16_f32 v61, v32, v33
	v_cvt_pk_bf16_f32 v27, v34, v35
	v_mov_b64_e32 v[32:33], v[134:135]
	v_mov_b64_e32 v[34:35], v[136:137]
	v_mov_b64_e32 v[40:41], v[138:139]
	v_mov_b64_e32 v[42:43], v[140:141]
	v_sub_f32_e32 v49, v2, v118
	v_mul_f32_e32 v49, 0x3fb8aa3b, v49
	v_cvt_pk_bf16_f32 v26, v50, v51
	v_sub_f32_e32 v48, v118, v2
	v_exp_f32_e32 v50, v49
	v_sub_f32_e32 v49, v117, v88
	v_mul_f32_e32 v48, 0x3fb8aa3b, v48
	v_mul_f32_e32 v49, 0x3fb8aa3b, v49
	v_exp_f32_e32 v48, v48
	v_exp_f32_e32 v49, v49
	s_waitcnt vmcnt(0) lgkmcnt(0)
	v_lshlrev_b32_e32 v56, 16, v40
	v_and_b32_e32 v57, 0xffff0000, v40
	v_mul_f32_e32 v40, 0xbfb8aa3b, v56
	v_exp_f32_e32 v40, v40
	s_nop 0
	v_add_f32_e32 v40, 1.0, v40
	v_rcp_f32_e32 v58, v40
	v_mul_f32_e32 v40, 0xbfb8aa3b, v57
	v_exp_f32_e32 v40, v40
	s_nop 0
	v_add_f32_e32 v40, 1.0, v40
	v_rcp_f32_e32 v59, v40
	v_sub_f32_e32 v40, v88, v117
	v_mul_f32_e32 v40, 0x3fb8aa3b, v40
	v_exp_f32_e32 v51, v40
	v_pk_mul_f32 v[56:57], v[58:59], v[56:57]
	v_lshlrev_b32_e32 v40, 16, v32
	v_pk_mul_f32 v[48:49], v[48:49], v[56:57]
	v_mul_f32_e64 v56, |v40|, s26
	v_exp_f32_e32 v56, v56
	v_and_b32_e32 v32, 0xffff0000, v32
	v_cmp_le_f32_e32 vcc, 0, v40
	v_cmp_le_f32_e64 s[38:39], 0, v32
	v_add_f32_e32 v57, 1.0, v56
	v_rcp_f32_e32 v58, v57
	v_mul_f32_e64 v57, |v32|, s26
	v_exp_f32_e32 v57, v57
	v_sub_f32_e32 v32, v116, v89
	v_mul_f32_e32 v32, 0x3fb8aa3b, v32
	v_cvt_pk_bf16_f32 v48, v48, v49
	v_add_f32_e32 v59, 1.0, v57
	v_rcp_f32_e32 v59, v59
	s_nop 0
	v_pk_mul_f32 v[56:57], v[56:57], v[58:59]
	s_nop 0
	v_cndmask_b32_e64 v57, v59, v57, s[38:39]
	v_cndmask_b32_e32 v56, v58, v56, vcc
	v_pk_mul_f32 v[56:57], v[70:71], v[56:57]
	v_lshlrev_b32_e32 v58, 16, v41
	v_pk_mul_f32 v[56:57], v[50:51], v[56:57]
	v_exp_f32_e32 v50, v32
	v_sub_f32_e32 v32, v89, v116
	v_mul_f32_e32 v32, 0x3fb8aa3b, v32
	v_exp_f32_e32 v40, v32
	v_sub_f32_e32 v32, v115, v90
	v_mul_f32_e32 v32, 0x3fb8aa3b, v32
	v_exp_f32_e32 v51, v32
	v_mul_f32_e32 v32, 0xbfb8aa3b, v58
	v_exp_f32_e32 v32, v32
	v_and_b32_e32 v59, 0xffff0000, v41
	v_add_f32_e32 v32, 1.0, v32
	v_rcp_f32_e32 v78, v32
	v_mul_f32_e32 v32, 0xbfb8aa3b, v59
	v_exp_f32_e32 v32, v32
	s_nop 0
	v_add_f32_e32 v32, 1.0, v32
	v_rcp_f32_e32 v79, v32
	v_sub_f32_e32 v32, v90, v115
	v_mul_f32_e32 v32, 0x3fb8aa3b, v32
	v_exp_f32_e32 v41, v32
	v_pk_mul_f32 v[58:59], v[78:79], v[58:59]
	v_lshlrev_b32_e32 v78, 16, v33
	v_mul_f32_e64 v32, |v78|, s26
	v_exp_f32_e32 v32, v32
	v_and_b32_e32 v79, 0xffff0000, v33
	v_pk_mul_f32 v[50:51], v[50:51], v[58:59]
	v_cmp_le_f32_e32 vcc, 0, v78
	v_add_f32_e32 v33, 1.0, v32
	v_rcp_f32_e32 v58, v33
	v_mul_f32_e64 v33, |v79|, s26
	v_exp_f32_e32 v33, v33
	v_lshlrev_b32_e32 v78, 16, v42
	v_cmp_le_f32_e64 s[38:39], 0, v79
	v_and_b32_e32 v79, 0xffff0000, v42
	v_mul_f32_e32 v42, 0xbfb8aa3b, v78
	v_add_f32_e32 v59, 1.0, v33
	v_exp_f32_e32 v42, v42
	v_rcp_f32_e32 v59, v59
	v_cvt_pk_bf16_f32 v49, v50, v51
	v_add_f32_e32 v42, 1.0, v42
	v_pk_mul_f32 v[32:33], v[32:33], v[58:59]
	v_rcp_f32_e32 v116, v42
	v_mul_f32_e32 v42, 0xbfb8aa3b, v79
	v_cndmask_b32_e64 v33, v59, v33, s[38:39]
; __device__ __forceinline__ void ld8bf(const bf16_t* p, float (&o)[8]) { unpack8(*(const u32x4*)p, o); }
; __device__ __forceinline__ float sigmoidf_(float x) { return __builtin_amdgcn_rcpf(1.0f + __expf(-x)); }
; __device__ __forceinline__ bf16x8 pack_frag(const float (&v)[8]) { return __builtin_bit_cast(bf16x8, pack8(v)); }
; __device__ __forceinline__ void hg_lf_key(float fp, float lb, float& lf, float& key) {
;     const float e = __expf(-fabsf(fp));
;     const float rc = __builtin_amdgcn_rcpf(1.0f + e);
;     const float sp = fp >= 0.f ? rc : e * rc;
;     const float sn = fp >= 0.f ? e * rc : rc;
;     const float lsig = (fp >= 0.f ? 0.f : fp) + __logf(rc);
;     lf = (lb == 0.f) ? lsig : __logf(lb + (1.0f - lb) * sp); key = (1.0f - lb) * sn;
; __device__ __forceinline__ void w_hg_m3(const Args& a, int l, unsigned char* ws, const bf16_t* proj, bf16_t* y, LAS unsigned char* wl, int b, int ck_, int h, int lane) {
;     ...
;         for (int tb = 0; tb < 4; ++tb) { float fp[8], qv[8], a1[8], a2[8];
;             ld8bf(fsrc + (size_t)(16 * tb + lo) * NIN, fp); ld8bf(proj + (size_t)(row0 + 16 * tb + lo) * NIN + C_HQ + 64 * h + 32 * kk + 8 * fq, qv);
; #pragma unroll
;             for (int j = 0; j < 8; ++j) { float lf, key; hg_lf_key(fp[j], lbv[j], lf, key);
;                 const float q = qv[j] * sigmoidf_(qv[j]); a1[j] = q * __expf(bb[tb][j] - r31[j]); a2[j] = key * __expf(r31[j] - bb[tb][j]); }
;             Qf[tb][kk] = pack_frag(a1); Kf[tb][kk] = pack_frag(a2); }
	v_cndmask_b32_e32 v32, v58, v32, vcc
	v_exp_f32_e32 v42, v42
	v_pk_mul_f32 v[32:33], v[72:73], v[32:33]
	v_add_f32_e32 v42, 1.0, v42
	v_pk_mul_f32 v[40:41], v[40:41], v[32:33]
	v_sub_f32_e32 v33, v91, v113
	v_mul_f32_e32 v33, 0x3fb8aa3b, v33
	v_sub_f32_e32 v32, v113, v91
	v_exp_f32_e32 v58, v33
	v_sub_f32_e32 v33, v112, v92
	v_mul_f32_e32 v32, 0x3fb8aa3b, v32
	v_mul_f32_e32 v33, 0x3fb8aa3b, v33
	v_rcp_f32_e32 v117, v42
	v_exp_f32_e32 v32, v32
	v_exp_f32_e32 v33, v33
	v_sub_f32_e32 v42, v92, v112
	v_mul_f32_e32 v42, 0x3fb8aa3b, v42
	v_pk_mul_f32 v[78:79], v[116:117], v[78:79]
	v_exp_f32_e32 v59, v42
	v_lshlrev_b32_e32 v42, 16, v34
	v_pk_mul_f32 v[32:33], v[32:33], v[78:79]
	v_mul_f32_e64 v78, |v42|, s26
	v_exp_f32_e32 v78, v78
	v_and_b32_e32 v34, 0xffff0000, v34
	v_cmp_le_f32_e32 vcc, 0, v42
	v_cmp_le_f32_e64 s[38:39], 0, v34
	v_add_f32_e32 v79, 1.0, v78
	v_rcp_f32_e32 v112, v79
	v_mul_f32_e64 v79, |v34|, s26
	v_exp_f32_e32 v79, v79
	v_sub_f32_e32 v34, v111, v93
	v_mul_f32_e32 v34, 0x3fb8aa3b, v34
	v_cvt_pk_bf16_f32 v50, v32, v33
	v_add_f32_e32 v113, 1.0, v79
	v_rcp_f32_e32 v113, v113
	v_cvt_pk_bf16_f32 v33, v40, v41
	v_cvt_pk_bf16_f32 v32, v56, v57
	v_sub_f32_e32 v57, v2, v109
	v_pk_mul_f32 v[78:79], v[78:79], v[112:113]
	v_mul_f32_e32 v57, 0x3fb8aa3b, v57
	v_cndmask_b32_e64 v79, v113, v79, s[38:39]
	v_cndmask_b32_e32 v78, v112, v78, vcc
	v_pk_mul_f32 v[78:79], v[74:75], v[78:79]
	v_lshlrev_b32_e32 v112, 16, v43
	v_pk_mul_f32 v[58:59], v[58:59], v[78:79]
	v_exp_f32_e32 v78, v34
	v_sub_f32_e32 v34, v93, v111
	v_mul_f32_e32 v34, 0x3fb8aa3b, v34
	v_exp_f32_e32 v42, v34
	v_sub_f32_e32 v34, v110, v94
	v_mul_f32_e32 v34, 0x3fb8aa3b, v34
	v_exp_f32_e32 v79, v34
	v_mul_f32_e32 v34, 0xbfb8aa3b, v112
	v_exp_f32_e32 v34, v34
	v_and_b32_e32 v113, 0xffff0000, v43
	v_sub_f32_e32 v56, v109, v2
	v_mul_f32_e32 v56, 0x3fb8aa3b, v56
	v_add_f32_e32 v34, 1.0, v34
	v_rcp_f32_e32 v116, v34
	v_mul_f32_e32 v34, 0xbfb8aa3b, v113
	v_exp_f32_e32 v34, v34
	v_exp_f32_e32 v56, v56
	v_add_f32_e32 v34, 1.0, v34
	v_rcp_f32_e32 v117, v34
	v_sub_f32_e32 v34, v94, v110
	v_mul_f32_e32 v34, 0x3fb8aa3b, v34
	v_exp_f32_e32 v43, v34
	v_pk_mul_f32 v[112:113], v[116:117], v[112:113]
	s_nop 0
	v_pk_mul_f32 v[78:79], v[78:79], v[112:113]
	v_lshlrev_b32_e32 v112, 16, v35
	v_mul_f32_e64 v34, |v112|, s26
	v_exp_f32_e32 v34, v34
	v_and_b32_e32 v113, 0xffff0000, v35
	v_cmp_le_f32_e32 vcc, 0, v112
	v_cmp_le_f32_e64 s[38:39], 0, v113
	v_add_f32_e32 v35, 1.0, v34
	v_rcp_f32_e32 v110, v35
	v_mul_f32_e64 v35, |v113|, s26
	v_exp_f32_e32 v35, v35
	v_cvt_pk_bf16_f32 v51, v78, v79
	v_add_f32_e32 v111, 1.0, v35
	v_rcp_f32_e32 v111, v111
	s_nop 0
	v_pk_mul_f32 v[34:35], v[34:35], v[110:111]
	s_nop 0
	v_cndmask_b32_e64 v35, v111, v35, s[38:39]
	v_cndmask_b32_e32 v34, v110, v34, vcc
	v_pk_mul_f32 v[34:35], v[68:69], v[34:35]
	s_nop 0
	v_pk_mul_f32 v[42:43], v[42:43], v[34:35]
	v_cvt_pk_bf16_f32 v34, v58, v59
	v_cvt_pk_bf16_f32 v35, v42, v43
	v_mov_b64_e32 v[40:41], v[142:143]
	v_mov_b64_e32 v[42:43], v[144:145]
	s_nop 0
	v_mov_b64_e32 v[36:37], v[146:147]
	v_mov_b64_e32 v[38:39], v[148:149]
	v_exp_f32_e32 v58, v57
	v_sub_f32_e32 v57, v107, v88
	v_mul_f32_e32 v57, 0x3fb8aa3b, v57
	v_exp_f32_e32 v57, v57
	s_waitcnt vmcnt(0) lgkmcnt(0)
	v_and_b32_e32 v109, 0xffff0000, v41
	v_lshlrev_b32_e32 v78, 16, v36
	v_and_b32_e32 v79, 0xffff0000, v36
	v_mul_f32_e32 v36, 0xbfb8aa3b, v78
	v_exp_f32_e32 v36, v36
	s_nop 0
	v_add_f32_e32 v36, 1.0, v36
	v_rcp_f32_e32 v110, v36
	v_mul_f32_e32 v36, 0xbfb8aa3b, v79
	v_exp_f32_e32 v36, v36
	s_nop 0
	v_add_f32_e32 v36, 1.0, v36
	v_rcp_f32_e32 v111, v36
	v_sub_f32_e32 v36, v88, v107
	v_mul_f32_e32 v36, 0x3fb8aa3b, v36
	v_exp_f32_e32 v59, v36
	v_pk_mul_f32 v[78:79], v[110:111], v[78:79]
	v_lshlrev_b32_e32 v36, 16, v40
	v_pk_mul_f32 v[56:57], v[56:57], v[78:79]
	v_mul_f32_e64 v78, |v36|, s26
	v_exp_f32_e32 v78, v78
	v_and_b32_e32 v40, 0xffff0000, v40
	v_cmp_le_f32_e32 vcc, 0, v36
	v_cmp_le_f32_e64 s[38:39], 0, v40
	v_add_f32_e32 v79, 1.0, v78
	v_rcp_f32_e32 v110, v79
	v_mul_f32_e64 v79, |v40|, s26
	v_exp_f32_e32 v79, v79
	v_sub_f32_e32 v36, v106, v89
	v_mul_f32_e32 v36, 0x3fb8aa3b, v36
	v_sub_f32_e32 v40, v105, v90
	v_add_f32_e32 v107, 1.0, v79
	v_rcp_f32_e32 v111, v107
	v_and_b32_e32 v107, 0xffff0000, v37
	v_mul_f32_e32 v40, 0x3fb8aa3b, v40
	v_pk_mul_f32 v[78:79], v[78:79], v[110:111]
	s_nop 0
	v_cndmask_b32_e64 v79, v111, v79, s[38:39]
	v_cndmask_b32_e32 v78, v110, v78, vcc
	v_pk_mul_f32 v[78:79], v[70:71], v[78:79]
	v_cmp_le_f32_e64 s[38:39], 0, v109
	v_pk_mul_f32 v[58:59], v[58:59], v[78:79]
	v_exp_f32_e32 v78, v36
	v_sub_f32_e32 v36, v89, v106
	v_lshlrev_b32_e32 v106, 16, v37
	v_mul_f32_e32 v37, 0xbfb8aa3b, v106
	v_exp_f32_e32 v37, v37
	v_exp_f32_e32 v79, v40
	v_mul_f32_e32 v36, 0x3fb8aa3b, v36
	v_exp_f32_e32 v36, v36
	v_add_f32_e32 v37, 1.0, v37
	v_rcp_f32_e32 v110, v37
	v_mul_f32_e32 v37, 0xbfb8aa3b, v107
	v_exp_f32_e32 v37, v37
	s_nop 0
	v_add_f32_e32 v37, 1.0, v37
	v_rcp_f32_e32 v111, v37
	v_sub_f32_e32 v37, v90, v105
	v_lshlrev_b32_e32 v105, 16, v41
	v_mul_f32_e64 v40, |v105|, s26
	v_exp_f32_e32 v40, v40
	v_pk_mul_f32 v[106:107], v[110:111], v[106:107]
	v_mul_f32_e32 v37, 0x3fb8aa3b, v37
	v_pk_mul_f32 v[78:79], v[78:79], v[106:107]
	v_add_f32_e32 v41, 1.0, v40
	v_rcp_f32_e32 v106, v41
	v_mul_f32_e64 v41, |v109|, s26
	v_exp_f32_e32 v41, v41
	v_exp_f32_e32 v37, v37
	v_cmp_le_f32_e32 vcc, 0, v105
	v_and_b32_e32 v105, 0xffff0000, v38
	v_add_f32_e32 v107, 1.0, v41
	v_rcp_f32_e32 v107, v107
	s_nop 0
	v_pk_mul_f32 v[40:41], v[40:41], v[106:107]
	s_nop 0
	v_cndmask_b32_e64 v41, v107, v41, s[38:39]
	v_cndmask_b32_e32 v40, v106, v40, vcc
	v_pk_mul_f32 v[40:41], v[72:73], v[40:41]
; __device__ __forceinline__ void ld8bf(const bf16_t* p, float (&o)[8]) { unpack8(*(const u32x4*)p, o); }
; __device__ __forceinline__ float sigmoidf_(float x) { return __builtin_amdgcn_rcpf(1.0f + __expf(-x)); }
; __device__ __forceinline__ bf16x8 pack_frag(const float (&v)[8]) { return __builtin_bit_cast(bf16x8, pack8(v)); }
; __device__ __forceinline__ void hg_lf_key(float fp, float lb, float& lf, float& key) {
;     const float e = __expf(-fabsf(fp));
;     const float rc = __builtin_amdgcn_rcpf(1.0f + e);
;     const float sp = fp >= 0.f ? rc : e * rc;
;     const float sn = fp >= 0.f ? e * rc : rc;
;     const float lsig = (fp >= 0.f ? 0.f : fp) + __logf(rc);
;     lf = (lb == 0.f) ? lsig : __logf(lb + (1.0f - lb) * sp); key = (1.0f - lb) * sn;
; __device__ __forceinline__ void w_hg_m3(const Args& a, int l, unsigned char* ws, const bf16_t* proj, bf16_t* y, LAS unsigned char* wl, int b, int ck_, int h, int lane) {
;     ...
;         for (int tb = 0; tb < 4; ++tb) { float fp[8], qv[8], a1[8], a2[8];
;             ld8bf(fsrc + (size_t)(16 * tb + lo) * NIN, fp); ld8bf(proj + (size_t)(row0 + 16 * tb + lo) * NIN + C_HQ + 64 * h + 32 * kk + 8 * fq, qv);
; #pragma unroll
;             for (int j = 0; j < 8; ++j) { float lf, key; hg_lf_key(fp[j], lbv[j], lf, key);
;                 const float q = qv[j] * sigmoidf_(qv[j]); a1[j] = q * __expf(bb[tb][j] - r31[j]); a2[j] = key * __expf(r31[j] - bb[tb][j]); }
;             Qf[tb][kk] = pack_frag(a1); Kf[tb][kk] = pack_frag(a2); }
	s_nop 0
	v_pk_mul_f32 v[106:107], v[36:37], v[40:41]
	v_sub_f32_e32 v36, v104, v91
	v_sub_f32_e32 v37, v91, v104
	v_lshlrev_b32_e32 v104, 16, v38
	v_mul_f32_e32 v38, 0xbfb8aa3b, v104
	v_exp_f32_e32 v38, v38
	v_mul_f32_e32 v37, 0x3fb8aa3b, v37
	v_exp_f32_e32 v40, v37
	v_sub_f32_e32 v37, v103, v92
	v_add_f32_e32 v38, 1.0, v38
	v_rcp_f32_e32 v110, v38
	v_mul_f32_e32 v38, 0xbfb8aa3b, v105
	v_exp_f32_e32 v38, v38
	v_mul_f32_e32 v36, 0x3fb8aa3b, v36
	v_mul_f32_e32 v37, 0x3fb8aa3b, v37
	v_exp_f32_e32 v36, v36
	v_add_f32_e32 v38, 1.0, v38
	v_rcp_f32_e32 v111, v38
	v_exp_f32_e32 v37, v37
	v_sub_f32_e32 v38, v92, v103
	v_mul_f32_e32 v38, 0x3fb8aa3b, v38
	v_exp_f32_e32 v41, v38
	v_lshlrev_b32_e32 v38, 16, v42
	v_pk_mul_f32 v[104:105], v[110:111], v[104:105]
	v_mul_f32_e64 v103, |v38|, s26
	v_pk_mul_f32 v[36:37], v[36:37], v[104:105]
	v_exp_f32_e32 v104, v103
	v_and_b32_e32 v42, 0xffff0000, v42
	v_cmp_le_f32_e32 vcc, 0, v38
	v_cmp_le_f32_e64 s[38:39], 0, v42
	v_add_f32_e32 v103, 1.0, v104
	v_rcp_f32_e32 v110, v103
	v_mul_f32_e64 v103, |v42|, s26
	v_exp_f32_e32 v105, v103
	v_sub_f32_e32 v38, v67, v93
	v_mul_f32_e32 v38, 0x3fb8aa3b, v38
	v_add_f32_e32 v103, 1.0, v105
	v_rcp_f32_e32 v111, v103
	s_nop 0
	v_pk_mul_f32 v[104:105], v[104:105], v[110:111]
	s_nop 0
	v_cndmask_b32_e32 v104, v110, v104, vcc
	v_lshlrev_b32_e32 v110, 16, v39
	v_cndmask_b32_e64 v105, v111, v105, s[38:39]
	v_and_b32_e32 v111, 0xffff0000, v39
	v_mul_f32_e32 v39, 0xbfb8aa3b, v110
	v_exp_f32_e32 v39, v39
	v_pk_mul_f32 v[104:105], v[74:75], v[104:105]
	v_add_f32_e32 v39, 1.0, v39
	v_rcp_f32_e32 v112, v39
	v_mul_f32_e32 v39, 0xbfb8aa3b, v111
	v_exp_f32_e32 v39, v39
	v_pk_mul_f32 v[104:105], v[40:41], v[104:105]
	v_sub_f32_e32 v41, v66, v94
	v_mul_f32_e32 v41, 0x3fb8aa3b, v41
	v_add_f32_e32 v39, 1.0, v39
	v_rcp_f32_e32 v113, v39
	v_exp_f32_e32 v40, v38
	v_exp_f32_e32 v41, v41
	v_sub_f32_e32 v39, v94, v66
	v_pk_mul_f32 v[110:111], v[112:113], v[110:111]
	v_lshlrev_b32_e32 v66, 16, v43
	v_pk_mul_f32 v[110:111], v[40:41], v[110:111]
	v_mul_f32_e64 v40, |v66|, s26
	v_exp_f32_e32 v40, v40
	v_sub_f32_e32 v38, v93, v67
	v_and_b32_e32 v67, 0xffff0000, v43
	v_mul_f32_e32 v38, 0x3fb8aa3b, v38
	v_add_f32_e32 v41, 1.0, v40
	v_rcp_f32_e32 v42, v41
	v_mul_f32_e64 v41, |v67|, s26
	v_exp_f32_e32 v41, v41
	v_mul_f32_e32 v39, 0x3fb8aa3b, v39
	v_exp_f32_e32 v38, v38
	v_exp_f32_e32 v39, v39
	v_add_f32_e32 v43, 1.0, v41
	v_rcp_f32_e32 v43, v43
	v_cmp_le_f32_e32 vcc, 0, v66
	v_cmp_le_f32_e64 s[38:39], 0, v67
	v_pk_mul_f32 v[40:41], v[40:41], v[42:43]
	s_nop 0
	v_cndmask_b32_e64 v41, v43, v41, s[38:39]
	v_cndmask_b32_e32 v40, v42, v40, vcc
	v_pk_mul_f32 v[40:41], v[68:69], v[40:41]
	v_cvt_pk_bf16_f32 v42, v36, v37
	v_pk_mul_f32 v[66:67], v[38:39], v[40:41]
	v_cvt_pk_bf16_f32 v40, v56, v57
	v_cvt_pk_bf16_f32 v36, v58, v59
	v_cvt_pk_bf16_f32 v39, v66, v67
	v_mov_b64_e32 v[56:57], v[150:151]
	v_mov_b64_e32 v[58:59], v[152:153]
	s_nop 0
	v_mov_b64_e32 v[64:65], v[122:123]
	v_mov_b64_e32 v[66:67], v[124:125]
	v_sub_f32_e32 v76, v102, v2
	v_sub_f32_e32 v77, v2, v102
	v_cvt_pk_bf16_f32 v38, v104, v105
	v_mul_f32_e32 v77, 0x3fb8aa3b, v77
	v_cvt_pk_bf16_f32 v41, v78, v79
	v_exp_f32_e32 v78, v77
	v_sub_f32_e32 v77, v101, v88
	v_mul_f32_e32 v76, 0x3fb8aa3b, v76
	v_mul_f32_e32 v77, 0x3fb8aa3b, v77
	v_exp_f32_e32 v76, v76
	v_exp_f32_e32 v77, v77
	v_mul_f32_e32 v2, 0x3fb8aa3b, v2
	v_cvt_pk_bf16_f32 v37, v106, v107
	v_cvt_pk_bf16_f32 v43, v110, v111
	s_waitcnt vmcnt(0) lgkmcnt(0)
	v_lshlrev_b32_e32 v102, 16, v64
	v_and_b32_e32 v103, 0xffff0000, v64
	v_mul_f32_e32 v64, 0xbfb8aa3b, v102
	v_exp_f32_e32 v64, v64
	s_nop 0
	v_add_f32_e32 v64, 1.0, v64
	v_rcp_f32_e32 v104, v64
	v_mul_f32_e32 v64, 0xbfb8aa3b, v103
	v_exp_f32_e32 v64, v64
	s_nop 0
	v_add_f32_e32 v64, 1.0, v64
	v_rcp_f32_e32 v105, v64
	v_sub_f32_e32 v64, v88, v101
	v_mul_f32_e32 v64, 0x3fb8aa3b, v64
	v_exp_f32_e32 v79, v64
	v_lshlrev_b32_e32 v64, 16, v56
	v_pk_mul_f32 v[102:103], v[104:105], v[102:103]
	v_mul_f32_e64 v101, |v64|, s26
	v_pk_mul_f32 v[76:77], v[76:77], v[102:103]
	v_exp_f32_e32 v102, v101
	v_and_b32_e32 v56, 0xffff0000, v56
	v_cmp_le_f32_e32 vcc, 0, v64
	v_cmp_le_f32_e64 s[38:39], 0, v56
	v_add_f32_e32 v101, 1.0, v102
	v_rcp_f32_e32 v104, v101
	v_mul_f32_e64 v101, |v56|, s26
	v_exp_f32_e32 v103, v101
	v_sub_f32_e32 v56, v100, v89
	v_mul_f32_e32 v56, 0x3fb8aa3b, v56
	v_lshlrev_b32_e32 v64, 16, v65
	v_add_f32_e32 v101, 1.0, v103
	v_rcp_f32_e32 v105, v101
	v_and_b32_e32 v65, 0xffff0000, v65
	v_pk_mul_f32 v[102:103], v[102:103], v[104:105]
	s_nop 0
	v_cndmask_b32_e64 v103, v105, v103, s[38:39]
	v_cndmask_b32_e32 v102, v104, v102, vcc
	v_pk_mul_f32 v[70:71], v[70:71], v[102:103]
	s_nop 0
	v_pk_mul_f32 v[70:71], v[78:79], v[70:71]
	v_exp_f32_e32 v78, v56
	v_sub_f32_e32 v56, v89, v100
	v_mul_f32_e32 v56, 0x3fb8aa3b, v56
	v_exp_f32_e32 v100, v56
	v_sub_f32_e32 v56, v99, v90
	v_mul_f32_e32 v56, 0x3fb8aa3b, v56
	v_exp_f32_e32 v79, v56
	v_mul_f32_e32 v56, 0xbfb8aa3b, v64
	v_exp_f32_e32 v56, v56
	s_nop 0
	v_add_f32_e32 v56, 1.0, v56
	v_rcp_f32_e32 v102, v56
	v_mul_f32_e32 v56, 0xbfb8aa3b, v65
	v_exp_f32_e32 v56, v56
	s_nop 0
	v_add_f32_e32 v56, 1.0, v56
	v_rcp_f32_e32 v103, v56
	v_sub_f32_e32 v56, v90, v99
	v_mul_f32_e32 v56, 0x3fb8aa3b, v56
	v_lshlrev_b32_e32 v99, 16, v57
	v_exp_f32_e32 v101, v56
	v_mul_f32_e64 v56, |v99|, s26
	v_exp_f32_e32 v56, v56
	v_pk_mul_f32 v[64:65], v[102:103], v[64:65]
	v_and_b32_e32 v102, 0xffff0000, v57
	v_pk_mul_f32 v[64:65], v[78:79], v[64:65]
	v_add_f32_e32 v57, 1.0, v56
	v_rcp_f32_e32 v78, v57
	v_mul_f32_e64 v57, |v102|, s26
	v_exp_f32_e32 v57, v57
	v_cmp_le_f32_e32 vcc, 0, v99
	v_cmp_le_f32_e64 s[38:39], 0, v102
; __device__ __forceinline__ void ld8bf(const bf16_t* p, float (&o)[8]) { unpack8(*(const u32x4*)p, o); }
; __device__ __forceinline__ float sigmoidf_(float x) { return __builtin_amdgcn_rcpf(1.0f + __expf(-x)); }
; __device__ __forceinline__ bf16x8 pack_frag(const float (&v)[8]) { return __builtin_bit_cast(bf16x8, pack8(v)); }
; __device__ __forceinline__ void w_hg_m3(const Args& a, int l, unsigned char* ws, const bf16_t* proj, bf16_t* y, LAS unsigned char* wl, int b, int ck_, int h, int lane) {
;     ...
;                 const float q = qv[j] * sigmoidf_(qv[j]); a1[j] = q * __expf(bb[tb][j] - r31[j]); a2[j] = key * __expf(r31[j] - bb[tb][j]); }
;             Qf[tb][kk] = pack_frag(a1); Kf[tb][kk] = pack_frag(a2); }
; #pragma unroll
;         for (int j = 0; j < 8; ++j) er[kk][j] = __expf(r31[j]);
;         __builtin_amdgcn_sched_barrier(0);
;     }
; #pragma unroll
;     for (int kk = 0; kk < 2; ++kk)
; #pragma unroll
;         for (int eb = 0; eb < 4; ++eb) { float sv[8]; ld8bf(Sb + (16 * eb + lo) * 64 + 32 * kk + 8 * fq, sv);
; #pragma unroll
;             for (int j = 0; j < 8; ++j) sv[j] *= er[kk][j];
;             Sf[eb][kk] = pack_frag(sv); }
	v_and_b32_e32 v99, 0xffff0000, v66
	v_add_f32_e32 v79, 1.0, v57
	v_rcp_f32_e32 v79, v79
	s_nop 0
	v_pk_mul_f32 v[56:57], v[56:57], v[78:79]
	s_nop 0
	v_cndmask_b32_e64 v57, v79, v57, s[38:39]
	v_cndmask_b32_e32 v56, v78, v56, vcc
	v_pk_mul_f32 v[56:57], v[72:73], v[56:57]
	s_nop 0
	v_pk_mul_f32 v[72:73], v[100:101], v[56:57]
	v_sub_f32_e32 v56, v98, v91
	v_sub_f32_e32 v57, v91, v98
	v_lshlrev_b32_e32 v98, 16, v66
	v_mul_f32_e32 v66, 0xbfb8aa3b, v98
	v_exp_f32_e32 v66, v66
	v_mul_f32_e32 v57, 0x3fb8aa3b, v57
	v_exp_f32_e32 v78, v57
	v_sub_f32_e32 v57, v97, v92
	v_add_f32_e32 v66, 1.0, v66
	v_rcp_f32_e32 v100, v66
	v_mul_f32_e32 v66, 0xbfb8aa3b, v99
	v_exp_f32_e32 v66, v66
	v_mul_f32_e32 v56, 0x3fb8aa3b, v56
	v_mul_f32_e32 v57, 0x3fb8aa3b, v57
	v_exp_f32_e32 v56, v56
	v_add_f32_e32 v66, 1.0, v66
	v_rcp_f32_e32 v101, v66
	v_exp_f32_e32 v57, v57
	v_lshlrev_b32_e32 v66, 16, v58
	v_and_b32_e32 v58, 0xffff0000, v58
	v_pk_mul_f32 v[98:99], v[100:101], v[98:99]
	v_cmp_le_f32_e32 vcc, 0, v66
	v_pk_mul_f32 v[98:99], v[56:57], v[98:99]
	v_sub_f32_e32 v56, v92, v97
	v_mul_f32_e32 v56, 0x3fb8aa3b, v56
	v_exp_f32_e32 v79, v56
	v_mul_f32_e64 v56, |v66|, s26
	v_exp_f32_e32 v56, v56
	v_cmp_le_f32_e64 s[38:39], 0, v58
	v_add_f32_e32 v57, 1.0, v56
	v_rcp_f32_e32 v100, v57
	v_mul_f32_e64 v57, |v58|, s26
	v_exp_f32_e32 v57, v57
	s_nop 0
	v_add_f32_e32 v97, 1.0, v57
	v_rcp_f32_e32 v101, v97
	s_nop 0
	v_pk_mul_f32 v[56:57], v[56:57], v[100:101]
	s_nop 0
	v_cndmask_b32_e64 v57, v101, v57, s[38:39]
	v_cndmask_b32_e32 v56, v100, v56, vcc
	v_pk_mul_f32 v[56:57], v[74:75], v[56:57]
	v_exp_f32_e32 v100, v2
	v_pk_mul_f32 v[74:75], v[78:79], v[56:57]
	v_lshlrev_b32_e32 v78, 16, v67
	v_mul_f32_e32 v58, 0xbfb8aa3b, v78
	v_exp_f32_e32 v58, v58
	v_and_b32_e32 v79, 0xffff0000, v67
	v_sub_f32_e32 v56, v96, v93
	v_sub_f32_e32 v57, v93, v96
	v_add_f32_e32 v58, 1.0, v58
	v_rcp_f32_e32 v96, v58
	v_mul_f32_e32 v58, 0xbfb8aa3b, v79
	v_exp_f32_e32 v58, v58
	v_mul_f32_e32 v57, 0x3fb8aa3b, v57
	v_exp_f32_e32 v66, v57
	v_sub_f32_e32 v57, v95, v94
	v_add_f32_e32 v58, 1.0, v58
	v_mul_f32_e32 v56, 0x3fb8aa3b, v56
	v_mul_f32_e32 v57, 0x3fb8aa3b, v57
	v_rcp_f32_e32 v97, v58
	v_exp_f32_e32 v56, v56
	v_exp_f32_e32 v57, v57
	v_mul_f32_e32 v2, 0x3fb8aa3b, v88
	v_pk_mul_f32 v[78:79], v[96:97], v[78:79]
	v_and_b32_e32 v96, 0xffff0000, v59
	v_pk_mul_f32 v[78:79], v[56:57], v[78:79]
	v_sub_f32_e32 v56, v94, v95
	v_mul_f32_e32 v56, 0x3fb8aa3b, v56
	v_lshlrev_b32_e32 v95, 16, v59
	v_exp_f32_e32 v67, v56
	v_mul_f32_e64 v56, |v95|, s26
	v_exp_f32_e32 v56, v56
	v_exp_f32_e32 v101, v2
	v_mul_f32_e32 v2, 0x3fb8aa3b, v89
	v_exp_f32_e32 v102, v2
	v_add_f32_e32 v57, 1.0, v56
	v_rcp_f32_e32 v58, v57
	v_mul_f32_e64 v57, |v96|, s26
	v_exp_f32_e32 v57, v57
	v_mul_f32_e32 v2, 0x3fb8aa3b, v90
	v_cmp_le_f32_e32 vcc, 0, v95
	v_cmp_le_f32_e64 s[38:39], 0, v96
	v_add_f32_e32 v59, 1.0, v57
	v_rcp_f32_e32 v59, v59
	v_exp_f32_e32 v103, v2
	v_mul_f32_e32 v2, 0x3fb8aa3b, v91
	v_exp_f32_e32 v104, v2
	v_pk_mul_f32 v[56:57], v[56:57], v[58:59]
	v_mul_f32_e32 v2, 0x3fb8aa3b, v92
	v_cndmask_b32_e64 v57, v59, v57, s[38:39]
	v_cndmask_b32_e32 v56, v58, v56, vcc
	v_pk_mul_f32 v[56:57], v[68:69], v[56:57]
	v_exp_f32_e32 v105, v2
	v_mul_f32_e32 v2, 0x3fb8aa3b, v93
	v_pk_mul_f32 v[66:67], v[66:67], v[56:57]
	v_exp_f32_e32 v106, v2
	v_mul_f32_e32 v2, 0x3fb8aa3b, v94
	v_cvt_pk_bf16_f32 v56, v76, v77
	v_cvt_pk_bf16_f32 v57, v64, v65
	v_cvt_pk_bf16_f32 v58, v98, v99
	v_cvt_pk_bf16_f32 v59, v78, v79
	v_cvt_pk_bf16_f32 v68, v70, v71
	v_cvt_pk_bf16_f32 v69, v72, v73
	v_cvt_pk_bf16_f32 v70, v74, v75
	v_cvt_pk_bf16_f32 v71, v66, v67
	v_exp_f32_e32 v107, v2
	s_add_u32 s20, s80, s40
	s_addc_u32 s21, s81, s41
	v_lshl_add_u64 v[94:95], v[0:1], 1, s[20:21]
	v_lshlrev_b32_e32 v2, 7, v114
	v_lshl_add_u64 v[0:1], v[94:95], 0, v[2:3]
	global_load_dwordx4 v[146:149], v[0:1], off
	global_load_dwordx4 v[150:153], v[0:1], off offset:2048
	global_load_dwordx4 v[122:125], v[0:1], off offset:64
	global_load_dwordx4 v[134:137], v[0:1], off offset:2112
	v_mov_b32_e32 v130, 0x1000
	v_mov_b32_e32 v131, 0
	v_lshl_add_u64 v[186:187], v[0:1], 0, v[130:131]
	global_load_dwordx4 v[188:191], v[186:187], off
	global_load_dwordx4 v[192:195], v[186:187], off offset:2048
	global_load_dwordx4 v[196:199], v[186:187], off offset:64
	v_or_b32_e32 v92, 0x1000, v2
	v_mov_b32_e32 v93, v3
	v_or_b32_e32 v2, 0x1800, v2
	s_add_u32 s20, s67, s88
	v_lshlrev_b32_e32 v120, 2, v108
	s_addc_u32 s21, s68, 0
	v_cmp_gt_i32_e64 s[40:41], v120, v114
	s_add_u32 s48, s20, 0x1600
	s_mov_b32 s20, 12
	s_addc_u32 s49, s21, 0
	v_cmp_lt_i32_e64 s[42:43], v120, v114
	v_ashrrev_i32_e32 v121, 31, v120
	s_waitcnt vmcnt(0)
	v_mov_b64_e32 v[64:65], v[146:147]
	v_mov_b64_e32 v[66:67], v[148:149]
	v_lshlrev_b32_e32 v72, 16, v64
	v_and_b32_e32 v73, 0xffff0000, v64
	v_lshlrev_b32_e32 v64, 16, v65
	v_and_b32_e32 v65, 0xffff0000, v65
	v_pk_mul_f32 v[74:75], v[84:85], v[64:65]
	v_lshlrev_b32_e32 v64, 16, v66
	v_and_b32_e32 v65, 0xffff0000, v66
	v_pk_mul_f32 v[72:73], v[86:87], v[72:73]
	v_pk_mul_f32 v[76:77], v[82:83], v[64:65]
	v_lshlrev_b32_e32 v64, 16, v67
	v_and_b32_e32 v65, 0xffff0000, v67
	v_pk_mul_f32 v[78:79], v[80:81], v[64:65]
	v_cvt_pk_bf16_f32 v64, v72, v73
	v_cvt_pk_bf16_f32 v65, v74, v75
	v_mov_b64_e32 v[72:73], v[150:151]
	v_mov_b64_e32 v[74:75], v[152:153]
	v_cvt_pk_bf16_f32 v66, v76, v77
	v_cvt_pk_bf16_f32 v67, v78, v79
	s_waitcnt vmcnt(0)
; __device__ __forceinline__ void ld8bf(const bf16_t* p, float (&o)[8]) { unpack8(*(const u32x4*)p, o); }
; __device__ __forceinline__ bf16x8 pack_frag(const float (&v)[8]) { return __builtin_bit_cast(bf16x8, pack8(v)); }
; template <int KIND>
; __device__ __forceinline__ void w_m3_core(const bf16x8 (&Qf)[4][2], const bf16x8 (&Kf)[4][2], const bf16x8 (&Sf)[4][2], const LAS bf16_t* vT, float lg,
;                                           const bf16_t* gsrc, const float* nw, bf16_t* ydst, int lo, int fq) {
;     ...
;             float pv[8];
; #pragma unroll
;             for (int hh = 0; hh < 2; ++hh) { const int mb = 2 * kk2 + hh;
;                 if (mb <= nb) { f32x4 s = {0.f, 0.f, 0.f, 0.f};
;                     s = __builtin_amdgcn_mfma_f32_16x16x32_bf16(Kf[mb][0], Qf[nb][0], s, 0, 0, 0); s = __builtin_amdgcn_mfma_f32_16x16x32_bf16(Kf[mb][1], Qf[nb][1], s, 0, 0, 0);
; #pragma unroll
;                     for (int r = 0; r < 4; ++r) { const int m = 16 * mb + 4 * fq + r, n = 16 * nb + lo; float v = s[r];
;                         if (KIND == 0) v *= __expf((float)(n - m) * lg);
;                         if (mb == nb) v = (m <= n) ? v : 0.f;
;                         pv[4 * hh + r] = v; }
;                 } else {
; #pragma unroll
;                     for (int r = 0; r < 4; ++r) pv[4 * hh + r] = 0.f; }
;             }
;             const bf16x8 Pf = pack_frag(pv);
; #pragma unroll
;             for (int eb = 0; eb < 4; ++eb)
;                 O[eb] = __builtin_amdgcn_mfma_f32_16x16x32_bf16(tr_frag(vT, 32 * kk2 + 4 * fq, 32 * kk2 + 16 + 4 * fq, 16 * eb, lo), Pf, O[eb], 0, 0, 0);
; __device__ __forceinline__ void w_hg_m3(const Args& a, int l, unsigned char* ws, const bf16_t* proj, bf16_t* y, LAS unsigned char* wl, int b, int ck_, int h, int lane) {
;     ...
; #pragma unroll
;     for (int kk = 0; kk < 2; ++kk)
; #pragma unroll
;         for (int eb = 0; eb < 4; ++eb) { float sv[8]; ld8bf(Sb + (16 * eb + lo) * 64 + 32 * kk + 8 * fq, sv);
; #pragma unroll
;             for (int j = 0; j < 8; ++j) sv[j] *= er[kk][j];
;             Sf[eb][kk] = pack_frag(sv); }
	v_lshlrev_b32_e32 v76, 16, v72
	v_and_b32_e32 v77, 0xffff0000, v72
	v_lshlrev_b32_e32 v72, 16, v73
	v_and_b32_e32 v73, 0xffff0000, v73
	v_pk_mul_f32 v[78:79], v[84:85], v[72:73]
	v_lshlrev_b32_e32 v72, 16, v74
	v_and_b32_e32 v73, 0xffff0000, v74
	v_pk_mul_f32 v[76:77], v[86:87], v[76:77]
	v_pk_mul_f32 v[88:89], v[82:83], v[72:73]
	v_lshlrev_b32_e32 v72, 16, v75
	v_and_b32_e32 v73, 0xffff0000, v75
	v_pk_mul_f32 v[90:91], v[80:81], v[72:73]
	v_cvt_pk_bf16_f32 v72, v76, v77
	v_lshl_add_u64 v[76:77], v[94:95], 0, v[92:93]
	v_cvt_pk_bf16_f32 v73, v78, v79
	v_mov_b64_e32 v[76:77], v[188:189]
	v_mov_b64_e32 v[78:79], v[190:191]
	v_cvt_pk_bf16_f32 v74, v88, v89
	v_cvt_pk_bf16_f32 v75, v90, v91
	s_waitcnt vmcnt(0)
	v_lshlrev_b32_e32 v88, 16, v76
	v_and_b32_e32 v89, 0xffff0000, v76
	v_lshlrev_b32_e32 v76, 16, v77
	v_and_b32_e32 v77, 0xffff0000, v77
	v_pk_mul_f32 v[90:91], v[84:85], v[76:77]
	v_lshlrev_b32_e32 v76, 16, v78
	v_and_b32_e32 v77, 0xffff0000, v78
	v_pk_mul_f32 v[88:89], v[86:87], v[88:89]
	v_pk_mul_f32 v[96:97], v[82:83], v[76:77]
	v_lshlrev_b32_e32 v76, 16, v79
	v_and_b32_e32 v77, 0xffff0000, v79
	v_pk_mul_f32 v[98:99], v[80:81], v[76:77]
	v_cvt_pk_bf16_f32 v76, v88, v89
	v_lshl_add_u64 v[88:89], v[94:95], 0, v[2:3]
	v_cvt_pk_bf16_f32 v77, v90, v91
	v_mov_b64_e32 v[88:89], v[192:193]
	v_mov_b64_e32 v[90:91], v[194:195]
	v_cvt_pk_bf16_f32 v78, v96, v97
	v_cvt_pk_bf16_f32 v79, v98, v99
	v_mfma_f32_16x16x32_bf16 v[116:119], v[72:75], v[52:55], 0
	s_waitcnt vmcnt(0)
	v_lshlrev_b32_e32 v96, 16, v88
	v_and_b32_e32 v97, 0xffff0000, v88
	v_lshlrev_b32_e32 v88, 16, v89
	v_and_b32_e32 v89, 0xffff0000, v89
	v_pk_mul_f32 v[84:85], v[84:85], v[88:89]
	v_lshlrev_b32_e32 v88, 16, v90
	v_and_b32_e32 v89, 0xffff0000, v90
	v_pk_mul_f32 v[86:87], v[86:87], v[96:97]
	v_pk_mul_f32 v[82:83], v[82:83], v[88:89]
	v_lshlrev_b32_e32 v88, 16, v91
	v_and_b32_e32 v89, 0xffff0000, v91
	v_pk_mul_f32 v[88:89], v[80:81], v[88:89]
	v_cvt_pk_bf16_f32 v80, v86, v87
	v_cvt_pk_bf16_f32 v81, v84, v85
	v_mov_b64_e32 v[84:85], v[122:123]
	v_mov_b64_e32 v[86:87], v[124:125]
	v_cvt_pk_bf16_f32 v82, v82, v83
	v_cvt_pk_bf16_f32 v83, v88, v89
	v_lshl_add_u64 v[96:97], v[94:95], 0, 64
	v_mfma_f32_16x16x32_bf16 v[138:141], v[76:79], v[52:55], 0
	s_waitcnt vmcnt(0)
	v_lshlrev_b32_e32 v88, 16, v84
	v_and_b32_e32 v89, 0xffff0000, v84
	v_lshlrev_b32_e32 v84, 16, v85
	v_and_b32_e32 v85, 0xffff0000, v85
	v_pk_mul_f32 v[90:91], v[102:103], v[84:85]
	v_lshlrev_b32_e32 v84, 16, v86
	v_and_b32_e32 v85, 0xffff0000, v86
	v_pk_mul_f32 v[88:89], v[100:101], v[88:89]
	v_pk_mul_f32 v[94:95], v[104:105], v[84:85]
	v_lshlrev_b32_e32 v84, 16, v87
	v_and_b32_e32 v85, 0xffff0000, v87
	v_pk_mul_f32 v[98:99], v[106:107], v[84:85]
	v_cvt_pk_bf16_f32 v84, v88, v89
	v_cvt_pk_bf16_f32 v85, v90, v91
	v_mov_b64_e32 v[88:89], v[134:135]
	v_mov_b64_e32 v[90:91], v[136:137]
	v_cvt_pk_bf16_f32 v86, v94, v95
	v_cvt_pk_bf16_f32 v87, v98, v99
	s_waitcnt vmcnt(0)
	v_lshlrev_b32_e32 v0, 16, v88
	v_and_b32_e32 v1, 0xffff0000, v88
	v_lshlrev_b32_e32 v88, 16, v89
	v_and_b32_e32 v89, 0xffff0000, v89
	v_pk_mul_f32 v[94:95], v[102:103], v[88:89]
	v_lshlrev_b32_e32 v88, 16, v90
	v_and_b32_e32 v89, 0xffff0000, v90
	v_pk_mul_f32 v[0:1], v[100:101], v[0:1]
	v_pk_mul_f32 v[98:99], v[104:105], v[88:89]
	v_lshlrev_b32_e32 v88, 16, v91
	v_and_b32_e32 v89, 0xffff0000, v91
	v_pk_mul_f32 v[110:111], v[106:107], v[88:89]
	v_cvt_pk_bf16_f32 v88, v0, v1
	v_lshl_add_u64 v[0:1], v[96:97], 0, v[92:93]
	v_cvt_pk_bf16_f32 v89, v94, v95
	v_mov_b64_e32 v[92:93], v[196:197]
	v_mov_b64_e32 v[94:95], v[198:199]
	v_cvt_pk_bf16_f32 v90, v98, v99
	v_cvt_pk_bf16_f32 v91, v110, v111
	s_waitcnt vmcnt(0)
	v_lshlrev_b32_e32 v0, 16, v92
	v_and_b32_e32 v1, 0xffff0000, v92
	v_lshlrev_b32_e32 v92, 16, v93
	v_and_b32_e32 v93, 0xffff0000, v93
	v_pk_mul_f32 v[98:99], v[102:103], v[92:93]
	v_lshlrev_b32_e32 v92, 16, v94
	v_and_b32_e32 v93, 0xffff0000, v94
	v_pk_mul_f32 v[0:1], v[100:101], v[0:1]
	v_pk_mul_f32 v[110:111], v[104:105], v[92:93]
	v_lshlrev_b32_e32 v92, 16, v95
	v_and_b32_e32 v93, 0xffff0000, v95
	v_pk_mul_f32 v[112:113], v[106:107], v[92:93]
	v_cvt_pk_bf16_f32 v92, v0, v1
	v_lshl_add_u64 v[0:1], v[96:97], 0, v[2:3]
	v_cvt_pk_bf16_f32 v93, v98, v99
	global_load_dwordx4 v[96:99], v[0:1], off
	v_or_b32_e32 v2, 2, v120
	s_waitcnt lgkmcnt(0)
	s_ashr_i32 s21, s20, 31
	v_cmp_gt_i32_e64 s[38:39], v2, v114
	s_lshl_b64 s[20:21], s[20:21], 3
	s_add_u32 s20, s0, s20
	s_addc_u32 s21, s1, s21
	v_cvt_pk_bf16_f32 v94, v110, v111
	s_load_dwordx2 s[20:21], s[20:21], 0x0
	v_cvt_pk_bf16_f32 v95, v112, v113
	v_mfma_f32_16x16x32_bf16 v[142:145], v[88:91], v[60:63], v[116:119]
	s_lshl_b64 s[34:35], s[36:37], 2
	s_waitcnt lgkmcnt(0)
	s_add_u32 s27, s20, s34
	v_mfma_f32_16x16x32_bf16 v[138:141], v[92:95], v[60:63], v[138:141]
	s_addc_u32 s35, s21, s35
	s_lshl_b64 s[20:21], s[24:25], 2
	s_add_u32 s34, s27, s20
	s_addc_u32 s35, s35, s21
	v_lshl_add_u64 v[186:187], v[120:121], 2, s[34:35]
	global_load_dwordx4 v[146:149], v[186:187], off
	global_load_dwordx4 v[150:153], v[186:187], off offset:64
	global_load_dwordx4 v[188:191], v[186:187], off offset:128
	global_load_dwordx4 v[192:195], v[186:187], off offset:192
	s_lshl_b64 s[20:21], s[86:87], 11
	s_add_u32 s20, s10, s20
	s_addc_u32 s21, s11, s21
	s_add_u32 s46, s20, s88
	s_addc_u32 s47, s21, 0
	s_waitcnt vmcnt(0)
; template <int KIND>
; __device__ __forceinline__ void w_m3_core(const bf16x8 (&Qf)[4][2], const bf16x8 (&Kf)[4][2], const bf16x8 (&Sf)[4][2], const LAS bf16_t* vT, float lg,
;                                           const bf16_t* gsrc, const float* nw, bf16_t* ydst, int lo, int fq) {
;     ...
;             float pv[8];
; #pragma unroll
;             for (int hh = 0; hh < 2; ++hh) { const int mb = 2 * kk2 + hh;
;                 if (mb <= nb) { f32x4 s = {0.f, 0.f, 0.f, 0.f};
;                     s = __builtin_amdgcn_mfma_f32_16x16x32_bf16(Kf[mb][0], Qf[nb][0], s, 0, 0, 0); s = __builtin_amdgcn_mfma_f32_16x16x32_bf16(Kf[mb][1], Qf[nb][1], s, 0, 0, 0);
; #pragma unroll
;                     for (int r = 0; r < 4; ++r) { const int m = 16 * mb + 4 * fq + r, n = 16 * nb + lo; float v = s[r];
;                         if (KIND == 0) v *= __expf((float)(n - m) * lg);
;                         if (mb == nb) v = (m <= n) ? v : 0.f;
;                         pv[4 * hh + r] = v; }
;                 } else {
; #pragma unroll
;                     for (int r = 0; r < 4; ++r) pv[4 * hh + r] = 0.f; }
;             }
;             const bf16x8 Pf = pack_frag(pv);
; #pragma unroll
;             for (int eb = 0; eb < 4; ++eb)
;                 O[eb] = __builtin_amdgcn_mfma_f32_16x16x32_bf16(tr_frag(vT, 32 * kk2 + 4 * fq, 32 * kk2 + 16 + 4 * fq, 16 * eb, lo), Pf, O[eb], 0, 0, 0);
;         }
; #pragma unroll
;         for (int kk = 0; kk < 2; ++kk)
; #pragma unroll
;             for (int eb = 0; eb < 4; ++eb) O2[eb] = __builtin_amdgcn_mfma_f32_16x16x32_bf16(Sf[eb][kk], Qf[nb][kk], O2[eb], 0, 0, 0);
;         const float osc = KIND == 0 ? __expf((float)(16 * nb + lo + 1) * lg) : 1.0f;
; #pragma unroll
;         for (int eb = 0; eb < 4; ++eb) O[eb] = O[eb] + O2[eb] * osc;
;         float ss = 0.f;
; #pragma unroll
;         for (int eb = 0; eb < 4; ++eb) ss += (O[eb][0] * O[eb][0] + O[eb][1] * O[eb][1]) + (O[eb][2] * O[eb][2] + O[eb][3] * O[eb][3]);
;         { const int ln = (fq << 4) | lo; ss += bperm_f(ln ^ 16, ss); ss += bperm_f(ln ^ 32, ss); }
;         const float rs = rsqrtf(ss * (1.0f / 64.0f) + EPS);
;         const size_t n = 16 * nb + lo;
; #pragma unroll
;         for (int eb = 0; eb < 4; ++eb) { const int e0 = 16 * eb + 4 * fq;
;             const unsigned long long gw_ = *(const unsigned long long*)(gsrc + n * NIN + e0); const f32x4 w4 = *(const f32x4*)(nw + e0);
	v_permlane16_swap_b32_e32 v222, v224
	v_permlane16_swap_b32_e32 v223, v225
	v_permlane16_swap_b32_e32 v226, v228
	v_permlane16_swap_b32_e32 v227, v229
	v_permlane16_swap_b32_e32 v230, v232
	v_permlane16_swap_b32_e32 v231, v233
	v_permlane16_swap_b32_e32 v234, v236
	v_permlane16_swap_b32_e32 v235, v237
	v_permlane16_swap_b32_e32 v238, v240
	v_permlane16_swap_b32_e32 v239, v241
	v_permlane16_swap_b32_e32 v242, v244
	v_permlane16_swap_b32_e32 v243, v245
	v_permlane16_swap_b32_e32 v246, v248
	v_permlane16_swap_b32_e32 v247, v249
	v_permlane16_swap_b32_e32 v250, v252
	v_permlane16_swap_b32_e32 v251, v253
	v_lshlrev_b32_e32 v0, 16, v96
	v_and_b32_e32 v1, 0xffff0000, v96
	v_lshlrev_b32_e32 v96, 16, v97
	v_and_b32_e32 v97, 0xffff0000, v97
	v_pk_mul_f32 v[0:1], v[100:101], v[0:1]
	v_pk_mul_f32 v[100:101], v[102:103], v[96:97]
	v_lshlrev_b32_e32 v96, 16, v98
	v_and_b32_e32 v97, 0xffff0000, v98
	v_pk_mul_f32 v[102:103], v[104:105], v[96:97]
	v_lshlrev_b32_e32 v96, 16, v99
	v_and_b32_e32 v97, 0xffff0000, v99
	v_pk_mul_f32 v[104:105], v[106:107], v[96:97]
	v_cvt_pk_bf16_f32 v97, v100, v101
	v_cvt_pk_bf16_f32 v98, v102, v103
	v_mfma_f32_16x16x32_bf16 v[100:103], v[20:23], v[52:55], 0
	v_cvt_pk_bf16_f32 v96, v0, v1
	v_lshrrev_b32_e32 v0, 2, v114
	v_lshlrev_b32_e32 v1, 3, v114
	v_mfma_f32_16x16x32_bf16 v[100:103], v[24:27], v[60:63], v[100:103]
	v_cvt_pk_bf16_f32 v99, v104, v105
	v_or_b32_e32 v104, v120, v0
	v_lshlrev_b32_e32 v0, 2, v114
	v_and_b32_e32 v105, 24, v1
	v_lshlrev_b32_e32 v1, 6, v108
	v_bitop3_b32 v130, v1, 64, v0 bitop3:0x36
	v_bitop3_b32 v129, v1, s96, v0 bitop3:0x36
	s_nop 0
	v_cndmask_b32_e64 v0, v100, 0, s[40:41]
	v_or_b32_e32 v100, 3, v120
	v_cmp_gt_i32_e32 vcc, v100, v114
	v_cndmask_b32_e64 v1, 0, v101, s[42:43]
	v_cndmask_b32_e64 v2, v102, 0, s[38:39]
	v_cndmask_b32_e64 v100, v103, 0, vcc
	v_cvt_pk_bf16_f32 v0, v0, v1
	v_cvt_pk_bf16_f32 v1, v2, v100
	v_mul_lo_u32 v100, v104, s23
	v_add3_u32 v131, s2, v105, v100
	ds_read_b64_tr_b16 v[102:103], v131 offset:2304
	ds_read_b64_tr_b16 v[100:101], v131
	ds_read_b64_tr_b16 v[104:105], v131 offset:32
	ds_read_b64_tr_b16 v[106:107], v131 offset:2336
	ds_read_b64_tr_b16 v[108:109], v131 offset:64
	ds_read_b64_tr_b16 v[110:111], v131 offset:2368
	v_mov_b32_e32 v2, v3
	s_waitcnt lgkmcnt(0)
	s_nop 0
	v_mfma_f32_16x16x32_bf16 v[122:125], v[108:111], v[0:3], 0
	ds_read_b64_tr_b16 v[108:109], v131 offset:96
	ds_read_b64_tr_b16 v[110:111], v131 offset:2400
	s_waitcnt lgkmcnt(0)
	v_mfma_f32_16x16x32_bf16 v[134:137], v[108:111], v[0:3], 0
	v_mfma_f32_16x16x32_bf16 v[108:111], v[64:67], v[52:55], 0
	v_mfma_f32_16x16x32_bf16 v[52:55], v[80:83], v[52:55], 0
	v_mfma_f32_16x16x32_bf16 v[100:103], v[100:103], v[0:3], 0
	v_mfma_f32_16x16x32_bf16 v[108:111], v[84:87], v[60:63], v[108:111]
	v_mfma_f32_16x16x32_bf16 v[104:107], v[104:107], v[0:3], 0
	v_mfma_f32_16x16x32_bf16 v[52:55], v[96:99], v[60:63], v[52:55]
	s_nop 5
	v_add_f32_e64 v116, v102, v110
	v_add_f32_e64 v117, v103, v111
	v_pk_add_f32 v[118:119], v[100:101], v[108:109]
	v_pk_add_f32 v[112:113], v[104:105], v[142:143]
	v_pk_add_f32 v[110:111], v[106:107], v[144:145]
	v_pk_add_f32 v[108:109], v[122:123], v[138:139]
	v_pk_add_f32 v[0:1], v[136:137], v[54:55]
	v_pk_add_f32 v[104:105], v[134:135], v[52:53]
	v_pk_mul_f32 v[52:53], v[116:117], v[116:117]
	v_pk_mul_f32 v[54:55], v[118:119], v[118:119]
	v_mul_f32_e32 v2, v104, v104
	v_pk_mov_b32 v[60:61], v[54:55], v[52:53] op_sel:[1,0]
	v_mov_b32_e32 v55, v53
	v_pk_add_f32 v[52:53], v[60:61], v[54:55]
	v_pk_mul_f32 v[54:55], v[110:111], v[110:111]
	v_pk_mul_f32 v[60:61], v[112:113], v[112:113]
	v_pk_add_f32 v[52:53], v[52:53], v[52:53] op_sel:[0,1] op_sel_hi:[1,0]
	v_pk_mov_b32 v[62:63], v[60:61], v[54:55] op_sel:[1,0]
	v_mov_b32_e32 v61, v55
	v_pk_add_f32 v[54:55], v[62:63], v[60:61]
	v_mul_f32_e32 v60, v105, v105
	v_pk_add_f32 v[54:55], v[54:55], v[54:55] op_sel:[0,1] op_sel_hi:[1,0]
	v_pk_add_f32 v[106:107], v[124:125], v[140:141]
	v_mov_b32_e32 v53, v2
	v_mov_b32_e32 v55, v60
	v_mul_f32_e32 v2, v109, v109
	v_mul_f32_e32 v61, v0, v0
	v_pk_add_f32 v[52:53], v[52:53], v[54:55]
	v_pk_fma_f32 v[54:55], v[108:109], v[108:109], v[2:3] op_sel_hi:[1,1,0]
	v_mul_f32_e32 v2, v107, v107
	v_mul_f32_e32 v62, v1, v1
	v_mov_b32_e32 v55, v61
	v_pk_fma_f32 v[60:61], v[106:107], v[106:107], v[2:3] op_sel_hi:[1,1,0]
	v_mov_b64_e32 v[100:101], s[48:49]
	v_mov_b32_e32 v61, v62
	v_pk_add_f32 v[54:55], v[54:55], v[60:61]
	v_lshlrev_b64 v[62:63], 1, v[120:121]
	v_pk_add_f32 v[52:53], v[52:53], v[54:55]
	v_lshl_add_u64 v[60:61], v[120:121], 2, s[34:35]
	v_add_f32_e32 v2, v52, v53
	ds_bpermute_b32 v52, v130, v2
	s_waitcnt lgkmcnt(0)
	v_add_f32_e32 v2, v2, v52
	ds_bpermute_b32 v52, v129, v2
	s_waitcnt lgkmcnt(0)
	v_add_f32_e32 v2, v2, v52
	v_fmamk_f32 v2, v2, 0x3c800000, v200
	v_cmp_gt_f32_e64 s[44:45], s29, v2
	v_mul_f32_e32 v52, 0x4b800000, v2
	s_nop 0
	v_cndmask_b32_e64 v2, v2, v52, s[44:45]
	v_rsq_f32_e32 v2, v2
	s_nop 0
	v_mul_f32_e32 v52, 0x45800000, v2
	v_cndmask_b32_e64 v102, v2, v52, s[44:45]
	v_mad_u64_u32 v[52:53], s[20:21], v114, s72, v[100:101]
	v_lshlrev_b32_e32 v2, 11, v114
	v_lshl_add_u64 v[114:115], v[52:53], 0, v[62:63]
	v_mov_b64_e32 v[124:125], v[222:223]
	v_mov_b64_e32 v[52:53], v[146:147]
	v_mov_b64_e32 v[54:55], v[148:149]
	v_lshl_add_u64 v[122:123], s[46:47], 0, v[2:3]
	v_pk_mul_f32 v[118:119], v[118:119], v[102:103] op_sel_hi:[1,0]
	v_pk_mul_f32 v[116:117], v[116:117], v[102:103] op_sel_hi:[1,0]
	v_pk_mul_f32 v[112:113], v[112:113], v[102:103] op_sel_hi:[1,0]
	v_pk_mul_f32 v[110:111], v[110:111], v[102:103] op_sel_hi:[1,0]
	s_waitcnt lgkmcnt(0)
; __device__ __forceinline__ unsigned pk2(float lo, float hi) { const f32x2_t v = {lo, hi}; const bf16x2_t b = __builtin_convertvector(v, bf16x2_t); return __builtin_bit_cast(unsigned, b); }
; __device__ __forceinline__ float sigmoidf_(float x) { return __builtin_amdgcn_rcpf(1.0f + __expf(-x)); }
; __device__ __forceinline__ float bperm_f(int src_lane, float v) { return __builtin_bit_cast(float, __builtin_amdgcn_ds_bpermute(src_lane << 2, __builtin_bit_cast(int, v))); }
; template <int KIND>
; __device__ __forceinline__ void w_m3_core(const bf16x8 (&Qf)[4][2], const bf16x8 (&Kf)[4][2], const bf16x8 (&Sf)[4][2], const LAS bf16_t* vT, float lg,
;                                           const bf16_t* gsrc, const float* nw, bf16_t* ydst, int lo, int fq) {
;     ...
;         const float osc = KIND == 0 ? __expf((float)(16 * nb + lo + 1) * lg) : 1.0f;
; #pragma unroll
;         for (int eb = 0; eb < 4; ++eb) O[eb] = O[eb] + O2[eb] * osc;
;         float ss = 0.f;
; #pragma unroll
;         for (int eb = 0; eb < 4; ++eb) ss += (O[eb][0] * O[eb][0] + O[eb][1] * O[eb][1]) + (O[eb][2] * O[eb][2] + O[eb][3] * O[eb][3]);
;         { const int ln = (fq << 4) | lo; ss += bperm_f(ln ^ 16, ss); ss += bperm_f(ln ^ 32, ss); }
;         const float rs = rsqrtf(ss * (1.0f / 64.0f) + EPS);
;         const size_t n = 16 * nb + lo;
; #pragma unroll
;         for (int eb = 0; eb < 4; ++eb) { const int e0 = 16 * eb + 4 * fq;
;             const unsigned long long gw_ = *(const unsigned long long*)(gsrc + n * NIN + e0); const f32x4 w4 = *(const f32x4*)(nw + e0);
;             const float g0 = __uint_as_float((unsigned)gw_ << 16), g1 = __uint_as_float((unsigned)gw_ & 0xffff0000u), g2 = __uint_as_float((unsigned)(gw_ >> 32) << 16), g3 = __uint_as_float((unsigned)(gw_ >> 32) & 0xffff0000u);
;             const float o0 = O[eb][0] * rs * w4[0] * (g0 * sigmoidf_(g0)), o1 = O[eb][1] * rs * w4[1] * (g1 * sigmoidf_(g1));
;             const float o2 = O[eb][2] * rs * w4[2] * (g2 * sigmoidf_(g2)), o3 = O[eb][3] * rs * w4[3] * (g3 * sigmoidf_(g3));
;             *(unsigned long long*)(ydst + n * DM + e0) = (unsigned long long)pk2(o0, o1) | ((unsigned long long)pk2(o2, o3) << 32); }
	v_lshlrev_b32_e32 v120, 16, v124
	v_mul_f32_e32 v2, 0xbfb8aa3b, v120
	v_exp_f32_e32 v2, v2
	v_and_b32_e32 v121, 0xffff0000, v124
	v_lshlrev_b32_e32 v124, 16, v125
	v_and_b32_e32 v125, 0xffff0000, v125
	v_add_f32_e32 v2, 1.0, v2
	v_rcp_f32_e32 v134, v2
	v_mul_f32_e32 v2, 0xbfb8aa3b, v121
	v_exp_f32_e32 v2, v2
	v_pk_mul_f32 v[52:53], v[52:53], v[118:119]
	v_pk_mul_f32 v[54:55], v[54:55], v[116:117]
	v_add_f32_e32 v2, 1.0, v2
	v_rcp_f32_e32 v135, v2
	v_mul_f32_e32 v2, 0xbfb8aa3b, v124
	v_exp_f32_e32 v2, v2
	v_pk_mul_f32 v[118:119], v[134:135], v[120:121]
	s_nop 0
	v_pk_mul_f32 v[52:53], v[118:119], v[52:53]
	v_add_f32_e32 v2, 1.0, v2
	v_rcp_f32_e32 v118, v2
	v_mul_f32_e32 v2, 0xbfb8aa3b, v125
	v_exp_f32_e32 v2, v2
	s_nop 0
	v_add_f32_e32 v2, 1.0, v2
	v_rcp_f32_e32 v119, v2
	s_nop 0
	v_pk_mul_f32 v[116:117], v[118:119], v[124:125]
	s_nop 0
	v_pk_mul_f32 v[54:55], v[116:117], v[54:55]
	v_cvt_pk_bf16_f32 v116, v52, v53
	v_cvt_pk_bf16_f32 v117, v54, v55
	v_lshl_add_u64 v[52:53], v[122:123], 0, v[62:63]
	v_and_b32_e32 v142, 16, v132
	v_lshrrev_b32_e32 v143, 1, v142
	v_add_u32_e32 v142, v142, v143
	v_mov_b32_e32 v143, 0
	v_lshl_add_u64 v[52:53], v[52:53], 0, v[142:143]
	v_mov_b64_e32 v[196:197], v[116:117]
	v_mov_b64_e32 v[54:55], v[224:225]
	s_nop 0
	v_mov_b64_e32 v[116:117], v[150:151]
	v_mov_b64_e32 v[118:119], v[152:153]
	s_waitcnt lgkmcnt(0)
	v_lshlrev_b32_e32 v120, 16, v54
	v_mul_f32_e32 v2, 0xbfb8aa3b, v120
	v_exp_f32_e32 v2, v2
	v_and_b32_e32 v121, 0xffff0000, v54
	v_lshlrev_b32_e32 v54, 16, v55
	v_and_b32_e32 v55, 0xffff0000, v55
	v_add_f32_e32 v2, 1.0, v2
	v_rcp_f32_e32 v122, v2
	v_mul_f32_e32 v2, 0xbfb8aa3b, v121
	v_exp_f32_e32 v2, v2
	v_pk_mul_f32 v[112:113], v[116:117], v[112:113]
	v_pk_mul_f32 v[110:111], v[118:119], v[110:111]
	v_mul_f32_e32 v118, v109, v102
	v_add_f32_e32 v2, 1.0, v2
	v_rcp_f32_e32 v123, v2
	v_mul_f32_e32 v2, 0xbfb8aa3b, v54
	v_exp_f32_e32 v2, v2
	v_pk_mul_f32 v[116:117], v[122:123], v[120:121]
	s_nop 0
	v_pk_mul_f32 v[112:113], v[116:117], v[112:113]
	v_add_f32_e32 v2, 1.0, v2
	v_rcp_f32_e32 v116, v2
	v_mul_f32_e32 v2, 0xbfb8aa3b, v55
	v_exp_f32_e32 v2, v2
	v_mul_f32_e32 v120, v106, v102
	v_add_f32_e32 v2, 1.0, v2
	v_rcp_f32_e32 v117, v2
	s_nop 0
	v_pk_mul_f32 v[54:55], v[116:117], v[54:55]
	s_nop 0
	v_pk_mul_f32 v[54:55], v[54:55], v[110:111]
	v_cvt_pk_bf16_f32 v110, v112, v113
	v_cvt_pk_bf16_f32 v111, v54, v55
	v_mov_b64_e32 v[198:199], v[110:111]
	s_nop 1
	v_permlane16_swap_b32_e32 v196, v198
	v_permlane16_swap_b32_e32 v197, v199
	global_store_dwordx4 v[52:53], v[196:199], off offset:1536
	v_mov_b64_e32 v[54:55], v[226:227]
	s_nop 0
	v_mov_b64_e32 v[110:111], v[188:189]
	v_mov_b64_e32 v[112:113], v[190:191]
	v_mul_f32_e32 v116, v108, v102
	s_waitcnt lgkmcnt(0)
	v_lshlrev_b32_e32 v117, 16, v54
	v_mul_f32_e32 v2, 0xbfb8aa3b, v117
	v_exp_f32_e32 v2, v2
	v_and_b32_e32 v119, 0xffff0000, v54
	v_lshlrev_b32_e32 v121, 16, v55
	v_and_b32_e32 v55, 0xffff0000, v55
	v_add_f32_e32 v2, 1.0, v2
	v_rcp_f32_e32 v123, v2
	v_mul_f32_e32 v2, 0xbfb8aa3b, v119
	v_exp_f32_e32 v2, v2
	v_mov_b32_e32 v108, v111
	v_mul_f32_e32 v54, v107, v102
	v_mov_b32_e32 v122, v110
	v_add_f32_e32 v2, 1.0, v2
	v_rcp_f32_e32 v109, v2
	v_mul_f32_e32 v2, 0xbfb8aa3b, v121
	v_exp_f32_e32 v2, v2
	v_pk_mul_f32 v[116:117], v[122:123], v[116:117]
	v_pk_mul_f32 v[108:109], v[108:109], v[118:119]
	v_mov_b32_e32 v110, v112
	v_add_f32_e32 v2, 1.0, v2
	v_rcp_f32_e32 v111, v2
	v_mul_f32_e32 v2, 0xbfb8aa3b, v55
	v_exp_f32_e32 v2, v2
	v_mov_b32_e32 v106, v113
	v_pk_mul_f32 v[110:111], v[110:111], v[120:121]
	v_mul_f32_e32 v112, v105, v102
	v_add_f32_e32 v2, 1.0, v2
	v_rcp_f32_e32 v107, v2
	s_nop 0
	v_pk_mul_f32 v[54:55], v[106:107], v[54:55]
	v_mov_b32_e32 v106, v116
	v_mov_b32_e32 v107, v108
	v_mov_b32_e32 v108, v117
	v_pk_mul_f32 v[106:107], v[106:107], v[108:109]
	v_mov_b32_e32 v108, v110
	v_mov_b32_e32 v109, v54
	v_mov_b32_e32 v54, v111
	v_pk_mul_f32 v[54:55], v[108:109], v[54:55]
	v_cvt_pk_bf16_f32 v106, v106, v107
	v_cvt_pk_bf16_f32 v107, v54, v55
	v_mov_b64_e32 v[196:197], v[106:107]
	v_mov_b64_e32 v[54:55], v[228:229]
	s_nop 0
	v_mov_b64_e32 v[106:107], v[192:193]
	v_mov_b64_e32 v[108:109], v[194:195]
	v_mul_f32_e32 v114, v0, v102
	v_mul_f32_e32 v110, v104, v102
	s_waitcnt lgkmcnt(0)
	v_lshlrev_b32_e32 v111, 16, v54
	v_lshlrev_b32_e32 v115, 16, v55
	v_mul_f32_e32 v2, 0xbfb8aa3b, v111
	v_mul_f32_e32 v0, 0xbfb8aa3b, v115
	v_exp_f32_e32 v2, v2
	v_exp_f32_e32 v0, v0
	v_and_b32_e32 v113, 0xffff0000, v54
	v_and_b32_e32 v55, 0xffff0000, v55
	v_add_f32_e32 v2, 1.0, v2
	v_add_f32_e32 v0, 1.0, v0
	v_rcp_f32_e32 v117, v2
	v_mul_f32_e32 v2, 0xbfb8aa3b, v113
	v_mov_b32_e32 v104, v107
	v_rcp_f32_e32 v107, v0
	v_mul_f32_e32 v0, 0xbfb8aa3b, v55
	v_exp_f32_e32 v2, v2
	v_exp_f32_e32 v0, v0
	v_mul_f32_e32 v54, v1, v102
	v_mov_b32_e32 v116, v106
	v_add_f32_e32 v2, 1.0, v2
	v_add_f32_e32 v0, 1.0, v0
	v_rcp_f32_e32 v105, v2
	v_rcp_f32_e32 v1, v0
	v_mov_b32_e32 v106, v108
	v_mov_b32_e32 v0, v109
	v_pk_mul_f32 v[110:111], v[116:117], v[110:111]
	v_pk_mul_f32 v[104:105], v[104:105], v[112:113]
	v_pk_mul_f32 v[106:107], v[106:107], v[114:115]
	v_pk_mul_f32 v[0:1], v[0:1], v[54:55]
	v_mov_b32_e32 v54, v110
	v_mov_b32_e32 v55, v104
	v_mov_b32_e32 v104, v111
	v_mov_b32_e32 v102, v106
	v_mov_b32_e32 v103, v0
	v_mov_b32_e32 v0, v107
	v_pk_mul_f32 v[54:55], v[54:55], v[104:105]
	v_pk_mul_f32 v[0:1], v[102:103], v[0:1]
	v_cvt_pk_bf16_f32 v54, v54, v55
	v_cvt_pk_bf16_f32 v55, v0, v1
	v_mov_b64_e32 v[198:199], v[54:55]
	s_nop 1
	v_permlane16_swap_b32_e32 v196, v198
	v_permlane16_swap_b32_e32 v197, v199
	global_store_dwordx4 v[52:53], v[196:199], off offset:1600
	v_mfma_f32_16x16x32_bf16 v[102:105], v[16:19], v[44:47], 0
	v_mfma_f32_16x16x32_bf16 v[52:55], v[20:23], v[44:47], 0
	v_mfma_f32_16x16x32_bf16 v[102:105], v[32:35], v[48:51], v[102:105]
	v_mfma_f32_16x16x32_bf16 v[52:55], v[24:27], v[48:51], v[52:55]
	v_mfma_f32_16x16x32_bf16 v[134:137], v[76:79], v[44:47], 0
	s_nop 5
	v_cndmask_b32_e64 v0, v102, 0, s[40:41]
	v_cndmask_b32_e64 v2, v104, 0, s[38:39]
	v_cndmask_b32_e64 v102, v105, 0, vcc
	v_cndmask_b32_e64 v1, 0, v103, s[42:43]
	v_cvt_pk_bf16_f32 v52, v52, v53
	v_cvt_pk_bf16_f32 v53, v54, v55
	v_cvt_pk_bf16_f32 v55, v2, v102
	ds_read_b64_tr_b16 v[104:105], v131 offset:2304
	ds_read_b64_tr_b16 v[102:103], v131
	ds_read_b64_tr_b16 v[106:107], v131 offset:32
	ds_read_b64_tr_b16 v[108:109], v131 offset:2336
	v_cvt_pk_bf16_f32 v54, v0, v1
	v_mfma_f32_16x16x32_bf16 v[134:137], v[92:95], v[48:51], v[134:137]
	s_waitcnt lgkmcnt(0)
; __device__ __forceinline__ unsigned pk2(float lo, float hi) { const f32x2_t v = {lo, hi}; const bf16x2_t b = __builtin_convertvector(v, bf16x2_t); return __builtin_bit_cast(unsigned, b); }
; __device__ __forceinline__ float sigmoidf_(float x) { return __builtin_amdgcn_rcpf(1.0f + __expf(-x)); }
; __device__ __forceinline__ float bperm_f(int src_lane, float v) { return __builtin_bit_cast(float, __builtin_amdgcn_ds_bpermute(src_lane << 2, __builtin_bit_cast(int, v))); }
; template <int KIND>
; __device__ __forceinline__ void w_m3_core(const bf16x8 (&Qf)[4][2], const bf16x8 (&Kf)[4][2], const bf16x8 (&Sf)[4][2], const LAS bf16_t* vT, float lg,
;                                           const bf16_t* gsrc, const float* nw, bf16_t* ydst, int lo, int fq) {
;     ...
;         for (int kk = 0; kk < 2; ++kk)
; #pragma unroll
;             for (int eb = 0; eb < 4; ++eb) O2[eb] = __builtin_amdgcn_mfma_f32_16x16x32_bf16(Sf[eb][kk], Qf[nb][kk], O2[eb], 0, 0, 0);
;         const float osc = KIND == 0 ? __expf((float)(16 * nb + lo + 1) * lg) : 1.0f;
; #pragma unroll
;         for (int eb = 0; eb < 4; ++eb) O[eb] = O[eb] + O2[eb] * osc;
;         float ss = 0.f;
; #pragma unroll
;         for (int eb = 0; eb < 4; ++eb) ss += (O[eb][0] * O[eb][0] + O[eb][1] * O[eb][1]) + (O[eb][2] * O[eb][2] + O[eb][3] * O[eb][3]);
;         { const int ln = (fq << 4) | lo; ss += bperm_f(ln ^ 16, ss); ss += bperm_f(ln ^ 32, ss); }
;         const float rs = rsqrtf(ss * (1.0f / 64.0f) + EPS);
;         const size_t n = 16 * nb + lo;
; #pragma unroll
;         for (int eb = 0; eb < 4; ++eb) { const int e0 = 16 * eb + 4 * fq;
;             const unsigned long long gw_ = *(const unsigned long long*)(gsrc + n * NIN + e0); const f32x4 w4 = *(const f32x4*)(nw + e0);
;             const float g0 = __uint_as_float((unsigned)gw_ << 16), g1 = __uint_as_float((unsigned)gw_ & 0xffff0000u), g2 = __uint_as_float((unsigned)(gw_ >> 32) << 16), g3 = __uint_as_float((unsigned)(gw_ >> 32) & 0xffff0000u);
;             const float o0 = O[eb][0] * rs * w4[0] * (g0 * sigmoidf_(g0)), o1 = O[eb][1] * rs * w4[1] * (g1 * sigmoidf_(g1));
;             const float o2 = O[eb][2] * rs * w4[2] * (g2 * sigmoidf_(g2)), o3 = O[eb][3] * rs * w4[3] * (g3 * sigmoidf_(g3));
;             *(unsigned long long*)(ydst + n * DM + e0) = (unsigned long long)pk2(o0, o1) | ((unsigned long long)pk2(o2, o3) << 32); }
	v_mfma_f32_16x16x32_bf16 v[112:115], v[106:109], v[52:55], 0
	ds_read_b64_tr_b16 v[106:107], v131 offset:64
	ds_read_b64_tr_b16 v[108:109], v131 offset:2368
	s_waitcnt lgkmcnt(0)
	v_mfma_f32_16x16x32_bf16 v[116:119], v[106:109], v[52:55], 0
	ds_read_b64_tr_b16 v[106:107], v131 offset:96
	ds_read_b64_tr_b16 v[108:109], v131 offset:2400
	v_mfma_f32_16x16x32_bf16 v[102:105], v[102:105], v[52:55], 0
	s_waitcnt lgkmcnt(0)
	v_mfma_f32_16x16x32_bf16 v[120:123], v[106:109], v[52:55], 0
	v_mfma_f32_16x16x32_bf16 v[52:55], v[64:67], v[44:47], 0
	v_mfma_f32_16x16x32_bf16 v[106:109], v[72:75], v[44:47], 0
	v_mfma_f32_16x16x32_bf16 v[44:47], v[80:83], v[44:47], 0
	v_mfma_f32_16x16x32_bf16 v[52:55], v[84:87], v[48:51], v[52:55]
	v_mfma_f32_16x16x32_bf16 v[44:47], v[96:99], v[48:51], v[44:47]
	v_mfma_f32_16x16x32_bf16 v[138:141], v[88:91], v[48:51], v[106:109]
	s_nop 5
	v_add_f32_e64 v110, v102, v52
	v_add_f32_e64 v111, v103, v53
	v_pk_add_f32 v[0:1], v[122:123], v[46:47]
	v_pk_add_f32 v[50:51], v[120:121], v[44:45]
	v_pk_add_f32 v[108:109], v[104:105], v[54:55]
	v_pk_mul_f32 v[46:47], v[110:111], v[110:111]
	v_pk_mul_f32 v[44:45], v[108:109], v[108:109]
	v_pk_add_f32 v[104:105], v[114:115], v[140:141]
	v_pk_add_f32 v[106:107], v[112:113], v[138:139]
	v_pk_mov_b32 v[48:49], v[46:47], v[44:45] op_sel:[1,0]
	v_mov_b32_e32 v47, v45
	v_pk_add_f32 v[44:45], v[48:49], v[46:47]
	v_pk_mul_f32 v[46:47], v[104:105], v[104:105]
	v_pk_mul_f32 v[48:49], v[106:107], v[106:107]
	v_pk_add_f32 v[54:55], v[116:117], v[134:135]
	v_pk_mov_b32 v[102:103], v[48:49], v[46:47] op_sel:[1,0]
	v_mov_b32_e32 v49, v47
	v_pk_add_f32 v[46:47], v[102:103], v[48:49]
	v_mul_f32_e32 v2, v50, v50
	v_mul_f32_e32 v48, v51, v51
	v_pk_add_f32 v[44:45], v[44:45], v[44:45] op_sel:[0,1] op_sel_hi:[1,0]
	v_pk_add_f32 v[46:47], v[46:47], v[46:47] op_sel:[0,1] op_sel_hi:[1,0]
	v_pk_add_f32 v[52:53], v[118:119], v[136:137]
	v_mov_b32_e32 v45, v2
	v_mov_b32_e32 v47, v48
	v_mul_f32_e32 v2, v55, v55
	v_mul_f32_e32 v49, v0, v0
	v_pk_add_f32 v[44:45], v[44:45], v[46:47]
	v_pk_fma_f32 v[46:47], v[54:55], v[54:55], v[2:3] op_sel_hi:[1,1,0]
	v_mul_f32_e32 v2, v53, v53
	v_mul_f32_e32 v102, v1, v1
	v_mov_b32_e32 v47, v49
	v_pk_fma_f32 v[48:49], v[52:53], v[52:53], v[2:3] op_sel_hi:[1,1,0]
	s_nop 0
	v_mov_b32_e32 v49, v102
	v_pk_add_f32 v[46:47], v[46:47], v[48:49]
	s_nop 0
	v_pk_add_f32 v[44:45], v[44:45], v[46:47]
	s_nop 0
	v_add_f32_e32 v2, v44, v45
	ds_bpermute_b32 v44, v130, v2
	s_waitcnt lgkmcnt(0)
	v_add_f32_e32 v2, v2, v44
	ds_bpermute_b32 v44, v129, v2
	s_waitcnt lgkmcnt(0)
	v_add_f32_e32 v2, v2, v44
	v_fmamk_f32 v2, v2, 0x3c800000, v200
	v_cmp_gt_f32_e64 s[44:45], s29, v2
	v_mul_f32_e32 v44, 0x4b800000, v2
	s_nop 0
	v_cndmask_b32_e64 v2, v2, v44, s[44:45]
	v_rsq_f32_e32 v2, v2
	s_nop 0
	v_mul_f32_e32 v44, 0x45800000, v2
	v_cndmask_b32_e64 v48, v2, v44, s[44:45]
	v_mad_u64_u32 v[44:45], s[20:21], v128, s72, v[100:101]
	v_lshl_add_u64 v[102:103], v[44:45], 0, v[62:63]
	v_mov_b64_e32 v[114:115], v[230:231]
	v_mov_b64_e32 v[44:45], v[146:147]
	v_mov_b64_e32 v[46:47], v[148:149]
	v_lshlrev_b32_e32 v2, 11, v128
	v_lshl_add_u64 v[112:113], s[46:47], 0, v[2:3]
	v_pk_mul_f32 v[110:111], v[110:111], v[48:49] op_sel_hi:[1,0]
	v_pk_mul_f32 v[108:109], v[108:109], v[48:49] op_sel_hi:[1,0]
	v_pk_mul_f32 v[106:107], v[106:107], v[48:49] op_sel_hi:[1,0]
	v_pk_mul_f32 v[104:105], v[104:105], v[48:49] op_sel_hi:[1,0]
	s_waitcnt lgkmcnt(0)
	v_lshlrev_b32_e32 v116, 16, v114
	v_mul_f32_e32 v2, 0xbfb8aa3b, v116
	v_exp_f32_e32 v2, v2
	v_and_b32_e32 v117, 0xffff0000, v114
	v_lshlrev_b32_e32 v114, 16, v115
	v_and_b32_e32 v115, 0xffff0000, v115
	v_add_f32_e32 v2, 1.0, v2
	v_rcp_f32_e32 v118, v2
	v_mul_f32_e32 v2, 0xbfb8aa3b, v117
	v_exp_f32_e32 v2, v2
	v_pk_mul_f32 v[44:45], v[44:45], v[110:111]
	v_pk_mul_f32 v[46:47], v[46:47], v[108:109]
	v_add_f32_e32 v2, 1.0, v2
	v_rcp_f32_e32 v119, v2
	v_mul_f32_e32 v2, 0xbfb8aa3b, v114
	v_exp_f32_e32 v2, v2
	v_pk_mul_f32 v[110:111], v[118:119], v[116:117]
	s_nop 0
	v_pk_mul_f32 v[44:45], v[110:111], v[44:45]
	v_add_f32_e32 v2, 1.0, v2
	v_rcp_f32_e32 v110, v2
	v_mul_f32_e32 v2, 0xbfb8aa3b, v115
	v_exp_f32_e32 v2, v2
	s_nop 0
	v_add_f32_e32 v2, 1.0, v2
	v_rcp_f32_e32 v111, v2
	s_nop 0
	v_pk_mul_f32 v[108:109], v[110:111], v[114:115]
	s_nop 0
	v_pk_mul_f32 v[46:47], v[108:109], v[46:47]
	v_cvt_pk_bf16_f32 v108, v44, v45
	v_cvt_pk_bf16_f32 v109, v46, v47
	v_lshl_add_u64 v[44:45], v[112:113], 0, v[62:63]
	v_lshl_add_u64 v[44:45], v[44:45], 0, v[142:143]
	v_mov_b64_e32 v[196:197], v[108:109]
	v_mov_b64_e32 v[46:47], v[232:233]
	s_nop 0
	v_mov_b64_e32 v[108:109], v[150:151]
	v_mov_b64_e32 v[110:111], v[152:153]
	s_waitcnt lgkmcnt(0)
	v_lshlrev_b32_e32 v112, 16, v46
	v_mul_f32_e32 v2, 0xbfb8aa3b, v112
	v_exp_f32_e32 v2, v2
	v_and_b32_e32 v113, 0xffff0000, v46
	v_lshlrev_b32_e32 v46, 16, v47
	v_and_b32_e32 v47, 0xffff0000, v47
	v_add_f32_e32 v2, 1.0, v2
	v_rcp_f32_e32 v114, v2
	v_mul_f32_e32 v2, 0xbfb8aa3b, v113
	v_exp_f32_e32 v2, v2
	v_pk_mul_f32 v[106:107], v[108:109], v[106:107]
	v_pk_mul_f32 v[104:105], v[110:111], v[104:105]
	v_mul_f32_e32 v110, v55, v48
	v_add_f32_e32 v2, 1.0, v2
	v_rcp_f32_e32 v115, v2
	v_mul_f32_e32 v2, 0xbfb8aa3b, v46
	v_exp_f32_e32 v2, v2
	v_pk_mul_f32 v[108:109], v[114:115], v[112:113]
	s_nop 0
	v_pk_mul_f32 v[106:107], v[108:109], v[106:107]
	v_add_f32_e32 v2, 1.0, v2
	v_rcp_f32_e32 v108, v2
	v_mul_f32_e32 v2, 0xbfb8aa3b, v47
	v_exp_f32_e32 v2, v2
	v_mul_f32_e32 v112, v52, v48
	v_add_f32_e32 v2, 1.0, v2
	v_rcp_f32_e32 v109, v2
	s_nop 0
	v_pk_mul_f32 v[46:47], v[108:109], v[46:47]
	s_nop 0
	v_pk_mul_f32 v[46:47], v[46:47], v[104:105]
	v_cvt_pk_bf16_f32 v104, v106, v107
	v_cvt_pk_bf16_f32 v105, v46, v47
	v_mov_b64_e32 v[198:199], v[104:105]
	s_nop 1
	v_permlane16_swap_b32_e32 v196, v198
	v_permlane16_swap_b32_e32 v197, v199
	global_store_dwordx4 v[44:45], v[196:199], off offset:1536
	v_mov_b64_e32 v[46:47], v[234:235]
	s_nop 0
	v_mov_b64_e32 v[104:105], v[188:189]
	v_mov_b64_e32 v[106:107], v[190:191]
	v_mul_f32_e32 v108, v54, v48
	s_waitcnt lgkmcnt(0)
; __device__ __forceinline__ float sigmoidf_(float x) { return __builtin_amdgcn_rcpf(1.0f + __expf(-x)); }
; template <int KIND>
; __device__ __forceinline__ void w_m3_core(const bf16x8 (&Qf)[4][2], const bf16x8 (&Kf)[4][2], const bf16x8 (&Sf)[4][2], const LAS bf16_t* vT, float lg,
;                                           const bf16_t* gsrc, const float* nw, bf16_t* ydst, int lo, int fq) {
;     ...
;             float pv[8];
; #pragma unroll
;             for (int hh = 0; hh < 2; ++hh) { const int mb = 2 * kk2 + hh;
;                 if (mb <= nb) { f32x4 s = {0.f, 0.f, 0.f, 0.f};
;                     s = __builtin_amdgcn_mfma_f32_16x16x32_bf16(Kf[mb][0], Qf[nb][0], s, 0, 0, 0); s = __builtin_amdgcn_mfma_f32_16x16x32_bf16(Kf[mb][1], Qf[nb][1], s, 0, 0, 0);
; #pragma unroll
;                     for (int r = 0; r < 4; ++r) { const int m = 16 * mb + 4 * fq + r, n = 16 * nb + lo; float v = s[r];
;                         if (KIND == 0) v *= __expf((float)(n - m) * lg);
;                         if (mb == nb) v = (m <= n) ? v : 0.f;
;                         pv[4 * hh + r] = v; }
;                 } else {
; #pragma unroll
;                     for (int r = 0; r < 4; ++r) pv[4 * hh + r] = 0.f; }
;             }
;             const bf16x8 Pf = pack_frag(pv);
; #pragma unroll
;             for (int eb = 0; eb < 4; ++eb)
;                 O[eb] = __builtin_amdgcn_mfma_f32_16x16x32_bf16(tr_frag(vT, 32 * kk2 + 4 * fq, 32 * kk2 + 16 + 4 * fq, 16 * eb, lo), Pf, O[eb], 0, 0, 0);
;     ...
;         for (int eb = 0; eb < 4; ++eb) { const int e0 = 16 * eb + 4 * fq;
;             const unsigned long long gw_ = *(const unsigned long long*)(gsrc + n * NIN + e0); const f32x4 w4 = *(const f32x4*)(nw + e0);
;             const float g0 = __uint_as_float((unsigned)gw_ << 16), g1 = __uint_as_float((unsigned)gw_ & 0xffff0000u), g2 = __uint_as_float((unsigned)(gw_ >> 32) << 16), g3 = __uint_as_float((unsigned)(gw_ >> 32) & 0xffff0000u);
;             const float o0 = O[eb][0] * rs * w4[0] * (g0 * sigmoidf_(g0)), o1 = O[eb][1] * rs * w4[1] * (g1 * sigmoidf_(g1));
;             const float o2 = O[eb][2] * rs * w4[2] * (g2 * sigmoidf_(g2)), o3 = O[eb][3] * rs * w4[3] * (g3 * sigmoidf_(g3));
;             *(unsigned long long*)(ydst + n * DM + e0) = (unsigned long long)pk2(o0, o1) | ((unsigned long long)pk2(o2, o3) << 32); }
	v_lshlrev_b32_e32 v109, 16, v46
	v_mul_f32_e32 v2, 0xbfb8aa3b, v109
	v_exp_f32_e32 v2, v2
	v_and_b32_e32 v111, 0xffff0000, v46
	v_lshlrev_b32_e32 v113, 16, v47
	v_and_b32_e32 v47, 0xffff0000, v47
	v_add_f32_e32 v2, 1.0, v2
	v_rcp_f32_e32 v115, v2
	v_mul_f32_e32 v2, 0xbfb8aa3b, v111
	v_exp_f32_e32 v2, v2
	v_mov_b32_e32 v54, v105
	v_mul_f32_e32 v46, v53, v48
	v_mov_b32_e32 v114, v104
	v_add_f32_e32 v2, 1.0, v2
	v_rcp_f32_e32 v55, v2
	v_mul_f32_e32 v2, 0xbfb8aa3b, v113
	v_exp_f32_e32 v2, v2
	v_pk_mul_f32 v[108:109], v[114:115], v[108:109]
	v_pk_mul_f32 v[54:55], v[54:55], v[110:111]
	v_mov_b32_e32 v104, v106
	v_add_f32_e32 v2, 1.0, v2
	v_rcp_f32_e32 v105, v2
	v_mul_f32_e32 v2, 0xbfb8aa3b, v47
	v_exp_f32_e32 v2, v2
	v_mov_b32_e32 v52, v107
	v_pk_mul_f32 v[104:105], v[104:105], v[112:113]
	v_mul_f32_e32 v106, v0, v48
	v_add_f32_e32 v2, 1.0, v2
	v_rcp_f32_e32 v53, v2
	s_nop 0
	v_pk_mul_f32 v[46:47], v[52:53], v[46:47]
	v_mov_b32_e32 v52, v108
	v_mov_b32_e32 v53, v54
	v_mov_b32_e32 v54, v109
	v_pk_mul_f32 v[52:53], v[52:53], v[54:55]
	v_mov_b32_e32 v54, v104
	v_mov_b32_e32 v55, v46
	v_mov_b32_e32 v46, v105
	v_pk_mul_f32 v[46:47], v[54:55], v[46:47]
	v_cvt_pk_bf16_f32 v52, v52, v53
	v_cvt_pk_bf16_f32 v53, v46, v47
	v_mov_b64_e32 v[196:197], v[52:53]
	v_mov_b64_e32 v[46:47], v[236:237]
	s_nop 0
	v_mov_b64_e32 v[52:53], v[192:193]
	v_mov_b64_e32 v[54:55], v[194:195]
	v_mul_f32_e32 v102, v50, v48
	v_mul_f32_e32 v104, v51, v48
	s_waitcnt lgkmcnt(0)
	v_lshlrev_b32_e32 v103, 16, v46
	v_lshlrev_b32_e32 v107, 16, v47
	v_mul_f32_e32 v2, 0xbfb8aa3b, v103
	v_mul_f32_e32 v0, 0xbfb8aa3b, v107
	v_exp_f32_e32 v2, v2
	v_exp_f32_e32 v0, v0
	v_and_b32_e32 v105, 0xffff0000, v46
	v_and_b32_e32 v47, 0xffff0000, v47
	v_add_f32_e32 v2, 1.0, v2
	v_add_f32_e32 v0, 1.0, v0
	v_rcp_f32_e32 v109, v2
	v_mul_f32_e32 v2, 0xbfb8aa3b, v105
	v_mov_b32_e32 v50, v53
	v_rcp_f32_e32 v53, v0
	v_mul_f32_e32 v0, 0xbfb8aa3b, v47
	v_exp_f32_e32 v2, v2
	v_exp_f32_e32 v0, v0
	v_mul_f32_e32 v46, v1, v48
	v_mov_b32_e32 v108, v52
	v_add_f32_e32 v2, 1.0, v2
	v_add_f32_e32 v0, 1.0, v0
	v_rcp_f32_e32 v51, v2
	v_rcp_f32_e32 v1, v0
	v_mov_b32_e32 v52, v54
	v_mov_b32_e32 v0, v55
	v_pk_mul_f32 v[102:103], v[108:109], v[102:103]
	v_pk_mul_f32 v[50:51], v[50:51], v[104:105]
	v_pk_mul_f32 v[52:53], v[52:53], v[106:107]
	v_pk_mul_f32 v[0:1], v[0:1], v[46:47]
	v_mov_b32_e32 v46, v102
	v_mov_b32_e32 v47, v50
	v_mov_b32_e32 v50, v103
	v_mov_b32_e32 v48, v52
	v_mov_b32_e32 v49, v0
	v_mov_b32_e32 v0, v53
	v_pk_mul_f32 v[46:47], v[46:47], v[50:51]
	v_pk_mul_f32 v[0:1], v[48:49], v[0:1]
	v_cvt_pk_bf16_f32 v46, v46, v47
	v_cvt_pk_bf16_f32 v47, v0, v1
	v_mov_b64_e32 v[198:199], v[46:47]
	s_nop 1
	v_permlane16_swap_b32_e32 v196, v198
	v_permlane16_swap_b32_e32 v197, v199
	global_store_dwordx4 v[44:45], v[196:199], off offset:1600
	v_mfma_f32_16x16x32_bf16 v[44:47], v[20:23], v[28:31], 0
	v_mfma_f32_16x16x32_bf16 v[48:51], v[16:19], v[28:31], 0
	v_mfma_f32_16x16x32_bf16 v[44:47], v[24:27], v[40:43], v[44:47]
	v_mfma_f32_16x16x32_bf16 v[48:51], v[32:35], v[40:43], v[48:51]
	s_nop 6
	v_cvt_pk_bf16_f32 v44, v44, v45
	v_cvt_pk_bf16_f32 v45, v46, v47
	v_cvt_pk_bf16_f32 v46, v48, v49
	v_cvt_pk_bf16_f32 v47, v50, v51
	ds_read_b64_tr_b16 v[50:51], v131 offset:2304
	ds_read_b64_tr_b16 v[48:49], v131
	ds_read_b64_tr_b16 v[52:53], v131 offset:32
	ds_read_b64_tr_b16 v[54:55], v131 offset:2336
	ds_read_b64_tr_b16 v[102:103], v131 offset:64
	ds_read_b64_tr_b16 v[104:105], v131 offset:2368
	ds_read_b64_tr_b16 v[106:107], v131 offset:96
	ds_read_b64_tr_b16 v[108:109], v131 offset:2400
	s_waitcnt lgkmcnt(0)
	v_mfma_f32_16x16x32_bf16 v[48:51], v[48:51], v[44:47], 0
	v_mfma_f32_16x16x32_bf16 v[52:55], v[52:55], v[44:47], 0
	v_mfma_f32_16x16x32_bf16 v[102:105], v[102:105], v[44:47], 0
	v_mfma_f32_16x16x32_bf16 v[44:47], v[106:109], v[44:47], 0
	v_mfma_f32_16x16x32_bf16 v[106:109], v[12:15], v[28:31], 0
	v_mfma_f32_16x16x32_bf16 v[106:109], v[36:39], v[40:43], v[106:109]
	s_nop 7
	v_cndmask_b32_e64 v0, v106, 0, s[40:41]
	v_cndmask_b32_e64 v1, 0, v107, s[42:43]
	v_cndmask_b32_e64 v2, v108, 0, s[38:39]
	v_cndmask_b32_e64 v106, v109, 0, vcc
	v_cvt_pk_bf16_f32 v0, v0, v1
	v_cvt_pk_bf16_f32 v1, v2, v106
	ds_read_b64_tr_b16 v[106:107], v131 offset:4608
	ds_read_b64_tr_b16 v[108:109], v131 offset:6912
	v_mov_b32_e32 v2, v3
	s_waitcnt lgkmcnt(0)
	s_nop 0
	v_mfma_f32_16x16x32_bf16 v[48:51], v[106:109], v[0:3], v[48:51]
	ds_read_b64_tr_b16 v[106:107], v131 offset:4640
	ds_read_b64_tr_b16 v[108:109], v131 offset:6944
	s_waitcnt lgkmcnt(0)
	v_mfma_f32_16x16x32_bf16 v[106:109], v[106:109], v[0:3], v[52:55]
	s_nop 2
	ds_read_b64_tr_b16 v[52:53], v131 offset:4672
	ds_read_b64_tr_b16 v[54:55], v131 offset:6976
	s_waitcnt lgkmcnt(0)
	v_mfma_f32_16x16x32_bf16 v[110:113], v[52:55], v[0:3], v[102:105]
	ds_read_b64_tr_b16 v[52:53], v131 offset:4704
	ds_read_b64_tr_b16 v[54:55], v131 offset:7008
	s_waitcnt lgkmcnt(0)
; __device__ __forceinline__ unsigned pk2(float lo, float hi) { const f32x2_t v = {lo, hi}; const bf16x2_t b = __builtin_convertvector(v, bf16x2_t); return __builtin_bit_cast(unsigned, b); }
; __device__ __forceinline__ float sigmoidf_(float x) { return __builtin_amdgcn_rcpf(1.0f + __expf(-x)); }
; __device__ __forceinline__ float bperm_f(int src_lane, float v) { return __builtin_bit_cast(float, __builtin_amdgcn_ds_bpermute(src_lane << 2, __builtin_bit_cast(int, v))); }
; template <int KIND>
; __device__ __forceinline__ void w_m3_core(const bf16x8 (&Qf)[4][2], const bf16x8 (&Kf)[4][2], const bf16x8 (&Sf)[4][2], const LAS bf16_t* vT, float lg,
;                                           const bf16_t* gsrc, const float* nw, bf16_t* ydst, int lo, int fq) {
;     ...
;         for (int kk = 0; kk < 2; ++kk)
; #pragma unroll
;             for (int eb = 0; eb < 4; ++eb) O2[eb] = __builtin_amdgcn_mfma_f32_16x16x32_bf16(Sf[eb][kk], Qf[nb][kk], O2[eb], 0, 0, 0);
;         const float osc = KIND == 0 ? __expf((float)(16 * nb + lo + 1) * lg) : 1.0f;
; #pragma unroll
;         for (int eb = 0; eb < 4; ++eb) O[eb] = O[eb] + O2[eb] * osc;
;         float ss = 0.f;
; #pragma unroll
;         for (int eb = 0; eb < 4; ++eb) ss += (O[eb][0] * O[eb][0] + O[eb][1] * O[eb][1]) + (O[eb][2] * O[eb][2] + O[eb][3] * O[eb][3]);
;         { const int ln = (fq << 4) | lo; ss += bperm_f(ln ^ 16, ss); ss += bperm_f(ln ^ 32, ss); }
;         const float rs = rsqrtf(ss * (1.0f / 64.0f) + EPS);
;         const size_t n = 16 * nb + lo;
; #pragma unroll
;         for (int eb = 0; eb < 4; ++eb) { const int e0 = 16 * eb + 4 * fq;
;             const unsigned long long gw_ = *(const unsigned long long*)(gsrc + n * NIN + e0); const f32x4 w4 = *(const f32x4*)(nw + e0);
;             const float g0 = __uint_as_float((unsigned)gw_ << 16), g1 = __uint_as_float((unsigned)gw_ & 0xffff0000u), g2 = __uint_as_float((unsigned)(gw_ >> 32) << 16), g3 = __uint_as_float((unsigned)(gw_ >> 32) & 0xffff0000u);
;             const float o0 = O[eb][0] * rs * w4[0] * (g0 * sigmoidf_(g0)), o1 = O[eb][1] * rs * w4[1] * (g1 * sigmoidf_(g1));
;             const float o2 = O[eb][2] * rs * w4[2] * (g2 * sigmoidf_(g2)), o3 = O[eb][3] * rs * w4[3] * (g3 * sigmoidf_(g3));
;             *(unsigned long long*)(ydst + n * DM + e0) = (unsigned long long)pk2(o0, o1) | ((unsigned long long)pk2(o2, o3) << 32); }
	v_mfma_f32_16x16x32_bf16 v[114:117], v[52:55], v[0:3], v[44:47]
	v_mfma_f32_16x16x32_bf16 v[44:47], v[64:67], v[28:31], 0
	v_mfma_f32_16x16x32_bf16 v[52:55], v[72:75], v[28:31], 0
	v_mfma_f32_16x16x32_bf16 v[102:105], v[76:79], v[28:31], 0
	v_mfma_f32_16x16x32_bf16 v[28:31], v[80:83], v[28:31], 0
	v_mfma_f32_16x16x32_bf16 v[44:47], v[84:87], v[40:43], v[44:47]
	v_mfma_f32_16x16x32_bf16 v[28:31], v[96:99], v[40:43], v[28:31]
	v_mfma_f32_16x16x32_bf16 v[118:121], v[88:91], v[40:43], v[52:55]
	v_mfma_f32_16x16x32_bf16 v[122:125], v[92:95], v[40:43], v[102:105]
	s_nop 4
	v_add_f32_e64 v54, v50, v46
	v_add_f32_e64 v55, v51, v47
	v_pk_add_f32 v[0:1], v[116:117], v[30:31]
	v_pk_add_f32 v[42:43], v[114:115], v[28:29]
	v_pk_add_f32 v[102:103], v[48:49], v[44:45]
	v_pk_mul_f32 v[28:29], v[54:55], v[54:55]
	v_pk_mul_f32 v[30:31], v[102:103], v[102:103]
	v_pk_add_f32 v[50:51], v[108:109], v[120:121]
	v_pk_add_f32 v[52:53], v[106:107], v[118:119]
	v_pk_mov_b32 v[40:41], v[30:31], v[28:29] op_sel:[1,0]
	v_mov_b32_e32 v31, v29
	v_pk_add_f32 v[28:29], v[40:41], v[30:31]
	v_pk_mul_f32 v[30:31], v[50:51], v[50:51]
	v_pk_mul_f32 v[40:41], v[52:53], v[52:53]
	v_pk_add_f32 v[46:47], v[110:111], v[122:123]
	v_pk_mov_b32 v[48:49], v[40:41], v[30:31] op_sel:[1,0]
	v_mov_b32_e32 v41, v31
	v_pk_add_f32 v[30:31], v[48:49], v[40:41]
	v_mul_f32_e32 v2, v42, v42
	v_mul_f32_e32 v40, v43, v43
	v_pk_add_f32 v[28:29], v[28:29], v[28:29] op_sel:[0,1] op_sel_hi:[1,0]
	v_pk_add_f32 v[30:31], v[30:31], v[30:31] op_sel:[0,1] op_sel_hi:[1,0]
	v_pk_add_f32 v[44:45], v[112:113], v[124:125]
	v_mov_b32_e32 v29, v2
	v_mov_b32_e32 v31, v40
	v_mul_f32_e32 v2, v47, v47
	v_mul_f32_e32 v41, v0, v0
	v_pk_add_f32 v[28:29], v[28:29], v[30:31]
	v_pk_fma_f32 v[30:31], v[46:47], v[46:47], v[2:3] op_sel_hi:[1,1,0]
	v_mul_f32_e32 v2, v45, v45
	v_mul_f32_e32 v48, v1, v1
	v_mov_b32_e32 v31, v41
	v_pk_fma_f32 v[40:41], v[44:45], v[44:45], v[2:3] op_sel_hi:[1,1,0]
	s_nop 0
	v_mov_b32_e32 v41, v48
	v_pk_add_f32 v[30:31], v[30:31], v[40:41]
	s_nop 0
	v_pk_add_f32 v[28:29], v[28:29], v[30:31]
	s_nop 0
	v_add_f32_e32 v2, v28, v29
	ds_bpermute_b32 v28, v130, v2
	s_waitcnt lgkmcnt(0)
	v_add_f32_e32 v2, v2, v28
	ds_bpermute_b32 v28, v129, v2
	s_waitcnt lgkmcnt(0)
	v_add_f32_e32 v2, v2, v28
	v_fmamk_f32 v2, v2, 0x3c800000, v200
	v_cmp_gt_f32_e64 s[44:45], s29, v2
	v_mul_f32_e32 v28, 0x4b800000, v2
	s_nop 0
	v_cndmask_b32_e64 v2, v2, v28, s[44:45]
	v_rsq_f32_e32 v2, v2
	s_nop 0
	v_mul_f32_e32 v28, 0x45800000, v2
	v_cndmask_b32_e64 v40, v2, v28, s[44:45]
	v_mad_u64_u32 v[28:29], s[20:21], v127, s72, v[100:101]
	v_lshl_add_u64 v[48:49], v[28:29], 0, v[62:63]
	v_mov_b64_e32 v[106:107], v[238:239]
	v_mov_b64_e32 v[28:29], v[146:147]
	v_mov_b64_e32 v[30:31], v[148:149]
	v_lshlrev_b32_e32 v2, 11, v127
	v_lshl_add_u64 v[104:105], s[46:47], 0, v[2:3]
	v_pk_mul_f32 v[102:103], v[102:103], v[40:41] op_sel_hi:[1,0]
	v_pk_mul_f32 v[54:55], v[54:55], v[40:41] op_sel_hi:[1,0]
	v_pk_mul_f32 v[52:53], v[52:53], v[40:41] op_sel_hi:[1,0]
	v_pk_mul_f32 v[50:51], v[50:51], v[40:41] op_sel_hi:[1,0]
	s_waitcnt lgkmcnt(0)
	v_lshlrev_b32_e32 v108, 16, v106
	v_mul_f32_e32 v2, 0xbfb8aa3b, v108
	v_exp_f32_e32 v2, v2
	v_and_b32_e32 v109, 0xffff0000, v106
	v_lshlrev_b32_e32 v106, 16, v107
	v_and_b32_e32 v107, 0xffff0000, v107
	v_add_f32_e32 v2, 1.0, v2
	v_rcp_f32_e32 v110, v2
	v_mul_f32_e32 v2, 0xbfb8aa3b, v109
	v_exp_f32_e32 v2, v2
	v_pk_mul_f32 v[28:29], v[28:29], v[102:103]
	v_pk_mul_f32 v[30:31], v[30:31], v[54:55]
	v_add_f32_e32 v2, 1.0, v2
	v_rcp_f32_e32 v111, v2
	v_mul_f32_e32 v2, 0xbfb8aa3b, v106
	v_exp_f32_e32 v2, v2
	v_pk_mul_f32 v[102:103], v[110:111], v[108:109]
	s_nop 0
	v_pk_mul_f32 v[28:29], v[102:103], v[28:29]
	v_add_f32_e32 v2, 1.0, v2
	v_rcp_f32_e32 v102, v2
	v_mul_f32_e32 v2, 0xbfb8aa3b, v107
	v_exp_f32_e32 v2, v2
	s_nop 0
	v_add_f32_e32 v2, 1.0, v2
	v_rcp_f32_e32 v103, v2
	s_nop 0
	v_pk_mul_f32 v[54:55], v[102:103], v[106:107]
	s_nop 0
	v_pk_mul_f32 v[30:31], v[54:55], v[30:31]
	v_cvt_pk_bf16_f32 v54, v28, v29
	v_cvt_pk_bf16_f32 v55, v30, v31
	v_lshl_add_u64 v[28:29], v[104:105], 0, v[62:63]
	v_lshl_add_u64 v[28:29], v[28:29], 0, v[142:143]
	v_mov_b64_e32 v[196:197], v[54:55]
	v_mov_b64_e32 v[30:31], v[240:241]
	v_mov_b64_e32 v[102:103], v[150:151]
	v_mov_b64_e32 v[104:105], v[152:153]
	s_waitcnt lgkmcnt(0)
	v_lshlrev_b32_e32 v54, 16, v30
	v_mul_f32_e32 v2, 0xbfb8aa3b, v54
	v_exp_f32_e32 v2, v2
	v_and_b32_e32 v55, 0xffff0000, v30
	v_lshlrev_b32_e32 v30, 16, v31
	v_and_b32_e32 v31, 0xffff0000, v31
	v_add_f32_e32 v2, 1.0, v2
	v_rcp_f32_e32 v106, v2
	v_mul_f32_e32 v2, 0xbfb8aa3b, v55
	v_exp_f32_e32 v2, v2
	v_pk_mul_f32 v[52:53], v[102:103], v[52:53]
	v_pk_mul_f32 v[50:51], v[104:105], v[50:51]
	v_mul_f32_e32 v102, v47, v40
	v_add_f32_e32 v2, 1.0, v2
	v_rcp_f32_e32 v107, v2
	v_mul_f32_e32 v2, 0xbfb8aa3b, v30
	v_exp_f32_e32 v2, v2
	v_mul_f32_e32 v104, v44, v40
	v_pk_mul_f32 v[54:55], v[106:107], v[54:55]
	v_add_f32_e32 v2, 1.0, v2
	v_pk_mul_f32 v[52:53], v[54:55], v[52:53]
	v_rcp_f32_e32 v54, v2
	v_mul_f32_e32 v2, 0xbfb8aa3b, v31
	v_exp_f32_e32 v2, v2
	s_nop 0
	v_add_f32_e32 v2, 1.0, v2
	v_rcp_f32_e32 v55, v2
	s_nop 0
	v_pk_mul_f32 v[30:31], v[54:55], v[30:31]
	s_nop 0
	v_pk_mul_f32 v[30:31], v[30:31], v[50:51]
	v_cvt_pk_bf16_f32 v50, v52, v53
	v_cvt_pk_bf16_f32 v51, v30, v31
	v_mov_b64_e32 v[198:199], v[50:51]
	s_nop 1
	v_permlane16_swap_b32_e32 v196, v198
	v_permlane16_swap_b32_e32 v197, v199
	global_store_dwordx4 v[28:29], v[196:199], off offset:1536
	v_mov_b64_e32 v[30:31], v[242:243]
	s_nop 0
	v_mov_b64_e32 v[50:51], v[188:189]
	v_mov_b64_e32 v[52:53], v[190:191]
	v_mul_f32_e32 v54, v46, v40
	s_waitcnt lgkmcnt(0)
; __device__ __forceinline__ float sigmoidf_(float x) { return __builtin_amdgcn_rcpf(1.0f + __expf(-x)); }
; template <int KIND>
; __device__ __forceinline__ void w_m3_core(const bf16x8 (&Qf)[4][2], const bf16x8 (&Kf)[4][2], const bf16x8 (&Sf)[4][2], const LAS bf16_t* vT, float lg,
;                                           const bf16_t* gsrc, const float* nw, bf16_t* ydst, int lo, int fq) {
;     ...
;             float pv[8];
; #pragma unroll
;             for (int hh = 0; hh < 2; ++hh) { const int mb = 2 * kk2 + hh;
;                 if (mb <= nb) { f32x4 s = {0.f, 0.f, 0.f, 0.f};
;                     s = __builtin_amdgcn_mfma_f32_16x16x32_bf16(Kf[mb][0], Qf[nb][0], s, 0, 0, 0); s = __builtin_amdgcn_mfma_f32_16x16x32_bf16(Kf[mb][1], Qf[nb][1], s, 0, 0, 0);
; #pragma unroll
;                     for (int r = 0; r < 4; ++r) { const int m = 16 * mb + 4 * fq + r, n = 16 * nb + lo; float v = s[r];
;                         if (KIND == 0) v *= __expf((float)(n - m) * lg);
;                         if (mb == nb) v = (m <= n) ? v : 0.f;
;                         pv[4 * hh + r] = v; }
;                 } else {
; #pragma unroll
;                     for (int r = 0; r < 4; ++r) pv[4 * hh + r] = 0.f; }
;             }
;             const bf16x8 Pf = pack_frag(pv);
; #pragma unroll
;             for (int eb = 0; eb < 4; ++eb)
;                 O[eb] = __builtin_amdgcn_mfma_f32_16x16x32_bf16(tr_frag(vT, 32 * kk2 + 4 * fq, 32 * kk2 + 16 + 4 * fq, 16 * eb, lo), Pf, O[eb], 0, 0, 0);
;     ...
;         for (int eb = 0; eb < 4; ++eb) { const int e0 = 16 * eb + 4 * fq;
;             const unsigned long long gw_ = *(const unsigned long long*)(gsrc + n * NIN + e0); const f32x4 w4 = *(const f32x4*)(nw + e0);
;             const float g0 = __uint_as_float((unsigned)gw_ << 16), g1 = __uint_as_float((unsigned)gw_ & 0xffff0000u), g2 = __uint_as_float((unsigned)(gw_ >> 32) << 16), g3 = __uint_as_float((unsigned)(gw_ >> 32) & 0xffff0000u);
;             const float o0 = O[eb][0] * rs * w4[0] * (g0 * sigmoidf_(g0)), o1 = O[eb][1] * rs * w4[1] * (g1 * sigmoidf_(g1));
;             const float o2 = O[eb][2] * rs * w4[2] * (g2 * sigmoidf_(g2)), o3 = O[eb][3] * rs * w4[3] * (g3 * sigmoidf_(g3));
;             *(unsigned long long*)(ydst + n * DM + e0) = (unsigned long long)pk2(o0, o1) | ((unsigned long long)pk2(o2, o3) << 32); }
	v_lshlrev_b32_e32 v55, 16, v30
	v_mul_f32_e32 v2, 0xbfb8aa3b, v55
	v_exp_f32_e32 v2, v2
	v_and_b32_e32 v103, 0xffff0000, v30
	v_lshlrev_b32_e32 v105, 16, v31
	v_and_b32_e32 v31, 0xffff0000, v31
	v_add_f32_e32 v2, 1.0, v2
	v_rcp_f32_e32 v107, v2
	v_mul_f32_e32 v2, 0xbfb8aa3b, v103
	v_exp_f32_e32 v2, v2
	v_mov_b32_e32 v46, v51
	v_mul_f32_e32 v30, v45, v40
	v_mov_b32_e32 v106, v50
	v_add_f32_e32 v2, 1.0, v2
	v_rcp_f32_e32 v47, v2
	v_mul_f32_e32 v2, 0xbfb8aa3b, v105
	v_exp_f32_e32 v2, v2
	v_pk_mul_f32 v[54:55], v[106:107], v[54:55]
	v_pk_mul_f32 v[46:47], v[46:47], v[102:103]
	v_mov_b32_e32 v50, v52
	v_add_f32_e32 v2, 1.0, v2
	v_rcp_f32_e32 v51, v2
	v_mul_f32_e32 v2, 0xbfb8aa3b, v31
	v_exp_f32_e32 v2, v2
	v_mov_b32_e32 v44, v53
	v_pk_mul_f32 v[50:51], v[50:51], v[104:105]
	v_mul_f32_e32 v52, v0, v40
	v_add_f32_e32 v2, 1.0, v2
	v_rcp_f32_e32 v45, v2
	s_nop 0
	v_pk_mul_f32 v[30:31], v[44:45], v[30:31]
	v_mov_b32_e32 v44, v54
	v_mov_b32_e32 v45, v46
	v_mov_b32_e32 v46, v55
	v_pk_mul_f32 v[44:45], v[44:45], v[46:47]
	v_mov_b32_e32 v46, v50
	v_mov_b32_e32 v47, v30
	v_mov_b32_e32 v30, v51
	v_pk_mul_f32 v[30:31], v[46:47], v[30:31]
	v_cvt_pk_bf16_f32 v44, v44, v45
	v_cvt_pk_bf16_f32 v45, v30, v31
	v_mov_b64_e32 v[196:197], v[44:45]
	v_mov_b64_e32 v[30:31], v[244:245]
	s_nop 0
	v_mov_b64_e32 v[44:45], v[192:193]
	v_mov_b64_e32 v[46:47], v[194:195]
	v_mul_f32_e32 v48, v42, v40
	v_mul_f32_e32 v50, v43, v40
	s_waitcnt lgkmcnt(0)
	v_lshlrev_b32_e32 v49, 16, v30
	v_lshlrev_b32_e32 v53, 16, v31
	v_mul_f32_e32 v2, 0xbfb8aa3b, v49
	v_mul_f32_e32 v0, 0xbfb8aa3b, v53
	v_exp_f32_e32 v2, v2
	v_exp_f32_e32 v0, v0
	v_and_b32_e32 v51, 0xffff0000, v30
	v_and_b32_e32 v31, 0xffff0000, v31
	v_add_f32_e32 v2, 1.0, v2
	v_add_f32_e32 v0, 1.0, v0
	v_rcp_f32_e32 v55, v2
	v_mul_f32_e32 v2, 0xbfb8aa3b, v51
	v_mov_b32_e32 v42, v45
	v_rcp_f32_e32 v45, v0
	v_mul_f32_e32 v0, 0xbfb8aa3b, v31
	v_exp_f32_e32 v2, v2
	v_exp_f32_e32 v0, v0
	v_mul_f32_e32 v30, v1, v40
	v_mov_b32_e32 v54, v44
	v_add_f32_e32 v2, 1.0, v2
	v_add_f32_e32 v0, 1.0, v0
	v_rcp_f32_e32 v43, v2
	v_rcp_f32_e32 v1, v0
	v_mov_b32_e32 v44, v46
	v_mov_b32_e32 v0, v47
	v_pk_mul_f32 v[48:49], v[54:55], v[48:49]
	v_pk_mul_f32 v[42:43], v[42:43], v[50:51]
	v_pk_mul_f32 v[44:45], v[44:45], v[52:53]
	v_pk_mul_f32 v[0:1], v[0:1], v[30:31]
	v_mov_b32_e32 v30, v48
	v_mov_b32_e32 v31, v42
	v_mov_b32_e32 v42, v49
	v_mov_b32_e32 v40, v44
	v_mov_b32_e32 v41, v0
	v_mov_b32_e32 v0, v45
	v_pk_mul_f32 v[30:31], v[30:31], v[42:43]
	v_pk_mul_f32 v[0:1], v[40:41], v[0:1]
	v_cvt_pk_bf16_f32 v30, v30, v31
	v_cvt_pk_bf16_f32 v31, v0, v1
	v_mov_b64_e32 v[198:199], v[30:31]
	s_nop 1
	v_permlane16_swap_b32_e32 v196, v198
	v_permlane16_swap_b32_e32 v197, v199
	global_store_dwordx4 v[28:29], v[196:199], off offset:1600
	v_mfma_f32_16x16x32_bf16 v[20:23], v[20:23], v[8:11], 0
	v_mfma_f32_16x16x32_bf16 v[20:23], v[24:27], v[56:59], v[20:23]
	ds_read_b64_tr_b16 v[26:27], v131 offset:2304
	ds_read_b64_tr_b16 v[24:25], v131
	v_mfma_f32_16x16x32_bf16 v[16:19], v[16:19], v[8:11], 0
	v_mfma_f32_16x16x32_bf16 v[16:19], v[32:35], v[56:59], v[16:19]
	s_nop 3
	v_cvt_pk_bf16_f32 v20, v20, v21
	v_cvt_pk_bf16_f32 v21, v22, v23
	v_mfma_f32_16x16x32_bf16 v[12:15], v[12:15], v[8:11], 0
	v_mfma_f32_16x16x32_bf16 v[4:7], v[4:7], v[8:11], 0
	v_cvt_pk_bf16_f32 v22, v16, v17
	v_cvt_pk_bf16_f32 v23, v18, v19
	v_mfma_f32_16x16x32_bf16 v[4:7], v[68:71], v[56:59], v[4:7]
	s_waitcnt lgkmcnt(0)
	v_mfma_f32_16x16x32_bf16 v[16:19], v[24:27], v[20:23], 0
	ds_read_b64_tr_b16 v[24:25], v131 offset:32
	ds_read_b64_tr_b16 v[26:27], v131 offset:2336
	ds_read_b64_tr_b16 v[28:29], v131 offset:64
	ds_read_b64_tr_b16 v[32:33], v131 offset:96
	ds_read_b64_tr_b16 v[30:31], v131 offset:2368
	ds_read_b64_tr_b16 v[34:35], v131 offset:2400
	v_mfma_f32_16x16x32_bf16 v[12:15], v[36:39], v[56:59], v[12:15]
	v_cndmask_b32_e64 v0, v4, 0, s[40:41]
	v_cndmask_b32_e64 v1, 0, v5, s[42:43]
	ds_read_b64_tr_b16 v[36:37], v131 offset:4608
	ds_read_b64_tr_b16 v[38:39], v131 offset:6912
	s_waitcnt lgkmcnt(0)
	v_mfma_f32_16x16x32_bf16 v[24:27], v[24:27], v[20:23], 0
	s_nop 1
	v_cvt_pk_bf16_f32 v4, v12, v13
	v_cvt_pk_bf16_f32 v5, v14, v15
	v_cndmask_b32_e64 v2, v6, 0, s[38:39]
	v_mfma_f32_16x16x32_bf16 v[28:31], v[28:31], v[20:23], 0
	v_cndmask_b32_e64 v7, v7, 0, vcc
	v_cvt_pk_bf16_f32 v6, v0, v1
	v_cvt_pk_bf16_f32 v7, v2, v7
	v_mfma_f32_16x16x32_bf16 v[12:15], v[32:35], v[20:23], 0
	ds_read_b64_tr_b16 v[20:21], v131 offset:6944
	v_mad_u64_u32 v[0:1], s[20:21], v126, s72, v[100:101]
	v_mfma_f32_16x16x32_bf16 v[32:35], v[36:39], v[4:7], v[16:19]
	s_nop 2
	ds_read_b64_tr_b16 v[18:19], v131 offset:4640
	ds_read_b64_tr_b16 v[16:17], v131 offset:4672
	s_waitcnt lgkmcnt(0)
	v_mfma_f32_16x16x32_bf16 v[20:23], v[18:21], v[4:7], v[24:27]
	ds_read_b64_tr_b16 v[18:19], v131 offset:6976
	s_nop 1
	ds_read_b64_tr_b16 v[24:25], v131 offset:4704
	ds_read_b64_tr_b16 v[26:27], v131 offset:7008
	s_waitcnt lgkmcnt(0)
; __device__ __forceinline__ unsigned pk2(float lo, float hi) { const f32x2_t v = {lo, hi}; const bf16x2_t b = __builtin_convertvector(v, bf16x2_t); return __builtin_bit_cast(unsigned, b); }
; __device__ __forceinline__ float sigmoidf_(float x) { return __builtin_amdgcn_rcpf(1.0f + __expf(-x)); }
; template <int KIND>
; __device__ __forceinline__ void w_m3_core(const bf16x8 (&Qf)[4][2], const bf16x8 (&Kf)[4][2], const bf16x8 (&Sf)[4][2], const LAS bf16_t* vT, float lg,
;                                           const bf16_t* gsrc, const float* nw, bf16_t* ydst, int lo, int fq) {
;     ...
;                 O[eb] = __builtin_amdgcn_mfma_f32_16x16x32_bf16(tr_frag(vT, 32 * kk2 + 4 * fq, 32 * kk2 + 16 + 4 * fq, 16 * eb, lo), Pf, O[eb], 0, 0, 0);
;         }
; #pragma unroll
;         for (int kk = 0; kk < 2; ++kk)
; #pragma unroll
;             for (int eb = 0; eb < 4; ++eb) O2[eb] = __builtin_amdgcn_mfma_f32_16x16x32_bf16(Sf[eb][kk], Qf[nb][kk], O2[eb], 0, 0, 0);
;         const float osc = KIND == 0 ? __expf((float)(16 * nb + lo + 1) * lg) : 1.0f;
; #pragma unroll
;         for (int eb = 0; eb < 4; ++eb) O[eb] = O[eb] + O2[eb] * osc;
;         float ss = 0.f;
; #pragma unroll
;         for (int eb = 0; eb < 4; ++eb) ss += (O[eb][0] * O[eb][0] + O[eb][1] * O[eb][1]) + (O[eb][2] * O[eb][2] + O[eb][3] * O[eb][3]);
;         { const int ln = (fq << 4) | lo; ss += bperm_f(ln ^ 16, ss); ss += bperm_f(ln ^ 32, ss); }
;         const float rs = rsqrtf(ss * (1.0f / 64.0f) + EPS);
;         const size_t n = 16 * nb + lo;
; #pragma unroll
;         for (int eb = 0; eb < 4; ++eb) { const int e0 = 16 * eb + 4 * fq;
;             const unsigned long long gw_ = *(const unsigned long long*)(gsrc + n * NIN + e0); const f32x4 w4 = *(const f32x4*)(nw + e0);
;             const float g0 = __uint_as_float((unsigned)gw_ << 16), g1 = __uint_as_float((unsigned)gw_ & 0xffff0000u), g2 = __uint_as_float((unsigned)(gw_ >> 32) << 16), g3 = __uint_as_float((unsigned)(gw_ >> 32) & 0xffff0000u);
;             const float o0 = O[eb][0] * rs * w4[0] * (g0 * sigmoidf_(g0)), o1 = O[eb][1] * rs * w4[1] * (g1 * sigmoidf_(g1));
;             const float o2 = O[eb][2] * rs * w4[2] * (g2 * sigmoidf_(g2)), o3 = O[eb][3] * rs * w4[3] * (g3 * sigmoidf_(g3));
;             *(unsigned long long*)(ydst + n * DM + e0) = (unsigned long long)pk2(o0, o1) | ((unsigned long long)pk2(o2, o3) << 32); }
	v_mfma_f32_16x16x32_bf16 v[16:19], v[16:19], v[4:7], v[28:31]
	v_mfma_f32_16x16x32_bf16 v[12:15], v[24:27], v[4:7], v[12:15]
	v_lshl_add_u64 v[6:7], v[0:1], 0, v[62:63]
	v_mov_b64_e32 v[44:45], v[246:247]
	v_mov_b64_e32 v[40:41], v[146:147]
	v_mov_b64_e32 v[42:43], v[148:149]
	v_mfma_f32_16x16x32_bf16 v[24:27], v[64:67], v[8:11], 0
	v_mfma_f32_16x16x32_bf16 v[28:31], v[72:75], v[8:11], 0
	v_mfma_f32_16x16x32_bf16 v[36:39], v[76:79], v[8:11], 0
	v_mfma_f32_16x16x32_bf16 v[8:11], v[80:83], v[8:11], 0
	v_mfma_f32_16x16x32_bf16 v[24:27], v[84:87], v[56:59], v[24:27]
	v_mfma_f32_16x16x32_bf16 v[8:11], v[96:99], v[56:59], v[8:11]
	v_mfma_f32_16x16x32_bf16 v[28:31], v[88:91], v[56:59], v[28:31]
	s_nop 5
	v_add_f32_e64 v26, v34, v26
	v_add_f32_e64 v27, v35, v27
	v_pk_add_f32 v[32:33], v[32:33], v[24:25]
	v_pk_add_f32 v[0:1], v[14:15], v[10:11]
	v_pk_add_f32 v[4:5], v[12:13], v[8:9]
	v_pk_mul_f32 v[8:9], v[26:27], v[26:27]
	v_pk_mul_f32 v[10:11], v[32:33], v[32:33]
	v_pk_add_f32 v[30:31], v[22:23], v[30:31]
	v_mfma_f32_16x16x32_bf16 v[22:25], v[92:95], v[56:59], v[36:39]
	v_add_f32_e64 v20, v20, v28
	v_add_f32_e64 v21, v21, v29
	v_pk_mov_b32 v[12:13], v[10:11], v[8:9] op_sel:[1,0]
	v_mov_b32_e32 v11, v9
	v_pk_add_f32 v[8:9], v[12:13], v[10:11]
	v_pk_mul_f32 v[10:11], v[30:31], v[30:31]
	v_pk_mul_f32 v[12:13], v[20:21], v[20:21]
	s_nop 0
	v_pk_add_f32 v[16:17], v[16:17], v[22:23]
	v_pk_mov_b32 v[14:15], v[12:13], v[10:11] op_sel:[1,0]
	v_mov_b32_e32 v13, v11
	v_pk_add_f32 v[10:11], v[14:15], v[12:13]
	v_mul_f32_e32 v2, v4, v4
	v_mul_f32_e32 v12, v5, v5
	v_pk_add_f32 v[8:9], v[8:9], v[8:9] op_sel:[0,1] op_sel_hi:[1,0]
	v_pk_add_f32 v[10:11], v[10:11], v[10:11] op_sel:[0,1] op_sel_hi:[1,0]
	v_pk_add_f32 v[18:19], v[18:19], v[24:25]
	v_mov_b32_e32 v9, v2
	v_mov_b32_e32 v11, v12
	v_mul_f32_e32 v2, v17, v17
	v_mul_f32_e32 v13, v0, v0
	v_pk_add_f32 v[8:9], v[8:9], v[10:11]
	v_pk_fma_f32 v[10:11], v[16:17], v[16:17], v[2:3] op_sel_hi:[1,1,0]
	v_mul_f32_e32 v2, v19, v19
	v_mul_f32_e32 v14, v1, v1
	v_mov_b32_e32 v11, v13
	v_pk_fma_f32 v[12:13], v[18:19], v[18:19], v[2:3] op_sel_hi:[1,1,0]
	s_waitcnt lgkmcnt(0)
	v_and_b32_e32 v15, 0xffff0000, v45
	v_mov_b32_e32 v13, v14
	v_pk_add_f32 v[10:11], v[10:11], v[12:13]
	v_lshlrev_b32_e32 v12, 16, v44
	v_pk_add_f32 v[8:9], v[8:9], v[10:11]
	v_and_b32_e32 v13, 0xffff0000, v44
	v_add_f32_e32 v2, v8, v9
	ds_bpermute_b32 v8, v130, v2
	v_mul_f32_e32 v9, 0xbfb8aa3b, v13
	v_exp_f32_e32 v9, v9
	v_lshlrev_b32_e32 v14, 16, v45
	s_waitcnt lgkmcnt(0)
	v_add_f32_e32 v2, v2, v8
	ds_bpermute_b32 v8, v129, v2
	s_waitcnt lgkmcnt(0)
	v_add_f32_e32 v2, v2, v8
	v_fmamk_f32 v2, v2, 0x3c800000, v200
	v_mul_f32_e32 v8, 0x4b800000, v2
	v_cmp_gt_f32_e32 vcc, s29, v2
	s_nop 1
	v_cndmask_b32_e32 v2, v2, v8, vcc
	v_rsq_f32_e32 v2, v2
	s_nop 0
	v_mul_f32_e32 v8, 0x45800000, v2
	v_cndmask_b32_e32 v8, v2, v8, vcc
	v_lshlrev_b32_e32 v2, 11, v126
	v_lshl_add_u64 v[10:11], s[46:47], 0, v[2:3]
	v_mul_f32_e32 v2, 0xbfb8aa3b, v12
	v_exp_f32_e32 v2, v2
	v_pk_mul_f32 v[24:25], v[32:33], v[8:9] op_sel_hi:[1,0]
	v_lshl_add_u64 v[10:11], v[10:11], 0, v[62:63]
	v_lshl_add_u64 v[10:11], v[10:11], 0, v[142:143]
	v_pk_mul_f32 v[24:25], v[40:41], v[24:25]
	v_add_f32_e32 v2, 1.0, v2
	v_rcp_f32_e32 v22, v2
	v_add_f32_e32 v2, 1.0, v9
	v_rcp_f32_e32 v23, v2
	v_mul_f32_e32 v2, 0xbfb8aa3b, v14
	v_exp_f32_e32 v2, v2
	v_mul_f32_e32 v9, 0xbfb8aa3b, v15
	v_exp_f32_e32 v9, v9
	v_pk_mul_f32 v[12:13], v[22:23], v[12:13]
	v_add_f32_e32 v2, 1.0, v2
	v_rcp_f32_e32 v22, v2
	v_add_f32_e32 v2, 1.0, v9
	v_rcp_f32_e32 v23, v2
	v_pk_mul_f32 v[12:13], v[12:13], v[24:25]
	v_pk_mul_f32 v[24:25], v[26:27], v[8:9] op_sel_hi:[1,0]
	v_cvt_pk_bf16_f32 v12, v12, v13
	v_pk_mul_f32 v[24:25], v[42:43], v[24:25]
	v_pk_mul_f32 v[14:15], v[22:23], v[14:15]
	v_pk_mul_f32 v[20:21], v[20:21], v[8:9] op_sel_hi:[1,0]
	v_pk_mul_f32 v[14:15], v[14:15], v[24:25]
	v_pk_mul_f32 v[24:25], v[30:31], v[8:9] op_sel_hi:[1,0]
	v_cvt_pk_bf16_f32 v13, v14, v15
	v_mov_b64_e32 v[196:197], v[12:13]
	v_mov_b64_e32 v[22:23], v[248:249]
	s_nop 0
	v_mov_b64_e32 v[12:13], v[150:151]
	v_mov_b64_e32 v[14:15], v[152:153]
	v_mul_f32_e32 v16, v16, v8
	v_mul_f32_e32 v18, v18, v8
	v_mul_f32_e32 v4, v4, v8
	v_mul_f32_e32 v0, v0, v8
	s_waitcnt lgkmcnt(0)
; __device__ __forceinline__ unsigned pk2(float lo, float hi) { const f32x2_t v = {lo, hi}; const bf16x2_t b = __builtin_convertvector(v, bf16x2_t); return __builtin_bit_cast(unsigned, b); }
; __device__ __forceinline__ float sigmoidf_(float x) { return __builtin_amdgcn_rcpf(1.0f + __expf(-x)); }
; template <int KIND>
; __device__ __forceinline__ void w_m3_core(const bf16x8 (&Qf)[4][2], const bf16x8 (&Kf)[4][2], const bf16x8 (&Sf)[4][2], const LAS bf16_t* vT, float lg,
;                                           const bf16_t* gsrc, const float* nw, bf16_t* ydst, int lo, int fq) {
;     ...
;         for (int eb = 0; eb < 4; ++eb) { const int e0 = 16 * eb + 4 * fq;
;             const unsigned long long gw_ = *(const unsigned long long*)(gsrc + n * NIN + e0); const f32x4 w4 = *(const f32x4*)(nw + e0);
;             const float g0 = __uint_as_float((unsigned)gw_ << 16), g1 = __uint_as_float((unsigned)gw_ & 0xffff0000u), g2 = __uint_as_float((unsigned)(gw_ >> 32) << 16), g3 = __uint_as_float((unsigned)(gw_ >> 32) & 0xffff0000u);
;             const float o0 = O[eb][0] * rs * w4[0] * (g0 * sigmoidf_(g0)), o1 = O[eb][1] * rs * w4[1] * (g1 * sigmoidf_(g1));
;             const float o2 = O[eb][2] * rs * w4[2] * (g2 * sigmoidf_(g2)), o3 = O[eb][3] * rs * w4[3] * (g3 * sigmoidf_(g3));
;             *(unsigned long long*)(ydst + n * DM + e0) = (unsigned long long)pk2(o0, o1) | ((unsigned long long)pk2(o2, o3) << 32); }
	v_lshlrev_b32_e32 v26, 16, v22
	v_and_b32_e32 v27, 0xffff0000, v22
	v_lshlrev_b32_e32 v22, 16, v23
	v_and_b32_e32 v23, 0xffff0000, v23
	v_mul_f32_e32 v2, 0xbfb8aa3b, v26
	v_mul_f32_e32 v9, 0xbfb8aa3b, v27
	v_mul_f32_e32 v28, 0xbfb8aa3b, v22
	v_mul_f32_e32 v29, 0xbfb8aa3b, v23
	v_exp_f32_e32 v2, v2
	v_exp_f32_e32 v9, v9
	v_exp_f32_e32 v28, v28
	v_exp_f32_e32 v29, v29
	v_add_f32_e32 v2, 1.0, v2
	v_add_f32_e32 v9, 1.0, v9
	v_add_f32_e32 v30, 1.0, v28
	v_add_f32_e32 v31, 1.0, v29
	v_rcp_f32_e32 v28, v2
	v_rcp_f32_e32 v29, v9
	v_rcp_f32_e32 v30, v30
	v_rcp_f32_e32 v31, v31
	v_pk_mul_f32 v[12:13], v[12:13], v[20:21]
	v_pk_mul_f32 v[14:15], v[14:15], v[24:25]
	v_pk_mul_f32 v[20:21], v[28:29], v[26:27]
	v_pk_mul_f32 v[22:23], v[30:31], v[22:23]
	v_pk_mul_f32 v[12:13], v[20:21], v[12:13]
	v_pk_mul_f32 v[14:15], v[22:23], v[14:15]
	v_cvt_pk_bf16_f32 v12, v12, v13
	v_cvt_pk_bf16_f32 v13, v14, v15
	v_mov_b64_e32 v[198:199], v[12:13]
	s_nop 1
	v_permlane16_swap_b32_e32 v196, v198
	v_permlane16_swap_b32_e32 v197, v199
	global_store_dwordx4 v[10:11], v[196:199], off offset:1536
	v_mov_b64_e32 v[20:21], v[250:251]
	s_nop 0
	v_mov_b64_e32 v[12:13], v[188:189]
	v_mov_b64_e32 v[14:15], v[190:191]
	v_mul_f32_e32 v22, v17, v8
	v_mul_f32_e32 v24, v19, v8
	s_waitcnt lgkmcnt(0)
	v_lshlrev_b32_e32 v17, 16, v20
	v_and_b32_e32 v23, 0xffff0000, v20
	v_lshlrev_b32_e32 v19, 16, v21
	v_and_b32_e32 v25, 0xffff0000, v21
	v_mov_b32_e32 v20, v13
	v_mov_b32_e32 v26, v15
	v_mul_f32_e32 v2, 0xbfb8aa3b, v17
	v_mul_f32_e32 v9, 0xbfb8aa3b, v23
	v_mul_f32_e32 v13, 0xbfb8aa3b, v19
	v_mul_f32_e32 v15, 0xbfb8aa3b, v25
	v_exp_f32_e32 v2, v2
	v_exp_f32_e32 v9, v9
	v_exp_f32_e32 v13, v13
	v_exp_f32_e32 v15, v15
	v_add_f32_e32 v2, 1.0, v2
	v_add_f32_e32 v9, 1.0, v9
	v_add_f32_e32 v27, 1.0, v13
	v_add_f32_e32 v28, 1.0, v15
	v_rcp_f32_e32 v13, v2
	v_rcp_f32_e32 v21, v9
	v_rcp_f32_e32 v15, v27
	v_rcp_f32_e32 v27, v28
	v_pk_mul_f32 v[12:13], v[12:13], v[16:17]
	v_pk_mul_f32 v[16:17], v[20:21], v[22:23]
	v_pk_mul_f32 v[14:15], v[14:15], v[18:19]
	v_pk_mul_f32 v[18:19], v[26:27], v[24:25]
	v_mov_b32_e32 v20, v12
	v_mov_b32_e32 v21, v16
	v_mov_b32_e32 v16, v13
	v_mov_b32_e32 v12, v14
	v_mov_b32_e32 v13, v18
	v_mov_b32_e32 v18, v15
	v_pk_mul_f32 v[14:15], v[20:21], v[16:17]
	v_pk_mul_f32 v[12:13], v[12:13], v[18:19]
	v_cvt_pk_bf16_f32 v14, v14, v15
	v_cvt_pk_bf16_f32 v15, v12, v13
	v_mov_b64_e32 v[196:197], v[14:15]
	v_mov_b64_e32 v[6:7], v[252:253]
	s_nop 0
	v_mov_b64_e32 v[12:13], v[192:193]
	v_mov_b64_e32 v[14:15], v[194:195]
	v_mul_f32_e32 v16, v5, v8
	v_mul_f32_e32 v8, v1, v8
	s_waitcnt lgkmcnt(0)
	v_lshlrev_b32_e32 v5, 16, v6
	v_and_b32_e32 v17, 0xffff0000, v6
	v_lshlrev_b32_e32 v1, 16, v7
	v_and_b32_e32 v9, 0xffff0000, v7
	v_mov_b32_e32 v6, v12
	v_mov_b32_e32 v12, v13
	v_mov_b32_e32 v18, v15
	v_mul_f32_e32 v2, 0xbfb8aa3b, v5
	v_mul_f32_e32 v7, 0xbfb8aa3b, v17
	v_mul_f32_e32 v13, 0xbfb8aa3b, v1
	v_mul_f32_e32 v15, 0xbfb8aa3b, v9
	v_exp_f32_e32 v2, v2
	v_exp_f32_e32 v7, v7
	v_exp_f32_e32 v13, v13
	v_exp_f32_e32 v15, v15
	v_add_f32_e32 v2, 1.0, v2
	v_add_f32_e32 v19, 1.0, v7
	v_add_f32_e32 v20, 1.0, v13
	v_add_f32_e32 v21, 1.0, v15
	v_rcp_f32_e32 v7, v2
	v_rcp_f32_e32 v13, v19
	v_rcp_f32_e32 v15, v20
	v_rcp_f32_e32 v19, v21
	v_pk_mul_f32 v[4:5], v[6:7], v[4:5]
	v_pk_mul_f32 v[6:7], v[12:13], v[16:17]
	v_pk_mul_f32 v[0:1], v[14:15], v[0:1]
	v_pk_mul_f32 v[8:9], v[18:19], v[8:9]
	v_mov_b32_e32 v12, v4
	v_mov_b32_e32 v13, v6
	v_mov_b32_e32 v6, v5
	v_mov_b32_e32 v4, v0
	v_mov_b32_e32 v5, v8
	v_mov_b32_e32 v8, v1
	v_pk_mul_f32 v[0:1], v[12:13], v[6:7]
	v_pk_mul_f32 v[4:5], v[4:5], v[8:9]
	v_cvt_pk_bf16_f32 v0, v0, v1
	v_cvt_pk_bf16_f32 v1, v4, v5
	v_mov_b64_e32 v[198:199], v[0:1]
	s_nop 1
	v_permlane16_swap_b32_e32 v196, v198
	v_permlane16_swap_b32_e32 v197, v199
	global_store_dwordx4 v[10:11], v[196:199], off offset:1600
	s_waitcnt lgkmcnt(0)
